# GEMM loops re-scheduled into 4 merged phases (32 MFMAs per segment, 8 barriers per K-pair, DMA order P8prev,P1|P2,P3|P4,P5|P6,P7, vmcnt 8/6/8/6)
# speedup vs baseline: 1.0149x; 1.0061x over previous
; #define PG8_STAGE(bufoff, gbase, voff) do { _Pragma("unroll") for (int _i = 0; _i < 2; ++_i) \
;         __builtin_amdgcn_global_load_lds((const unsigned*)((const char*)(gbase) + (voff)[_i]), (PG8_LAS unsigned*)(lds + (bufoff) + ldsw + _i * 8192), 16, 0, 0); } while (0)
; #define PG8_LDA(dst, b, h) do { _Pragma("unroll") for (int m = 0; m < 4; ++m) _Pragma("unroll") for (int k = 0; k < 2; ++k) dst[m][k] = *(const PG8_LAS bf16x8*)(lds + PG8_SA(b, h) + aoff + m * 2048 + k * 1024); } while (0)
; #define PG8_LDB(dst, b, h) do { _Pragma("unroll") for (int n = 0; n < 2; ++n) _Pragma("unroll") for (int k = 0; k < 2; ++k) dst[n][k] = *(const PG8_LAS bf16x8*)(lds + PG8_SB(b, h) + boff + n * 2048 + k * 1024); } while (0)
; #define PG8_MMA(ai, bj, At, Bt) do { __builtin_amdgcn_s_setprio(1); _Pragma("unroll") for (int m = 0; m < 4; ++m) _Pragma("unroll") for (int n = 0; n < 2; ++n) _Pragma("unroll") for (int k = 0; k < 2; ++k) \
;         acc[ai][bj][m][n] = __builtin_amdgcn_mfma_f32_16x16x32_bf16(Bt[n][k], At[m][k], acc[ai][bj][m][n], 0, 0, 0); __builtin_amdgcn_s_setprio(0); } while (0)
; template <class Epi, class Sched, bool STAMP = false>
; __device__ __forceinline__ void gemm_phase(PG8_LAS unsigned char* lds, const Gemm g, const Sched& S, const Epi& E, unsigned long long* stamps) {
;     ...
;         for (int t = 0; t < nt; t += 2) {
;             const bool last = (t == nt - 2);
;             const char* a1 = cA + (size_t)(t + 1) * kstep;
;             const char* a2 = last ? nA : cA + (size_t)(t + 2) * kstep; const char* b2 = last ? nB : cB + (size_t)(t + 2) * kstep;
;             const char* a3 = a2 + kstep; const char* b3 = b2 + kstep;
;             if (last && has_next) S.a_ready(nxt);
;             PG8_LDB(B0, 0, 0); PG8_SCHED; PG8_LDA(At, 0, 0); PG8_STAGE(PG8_SA(1, 1), a1 + hstep, voffA);
;             PG8_WAIT_L(8); PG8_BAR; PG8_WAIT_L(0); PG8_MMA(0, 0, At, B0); PG8_BAR; PG8_SCHED;
;             PG8_LDB(B1, 0, 1); PG8_STAGE(PG8_SB(0, 0), b2, voffB);
;             PG8_BAR; PG8_WAIT_L(0); PG8_MMA(0, 1, At, B1); PG8_BAR;
;             PG8_LDA(At, 0, 1); PG8_STAGE(PG8_SA(0, 0), a2, voffA);
;             PG8_BAR; PG8_WAIT_L(0); PG8_MMA(1, 0, At, B0); PG8_BAR; PG8_SCHED;
;             PG8_STAGE(PG8_SB(0, 1), b2 + hstep, voffB);
;             PG8_WAIT_V(6); PG8_BAR; PG8_MMA(1, 1, At, B1); PG8_BAR;
;     ...
;             PG8_STAGE(PG8_SB(1, 1), b3 + hstep, voffB);
.LBB0_62:
	s_add_u32 s75, s16, 0x100
	s_addc_u32 s76, s17, 0
	s_mov_b32 s77, -2
	s_cmp_eq_u32 s59, s99
	s_cbranch_scc1 .Lgu1_half_loop_z
	s_add_u32 s100, s75, 0x43f80
	s_addc_u32 s101, s76, 0
	s_mov_b32 m0, s65
	s_nop 0
	global_load_lds_dwordx4 v130, s[100:101]
	s_mov_b32 m0, s66
	s_nop 0
	global_load_lds_dwordx4 v128, s[100:101]
	ds_read_b128 v[140:143], v148
	ds_read_b128 v[166:169], v149
	ds_read_b128 v[170:173], v150
	ds_read_b128 v[174:177], v151
	s_add_u32 s16, s14, 0x100
	s_addc_u32 s17, s15, 0
	s_cmp_eq_u32 s77, 12
	s_cselect_b32 s29, s5, s17
	s_cselect_b32 s28, s4, s16
	s_cselect_b32 s19, s1, s76
	s_cselect_b32 s18, s0, s75
	s_mov_b32 m0, s68
	ds_read_b128 v[178:181], v146
	ds_read_b128 v[182:185], v146 offset:1024
	ds_read_b128 v[186:189], v146 offset:2048
	ds_read_b128 v[190:193], v146 offset:3072
	ds_read_b128 v[194:197], v146 offset:4096
	ds_read_b128 v[198:201], v146 offset:5120
	ds_read_b128 v[202:205], v146 offset:6144
	ds_read_b128 v[206:209], v146 offset:7168
	global_load_lds_dwordx4 v132, s[14:15]
	s_mov_b32 m0, s69
	s_nop 0
	global_load_lds_dwordx4 v134, s[14:15]
	ds_read_b128 v[210:213], v152
	ds_read_b128 v[214:217], v153
	ds_read_b128 v[218:221], v154
	ds_read_b128 v[222:225], v155
	s_waitcnt vmcnt(8)
	s_waitcnt lgkmcnt(0)
	s_barrier
	s_setprio 1
	v_mfma_f32_16x16x32_bf16 v[124:127], v[140:143], v[178:181], 0
	v_mfma_f32_16x16x32_bf16 v[120:123], v[170:173], v[178:181], 0
	v_mfma_f32_16x16x32_bf16 v[108:111], v[140:143], v[186:189], 0
	v_mfma_f32_16x16x32_bf16 v[104:107], v[170:173], v[186:189], 0
	v_mfma_f32_16x16x32_bf16 v[92:95], v[140:143], v[194:197], 0
	v_mfma_f32_16x16x32_bf16 v[88:91], v[170:173], v[194:197], 0
	v_mfma_f32_16x16x32_bf16 v[76:79], v[140:143], v[202:205], 0
	v_mfma_f32_16x16x32_bf16 v[72:75], v[170:173], v[202:205], 0
	v_mfma_f32_16x16x32_bf16 v[124:127], v[166:169], v[182:185], v[124:127]
	v_mfma_f32_16x16x32_bf16 v[120:123], v[174:177], v[182:185], v[120:123]
	v_mfma_f32_16x16x32_bf16 v[108:111], v[166:169], v[190:193], v[108:111]
	v_mfma_f32_16x16x32_bf16 v[104:107], v[174:177], v[190:193], v[104:107]
	v_mfma_f32_16x16x32_bf16 v[92:95], v[166:169], v[198:201], v[92:95]
	v_mfma_f32_16x16x32_bf16 v[88:91], v[174:177], v[198:201], v[88:91]
	v_mfma_f32_16x16x32_bf16 v[76:79], v[166:169], v[206:209], v[76:79]
	v_mfma_f32_16x16x32_bf16 v[72:75], v[174:177], v[206:209], v[72:75]
	v_mfma_f32_16x16x32_bf16 v[116:119], v[210:213], v[178:181], 0
	v_mfma_f32_16x16x32_bf16 v[112:115], v[218:221], v[178:181], 0
	v_mfma_f32_16x16x32_bf16 v[100:103], v[210:213], v[186:189], 0
	v_mfma_f32_16x16x32_bf16 v[96:99], v[218:221], v[186:189], 0
	v_mfma_f32_16x16x32_bf16 v[84:87], v[210:213], v[194:197], 0
	v_mfma_f32_16x16x32_bf16 v[80:83], v[218:221], v[194:197], 0
	v_mfma_f32_16x16x32_bf16 v[68:71], v[210:213], v[202:205], 0
	v_mfma_f32_16x16x32_bf16 v[64:67], v[218:221], v[202:205], 0
	v_mfma_f32_16x16x32_bf16 v[116:119], v[214:217], v[182:185], v[116:119]
	v_mfma_f32_16x16x32_bf16 v[112:115], v[222:225], v[182:185], v[112:115]
	v_mfma_f32_16x16x32_bf16 v[100:103], v[214:217], v[190:193], v[100:103]
	v_mfma_f32_16x16x32_bf16 v[96:99], v[222:225], v[190:193], v[96:99]
	v_mfma_f32_16x16x32_bf16 v[84:87], v[214:217], v[198:201], v[84:87]
	v_mfma_f32_16x16x32_bf16 v[80:83], v[222:225], v[198:201], v[80:83]
	v_mfma_f32_16x16x32_bf16 v[68:71], v[214:217], v[206:209], v[68:71]
	v_mfma_f32_16x16x32_bf16 v[64:67], v[222:225], v[206:209], v[64:67]
	s_setprio 0
	s_barrier
	s_mov_b32 m0, s52
	s_nop 0
	global_load_lds_dwordx4 v130, s[18:19]
	s_mov_b32 m0, s53
	s_nop 0
	global_load_lds_dwordx4 v128, s[18:19]
	s_mov_b32 m0, s33
	ds_read_b128 v[178:181], v146 offset:16384
	ds_read_b128 v[182:185], v146 offset:17408
	ds_read_b128 v[186:189], v146 offset:18432
	ds_read_b128 v[190:193], v146 offset:19456
	ds_read_b128 v[194:197], v146 offset:20480
	ds_read_b128 v[198:201], v146 offset:21504
	ds_read_b128 v[202:205], v146 offset:22528
	ds_read_b128 v[206:209], v146 offset:23552
	global_load_lds_dwordx4 v130, s[28:29]
	s_mov_b32 m0, s54
	s_nop 0
	global_load_lds_dwordx4 v128, s[28:29]
	s_waitcnt vmcnt(6)
	s_waitcnt lgkmcnt(0)
	s_barrier
	s_setprio 1
	v_mfma_f32_16x16x32_bf16 v[60:63], v[140:143], v[178:181], 0
	v_mfma_f32_16x16x32_bf16 v[56:59], v[170:173], v[178:181], 0
	v_mfma_f32_16x16x32_bf16 v[44:47], v[140:143], v[186:189], 0
	v_mfma_f32_16x16x32_bf16 v[40:43], v[170:173], v[186:189], 0
	v_mfma_f32_16x16x32_bf16 v[28:31], v[140:143], v[194:197], 0
	v_mfma_f32_16x16x32_bf16 v[24:27], v[170:173], v[194:197], 0
	v_mfma_f32_16x16x32_bf16 v[12:15], v[140:143], v[202:205], 0
	v_mfma_f32_16x16x32_bf16 v[8:11], v[170:173], v[202:205], 0
	v_mfma_f32_16x16x32_bf16 v[60:63], v[166:169], v[182:185], v[60:63]
	v_mfma_f32_16x16x32_bf16 v[56:59], v[174:177], v[182:185], v[56:59]
	v_mfma_f32_16x16x32_bf16 v[44:47], v[166:169], v[190:193], v[44:47]
	v_mfma_f32_16x16x32_bf16 v[40:43], v[174:177], v[190:193], v[40:43]
	v_mfma_f32_16x16x32_bf16 v[28:31], v[166:169], v[198:201], v[28:31]
	v_mfma_f32_16x16x32_bf16 v[24:27], v[174:177], v[198:201], v[24:27]
	v_mfma_f32_16x16x32_bf16 v[12:15], v[166:169], v[206:209], v[12:15]
	v_mfma_f32_16x16x32_bf16 v[8:11], v[174:177], v[206:209], v[8:11]
	v_mfma_f32_16x16x32_bf16 v[52:55], v[210:213], v[178:181], 0
	v_mfma_f32_16x16x32_bf16 v[48:51], v[218:221], v[178:181], 0
	v_mfma_f32_16x16x32_bf16 v[36:39], v[210:213], v[186:189], 0
	v_mfma_f32_16x16x32_bf16 v[32:35], v[218:221], v[186:189], 0
	v_mfma_f32_16x16x32_bf16 v[20:23], v[210:213], v[194:197], 0
	v_mfma_f32_16x16x32_bf16 v[16:19], v[218:221], v[194:197], 0
	v_mfma_f32_16x16x32_bf16 v[4:7], v[210:213], v[202:205], 0
	v_mfma_f32_16x16x32_bf16 v[0:3], v[218:221], v[202:205], 0
	v_mfma_f32_16x16x32_bf16 v[52:55], v[214:217], v[182:185], v[52:55]
	v_mfma_f32_16x16x32_bf16 v[48:51], v[222:225], v[182:185], v[48:51]
	v_mfma_f32_16x16x32_bf16 v[36:39], v[214:217], v[190:193], v[36:39]
	v_mfma_f32_16x16x32_bf16 v[32:35], v[222:225], v[190:193], v[32:35]
	v_mfma_f32_16x16x32_bf16 v[20:23], v[214:217], v[198:201], v[20:23]
	v_mfma_f32_16x16x32_bf16 v[16:19], v[222:225], v[198:201], v[16:19]
	v_mfma_f32_16x16x32_bf16 v[4:7], v[214:217], v[206:209], v[4:7]
	v_mfma_f32_16x16x32_bf16 v[0:3], v[222:225], v[206:209], v[0:3]
	s_setprio 0
	s_barrier
	s_branch .Lzp1_mid
; #define PG8_STAGE(bufoff, gbase, voff) do { _Pragma("unroll") for (int _i = 0; _i < 2; ++_i) \
;         __builtin_amdgcn_global_load_lds((const unsigned*)((const char*)(gbase) + (voff)[_i]), (PG8_LAS unsigned*)(lds + (bufoff) + ldsw + _i * 8192), 16, 0, 0); } while (0)
; #define PG8_LDA(dst, b, h) do { _Pragma("unroll") for (int m = 0; m < 4; ++m) _Pragma("unroll") for (int k = 0; k < 2; ++k) dst[m][k] = *(const PG8_LAS bf16x8*)(lds + PG8_SA(b, h) + aoff + m * 2048 + k * 1024); } while (0)
; #define PG8_LDB(dst, b, h) do { _Pragma("unroll") for (int n = 0; n < 2; ++n) _Pragma("unroll") for (int k = 0; k < 2; ++k) dst[n][k] = *(const PG8_LAS bf16x8*)(lds + PG8_SB(b, h) + boff + n * 2048 + k * 1024); } while (0)
; #define PG8_MMA(ai, bj, At, Bt) do { __builtin_amdgcn_s_setprio(1); _Pragma("unroll") for (int m = 0; m < 4; ++m) _Pragma("unroll") for (int n = 0; n < 2; ++n) _Pragma("unroll") for (int k = 0; k < 2; ++k) \
;         acc[ai][bj][m][n] = __builtin_amdgcn_mfma_f32_16x16x32_bf16(Bt[n][k], At[m][k], acc[ai][bj][m][n], 0, 0, 0); __builtin_amdgcn_s_setprio(0); } while (0)
; #define PG8_WAIT_V(n) asm volatile("s_waitcnt vmcnt(" #n ")" ::: "memory")
; template <class Epi, class Sched, bool STAMP = false>
; __device__ __forceinline__ void gemm_phase(PG8_LAS unsigned char* lds, const Gemm g, const Sched& S, const Epi& E, unsigned long long* stamps) {
;     ...
;             const bool last = (t == nt - 2);
;             const char* a1 = cA + (size_t)(t + 1) * kstep;
;             const char* a2 = last ? nA : cA + (size_t)(t + 2) * kstep; const char* b2 = last ? nB : cB + (size_t)(t + 2) * kstep;
;             const char* a3 = a2 + kstep; const char* b3 = b2 + kstep;
;             if (last && has_next) S.a_ready(nxt);
;             PG8_LDB(B0, 0, 0); PG8_SCHED; PG8_LDA(At, 0, 0); PG8_STAGE(PG8_SA(1, 1), a1 + hstep, voffA);
;             PG8_WAIT_L(8); PG8_BAR; PG8_WAIT_L(0); PG8_MMA(0, 0, At, B0); PG8_BAR; PG8_SCHED;
;             PG8_LDB(B1, 0, 1); PG8_STAGE(PG8_SB(0, 0), b2, voffB);
;             PG8_BAR; PG8_WAIT_L(0); PG8_MMA(0, 1, At, B1); PG8_BAR;
;             PG8_LDA(At, 0, 1); PG8_STAGE(PG8_SA(0, 0), a2, voffA);
;             PG8_BAR; PG8_WAIT_L(0); PG8_MMA(1, 0, At, B0); PG8_BAR; PG8_SCHED;
;             PG8_STAGE(PG8_SB(0, 1), b2 + hstep, voffB);
;             PG8_WAIT_V(6); PG8_BAR; PG8_MMA(1, 1, At, B1); PG8_BAR;
.LBB0_63:
	s_add_u32 s100, s75, 0x43f80
	s_addc_u32 s101, s76, 0
	s_mov_b32 m0, s65
	s_nop 0
	global_load_lds_dwordx4 v130, s[100:101]
	s_mov_b32 m0, s66
	s_nop 0
	global_load_lds_dwordx4 v128, s[100:101]
	ds_read_b128 v[140:143], v148
	ds_read_b128 v[166:169], v149
	ds_read_b128 v[170:173], v150
	ds_read_b128 v[174:177], v151
	s_add_u32 s16, s14, 0x100
	s_addc_u32 s17, s15, 0
	s_cmp_eq_u32 s77, 12
	s_cselect_b32 s29, s5, s17
	s_cselect_b32 s28, s4, s16
	s_cselect_b32 s19, s1, s76
	s_cselect_b32 s18, s0, s75
	s_mov_b32 m0, s68
	ds_read_b128 v[178:181], v146
	ds_read_b128 v[182:185], v146 offset:1024
	ds_read_b128 v[186:189], v146 offset:2048
	ds_read_b128 v[190:193], v146 offset:3072
	ds_read_b128 v[194:197], v146 offset:4096
	ds_read_b128 v[198:201], v146 offset:5120
	ds_read_b128 v[202:205], v146 offset:6144
	ds_read_b128 v[206:209], v146 offset:7168
	global_load_lds_dwordx4 v132, s[14:15]
	s_mov_b32 m0, s69
	s_nop 0
	global_load_lds_dwordx4 v134, s[14:15]
	ds_read_b128 v[210:213], v152
	ds_read_b128 v[214:217], v153
	ds_read_b128 v[218:221], v154
	ds_read_b128 v[222:225], v155
	s_waitcnt vmcnt(8)
	s_waitcnt lgkmcnt(0)
	s_barrier
	s_setprio 1
	v_mfma_f32_16x16x32_bf16 v[124:127], v[140:143], v[178:181], v[124:127]
	v_mfma_f32_16x16x32_bf16 v[120:123], v[170:173], v[178:181], v[120:123]
	v_mfma_f32_16x16x32_bf16 v[108:111], v[140:143], v[186:189], v[108:111]
	v_mfma_f32_16x16x32_bf16 v[104:107], v[170:173], v[186:189], v[104:107]
	v_mfma_f32_16x16x32_bf16 v[92:95], v[140:143], v[194:197], v[92:95]
	v_mfma_f32_16x16x32_bf16 v[88:91], v[170:173], v[194:197], v[88:91]
	v_mfma_f32_16x16x32_bf16 v[76:79], v[140:143], v[202:205], v[76:79]
	v_mfma_f32_16x16x32_bf16 v[72:75], v[170:173], v[202:205], v[72:75]
	v_mfma_f32_16x16x32_bf16 v[124:127], v[166:169], v[182:185], v[124:127]
	v_mfma_f32_16x16x32_bf16 v[120:123], v[174:177], v[182:185], v[120:123]
	v_mfma_f32_16x16x32_bf16 v[108:111], v[166:169], v[190:193], v[108:111]
	v_mfma_f32_16x16x32_bf16 v[104:107], v[174:177], v[190:193], v[104:107]
	v_mfma_f32_16x16x32_bf16 v[92:95], v[166:169], v[198:201], v[92:95]
	v_mfma_f32_16x16x32_bf16 v[88:91], v[174:177], v[198:201], v[88:91]
	v_mfma_f32_16x16x32_bf16 v[76:79], v[166:169], v[206:209], v[76:79]
	v_mfma_f32_16x16x32_bf16 v[72:75], v[174:177], v[206:209], v[72:75]
	v_mfma_f32_16x16x32_bf16 v[116:119], v[210:213], v[178:181], v[116:119]
	v_mfma_f32_16x16x32_bf16 v[112:115], v[218:221], v[178:181], v[112:115]
	v_mfma_f32_16x16x32_bf16 v[100:103], v[210:213], v[186:189], v[100:103]
	v_mfma_f32_16x16x32_bf16 v[96:99], v[218:221], v[186:189], v[96:99]
	v_mfma_f32_16x16x32_bf16 v[84:87], v[210:213], v[194:197], v[84:87]
	v_mfma_f32_16x16x32_bf16 v[80:83], v[218:221], v[194:197], v[80:83]
	v_mfma_f32_16x16x32_bf16 v[68:71], v[210:213], v[202:205], v[68:71]
	v_mfma_f32_16x16x32_bf16 v[64:67], v[218:221], v[202:205], v[64:67]
	v_mfma_f32_16x16x32_bf16 v[116:119], v[214:217], v[182:185], v[116:119]
	v_mfma_f32_16x16x32_bf16 v[112:115], v[222:225], v[182:185], v[112:115]
	v_mfma_f32_16x16x32_bf16 v[100:103], v[214:217], v[190:193], v[100:103]
	v_mfma_f32_16x16x32_bf16 v[96:99], v[222:225], v[190:193], v[96:99]
	v_mfma_f32_16x16x32_bf16 v[84:87], v[214:217], v[198:201], v[84:87]
	v_mfma_f32_16x16x32_bf16 v[80:83], v[222:225], v[198:201], v[80:83]
	v_mfma_f32_16x16x32_bf16 v[68:71], v[214:217], v[206:209], v[68:71]
	v_mfma_f32_16x16x32_bf16 v[64:67], v[222:225], v[206:209], v[64:67]
	s_setprio 0
	s_barrier
	s_mov_b32 m0, s52
	s_nop 0
	global_load_lds_dwordx4 v130, s[18:19]
	s_mov_b32 m0, s53
	s_nop 0
	global_load_lds_dwordx4 v128, s[18:19]
	s_mov_b32 m0, s33
	ds_read_b128 v[178:181], v146 offset:16384
	ds_read_b128 v[182:185], v146 offset:17408
	ds_read_b128 v[186:189], v146 offset:18432
	ds_read_b128 v[190:193], v146 offset:19456
	ds_read_b128 v[194:197], v146 offset:20480
	ds_read_b128 v[198:201], v146 offset:21504
	ds_read_b128 v[202:205], v146 offset:22528
	ds_read_b128 v[206:209], v146 offset:23552
	global_load_lds_dwordx4 v130, s[28:29]
	s_mov_b32 m0, s54
	s_nop 0
	global_load_lds_dwordx4 v128, s[28:29]
	s_waitcnt vmcnt(6)
	s_waitcnt lgkmcnt(0)
	s_barrier
	s_setprio 1
	v_mfma_f32_16x16x32_bf16 v[60:63], v[140:143], v[178:181], v[60:63]
	v_mfma_f32_16x16x32_bf16 v[56:59], v[170:173], v[178:181], v[56:59]
	v_mfma_f32_16x16x32_bf16 v[44:47], v[140:143], v[186:189], v[44:47]
	v_mfma_f32_16x16x32_bf16 v[40:43], v[170:173], v[186:189], v[40:43]
	v_mfma_f32_16x16x32_bf16 v[28:31], v[140:143], v[194:197], v[28:31]
	v_mfma_f32_16x16x32_bf16 v[24:27], v[170:173], v[194:197], v[24:27]
	v_mfma_f32_16x16x32_bf16 v[12:15], v[140:143], v[202:205], v[12:15]
	v_mfma_f32_16x16x32_bf16 v[8:11], v[170:173], v[202:205], v[8:11]
	v_mfma_f32_16x16x32_bf16 v[60:63], v[166:169], v[182:185], v[60:63]
	v_mfma_f32_16x16x32_bf16 v[56:59], v[174:177], v[182:185], v[56:59]
	v_mfma_f32_16x16x32_bf16 v[44:47], v[166:169], v[190:193], v[44:47]
	v_mfma_f32_16x16x32_bf16 v[40:43], v[174:177], v[190:193], v[40:43]
	v_mfma_f32_16x16x32_bf16 v[28:31], v[166:169], v[198:201], v[28:31]
	v_mfma_f32_16x16x32_bf16 v[24:27], v[174:177], v[198:201], v[24:27]
	v_mfma_f32_16x16x32_bf16 v[12:15], v[166:169], v[206:209], v[12:15]
	v_mfma_f32_16x16x32_bf16 v[8:11], v[174:177], v[206:209], v[8:11]
	v_mfma_f32_16x16x32_bf16 v[52:55], v[210:213], v[178:181], v[52:55]
	v_mfma_f32_16x16x32_bf16 v[48:51], v[218:221], v[178:181], v[48:51]
	v_mfma_f32_16x16x32_bf16 v[36:39], v[210:213], v[186:189], v[36:39]
	v_mfma_f32_16x16x32_bf16 v[32:35], v[218:221], v[186:189], v[32:35]
	v_mfma_f32_16x16x32_bf16 v[20:23], v[210:213], v[194:197], v[20:23]
	v_mfma_f32_16x16x32_bf16 v[16:19], v[218:221], v[194:197], v[16:19]
	v_mfma_f32_16x16x32_bf16 v[4:7], v[210:213], v[202:205], v[4:7]
	v_mfma_f32_16x16x32_bf16 v[0:3], v[218:221], v[202:205], v[0:3]
	v_mfma_f32_16x16x32_bf16 v[52:55], v[214:217], v[182:185], v[52:55]
	v_mfma_f32_16x16x32_bf16 v[48:51], v[222:225], v[182:185], v[48:51]
	v_mfma_f32_16x16x32_bf16 v[36:39], v[214:217], v[190:193], v[36:39]
	v_mfma_f32_16x16x32_bf16 v[32:35], v[222:225], v[190:193], v[32:35]
	v_mfma_f32_16x16x32_bf16 v[20:23], v[214:217], v[198:201], v[20:23]
	v_mfma_f32_16x16x32_bf16 v[16:19], v[222:225], v[198:201], v[16:19]
	v_mfma_f32_16x16x32_bf16 v[4:7], v[214:217], v[206:209], v[4:7]
	v_mfma_f32_16x16x32_bf16 v[0:3], v[222:225], v[206:209], v[0:3]
	s_setprio 0
	s_barrier
; #define PG8_STAGE(bufoff, gbase, voff) do { _Pragma("unroll") for (int _i = 0; _i < 2; ++_i) \
;         __builtin_amdgcn_global_load_lds((const unsigned*)((const char*)(gbase) + (voff)[_i]), (PG8_LAS unsigned*)(lds + (bufoff) + ldsw + _i * 8192), 16, 0, 0); } while (0)
; #define PG8_LDA(dst, b, h) do { _Pragma("unroll") for (int m = 0; m < 4; ++m) _Pragma("unroll") for (int k = 0; k < 2; ++k) dst[m][k] = *(const PG8_LAS bf16x8*)(lds + PG8_SA(b, h) + aoff + m * 2048 + k * 1024); } while (0)
; #define PG8_LDB(dst, b, h) do { _Pragma("unroll") for (int n = 0; n < 2; ++n) _Pragma("unroll") for (int k = 0; k < 2; ++k) dst[n][k] = *(const PG8_LAS bf16x8*)(lds + PG8_SB(b, h) + boff + n * 2048 + k * 1024); } while (0)
; #define PG8_MMA(ai, bj, At, Bt) do { __builtin_amdgcn_s_setprio(1); _Pragma("unroll") for (int m = 0; m < 4; ++m) _Pragma("unroll") for (int n = 0; n < 2; ++n) _Pragma("unroll") for (int k = 0; k < 2; ++k) \
;         acc[ai][bj][m][n] = __builtin_amdgcn_mfma_f32_16x16x32_bf16(Bt[n][k], At[m][k], acc[ai][bj][m][n], 0, 0, 0); __builtin_amdgcn_s_setprio(0); } while (0)
; #define PG8_WAIT_V(n) asm volatile("s_waitcnt vmcnt(" #n ")" ::: "memory")
; #define PG8_WAIT_L(n) asm volatile("s_waitcnt lgkmcnt(" #n ")" ::: "memory")
; #define PG8_BAR __builtin_amdgcn_s_barrier()
; #define PG8_SCHED __builtin_amdgcn_sched_barrier(0)
; template <class Epi, class Sched, bool STAMP = false>
; __device__ __forceinline__ void gemm_phase(PG8_LAS unsigned char* lds, const Gemm g, const Sched& S, const Epi& E, unsigned long long* stamps) {
;     ...
;             PG8_LDB(B0, 1, 0); PG8_SCHED; PG8_LDA(At, 1, 0); PG8_STAGE(PG8_SA(0, 1), a2 + hstep, voffA);
;             PG8_WAIT_L(8); PG8_BAR; PG8_WAIT_L(0); PG8_MMA(0, 0, At, B0); PG8_BAR; PG8_SCHED;
;             PG8_LDB(B1, 1, 1); PG8_STAGE(PG8_SB(1, 0), b3, voffB);
;             PG8_BAR; PG8_WAIT_L(0); PG8_MMA(0, 1, At, B1); PG8_BAR;
;             PG8_LDA(At, 1, 1); PG8_STAGE(PG8_SA(1, 0), a3, voffA);
;             PG8_BAR; PG8_WAIT_L(0); PG8_MMA(1, 0, At, B0); PG8_BAR; PG8_SCHED;
;             PG8_STAGE(PG8_SB(1, 1), b3 + hstep, voffB);
;             PG8_WAIT_V(6); PG8_BAR; PG8_MMA(1, 1, At, B1); PG8_BAR;
.Lzp1_mid:
	s_add_u32 s14, s18, 0x44000
	s_addc_u32 s15, s19, 0
	s_mov_b32 m0, s55
	s_nop 0
	global_load_lds_dwordx4 v130, s[14:15]
	s_mov_b32 m0, s56
	s_nop 0
	global_load_lds_dwordx4 v128, s[14:15]
	ds_read_b128 v[140:143], v156
	ds_read_b128 v[166:169], v157
	ds_read_b128 v[170:173], v159
	ds_read_b128 v[174:177], v160
	s_add_u32 s14, s28, 0x44000
	s_addc_u32 s15, s29, 0
	s_mov_b32 m0, s57
	ds_read_b128 v[178:181], v146 offset:32768
	ds_read_b128 v[182:185], v146 offset:33792
	ds_read_b128 v[186:189], v146 offset:34816
	ds_read_b128 v[190:193], v146 offset:35840
	ds_read_b128 v[194:197], v146 offset:36864
	ds_read_b128 v[198:201], v146 offset:37888
	ds_read_b128 v[202:205], v146 offset:38912
	ds_read_b128 v[206:209], v146 offset:39936
	global_load_lds_dwordx4 v130, s[14:15]
	s_mov_b32 m0, s58
	s_nop 0
	global_load_lds_dwordx4 v128, s[14:15]
	ds_read_b128 v[210:213], v161
	ds_read_b128 v[214:217], v162
	ds_read_b128 v[218:221], v163
	ds_read_b128 v[222:225], v164
	s_waitcnt vmcnt(8)
	s_waitcnt lgkmcnt(0)
	s_barrier
	s_setprio 1
	v_mfma_f32_16x16x32_bf16 v[124:127], v[140:143], v[178:181], v[124:127]
	v_mfma_f32_16x16x32_bf16 v[120:123], v[170:173], v[178:181], v[120:123]
	v_mfma_f32_16x16x32_bf16 v[108:111], v[140:143], v[186:189], v[108:111]
	v_mfma_f32_16x16x32_bf16 v[104:107], v[170:173], v[186:189], v[104:107]
	v_mfma_f32_16x16x32_bf16 v[92:95], v[140:143], v[194:197], v[92:95]
	v_mfma_f32_16x16x32_bf16 v[88:91], v[170:173], v[194:197], v[88:91]
	v_mfma_f32_16x16x32_bf16 v[76:79], v[140:143], v[202:205], v[76:79]
	v_mfma_f32_16x16x32_bf16 v[72:75], v[170:173], v[202:205], v[72:75]
	v_mfma_f32_16x16x32_bf16 v[124:127], v[166:169], v[182:185], v[124:127]
	v_mfma_f32_16x16x32_bf16 v[120:123], v[174:177], v[182:185], v[120:123]
	v_mfma_f32_16x16x32_bf16 v[108:111], v[166:169], v[190:193], v[108:111]
	v_mfma_f32_16x16x32_bf16 v[104:107], v[174:177], v[190:193], v[104:107]
	v_mfma_f32_16x16x32_bf16 v[92:95], v[166:169], v[198:201], v[92:95]
	v_mfma_f32_16x16x32_bf16 v[88:91], v[174:177], v[198:201], v[88:91]
	v_mfma_f32_16x16x32_bf16 v[76:79], v[166:169], v[206:209], v[76:79]
	v_mfma_f32_16x16x32_bf16 v[72:75], v[174:177], v[206:209], v[72:75]
	v_mfma_f32_16x16x32_bf16 v[116:119], v[210:213], v[178:181], v[116:119]
	v_mfma_f32_16x16x32_bf16 v[112:115], v[218:221], v[178:181], v[112:115]
	v_mfma_f32_16x16x32_bf16 v[100:103], v[210:213], v[186:189], v[100:103]
	v_mfma_f32_16x16x32_bf16 v[96:99], v[218:221], v[186:189], v[96:99]
	v_mfma_f32_16x16x32_bf16 v[84:87], v[210:213], v[194:197], v[84:87]
	v_mfma_f32_16x16x32_bf16 v[80:83], v[218:221], v[194:197], v[80:83]
	v_mfma_f32_16x16x32_bf16 v[68:71], v[210:213], v[202:205], v[68:71]
	v_mfma_f32_16x16x32_bf16 v[64:67], v[218:221], v[202:205], v[64:67]
	v_mfma_f32_16x16x32_bf16 v[116:119], v[214:217], v[182:185], v[116:119]
	v_mfma_f32_16x16x32_bf16 v[112:115], v[222:225], v[182:185], v[112:115]
	v_mfma_f32_16x16x32_bf16 v[100:103], v[214:217], v[190:193], v[100:103]
	v_mfma_f32_16x16x32_bf16 v[96:99], v[222:225], v[190:193], v[96:99]
	v_mfma_f32_16x16x32_bf16 v[84:87], v[214:217], v[198:201], v[84:87]
	v_mfma_f32_16x16x32_bf16 v[80:83], v[222:225], v[198:201], v[80:83]
	v_mfma_f32_16x16x32_bf16 v[68:71], v[214:217], v[206:209], v[68:71]
	v_mfma_f32_16x16x32_bf16 v[64:67], v[222:225], v[206:209], v[64:67]
	s_setprio 0
	s_barrier
	s_mov_b32 m0, s61
	s_add_u32 s100, s18, 0x80
	s_addc_u32 s101, s19, 0
	global_load_lds_dwordx4 v130, s[100:101]
	s_mov_b32 m0, s62
	s_nop 0
	global_load_lds_dwordx4 v128, s[100:101]
	s_mov_b32 m0, s63
	ds_read_b128 v[178:181], v146 offset:49152
	ds_read_b128 v[182:185], v146 offset:50176
	ds_read_b128 v[186:189], v146 offset:51200
	ds_read_b128 v[190:193], v146 offset:52224
	ds_read_b128 v[194:197], v146 offset:53248
	ds_read_b128 v[198:201], v146 offset:54272
	ds_read_b128 v[202:205], v146 offset:55296
	ds_read_b128 v[206:209], v146 offset:56320
	s_add_u32 s100, s28, 0x80
	s_addc_u32 s101, s29, 0
	global_load_lds_dwordx4 v130, s[100:101]
	s_mov_b32 m0, s64
	s_nop 0
	global_load_lds_dwordx4 v128, s[100:101]
	s_waitcnt vmcnt(6)
	s_waitcnt lgkmcnt(0)
	s_barrier
	s_setprio 1
	v_mfma_f32_16x16x32_bf16 v[60:63], v[140:143], v[178:181], v[60:63]
	v_mfma_f32_16x16x32_bf16 v[56:59], v[170:173], v[178:181], v[56:59]
	v_mfma_f32_16x16x32_bf16 v[44:47], v[140:143], v[186:189], v[44:47]
	v_mfma_f32_16x16x32_bf16 v[40:43], v[170:173], v[186:189], v[40:43]
	v_mfma_f32_16x16x32_bf16 v[28:31], v[140:143], v[194:197], v[28:31]
	v_mfma_f32_16x16x32_bf16 v[24:27], v[170:173], v[194:197], v[24:27]
	v_mfma_f32_16x16x32_bf16 v[12:15], v[140:143], v[202:205], v[12:15]
	v_mfma_f32_16x16x32_bf16 v[8:11], v[170:173], v[202:205], v[8:11]
	v_mfma_f32_16x16x32_bf16 v[60:63], v[166:169], v[182:185], v[60:63]
	v_mfma_f32_16x16x32_bf16 v[56:59], v[174:177], v[182:185], v[56:59]
	v_mfma_f32_16x16x32_bf16 v[44:47], v[166:169], v[190:193], v[44:47]
	v_mfma_f32_16x16x32_bf16 v[40:43], v[174:177], v[190:193], v[40:43]
	v_mfma_f32_16x16x32_bf16 v[28:31], v[166:169], v[198:201], v[28:31]
	v_mfma_f32_16x16x32_bf16 v[24:27], v[174:177], v[198:201], v[24:27]
	v_mfma_f32_16x16x32_bf16 v[12:15], v[166:169], v[206:209], v[12:15]
	v_mfma_f32_16x16x32_bf16 v[8:11], v[174:177], v[206:209], v[8:11]
	v_mfma_f32_16x16x32_bf16 v[52:55], v[210:213], v[178:181], v[52:55]
	v_mfma_f32_16x16x32_bf16 v[48:51], v[218:221], v[178:181], v[48:51]
	v_mfma_f32_16x16x32_bf16 v[36:39], v[210:213], v[186:189], v[36:39]
	v_mfma_f32_16x16x32_bf16 v[32:35], v[218:221], v[186:189], v[32:35]
	v_mfma_f32_16x16x32_bf16 v[20:23], v[210:213], v[194:197], v[20:23]
	v_mfma_f32_16x16x32_bf16 v[16:19], v[218:221], v[194:197], v[16:19]
	v_mfma_f32_16x16x32_bf16 v[4:7], v[210:213], v[202:205], v[4:7]
	v_mfma_f32_16x16x32_bf16 v[0:3], v[218:221], v[202:205], v[0:3]
	v_mfma_f32_16x16x32_bf16 v[52:55], v[214:217], v[182:185], v[52:55]
	v_mfma_f32_16x16x32_bf16 v[48:51], v[222:225], v[182:185], v[48:51]
	v_mfma_f32_16x16x32_bf16 v[36:39], v[214:217], v[190:193], v[36:39]
	v_mfma_f32_16x16x32_bf16 v[32:35], v[222:225], v[190:193], v[32:35]
	v_mfma_f32_16x16x32_bf16 v[20:23], v[214:217], v[198:201], v[20:23]
	v_mfma_f32_16x16x32_bf16 v[16:19], v[222:225], v[198:201], v[16:19]
	v_mfma_f32_16x16x32_bf16 v[4:7], v[214:217], v[206:209], v[4:7]
	v_mfma_f32_16x16x32_bf16 v[0:3], v[222:225], v[206:209], v[0:3]
	s_setprio 0
	s_add_i32 s77, s77, 2
	s_add_u32 s75, s75, 0x100
	s_addc_u32 s76, s76, 0
	s_cmp_gt_u32 s77, 13
	s_mov_b64 s[14:15], s[16:17]
	s_barrier
; DI float ex2(float x) { return __builtin_amdgcn_exp2f(x); }
;     DI void operator()(const f32x4 (&acc)[2][2][4][2], const Unit& u, int wr, int wc, int fr, int fq) const {
;         const int row0 = u.pm * BM + wr * 64 + fr, hcol0 = ((u.pn * BM + wc * 32) >> 1) + 4 * fq;
; #pragma unroll
;         for (int ai = 0; ai < 2; ++ai)
; #pragma unroll
;             for (int m = 0; m < 4; ++m) { u16* rowp = O + (size_t)(row0 + ai * HALF + m * 16) * ldc + hcol0;
; #pragma unroll
;                 for (int bj = 0; bj < 2; ++bj) { const f32x4 g = acc[ai][bj][m][0], up = acc[ai][bj][m][1]; float r[4];
; #pragma unroll
;                     for (int j = 0; j < 4; ++j) r[j] = g[j] * up[j] * __builtin_amdgcn_rcpf(1.f + ex2(-LOG2E * g[j]));
;                     uint2 w = {pack2(r[0], r[1]), pack2(r[2], r[3])}; *(uint2*)(rowp + bj * (HALF / 2)) = w; } }
	s_cbranch_scc0 .LBB0_63
	v_exp_f32_e64 v168, -v124
	v_exp_f32_e64 v169, -v125
	v_exp_f32_e64 v170, -v126
	v_exp_f32_e64 v171, -v127
	v_add_f32_e32 v168, 1.0, v168
	v_add_f32_e32 v169, 1.0, v169
	v_add_f32_e32 v170, 1.0, v170
	v_add_f32_e32 v171, 1.0, v171
	v_rcp_f32_e32 v168, v168
	v_rcp_f32_e32 v169, v169
	v_rcp_f32_e32 v170, v170
	v_rcp_f32_e32 v171, v171
	s_lshl_b32 s10, s74, 8
	v_pk_mul_f32 v[122:123], v[126:127], v[122:123]
	v_pk_mul_f32 v[120:121], v[124:125], v[120:121]
	s_or_b32 s10, s10, s60
	v_pk_mul_f32 v[120:121], v[120:121], v[168:169]
	v_pk_mul_f32 v[122:123], v[122:123], v[170:171]
	s_ashr_i32 s10, s10, 1
	v_cvt_pk_bf16_f32 v120, v120, v121
	v_cvt_pk_bf16_f32 v121, v122, v123
	v_or_b32_e32 v140, s10, v147
	v_exp_f32_e64 v122, -v116
	v_exp_f32_e64 v123, -v117
	v_lshl_add_u32 v165, s73, 8, v145
	v_ashrrev_i32_e32 v141, 31, v140
	v_mov_b64_e32 v[142:143], s[12:13]
	v_mad_i64_i32 v[166:167], s[14:15], v165, s70, v[142:143]
	v_lshlrev_b64 v[140:141], 1, v[140:141]
	v_lshl_add_u64 v[166:167], v[166:167], 0, v[140:141]
	global_store_dwordx2 v[166:167], v[120:121], off
	v_add_f32_e32 v120, 1.0, v122
	v_add_f32_e32 v121, 1.0, v123
	v_exp_f32_e64 v122, -v118
	v_exp_f32_e64 v123, -v119
	v_rcp_f32_e32 v120, v120
	v_rcp_f32_e32 v121, v121
	v_add_f32_e32 v122, 1.0, v122
	v_add_f32_e32 v123, 1.0, v123
	v_rcp_f32_e32 v122, v122
	v_rcp_f32_e32 v123, v123
	v_pk_mul_f32 v[114:115], v[118:119], v[114:115]
	v_pk_mul_f32 v[112:113], v[116:117], v[112:113]
	v_pk_mul_f32 v[112:113], v[112:113], v[120:121]
	v_pk_mul_f32 v[114:115], v[114:115], v[122:123]
	v_cvt_pk_bf16_f32 v112, v112, v113
	v_cvt_pk_bf16_f32 v113, v114, v115
	v_exp_f32_e64 v114, -v108
	v_exp_f32_e64 v115, -v109
	v_exp_f32_e64 v116, -v110
	v_exp_f32_e64 v117, -v111
	v_add_f32_e32 v114, 1.0, v114
	v_add_f32_e32 v115, 1.0, v115
	v_add_f32_e32 v116, 1.0, v116
	v_add_f32_e32 v117, 1.0, v117
	v_rcp_f32_e32 v114, v114
	v_rcp_f32_e32 v115, v115
	v_rcp_f32_e32 v116, v116
	v_rcp_f32_e32 v117, v117
	v_pk_mul_f32 v[106:107], v[110:111], v[106:107]
	v_pk_mul_f32 v[104:105], v[108:109], v[104:105]
	global_store_dwordx2 v[166:167], v[112:113], off offset:128
	v_pk_mul_f32 v[104:105], v[104:105], v[114:115]
	v_pk_mul_f32 v[106:107], v[106:107], v[116:117]
	v_cvt_pk_bf16_f32 v104, v104, v105
	v_cvt_pk_bf16_f32 v105, v106, v107
	v_exp_f32_e64 v106, -v100
	v_exp_f32_e64 v107, -v101
	v_or_b32_e32 v112, 16, v165
	v_mad_i64_i32 v[112:113], s[14:15], v112, s70, v[142:143]
	v_lshl_add_u64 v[112:113], v[112:113], 0, v[140:141]
	global_store_dwordx2 v[112:113], v[104:105], off
	v_add_f32_e32 v104, 1.0, v106
	v_add_f32_e32 v105, 1.0, v107
	v_exp_f32_e64 v106, -v102
	v_exp_f32_e64 v107, -v103
	v_rcp_f32_e32 v104, v104
	v_rcp_f32_e32 v105, v105
	v_add_f32_e32 v106, 1.0, v106
	v_add_f32_e32 v107, 1.0, v107
	v_rcp_f32_e32 v106, v106
	v_rcp_f32_e32 v107, v107
	v_pk_mul_f32 v[98:99], v[102:103], v[98:99]
	v_pk_mul_f32 v[96:97], v[100:101], v[96:97]
	v_pk_mul_f32 v[96:97], v[96:97], v[104:105]
	v_pk_mul_f32 v[98:99], v[98:99], v[106:107]
	v_cvt_pk_bf16_f32 v96, v96, v97
	v_cvt_pk_bf16_f32 v97, v98, v99
	v_exp_f32_e64 v98, -v92
	v_exp_f32_e64 v99, -v93
	v_exp_f32_e64 v100, -v94
	v_exp_f32_e64 v101, -v95
	v_add_f32_e32 v98, 1.0, v98
	v_add_f32_e32 v99, 1.0, v99
	v_add_f32_e32 v100, 1.0, v100
	v_add_f32_e32 v101, 1.0, v101
	v_rcp_f32_e32 v98, v98
	v_rcp_f32_e32 v99, v99
	v_rcp_f32_e32 v100, v100
	v_rcp_f32_e32 v101, v101
	v_pk_mul_f32 v[90:91], v[94:95], v[90:91]
	v_pk_mul_f32 v[88:89], v[92:93], v[88:89]
	global_store_dwordx2 v[112:113], v[96:97], off offset:128
	v_pk_mul_f32 v[88:89], v[88:89], v[98:99]
	v_pk_mul_f32 v[90:91], v[90:91], v[100:101]
	v_cvt_pk_bf16_f32 v88, v88, v89
	v_cvt_pk_bf16_f32 v89, v90, v91
	v_exp_f32_e64 v90, -v84
	v_exp_f32_e64 v91, -v85
	v_or_b32_e32 v96, 32, v165
	v_mad_i64_i32 v[96:97], s[14:15], v96, s70, v[142:143]
	v_lshl_add_u64 v[96:97], v[96:97], 0, v[140:141]
	global_store_dwordx2 v[96:97], v[88:89], off
	v_add_f32_e32 v88, 1.0, v90
	v_add_f32_e32 v89, 1.0, v91
	v_exp_f32_e64 v90, -v86
	v_exp_f32_e64 v91, -v87
	v_rcp_f32_e32 v88, v88
	v_rcp_f32_e32 v89, v89
	v_add_f32_e32 v90, 1.0, v90
	v_add_f32_e32 v91, 1.0, v91
	v_rcp_f32_e32 v90, v90
	v_rcp_f32_e32 v91, v91
	v_pk_mul_f32 v[82:83], v[86:87], v[82:83]
	v_pk_mul_f32 v[80:81], v[84:85], v[80:81]
	v_pk_mul_f32 v[80:81], v[80:81], v[88:89]
	v_pk_mul_f32 v[82:83], v[82:83], v[90:91]
	v_cvt_pk_bf16_f32 v80, v80, v81
	v_cvt_pk_bf16_f32 v81, v82, v83
	v_exp_f32_e64 v82, -v76
	v_exp_f32_e64 v83, -v77
	v_exp_f32_e64 v84, -v78
	v_exp_f32_e64 v85, -v79
	v_add_f32_e32 v82, 1.0, v82
	v_add_f32_e32 v83, 1.0, v83
	v_add_f32_e32 v84, 1.0, v84
	v_add_f32_e32 v85, 1.0, v85
	v_rcp_f32_e32 v82, v82
	v_rcp_f32_e32 v83, v83
	v_rcp_f32_e32 v84, v84
	v_rcp_f32_e32 v85, v85
	v_pk_mul_f32 v[74:75], v[78:79], v[74:75]
	v_pk_mul_f32 v[72:73], v[76:77], v[72:73]
	global_store_dwordx2 v[96:97], v[80:81], off offset:128
	v_pk_mul_f32 v[72:73], v[72:73], v[82:83]
	v_pk_mul_f32 v[74:75], v[74:75], v[84:85]
	v_cvt_pk_bf16_f32 v72, v72, v73
	v_cvt_pk_bf16_f32 v73, v74, v75
	v_exp_f32_e64 v74, -v68
	v_exp_f32_e64 v75, -v69
	v_or_b32_e32 v80, 48, v165
	v_mad_i64_i32 v[80:81], s[14:15], v80, s70, v[142:143]
	v_lshl_add_u64 v[80:81], v[80:81], 0, v[140:141]
	global_store_dwordx2 v[80:81], v[72:73], off
	v_add_f32_e32 v72, 1.0, v74
	v_add_f32_e32 v73, 1.0, v75
	v_exp_f32_e64 v74, -v70
	v_exp_f32_e64 v75, -v71
	v_rcp_f32_e32 v72, v72
	v_rcp_f32_e32 v73, v73
	v_add_f32_e32 v74, 1.0, v74
	v_add_f32_e32 v75, 1.0, v75
	v_rcp_f32_e32 v74, v74
	v_rcp_f32_e32 v75, v75
	v_pk_mul_f32 v[66:67], v[70:71], v[66:67]
	v_pk_mul_f32 v[64:65], v[68:69], v[64:65]
; DI float ex2(float x) { return __builtin_amdgcn_exp2f(x); }
;     DI void operator()(const f32x4 (&acc)[2][2][4][2], const Unit& u, int wr, int wc, int fr, int fq) const {
;         const int row0 = u.pm * BM + wr * 64 + fr, hcol0 = ((u.pn * BM + wc * 32) >> 1) + 4 * fq;
; #pragma unroll
;         for (int ai = 0; ai < 2; ++ai)
; #pragma unroll
;             for (int m = 0; m < 4; ++m) { u16* rowp = O + (size_t)(row0 + ai * HALF + m * 16) * ldc + hcol0;
; #pragma unroll
;                 for (int bj = 0; bj < 2; ++bj) { const f32x4 g = acc[ai][bj][m][0], up = acc[ai][bj][m][1]; float r[4];
; #pragma unroll
;                     for (int j = 0; j < 4; ++j) r[j] = g[j] * up[j] * __builtin_amdgcn_rcpf(1.f + ex2(-LOG2E * g[j]));
;                     uint2 w = {pack2(r[0], r[1]), pack2(r[2], r[3])}; *(uint2*)(rowp + bj * (HALF / 2)) = w; } }
; template <class Epi, class Sched, bool STAMP = false>
; __device__ __forceinline__ void gemm_phase(PG8_LAS unsigned char* lds, const Gemm g, const Sched& S, const Epi& E, unsigned long long* stamps) {
;     ...
;         if (!has_next) break;
; #pragma unroll
;         for (int a = 0; a < 2; ++a)
; #pragma unroll
;             for (int b = 0; b < 2; ++b)
; #pragma unroll
;                 for (int m = 0; m < 4; ++m)
; #pragma unroll
;                     for (int n = 0; n < 2; ++n) acc[a][b][m][n] = (f32x4){0.f, 0.f, 0.f, 0.f};
;         cur = nxt; cA = nA; cB = nB; ++ui;
	v_pk_mul_f32 v[64:65], v[64:65], v[72:73]
	v_pk_mul_f32 v[66:67], v[66:67], v[74:75]
	v_cvt_pk_bf16_f32 v64, v64, v65
	v_cvt_pk_bf16_f32 v65, v66, v67
	v_exp_f32_e64 v66, -v60
	v_exp_f32_e64 v67, -v61
	v_exp_f32_e64 v68, -v62
	v_exp_f32_e64 v69, -v63
	v_add_f32_e32 v66, 1.0, v66
	v_add_f32_e32 v67, 1.0, v67
	v_add_f32_e32 v68, 1.0, v68
	v_add_f32_e32 v69, 1.0, v69
	v_rcp_f32_e32 v66, v66
	v_rcp_f32_e32 v67, v67
	v_rcp_f32_e32 v68, v68
	v_rcp_f32_e32 v69, v69
	v_pk_mul_f32 v[58:59], v[62:63], v[58:59]
	v_pk_mul_f32 v[56:57], v[60:61], v[56:57]
	global_store_dwordx2 v[80:81], v[64:65], off offset:128
	v_pk_mul_f32 v[56:57], v[56:57], v[66:67]
	v_pk_mul_f32 v[58:59], v[58:59], v[68:69]
	v_cvt_pk_bf16_f32 v56, v56, v57
	v_cvt_pk_bf16_f32 v57, v58, v59
	v_exp_f32_e64 v58, -v52
	v_exp_f32_e64 v59, -v53
	v_add_u32_e32 v64, 0x80, v165
	v_mad_i64_i32 v[64:65], s[14:15], v64, s70, v[142:143]
	v_lshl_add_u64 v[64:65], v[64:65], 0, v[140:141]
	global_store_dwordx2 v[64:65], v[56:57], off
	v_add_f32_e32 v56, 1.0, v58
	v_add_f32_e32 v57, 1.0, v59
	v_exp_f32_e64 v58, -v54
	v_exp_f32_e64 v59, -v55
	v_rcp_f32_e32 v56, v56
	v_rcp_f32_e32 v57, v57
	v_add_f32_e32 v58, 1.0, v58
	v_add_f32_e32 v59, 1.0, v59
	v_rcp_f32_e32 v58, v58
	v_rcp_f32_e32 v59, v59
	v_pk_mul_f32 v[50:51], v[54:55], v[50:51]
	v_pk_mul_f32 v[48:49], v[52:53], v[48:49]
	v_pk_mul_f32 v[48:49], v[48:49], v[56:57]
	v_pk_mul_f32 v[50:51], v[50:51], v[58:59]
	v_cvt_pk_bf16_f32 v48, v48, v49
	v_cvt_pk_bf16_f32 v49, v50, v51
	v_exp_f32_e64 v50, -v44
	v_exp_f32_e64 v51, -v45
	v_exp_f32_e64 v52, -v46
	v_exp_f32_e64 v53, -v47
	v_add_f32_e32 v50, 1.0, v50
	v_add_f32_e32 v51, 1.0, v51
	v_add_f32_e32 v52, 1.0, v52
	v_add_f32_e32 v53, 1.0, v53
	v_rcp_f32_e32 v50, v50
	v_rcp_f32_e32 v51, v51
	v_rcp_f32_e32 v52, v52
	v_rcp_f32_e32 v53, v53
	v_pk_mul_f32 v[42:43], v[46:47], v[42:43]
	v_pk_mul_f32 v[40:41], v[44:45], v[40:41]
	global_store_dwordx2 v[64:65], v[48:49], off offset:128
	v_pk_mul_f32 v[40:41], v[40:41], v[50:51]
	v_pk_mul_f32 v[42:43], v[42:43], v[52:53]
	v_cvt_pk_bf16_f32 v40, v40, v41
	v_cvt_pk_bf16_f32 v41, v42, v43
	v_exp_f32_e64 v42, -v36
	v_exp_f32_e64 v43, -v37
	v_add_u32_e32 v48, 0x90, v165
	v_mad_i64_i32 v[48:49], s[14:15], v48, s70, v[142:143]
	v_lshl_add_u64 v[48:49], v[48:49], 0, v[140:141]
	global_store_dwordx2 v[48:49], v[40:41], off
	v_add_f32_e32 v40, 1.0, v42
	v_add_f32_e32 v41, 1.0, v43
	v_exp_f32_e64 v42, -v38
	v_exp_f32_e64 v43, -v39
	v_rcp_f32_e32 v40, v40
	v_rcp_f32_e32 v41, v41
	v_add_f32_e32 v42, 1.0, v42
	v_add_f32_e32 v43, 1.0, v43
	v_rcp_f32_e32 v42, v42
	v_rcp_f32_e32 v43, v43
	v_pk_mul_f32 v[34:35], v[38:39], v[34:35]
	v_pk_mul_f32 v[32:33], v[36:37], v[32:33]
	v_pk_mul_f32 v[32:33], v[32:33], v[40:41]
	v_pk_mul_f32 v[34:35], v[34:35], v[42:43]
	v_cvt_pk_bf16_f32 v32, v32, v33
	v_cvt_pk_bf16_f32 v33, v34, v35
	v_exp_f32_e64 v34, -v28
	v_exp_f32_e64 v35, -v29
	v_exp_f32_e64 v36, -v30
	v_exp_f32_e64 v37, -v31
	v_add_f32_e32 v34, 1.0, v34
	v_add_f32_e32 v35, 1.0, v35
	v_add_f32_e32 v36, 1.0, v36
	v_add_f32_e32 v37, 1.0, v37
	v_rcp_f32_e32 v34, v34
	v_rcp_f32_e32 v35, v35
	v_rcp_f32_e32 v36, v36
	v_rcp_f32_e32 v37, v37
	v_pk_mul_f32 v[26:27], v[30:31], v[26:27]
	v_pk_mul_f32 v[24:25], v[28:29], v[24:25]
	global_store_dwordx2 v[48:49], v[32:33], off offset:128
	v_pk_mul_f32 v[24:25], v[24:25], v[34:35]
	v_pk_mul_f32 v[26:27], v[26:27], v[36:37]
	v_cvt_pk_bf16_f32 v24, v24, v25
	v_cvt_pk_bf16_f32 v25, v26, v27
	v_exp_f32_e64 v26, -v20
	v_exp_f32_e64 v27, -v21
	v_add_u32_e32 v32, 0xa0, v165
	v_mad_i64_i32 v[32:33], s[14:15], v32, s70, v[142:143]
	v_lshl_add_u64 v[32:33], v[32:33], 0, v[140:141]
	global_store_dwordx2 v[32:33], v[24:25], off
	v_add_f32_e32 v24, 1.0, v26
	v_add_f32_e32 v25, 1.0, v27
	v_exp_f32_e64 v26, -v22
	v_exp_f32_e64 v27, -v23
	v_rcp_f32_e32 v24, v24
	v_rcp_f32_e32 v25, v25
	v_add_f32_e32 v26, 1.0, v26
	v_add_f32_e32 v27, 1.0, v27
	v_rcp_f32_e32 v26, v26
	v_rcp_f32_e32 v27, v27
	v_pk_mul_f32 v[18:19], v[22:23], v[18:19]
	v_pk_mul_f32 v[16:17], v[20:21], v[16:17]
	v_pk_mul_f32 v[16:17], v[16:17], v[24:25]
	v_pk_mul_f32 v[18:19], v[18:19], v[26:27]
	v_cvt_pk_bf16_f32 v16, v16, v17
	v_cvt_pk_bf16_f32 v17, v18, v19
	v_exp_f32_e64 v18, -v12
	v_exp_f32_e64 v19, -v13
	v_exp_f32_e64 v20, -v14
	v_exp_f32_e64 v21, -v15
	v_add_f32_e32 v18, 1.0, v18
	v_add_f32_e32 v19, 1.0, v19
	v_add_f32_e32 v20, 1.0, v20
	v_add_f32_e32 v21, 1.0, v21
	v_rcp_f32_e32 v18, v18
	v_rcp_f32_e32 v19, v19
	v_rcp_f32_e32 v20, v20
	v_rcp_f32_e32 v21, v21
	v_pk_mul_f32 v[10:11], v[14:15], v[10:11]
	v_pk_mul_f32 v[8:9], v[12:13], v[8:9]
	global_store_dwordx2 v[32:33], v[16:17], off offset:128
	v_pk_mul_f32 v[8:9], v[8:9], v[18:19]
	v_pk_mul_f32 v[10:11], v[10:11], v[20:21]
	v_cvt_pk_bf16_f32 v8, v8, v9
	v_cvt_pk_bf16_f32 v9, v10, v11
	v_exp_f32_e64 v10, -v4
	v_exp_f32_e64 v11, -v5
	v_add_u32_e32 v16, 0xb0, v165
	v_mad_i64_i32 v[16:17], s[14:15], v16, s70, v[142:143]
	v_lshl_add_u64 v[16:17], v[16:17], 0, v[140:141]
	global_store_dwordx2 v[16:17], v[8:9], off
	v_add_f32_e32 v8, 1.0, v10
	v_add_f32_e32 v9, 1.0, v11
	v_exp_f32_e64 v10, -v6
	v_exp_f32_e64 v11, -v7
	v_rcp_f32_e32 v8, v8
	v_rcp_f32_e32 v9, v9
	v_add_f32_e32 v10, 1.0, v10
	v_add_f32_e32 v11, 1.0, v11
	v_rcp_f32_e32 v10, v10
	v_rcp_f32_e32 v11, v11
	v_pk_mul_f32 v[2:3], v[6:7], v[2:3]
	v_pk_mul_f32 v[0:1], v[4:5], v[0:1]
	s_and_b64 vcc, exec, s[2:3]
	v_pk_mul_f32 v[0:1], v[0:1], v[8:9]
	v_pk_mul_f32 v[2:3], v[2:3], v[10:11]
	v_cvt_pk_bf16_f32 v0, v0, v1
	v_cvt_pk_bf16_f32 v1, v2, v3
	s_mov_b32 s74, s71
	s_mov_b32 s73, s72
	s_mov_b64 s[16:17], s[0:1]
	s_mov_b64 s[14:15], s[4:5]
	global_store_dwordx2 v[16:17], v[0:1], off offset:128
	s_cbranch_vccz .LBB0_56
	s_branch .Lgu1_done

; #define PG8_STAGE(bufoff, gbase, voff) do { _Pragma("unroll") for (int _i = 0; _i < 2; ++_i) \
;         __builtin_amdgcn_global_load_lds((const unsigned*)((const char*)(gbase) + (voff)[_i]), (PG8_LAS unsigned*)(lds + (bufoff) + ldsw + _i * 8192), 16, 0, 0); } while (0)
; #define PG8_LDA(dst, b, h) do { _Pragma("unroll") for (int m = 0; m < 4; ++m) _Pragma("unroll") for (int k = 0; k < 2; ++k) dst[m][k] = *(const PG8_LAS bf16x8*)(lds + PG8_SA(b, h) + aoff + m * 2048 + k * 1024); } while (0)
; #define PG8_LDB(dst, b, h) do { _Pragma("unroll") for (int n = 0; n < 2; ++n) _Pragma("unroll") for (int k = 0; k < 2; ++k) dst[n][k] = *(const PG8_LAS bf16x8*)(lds + PG8_SB(b, h) + boff + n * 2048 + k * 1024); } while (0)
; #define PG8_MMA(ai, bj, At, Bt) do { __builtin_amdgcn_s_setprio(1); _Pragma("unroll") for (int m = 0; m < 4; ++m) _Pragma("unroll") for (int n = 0; n < 2; ++n) _Pragma("unroll") for (int k = 0; k < 2; ++k) \
;         acc[ai][bj][m][n] = __builtin_amdgcn_mfma_f32_16x16x32_bf16(Bt[n][k], At[m][k], acc[ai][bj][m][n], 0, 0, 0); __builtin_amdgcn_s_setprio(0); } while (0)
; #define PG8_WAIT_V(n) asm volatile("s_waitcnt vmcnt(" #n ")" ::: "memory")
; #define PG8_WAIT_L(n) asm volatile("s_waitcnt lgkmcnt(" #n ")" ::: "memory")
; #define PG8_BAR __builtin_amdgcn_s_barrier()
; #define PG8_SCHED __builtin_amdgcn_sched_barrier(0)
; template <class Epi, class Sched, bool STAMP = false>
; __device__ __forceinline__ void gemm_phase(PG8_LAS unsigned char* lds, const Gemm g, const Sched& S, const Epi& E, unsigned long long* stamps) {
;     ...
;             PG8_LDB(B0, 0, 0); PG8_SCHED; PG8_LDA(At, 0, 0); PG8_STAGE(PG8_SA(1, 1), a1 + hstep, voffA);
;             PG8_WAIT_L(8); PG8_BAR; PG8_WAIT_L(0); PG8_MMA(0, 0, At, B0); PG8_BAR; PG8_SCHED;
;             PG8_LDB(B1, 0, 1); PG8_STAGE(PG8_SB(0, 0), b2, voffB);
;             PG8_BAR; PG8_WAIT_L(0); PG8_MMA(0, 1, At, B1); PG8_BAR;
;             PG8_LDA(At, 0, 1); PG8_STAGE(PG8_SA(0, 0), a2, voffA);
;             PG8_BAR; PG8_WAIT_L(0); PG8_MMA(1, 0, At, B0); PG8_BAR; PG8_SCHED;
;             PG8_STAGE(PG8_SB(0, 1), b2 + hstep, voffB);
;             PG8_WAIT_V(6); PG8_BAR; PG8_MMA(1, 1, At, B1); PG8_BAR;
;             PG8_LDB(B0, 1, 0); PG8_SCHED; PG8_LDA(At, 1, 0); PG8_STAGE(PG8_SA(0, 1), a2 + hstep, voffA);
;             PG8_WAIT_L(8); PG8_BAR; PG8_WAIT_L(0); PG8_MMA(0, 0, At, B0); PG8_BAR; PG8_SCHED;
.Lgu1_half_loop:
	s_add_u32 s100, s75, 0x43f80
	s_addc_u32 s101, s76, 0
	s_mov_b32 m0, s65
	s_nop 0
	global_load_lds_dwordx4 v130, s[100:101]
	s_mov_b32 m0, s66
	s_nop 0
	global_load_lds_dwordx4 v128, s[100:101]
	ds_read_b128 v[140:143], v148
	ds_read_b128 v[166:169], v149
	ds_read_b128 v[170:173], v150
	ds_read_b128 v[174:177], v151
	s_add_u32 s16, s14, 0x100
	s_addc_u32 s17, s15, 0
	s_cmp_eq_u32 s77, 12
	s_cselect_b32 s29, s5, s17
	s_cselect_b32 s28, s4, s16
	s_cselect_b32 s19, s1, s76
	s_cselect_b32 s18, s0, s75
	s_mov_b32 m0, s68
	ds_read_b128 v[178:181], v146
	ds_read_b128 v[182:185], v146 offset:1024
	ds_read_b128 v[186:189], v146 offset:2048
	ds_read_b128 v[190:193], v146 offset:3072
	ds_read_b128 v[194:197], v146 offset:4096
	ds_read_b128 v[198:201], v146 offset:5120
	ds_read_b128 v[202:205], v146 offset:6144
	ds_read_b128 v[206:209], v146 offset:7168
	global_load_lds_dwordx4 v132, s[14:15]
	s_mov_b32 m0, s69
	s_nop 0
	global_load_lds_dwordx4 v134, s[14:15]
	s_waitcnt vmcnt(8)
	s_waitcnt lgkmcnt(0)
	s_barrier
	s_setprio 1
	v_mfma_f32_16x16x32_bf16 v[124:127], v[140:143], v[178:181], v[124:127]
	v_mfma_f32_16x16x32_bf16 v[120:123], v[170:173], v[178:181], v[120:123]
	v_mfma_f32_16x16x32_bf16 v[108:111], v[140:143], v[186:189], v[108:111]
	v_mfma_f32_16x16x32_bf16 v[104:107], v[170:173], v[186:189], v[104:107]
	v_mfma_f32_16x16x32_bf16 v[92:95], v[140:143], v[194:197], v[92:95]
	v_mfma_f32_16x16x32_bf16 v[88:91], v[170:173], v[194:197], v[88:91]
	v_mfma_f32_16x16x32_bf16 v[76:79], v[140:143], v[202:205], v[76:79]
	v_mfma_f32_16x16x32_bf16 v[72:75], v[170:173], v[202:205], v[72:75]
	v_mfma_f32_16x16x32_bf16 v[124:127], v[166:169], v[182:185], v[124:127]
	v_mfma_f32_16x16x32_bf16 v[120:123], v[174:177], v[182:185], v[120:123]
	v_mfma_f32_16x16x32_bf16 v[108:111], v[166:169], v[190:193], v[108:111]
	v_mfma_f32_16x16x32_bf16 v[104:107], v[174:177], v[190:193], v[104:107]
	v_mfma_f32_16x16x32_bf16 v[92:95], v[166:169], v[198:201], v[92:95]
	v_mfma_f32_16x16x32_bf16 v[88:91], v[174:177], v[198:201], v[88:91]
	v_mfma_f32_16x16x32_bf16 v[76:79], v[166:169], v[206:209], v[76:79]
	v_mfma_f32_16x16x32_bf16 v[72:75], v[174:177], v[206:209], v[72:75]
	s_setprio 0
	s_barrier
	s_mov_b32 m0, s52
	s_nop 0
	global_load_lds_dwordx4 v130, s[18:19]
	s_mov_b32 m0, s53
	s_nop 0
	global_load_lds_dwordx4 v128, s[18:19]
	s_mov_b32 m0, s33
	ds_read_b128 v[178:181], v146 offset:16384
	ds_read_b128 v[182:185], v146 offset:17408
	ds_read_b128 v[186:189], v146 offset:18432
	ds_read_b128 v[190:193], v146 offset:19456
	ds_read_b128 v[194:197], v146 offset:20480
	ds_read_b128 v[198:201], v146 offset:21504
	ds_read_b128 v[202:205], v146 offset:22528
	ds_read_b128 v[206:209], v146 offset:23552
	global_load_lds_dwordx4 v130, s[28:29]
	s_mov_b32 m0, s54
	s_nop 0
	global_load_lds_dwordx4 v128, s[28:29]
	s_waitcnt vmcnt(6)
	s_waitcnt lgkmcnt(0)
	s_barrier
	s_setprio 1
	v_mfma_f32_16x16x32_bf16 v[60:63], v[140:143], v[178:181], v[60:63]
	v_mfma_f32_16x16x32_bf16 v[56:59], v[170:173], v[178:181], v[56:59]
	v_mfma_f32_16x16x32_bf16 v[44:47], v[140:143], v[186:189], v[44:47]
	v_mfma_f32_16x16x32_bf16 v[40:43], v[170:173], v[186:189], v[40:43]
	v_mfma_f32_16x16x32_bf16 v[28:31], v[140:143], v[194:197], v[28:31]
	v_mfma_f32_16x16x32_bf16 v[24:27], v[170:173], v[194:197], v[24:27]
	v_mfma_f32_16x16x32_bf16 v[12:15], v[140:143], v[202:205], v[12:15]
	v_mfma_f32_16x16x32_bf16 v[8:11], v[170:173], v[202:205], v[8:11]
	v_mfma_f32_16x16x32_bf16 v[60:63], v[166:169], v[182:185], v[60:63]
	v_mfma_f32_16x16x32_bf16 v[56:59], v[174:177], v[182:185], v[56:59]
	v_mfma_f32_16x16x32_bf16 v[44:47], v[166:169], v[190:193], v[44:47]
	v_mfma_f32_16x16x32_bf16 v[40:43], v[174:177], v[190:193], v[40:43]
	v_mfma_f32_16x16x32_bf16 v[28:31], v[166:169], v[198:201], v[28:31]
	v_mfma_f32_16x16x32_bf16 v[24:27], v[174:177], v[198:201], v[24:27]
	v_mfma_f32_16x16x32_bf16 v[12:15], v[166:169], v[206:209], v[12:15]
	v_mfma_f32_16x16x32_bf16 v[8:11], v[174:177], v[206:209], v[8:11]
	s_setprio 0
	s_barrier
	s_add_u32 s14, s18, 0x44000
	s_addc_u32 s15, s19, 0
	s_mov_b32 m0, s55
	s_nop 0
	global_load_lds_dwordx4 v130, s[14:15]
	s_mov_b32 m0, s56
	s_nop 0
	global_load_lds_dwordx4 v128, s[14:15]
	ds_read_b128 v[140:143], v156
	ds_read_b128 v[166:169], v157
	ds_read_b128 v[170:173], v159
	ds_read_b128 v[174:177], v160
	s_add_u32 s14, s28, 0x44000
	s_addc_u32 s15, s29, 0
	s_mov_b32 m0, s57
	ds_read_b128 v[178:181], v146 offset:32768
	ds_read_b128 v[182:185], v146 offset:33792
	ds_read_b128 v[186:189], v146 offset:34816
	ds_read_b128 v[190:193], v146 offset:35840
	ds_read_b128 v[194:197], v146 offset:36864
	ds_read_b128 v[198:201], v146 offset:37888
	ds_read_b128 v[202:205], v146 offset:38912
	ds_read_b128 v[206:209], v146 offset:39936
	global_load_lds_dwordx4 v130, s[14:15]
	s_mov_b32 m0, s58
	s_nop 0
	global_load_lds_dwordx4 v128, s[14:15]
	s_waitcnt vmcnt(8)
	s_waitcnt lgkmcnt(0)
	s_barrier
	s_setprio 1
	v_mfma_f32_16x16x32_bf16 v[124:127], v[140:143], v[178:181], v[124:127]
	v_mfma_f32_16x16x32_bf16 v[120:123], v[170:173], v[178:181], v[120:123]
	v_mfma_f32_16x16x32_bf16 v[108:111], v[140:143], v[186:189], v[108:111]
	v_mfma_f32_16x16x32_bf16 v[104:107], v[170:173], v[186:189], v[104:107]
	v_mfma_f32_16x16x32_bf16 v[92:95], v[140:143], v[194:197], v[92:95]
	v_mfma_f32_16x16x32_bf16 v[88:91], v[170:173], v[194:197], v[88:91]
	v_mfma_f32_16x16x32_bf16 v[76:79], v[140:143], v[202:205], v[76:79]
	v_mfma_f32_16x16x32_bf16 v[72:75], v[170:173], v[202:205], v[72:75]
	v_mfma_f32_16x16x32_bf16 v[124:127], v[166:169], v[182:185], v[124:127]
	v_mfma_f32_16x16x32_bf16 v[120:123], v[174:177], v[182:185], v[120:123]
	v_mfma_f32_16x16x32_bf16 v[108:111], v[166:169], v[190:193], v[108:111]
	v_mfma_f32_16x16x32_bf16 v[104:107], v[174:177], v[190:193], v[104:107]
	v_mfma_f32_16x16x32_bf16 v[92:95], v[166:169], v[198:201], v[92:95]
	v_mfma_f32_16x16x32_bf16 v[88:91], v[174:177], v[198:201], v[88:91]
	v_mfma_f32_16x16x32_bf16 v[76:79], v[166:169], v[206:209], v[76:79]
	v_mfma_f32_16x16x32_bf16 v[72:75], v[174:177], v[206:209], v[72:75]
	s_setprio 0
	s_barrier
; #define PG8_STAGE(bufoff, gbase, voff) do { _Pragma("unroll") for (int _i = 0; _i < 2; ++_i) \
;         __builtin_amdgcn_global_load_lds((const unsigned*)((const char*)(gbase) + (voff)[_i]), (PG8_LAS unsigned*)(lds + (bufoff) + ldsw + _i * 8192), 16, 0, 0); } while (0)
; #define PG8_LDA(dst, b, h) do { _Pragma("unroll") for (int m = 0; m < 4; ++m) _Pragma("unroll") for (int k = 0; k < 2; ++k) dst[m][k] = *(const PG8_LAS bf16x8*)(lds + PG8_SA(b, h) + aoff + m * 2048 + k * 1024); } while (0)
; #define PG8_LDB(dst, b, h) do { _Pragma("unroll") for (int n = 0; n < 2; ++n) _Pragma("unroll") for (int k = 0; k < 2; ++k) dst[n][k] = *(const PG8_LAS bf16x8*)(lds + PG8_SB(b, h) + boff + n * 2048 + k * 1024); } while (0)
; #define PG8_MMA(ai, bj, At, Bt) do { __builtin_amdgcn_s_setprio(1); _Pragma("unroll") for (int m = 0; m < 4; ++m) _Pragma("unroll") for (int n = 0; n < 2; ++n) _Pragma("unroll") for (int k = 0; k < 2; ++k) \
;         acc[ai][bj][m][n] = __builtin_amdgcn_mfma_f32_16x16x32_bf16(Bt[n][k], At[m][k], acc[ai][bj][m][n], 0, 0, 0); __builtin_amdgcn_s_setprio(0); } while (0)
; #define PG8_WAIT_V(n) asm volatile("s_waitcnt vmcnt(" #n ")" ::: "memory")
; #define PG8_WAIT_L(n) asm volatile("s_waitcnt lgkmcnt(" #n ")" ::: "memory")
; #define PG8_BAR __builtin_amdgcn_s_barrier()
; #define PG8_SCHED __builtin_amdgcn_sched_barrier(0)
; template <class Epi, class Sched, bool STAMP = false>
; __device__ __forceinline__ void gemm_phase(PG8_LAS unsigned char* lds, const Gemm g, const Sched& S, const Epi& E, unsigned long long* stamps) {
;     ...
;             PG8_LDB(B1, 1, 1); PG8_STAGE(PG8_SB(1, 0), b3, voffB);
;             PG8_BAR; PG8_WAIT_L(0); PG8_MMA(0, 1, At, B1); PG8_BAR;
;             PG8_LDA(At, 1, 1); PG8_STAGE(PG8_SA(1, 0), a3, voffA);
;             PG8_BAR; PG8_WAIT_L(0); PG8_MMA(1, 0, At, B0); PG8_BAR; PG8_SCHED;
;             PG8_STAGE(PG8_SB(1, 1), b3 + hstep, voffB);
;             PG8_WAIT_V(6); PG8_BAR; PG8_MMA(1, 1, At, B1); PG8_BAR;
	s_mov_b32 m0, s61
	s_add_u32 s100, s18, 0x80
	s_addc_u32 s101, s19, 0
	global_load_lds_dwordx4 v130, s[100:101]
	s_mov_b32 m0, s62
	s_nop 0
	global_load_lds_dwordx4 v128, s[100:101]
	s_mov_b32 m0, s63
	ds_read_b128 v[178:181], v146 offset:49152
	ds_read_b128 v[182:185], v146 offset:50176
	ds_read_b128 v[186:189], v146 offset:51200
	ds_read_b128 v[190:193], v146 offset:52224
	ds_read_b128 v[194:197], v146 offset:53248
	ds_read_b128 v[198:201], v146 offset:54272
	ds_read_b128 v[202:205], v146 offset:55296
	ds_read_b128 v[206:209], v146 offset:56320
	s_add_u32 s100, s28, 0x80
	s_addc_u32 s101, s29, 0
	global_load_lds_dwordx4 v130, s[100:101]
	s_mov_b32 m0, s64
	s_nop 0
	global_load_lds_dwordx4 v128, s[100:101]
	s_waitcnt vmcnt(6)
	s_waitcnt lgkmcnt(0)
	s_barrier
	s_setprio 1
	v_mfma_f32_16x16x32_bf16 v[60:63], v[140:143], v[178:181], v[60:63]
	v_mfma_f32_16x16x32_bf16 v[56:59], v[170:173], v[178:181], v[56:59]
	v_mfma_f32_16x16x32_bf16 v[44:47], v[140:143], v[186:189], v[44:47]
	v_mfma_f32_16x16x32_bf16 v[40:43], v[170:173], v[186:189], v[40:43]
	v_mfma_f32_16x16x32_bf16 v[28:31], v[140:143], v[194:197], v[28:31]
	v_mfma_f32_16x16x32_bf16 v[24:27], v[170:173], v[194:197], v[24:27]
	v_mfma_f32_16x16x32_bf16 v[12:15], v[140:143], v[202:205], v[12:15]
	v_mfma_f32_16x16x32_bf16 v[8:11], v[170:173], v[202:205], v[8:11]
	v_mfma_f32_16x16x32_bf16 v[60:63], v[166:169], v[182:185], v[60:63]
	v_mfma_f32_16x16x32_bf16 v[56:59], v[174:177], v[182:185], v[56:59]
	v_mfma_f32_16x16x32_bf16 v[44:47], v[166:169], v[190:193], v[44:47]
	v_mfma_f32_16x16x32_bf16 v[40:43], v[174:177], v[190:193], v[40:43]
	v_mfma_f32_16x16x32_bf16 v[28:31], v[166:169], v[198:201], v[28:31]
	v_mfma_f32_16x16x32_bf16 v[24:27], v[174:177], v[198:201], v[24:27]
	v_mfma_f32_16x16x32_bf16 v[12:15], v[166:169], v[206:209], v[12:15]
	v_mfma_f32_16x16x32_bf16 v[8:11], v[174:177], v[206:209], v[8:11]
	s_setprio 0
	s_add_i32 s77, s77, 2
	s_add_u32 s75, s75, 0x100
	s_addc_u32 s76, s76, 0
	s_cmp_gt_u32 s77, 13
	s_mov_b64 s[14:15], s[16:17]
	s_barrier
	s_cbranch_scc0 .Lgu1_half_loop
; DI float ex2(float x) { return __builtin_amdgcn_exp2f(x); }
;     DI void operator()(const f32x4 (&acc)[2][2][4][2], const Unit& u, int wr, int wc, int fr, int fq) const {
;         const int row0 = u.pm * BM + wr * 64 + fr, hcol0 = ((u.pn * BM + wc * 32) >> 1) + 4 * fq;
; #pragma unroll
;         for (int ai = 0; ai < 2; ++ai)
; #pragma unroll
;             for (int m = 0; m < 4; ++m) { u16* rowp = O + (size_t)(row0 + ai * HALF + m * 16) * ldc + hcol0;
; #pragma unroll
;                 for (int bj = 0; bj < 2; ++bj) { const f32x4 g = acc[ai][bj][m][0], up = acc[ai][bj][m][1]; float r[4];
; #pragma unroll
;                     for (int j = 0; j < 4; ++j) r[j] = g[j] * up[j] * __builtin_amdgcn_rcpf(1.f + ex2(-LOG2E * g[j]));
;                     uint2 w = {pack2(r[0], r[1]), pack2(r[2], r[3])}; *(uint2*)(rowp + bj * (HALF / 2)) = w; } }
;     }
	v_exp_f32_e64 v168, -v124
	v_exp_f32_e64 v169, -v125
	v_exp_f32_e64 v170, -v126
	v_exp_f32_e64 v171, -v127
	v_add_f32_e32 v168, 1.0, v168
	v_add_f32_e32 v169, 1.0, v169
	v_add_f32_e32 v170, 1.0, v170
	v_add_f32_e32 v171, 1.0, v171
	v_rcp_f32_e32 v168, v168
	v_rcp_f32_e32 v169, v169
	v_rcp_f32_e32 v170, v170
	v_rcp_f32_e32 v171, v171
	s_lshl_b32 s10, s74, 8
	v_pk_mul_f32 v[122:123], v[126:127], v[122:123]
	v_pk_mul_f32 v[120:121], v[124:125], v[120:121]
	s_or_b32 s10, s10, s60
	s_or_b32 s10, s10, s98
	v_pk_mul_f32 v[120:121], v[120:121], v[168:169]
	v_pk_mul_f32 v[122:123], v[122:123], v[170:171]
	s_ashr_i32 s10, s10, 1
	v_cvt_pk_bf16_f32 v120, v120, v121
	v_cvt_pk_bf16_f32 v121, v122, v123
	v_or_b32_e32 v140, s10, v147
	v_lshl_add_u32 v165, s73, 8, v145
	v_ashrrev_i32_e32 v141, 31, v140
	v_mov_b64_e32 v[142:143], s[12:13]
	v_mad_i64_i32 v[166:167], s[14:15], v165, s70, v[142:143]
	v_lshlrev_b64 v[140:141], 1, v[140:141]
	v_lshl_add_u64 v[166:167], v[166:167], 0, v[140:141]
	global_store_dwordx2 v[166:167], v[120:121], off
	v_exp_f32_e64 v114, -v108
	v_exp_f32_e64 v115, -v109
	v_exp_f32_e64 v116, -v110
	v_exp_f32_e64 v117, -v111
	v_add_f32_e32 v114, 1.0, v114
	v_add_f32_e32 v115, 1.0, v115
	v_add_f32_e32 v116, 1.0, v116
	v_add_f32_e32 v117, 1.0, v117
	v_rcp_f32_e32 v114, v114
	v_rcp_f32_e32 v115, v115
	v_rcp_f32_e32 v116, v116
	v_rcp_f32_e32 v117, v117
	v_pk_mul_f32 v[106:107], v[110:111], v[106:107]
	v_pk_mul_f32 v[104:105], v[108:109], v[104:105]
	v_pk_mul_f32 v[104:105], v[104:105], v[114:115]
	v_pk_mul_f32 v[106:107], v[106:107], v[116:117]
	v_cvt_pk_bf16_f32 v104, v104, v105
	v_cvt_pk_bf16_f32 v105, v106, v107
	v_or_b32_e32 v112, 16, v165
	v_mad_i64_i32 v[112:113], s[14:15], v112, s70, v[142:143]
	v_lshl_add_u64 v[112:113], v[112:113], 0, v[140:141]
	global_store_dwordx2 v[112:113], v[104:105], off
	v_exp_f32_e64 v98, -v92
	v_exp_f32_e64 v99, -v93
	v_exp_f32_e64 v100, -v94
	v_exp_f32_e64 v101, -v95
	v_add_f32_e32 v98, 1.0, v98
	v_add_f32_e32 v99, 1.0, v99
	v_add_f32_e32 v100, 1.0, v100
	v_add_f32_e32 v101, 1.0, v101
	v_rcp_f32_e32 v98, v98
	v_rcp_f32_e32 v99, v99
	v_rcp_f32_e32 v100, v100
	v_rcp_f32_e32 v101, v101
	v_pk_mul_f32 v[90:91], v[94:95], v[90:91]
	v_pk_mul_f32 v[88:89], v[92:93], v[88:89]
	v_pk_mul_f32 v[88:89], v[88:89], v[98:99]
	v_pk_mul_f32 v[90:91], v[90:91], v[100:101]
	v_cvt_pk_bf16_f32 v88, v88, v89
	v_cvt_pk_bf16_f32 v89, v90, v91
	v_or_b32_e32 v96, 32, v165
	v_mad_i64_i32 v[96:97], s[14:15], v96, s70, v[142:143]
	v_lshl_add_u64 v[96:97], v[96:97], 0, v[140:141]
	global_store_dwordx2 v[96:97], v[88:89], off
	v_exp_f32_e64 v82, -v76
	v_exp_f32_e64 v83, -v77
	v_exp_f32_e64 v84, -v78
	v_exp_f32_e64 v85, -v79
	v_add_f32_e32 v82, 1.0, v82
	v_add_f32_e32 v83, 1.0, v83
	v_add_f32_e32 v84, 1.0, v84
	v_add_f32_e32 v85, 1.0, v85
	v_rcp_f32_e32 v82, v82
	v_rcp_f32_e32 v83, v83
	v_rcp_f32_e32 v84, v84
	v_rcp_f32_e32 v85, v85
	v_pk_mul_f32 v[74:75], v[78:79], v[74:75]
	v_pk_mul_f32 v[72:73], v[76:77], v[72:73]
	v_pk_mul_f32 v[72:73], v[72:73], v[82:83]
	v_pk_mul_f32 v[74:75], v[74:75], v[84:85]
	v_cvt_pk_bf16_f32 v72, v72, v73
	v_cvt_pk_bf16_f32 v73, v74, v75
	v_or_b32_e32 v80, 48, v165
	v_mad_i64_i32 v[80:81], s[14:15], v80, s70, v[142:143]
	v_lshl_add_u64 v[80:81], v[80:81], 0, v[140:141]
	global_store_dwordx2 v[80:81], v[72:73], off
	v_exp_f32_e64 v66, -v60
	v_exp_f32_e64 v67, -v61
	v_exp_f32_e64 v68, -v62
	v_exp_f32_e64 v69, -v63
	v_add_f32_e32 v66, 1.0, v66
	v_add_f32_e32 v67, 1.0, v67
	v_add_f32_e32 v68, 1.0, v68
	v_add_f32_e32 v69, 1.0, v69
	v_rcp_f32_e32 v66, v66
	v_rcp_f32_e32 v67, v67
	v_rcp_f32_e32 v68, v68
	v_rcp_f32_e32 v69, v69
	v_pk_mul_f32 v[58:59], v[62:63], v[58:59]
	v_pk_mul_f32 v[56:57], v[60:61], v[56:57]
	v_pk_mul_f32 v[56:57], v[56:57], v[66:67]
	v_pk_mul_f32 v[58:59], v[58:59], v[68:69]
	v_cvt_pk_bf16_f32 v56, v56, v57
	v_cvt_pk_bf16_f32 v57, v58, v59
	v_add_u32_e32 v64, 0x80, v165
	v_mad_i64_i32 v[64:65], s[14:15], v64, s70, v[142:143]
	v_lshl_add_u64 v[64:65], v[64:65], 0, v[140:141]
	global_store_dwordx2 v[64:65], v[56:57], off
	v_exp_f32_e64 v50, -v44
	v_exp_f32_e64 v51, -v45
	v_exp_f32_e64 v52, -v46
	v_exp_f32_e64 v53, -v47
	v_add_f32_e32 v50, 1.0, v50
	v_add_f32_e32 v51, 1.0, v51
	v_add_f32_e32 v52, 1.0, v52
	v_add_f32_e32 v53, 1.0, v53
	v_rcp_f32_e32 v50, v50
	v_rcp_f32_e32 v51, v51
	v_rcp_f32_e32 v52, v52
	v_rcp_f32_e32 v53, v53
	v_pk_mul_f32 v[42:43], v[46:47], v[42:43]
	v_pk_mul_f32 v[40:41], v[44:45], v[40:41]
	v_pk_mul_f32 v[40:41], v[40:41], v[50:51]
	v_pk_mul_f32 v[42:43], v[42:43], v[52:53]
	v_cvt_pk_bf16_f32 v40, v40, v41
	v_cvt_pk_bf16_f32 v41, v42, v43
	v_add_u32_e32 v48, 0x90, v165
	v_mad_i64_i32 v[48:49], s[14:15], v48, s70, v[142:143]
	v_lshl_add_u64 v[48:49], v[48:49], 0, v[140:141]
	global_store_dwordx2 v[48:49], v[40:41], off
	v_exp_f32_e64 v34, -v28
	v_exp_f32_e64 v35, -v29
	v_exp_f32_e64 v36, -v30
	v_exp_f32_e64 v37, -v31
	v_add_f32_e32 v34, 1.0, v34
	v_add_f32_e32 v35, 1.0, v35
	v_add_f32_e32 v36, 1.0, v36
	v_add_f32_e32 v37, 1.0, v37
	v_rcp_f32_e32 v34, v34
	v_rcp_f32_e32 v35, v35
	v_rcp_f32_e32 v36, v36
	v_rcp_f32_e32 v37, v37
	v_pk_mul_f32 v[26:27], v[30:31], v[26:27]
	v_pk_mul_f32 v[24:25], v[28:29], v[24:25]
	v_pk_mul_f32 v[24:25], v[24:25], v[34:35]
	v_pk_mul_f32 v[26:27], v[26:27], v[36:37]
	v_cvt_pk_bf16_f32 v24, v24, v25
	v_cvt_pk_bf16_f32 v25, v26, v27
	v_add_u32_e32 v32, 0xa0, v165
	v_mad_i64_i32 v[32:33], s[14:15], v32, s70, v[142:143]
	v_lshl_add_u64 v[32:33], v[32:33], 0, v[140:141]
	global_store_dwordx2 v[32:33], v[24:25], off
	v_exp_f32_e64 v18, -v12
	v_exp_f32_e64 v19, -v13
	v_exp_f32_e64 v20, -v14
	v_exp_f32_e64 v21, -v15
	v_add_f32_e32 v18, 1.0, v18
	v_add_f32_e32 v19, 1.0, v19
	v_add_f32_e32 v20, 1.0, v20
	v_add_f32_e32 v21, 1.0, v21
	v_rcp_f32_e32 v18, v18
	v_rcp_f32_e32 v19, v19
	v_rcp_f32_e32 v20, v20
	v_rcp_f32_e32 v21, v21
	v_pk_mul_f32 v[10:11], v[14:15], v[10:11]
	v_pk_mul_f32 v[8:9], v[12:13], v[8:9]
	v_pk_mul_f32 v[8:9], v[8:9], v[18:19]
	v_pk_mul_f32 v[10:11], v[10:11], v[20:21]
	v_cvt_pk_bf16_f32 v8, v8, v9
	v_cvt_pk_bf16_f32 v9, v10, v11
	v_add_u32_e32 v16, 0xb0, v165
	v_mad_i64_i32 v[16:17], s[14:15], v16, s70, v[142:143]
	v_lshl_add_u64 v[16:17], v[16:17], 0, v[140:141]
	global_store_dwordx2 v[16:17], v[8:9], off
	s_and_b64 vcc, exec, s[2:3]
	s_mov_b32 s74, s71
	s_mov_b32 s73, s72
	s_mov_b64 s[16:17], s[0:1]
	s_mov_b64 s[14:15], s[4:5]

; #define PG8_STAGE(bufoff, gbase, voff) do { _Pragma("unroll") for (int _i = 0; _i < 2; ++_i) \
;         __builtin_amdgcn_global_load_lds((const unsigned*)((const char*)(gbase) + (voff)[_i]), (PG8_LAS unsigned*)(lds + (bufoff) + ldsw + _i * 8192), 16, 0, 0); } while (0)
; #define PG8_LDA(dst, b, h) do { _Pragma("unroll") for (int m = 0; m < 4; ++m) _Pragma("unroll") for (int k = 0; k < 2; ++k) dst[m][k] = *(const PG8_LAS bf16x8*)(lds + PG8_SA(b, h) + aoff + m * 2048 + k * 1024); } while (0)
; template <class Epi, class Sched, bool STAMP = false>
; __device__ __forceinline__ void gemm_phase(PG8_LAS unsigned char* lds, const Gemm g, const Sched& S, const Epi& E, unsigned long long* stamps) {
;     ...
;         for (int t = 0; t < nt; t += 2) {
;             const bool last = (t == nt - 2);
;             const char* a1 = cA + (size_t)(t + 1) * kstep;
;             const char* a2 = last ? nA : cA + (size_t)(t + 2) * kstep; const char* b2 = last ? nB : cB + (size_t)(t + 2) * kstep;
;             const char* a3 = a2 + kstep; const char* b3 = b2 + kstep;
;             if (last && has_next) S.a_ready(nxt);
;             PG8_LDB(B0, 0, 0); PG8_SCHED; PG8_LDA(At, 0, 0); PG8_STAGE(PG8_SA(1, 1), a1 + hstep, voffA);
;             PG8_WAIT_L(8); PG8_BAR; PG8_WAIT_L(0); PG8_MMA(0, 0, At, B0); PG8_BAR; PG8_SCHED;
;             PG8_LDB(B1, 0, 1); PG8_STAGE(PG8_SB(0, 0), b2, voffB);
;             PG8_BAR; PG8_WAIT_L(0); PG8_MMA(0, 1, At, B1); PG8_BAR;
;             PG8_LDA(At, 0, 1); PG8_STAGE(PG8_SA(0, 0), a2, voffA);
;             PG8_BAR; PG8_WAIT_L(0); PG8_MMA(1, 0, At, B0); PG8_BAR; PG8_SCHED;
;             PG8_STAGE(PG8_SB(0, 1), b2 + hstep, voffB);
;             PG8_WAIT_V(6); PG8_BAR; PG8_MMA(1, 1, At, B1); PG8_BAR;
;             PG8_LDB(B0, 1, 0); PG8_SCHED; PG8_LDA(At, 1, 0); PG8_STAGE(PG8_SA(0, 1), a2 + hstep, voffA);
;             PG8_WAIT_L(8); PG8_BAR; PG8_WAIT_L(0); PG8_MMA(0, 0, At, B0); PG8_BAR; PG8_SCHED;
;             PG8_LDB(B1, 1, 1); PG8_STAGE(PG8_SB(1, 0), b3, voffB);
;             PG8_BAR; PG8_WAIT_L(0); PG8_MMA(0, 1, At, B1); PG8_BAR;
;             PG8_LDA(At, 1, 1); PG8_STAGE(PG8_SA(1, 0), a3, voffA);
;             PG8_BAR; PG8_WAIT_L(0); PG8_MMA(1, 0, At, B0); PG8_BAR; PG8_SCHED;
;             PG8_STAGE(PG8_SB(1, 1), b3 + hstep, voffB);
;             PG8_WAIT_V(6); PG8_BAR; PG8_MMA(1, 1, At, B1); PG8_BAR;
;         }
.LBB0_96:
	s_add_u32 s88, s52, 0x100
	s_addc_u32 s89, s53, 0
	s_mov_b32 s90, -2
	s_add_u32 s100, s88, 0xb3f80
	s_addc_u32 s101, s89, 0
	s_mov_b32 m0, s72
	s_nop 0
	global_load_lds_dwordx4 v130, s[100:101]
	s_mov_b32 m0, s73
	s_nop 0
	global_load_lds_dwordx4 v134, s[100:101]
	ds_read_b128 v[166:169], v148
	ds_read_b128 v[170:173], v149
	ds_read_b128 v[174:177], v150
	ds_read_b128 v[178:181], v151
	s_add_u32 s52, s34, 0x100
	s_addc_u32 s53, s35, 0
	s_cmp_eq_u32 s90, 40
	s_cselect_b32 s57, s5, s53
	s_cselect_b32 s56, s4, s52
	s_cselect_b32 s55, s1, s89
	s_cselect_b32 s54, s0, s88
	s_mov_b32 m0, s76
	ds_read_b128 v[182:185], v146
	ds_read_b128 v[186:189], v146 offset:1024
	ds_read_b128 v[190:193], v146 offset:2048
	ds_read_b128 v[194:197], v146 offset:3072
	ds_read_b128 v[198:201], v146 offset:4096
	ds_read_b128 v[202:205], v146 offset:5120
	ds_read_b128 v[206:209], v146 offset:6144
	ds_read_b128 v[210:213], v146 offset:7168
	global_load_lds_dwordx4 v136, s[34:35]
	s_mov_b32 m0, s77
	s_nop 0
	global_load_lds_dwordx4 v138, s[34:35]
	ds_read_b128 v[214:217], v152
	ds_read_b128 v[218:221], v153
	ds_read_b128 v[222:225], v154
	ds_read_b128 v[226:229], v155
	s_waitcnt vmcnt(8)
	s_waitcnt lgkmcnt(0)
	s_barrier
	s_setprio 1
	v_mfma_f32_16x16x32_bf16 v[124:127], v[166:169], v[182:185], 0
	v_mfma_f32_16x16x32_bf16 v[120:123], v[174:177], v[182:185], 0
	v_mfma_f32_16x16x32_bf16 v[116:119], v[166:169], v[190:193], 0
	v_mfma_f32_16x16x32_bf16 v[112:115], v[174:177], v[190:193], 0
	v_mfma_f32_16x16x32_bf16 v[100:103], v[166:169], v[198:201], 0
	v_mfma_f32_16x16x32_bf16 v[96:99], v[174:177], v[198:201], 0
	v_mfma_f32_16x16x32_bf16 v[84:87], v[166:169], v[206:209], 0
	v_mfma_f32_16x16x32_bf16 v[80:83], v[174:177], v[206:209], 0
	v_mfma_f32_16x16x32_bf16 v[124:127], v[170:173], v[186:189], v[124:127]
	v_mfma_f32_16x16x32_bf16 v[120:123], v[178:181], v[186:189], v[120:123]
	v_mfma_f32_16x16x32_bf16 v[116:119], v[170:173], v[194:197], v[116:119]
	v_mfma_f32_16x16x32_bf16 v[112:115], v[178:181], v[194:197], v[112:115]
	v_mfma_f32_16x16x32_bf16 v[100:103], v[170:173], v[202:205], v[100:103]
	v_mfma_f32_16x16x32_bf16 v[96:99], v[178:181], v[202:205], v[96:99]
	v_mfma_f32_16x16x32_bf16 v[84:87], v[170:173], v[210:213], v[84:87]
	v_mfma_f32_16x16x32_bf16 v[80:83], v[178:181], v[210:213], v[80:83]
	v_mfma_f32_16x16x32_bf16 v[108:111], v[214:217], v[182:185], 0
	v_mfma_f32_16x16x32_bf16 v[104:107], v[222:225], v[182:185], 0
	v_mfma_f32_16x16x32_bf16 v[92:95], v[214:217], v[190:193], 0
	v_mfma_f32_16x16x32_bf16 v[88:91], v[222:225], v[190:193], 0
	v_mfma_f32_16x16x32_bf16 v[76:79], v[214:217], v[198:201], 0
	v_mfma_f32_16x16x32_bf16 v[72:75], v[222:225], v[198:201], 0
	v_mfma_f32_16x16x32_bf16 v[68:71], v[214:217], v[206:209], 0
	v_mfma_f32_16x16x32_bf16 v[64:67], v[222:225], v[206:209], 0
	v_mfma_f32_16x16x32_bf16 v[108:111], v[218:221], v[186:189], v[108:111]
	v_mfma_f32_16x16x32_bf16 v[104:107], v[226:229], v[186:189], v[104:107]
	v_mfma_f32_16x16x32_bf16 v[92:95], v[218:221], v[194:197], v[92:95]
	v_mfma_f32_16x16x32_bf16 v[88:91], v[226:229], v[194:197], v[88:91]
	v_mfma_f32_16x16x32_bf16 v[76:79], v[218:221], v[202:205], v[76:79]
	v_mfma_f32_16x16x32_bf16 v[72:75], v[226:229], v[202:205], v[72:75]
	v_mfma_f32_16x16x32_bf16 v[68:71], v[218:221], v[210:213], v[68:71]
	v_mfma_f32_16x16x32_bf16 v[64:67], v[226:229], v[210:213], v[64:67]
	s_setprio 0
	s_barrier
	s_mov_b32 m0, s61
	s_nop 0
	global_load_lds_dwordx4 v130, s[54:55]
	s_mov_b32 m0, s62
	s_nop 0
	global_load_lds_dwordx4 v134, s[54:55]
	s_mov_b32 m0, s60
	ds_read_b128 v[182:185], v146 offset:16384
	ds_read_b128 v[186:189], v146 offset:17408
	ds_read_b128 v[190:193], v146 offset:18432
	ds_read_b128 v[194:197], v146 offset:19456
	ds_read_b128 v[198:201], v146 offset:20480
	ds_read_b128 v[202:205], v146 offset:21504
	ds_read_b128 v[206:209], v146 offset:22528
	ds_read_b128 v[210:213], v146 offset:23552
	global_load_lds_dwordx4 v128, s[56:57]
	s_mov_b32 m0, s63
	s_nop 0
	global_load_lds_dwordx4 v132, s[56:57]
	s_waitcnt vmcnt(6)
	s_waitcnt lgkmcnt(0)
	s_barrier
	s_setprio 1
	v_mfma_f32_16x16x32_bf16 v[60:63], v[166:169], v[182:185], 0
	v_mfma_f32_16x16x32_bf16 v[56:59], v[174:177], v[182:185], 0
	v_mfma_f32_16x16x32_bf16 v[52:55], v[166:169], v[190:193], 0
	v_mfma_f32_16x16x32_bf16 v[48:51], v[174:177], v[190:193], 0
	v_mfma_f32_16x16x32_bf16 v[36:39], v[166:169], v[198:201], 0
	v_mfma_f32_16x16x32_bf16 v[32:35], v[174:177], v[198:201], 0
	v_mfma_f32_16x16x32_bf16 v[20:23], v[166:169], v[206:209], 0
	v_mfma_f32_16x16x32_bf16 v[16:19], v[174:177], v[206:209], 0
	v_mfma_f32_16x16x32_bf16 v[60:63], v[170:173], v[186:189], v[60:63]
	v_mfma_f32_16x16x32_bf16 v[56:59], v[178:181], v[186:189], v[56:59]
	v_mfma_f32_16x16x32_bf16 v[52:55], v[170:173], v[194:197], v[52:55]
	v_mfma_f32_16x16x32_bf16 v[48:51], v[178:181], v[194:197], v[48:51]
	v_mfma_f32_16x16x32_bf16 v[36:39], v[170:173], v[202:205], v[36:39]
	v_mfma_f32_16x16x32_bf16 v[32:35], v[178:181], v[202:205], v[32:35]
	v_mfma_f32_16x16x32_bf16 v[20:23], v[170:173], v[210:213], v[20:23]
	v_mfma_f32_16x16x32_bf16 v[16:19], v[178:181], v[210:213], v[16:19]
	v_mfma_f32_16x16x32_bf16 v[44:47], v[214:217], v[182:185], 0
	v_mfma_f32_16x16x32_bf16 v[40:43], v[222:225], v[182:185], 0
	v_mfma_f32_16x16x32_bf16 v[28:31], v[214:217], v[190:193], 0
	v_mfma_f32_16x16x32_bf16 v[24:27], v[222:225], v[190:193], 0
	v_mfma_f32_16x16x32_bf16 v[12:15], v[214:217], v[198:201], 0
	v_mfma_f32_16x16x32_bf16 v[8:11], v[222:225], v[198:201], 0
	v_mfma_f32_16x16x32_bf16 v[4:7], v[214:217], v[206:209], 0
	v_mfma_f32_16x16x32_bf16 v[0:3], v[222:225], v[206:209], 0
	v_mfma_f32_16x16x32_bf16 v[44:47], v[218:221], v[186:189], v[44:47]
	v_mfma_f32_16x16x32_bf16 v[40:43], v[226:229], v[186:189], v[40:43]
	v_mfma_f32_16x16x32_bf16 v[28:31], v[218:221], v[194:197], v[28:31]
	v_mfma_f32_16x16x32_bf16 v[24:27], v[226:229], v[194:197], v[24:27]
	v_mfma_f32_16x16x32_bf16 v[12:15], v[218:221], v[202:205], v[12:15]
	v_mfma_f32_16x16x32_bf16 v[8:11], v[226:229], v[202:205], v[8:11]
	v_mfma_f32_16x16x32_bf16 v[4:7], v[218:221], v[210:213], v[4:7]
	v_mfma_f32_16x16x32_bf16 v[0:3], v[226:229], v[210:213], v[0:3]
	s_setprio 0
	s_barrier
	s_branch .Lzp2_mid
; #define PG8_STAGE(bufoff, gbase, voff) do { _Pragma("unroll") for (int _i = 0; _i < 2; ++_i) \
;         __builtin_amdgcn_global_load_lds((const unsigned*)((const char*)(gbase) + (voff)[_i]), (PG8_LAS unsigned*)(lds + (bufoff) + ldsw + _i * 8192), 16, 0, 0); } while (0)
; #define PG8_LDA(dst, b, h) do { _Pragma("unroll") for (int m = 0; m < 4; ++m) _Pragma("unroll") for (int k = 0; k < 2; ++k) dst[m][k] = *(const PG8_LAS bf16x8*)(lds + PG8_SA(b, h) + aoff + m * 2048 + k * 1024); } while (0)
; template <class Epi, class Sched, bool STAMP = false>
; __device__ __forceinline__ void gemm_phase(PG8_LAS unsigned char* lds, const Gemm g, const Sched& S, const Epi& E, unsigned long long* stamps) {
;     ...
;         for (int t = 0; t < nt; t += 2) {
;             const bool last = (t == nt - 2);
;             const char* a1 = cA + (size_t)(t + 1) * kstep;
;             const char* a2 = last ? nA : cA + (size_t)(t + 2) * kstep; const char* b2 = last ? nB : cB + (size_t)(t + 2) * kstep;
;             const char* a3 = a2 + kstep; const char* b3 = b2 + kstep;
;             if (last && has_next) S.a_ready(nxt);
;             PG8_LDB(B0, 0, 0); PG8_SCHED; PG8_LDA(At, 0, 0); PG8_STAGE(PG8_SA(1, 1), a1 + hstep, voffA);
;             PG8_WAIT_L(8); PG8_BAR; PG8_WAIT_L(0); PG8_MMA(0, 0, At, B0); PG8_BAR; PG8_SCHED;
;             PG8_LDB(B1, 0, 1); PG8_STAGE(PG8_SB(0, 0), b2, voffB);
;             PG8_BAR; PG8_WAIT_L(0); PG8_MMA(0, 1, At, B1); PG8_BAR;
;             PG8_LDA(At, 0, 1); PG8_STAGE(PG8_SA(0, 0), a2, voffA);
;             PG8_BAR; PG8_WAIT_L(0); PG8_MMA(1, 0, At, B0); PG8_BAR; PG8_SCHED;
;             PG8_STAGE(PG8_SB(0, 1), b2 + hstep, voffB);
;             PG8_WAIT_V(6); PG8_BAR; PG8_MMA(1, 1, At, B1); PG8_BAR;
;             PG8_LDB(B0, 1, 0); PG8_SCHED; PG8_LDA(At, 1, 0); PG8_STAGE(PG8_SA(0, 1), a2 + hstep, voffA);
;             PG8_WAIT_L(8); PG8_BAR; PG8_WAIT_L(0); PG8_MMA(0, 0, At, B0); PG8_BAR; PG8_SCHED;
;             PG8_LDB(B1, 1, 1); PG8_STAGE(PG8_SB(1, 0), b3, voffB);
;             PG8_BAR; PG8_WAIT_L(0); PG8_MMA(0, 1, At, B1); PG8_BAR;
;             PG8_LDA(At, 1, 1); PG8_STAGE(PG8_SA(1, 0), a3, voffA);
;             PG8_BAR; PG8_WAIT_L(0); PG8_MMA(1, 0, At, B0); PG8_BAR; PG8_SCHED;
;             PG8_STAGE(PG8_SB(1, 1), b3 + hstep, voffB);
;             PG8_WAIT_V(6); PG8_BAR; PG8_MMA(1, 1, At, B1); PG8_BAR;
;         }
.LBB0_97:
	s_add_u32 s100, s88, 0xb3f80
	s_addc_u32 s101, s89, 0
	s_mov_b32 m0, s72
	s_nop 0
	global_load_lds_dwordx4 v130, s[100:101]
	s_mov_b32 m0, s73
	s_nop 0
	global_load_lds_dwordx4 v134, s[100:101]
	ds_read_b128 v[166:169], v148
	ds_read_b128 v[170:173], v149
	ds_read_b128 v[174:177], v150
	ds_read_b128 v[178:181], v151
	s_add_u32 s52, s34, 0x100
	s_addc_u32 s53, s35, 0
	s_cmp_eq_u32 s90, 40
	s_cselect_b32 s57, s5, s53
	s_cselect_b32 s56, s4, s52
	s_cselect_b32 s55, s1, s89
	s_cselect_b32 s54, s0, s88
	s_mov_b32 m0, s76
	ds_read_b128 v[182:185], v146
	ds_read_b128 v[186:189], v146 offset:1024
	ds_read_b128 v[190:193], v146 offset:2048
	ds_read_b128 v[194:197], v146 offset:3072
	ds_read_b128 v[198:201], v146 offset:4096
	ds_read_b128 v[202:205], v146 offset:5120
	ds_read_b128 v[206:209], v146 offset:6144
	ds_read_b128 v[210:213], v146 offset:7168
	global_load_lds_dwordx4 v136, s[34:35]
	s_mov_b32 m0, s77
	s_nop 0
	global_load_lds_dwordx4 v138, s[34:35]
	ds_read_b128 v[214:217], v152
	ds_read_b128 v[218:221], v153
	ds_read_b128 v[222:225], v154
	ds_read_b128 v[226:229], v155
	s_waitcnt vmcnt(8)
	s_waitcnt lgkmcnt(0)
	s_barrier
	s_setprio 1
	v_mfma_f32_16x16x32_bf16 v[124:127], v[166:169], v[182:185], v[124:127]
	v_mfma_f32_16x16x32_bf16 v[120:123], v[174:177], v[182:185], v[120:123]
	v_mfma_f32_16x16x32_bf16 v[116:119], v[166:169], v[190:193], v[116:119]
	v_mfma_f32_16x16x32_bf16 v[112:115], v[174:177], v[190:193], v[112:115]
	v_mfma_f32_16x16x32_bf16 v[100:103], v[166:169], v[198:201], v[100:103]
	v_mfma_f32_16x16x32_bf16 v[96:99], v[174:177], v[198:201], v[96:99]
	v_mfma_f32_16x16x32_bf16 v[84:87], v[166:169], v[206:209], v[84:87]
	v_mfma_f32_16x16x32_bf16 v[80:83], v[174:177], v[206:209], v[80:83]
	v_mfma_f32_16x16x32_bf16 v[124:127], v[170:173], v[186:189], v[124:127]
	v_mfma_f32_16x16x32_bf16 v[120:123], v[178:181], v[186:189], v[120:123]
	v_mfma_f32_16x16x32_bf16 v[116:119], v[170:173], v[194:197], v[116:119]
	v_mfma_f32_16x16x32_bf16 v[112:115], v[178:181], v[194:197], v[112:115]
	v_mfma_f32_16x16x32_bf16 v[100:103], v[170:173], v[202:205], v[100:103]
	v_mfma_f32_16x16x32_bf16 v[96:99], v[178:181], v[202:205], v[96:99]
	v_mfma_f32_16x16x32_bf16 v[84:87], v[170:173], v[210:213], v[84:87]
	v_mfma_f32_16x16x32_bf16 v[80:83], v[178:181], v[210:213], v[80:83]
	v_mfma_f32_16x16x32_bf16 v[108:111], v[214:217], v[182:185], v[108:111]
	v_mfma_f32_16x16x32_bf16 v[104:107], v[222:225], v[182:185], v[104:107]
	v_mfma_f32_16x16x32_bf16 v[92:95], v[214:217], v[190:193], v[92:95]
	v_mfma_f32_16x16x32_bf16 v[88:91], v[222:225], v[190:193], v[88:91]
	v_mfma_f32_16x16x32_bf16 v[76:79], v[214:217], v[198:201], v[76:79]
	v_mfma_f32_16x16x32_bf16 v[72:75], v[222:225], v[198:201], v[72:75]
	v_mfma_f32_16x16x32_bf16 v[68:71], v[214:217], v[206:209], v[68:71]
	v_mfma_f32_16x16x32_bf16 v[64:67], v[222:225], v[206:209], v[64:67]
	v_mfma_f32_16x16x32_bf16 v[108:111], v[218:221], v[186:189], v[108:111]
	v_mfma_f32_16x16x32_bf16 v[104:107], v[226:229], v[186:189], v[104:107]
	v_mfma_f32_16x16x32_bf16 v[92:95], v[218:221], v[194:197], v[92:95]
	v_mfma_f32_16x16x32_bf16 v[88:91], v[226:229], v[194:197], v[88:91]
	v_mfma_f32_16x16x32_bf16 v[76:79], v[218:221], v[202:205], v[76:79]
	v_mfma_f32_16x16x32_bf16 v[72:75], v[226:229], v[202:205], v[72:75]
	v_mfma_f32_16x16x32_bf16 v[68:71], v[218:221], v[210:213], v[68:71]
	v_mfma_f32_16x16x32_bf16 v[64:67], v[226:229], v[210:213], v[64:67]
	s_setprio 0
	s_barrier
	s_mov_b32 m0, s61
	s_nop 0
	global_load_lds_dwordx4 v130, s[54:55]
	s_mov_b32 m0, s62
	s_nop 0
	global_load_lds_dwordx4 v134, s[54:55]
	s_mov_b32 m0, s60
	ds_read_b128 v[182:185], v146 offset:16384
	ds_read_b128 v[186:189], v146 offset:17408
	ds_read_b128 v[190:193], v146 offset:18432
	ds_read_b128 v[194:197], v146 offset:19456
	ds_read_b128 v[198:201], v146 offset:20480
	ds_read_b128 v[202:205], v146 offset:21504
	ds_read_b128 v[206:209], v146 offset:22528
	ds_read_b128 v[210:213], v146 offset:23552
	global_load_lds_dwordx4 v128, s[56:57]
	s_mov_b32 m0, s63
	s_nop 0
	global_load_lds_dwordx4 v132, s[56:57]
	s_waitcnt vmcnt(6)
	s_waitcnt lgkmcnt(0)
	s_barrier
	s_setprio 1
	v_mfma_f32_16x16x32_bf16 v[60:63], v[166:169], v[182:185], v[60:63]
	v_mfma_f32_16x16x32_bf16 v[56:59], v[174:177], v[182:185], v[56:59]
	v_mfma_f32_16x16x32_bf16 v[52:55], v[166:169], v[190:193], v[52:55]
	v_mfma_f32_16x16x32_bf16 v[48:51], v[174:177], v[190:193], v[48:51]
	v_mfma_f32_16x16x32_bf16 v[36:39], v[166:169], v[198:201], v[36:39]
	v_mfma_f32_16x16x32_bf16 v[32:35], v[174:177], v[198:201], v[32:35]
	v_mfma_f32_16x16x32_bf16 v[20:23], v[166:169], v[206:209], v[20:23]
	v_mfma_f32_16x16x32_bf16 v[16:19], v[174:177], v[206:209], v[16:19]
	v_mfma_f32_16x16x32_bf16 v[60:63], v[170:173], v[186:189], v[60:63]
	v_mfma_f32_16x16x32_bf16 v[56:59], v[178:181], v[186:189], v[56:59]
	v_mfma_f32_16x16x32_bf16 v[52:55], v[170:173], v[194:197], v[52:55]
	v_mfma_f32_16x16x32_bf16 v[48:51], v[178:181], v[194:197], v[48:51]
	v_mfma_f32_16x16x32_bf16 v[36:39], v[170:173], v[202:205], v[36:39]
	v_mfma_f32_16x16x32_bf16 v[32:35], v[178:181], v[202:205], v[32:35]
	v_mfma_f32_16x16x32_bf16 v[20:23], v[170:173], v[210:213], v[20:23]
	v_mfma_f32_16x16x32_bf16 v[16:19], v[178:181], v[210:213], v[16:19]
	v_mfma_f32_16x16x32_bf16 v[44:47], v[214:217], v[182:185], v[44:47]
	v_mfma_f32_16x16x32_bf16 v[40:43], v[222:225], v[182:185], v[40:43]
	v_mfma_f32_16x16x32_bf16 v[28:31], v[214:217], v[190:193], v[28:31]
	v_mfma_f32_16x16x32_bf16 v[24:27], v[222:225], v[190:193], v[24:27]
	v_mfma_f32_16x16x32_bf16 v[12:15], v[214:217], v[198:201], v[12:15]
	v_mfma_f32_16x16x32_bf16 v[8:11], v[222:225], v[198:201], v[8:11]
	v_mfma_f32_16x16x32_bf16 v[4:7], v[214:217], v[206:209], v[4:7]
	v_mfma_f32_16x16x32_bf16 v[0:3], v[222:225], v[206:209], v[0:3]
	v_mfma_f32_16x16x32_bf16 v[44:47], v[218:221], v[186:189], v[44:47]
	v_mfma_f32_16x16x32_bf16 v[40:43], v[226:229], v[186:189], v[40:43]
	v_mfma_f32_16x16x32_bf16 v[28:31], v[218:221], v[194:197], v[28:31]
	v_mfma_f32_16x16x32_bf16 v[24:27], v[226:229], v[194:197], v[24:27]
	v_mfma_f32_16x16x32_bf16 v[12:15], v[218:221], v[202:205], v[12:15]
	v_mfma_f32_16x16x32_bf16 v[8:11], v[226:229], v[202:205], v[8:11]
	v_mfma_f32_16x16x32_bf16 v[4:7], v[218:221], v[210:213], v[4:7]
	v_mfma_f32_16x16x32_bf16 v[0:3], v[226:229], v[210:213], v[0:3]
	s_setprio 0
	s_barrier
; #define PG8_STAGE(bufoff, gbase, voff) do { _Pragma("unroll") for (int _i = 0; _i < 2; ++_i) \
;         __builtin_amdgcn_global_load_lds((const unsigned*)((const char*)(gbase) + (voff)[_i]), (PG8_LAS unsigned*)(lds + (bufoff) + ldsw + _i * 8192), 16, 0, 0); } while (0)
; #define PG8_LDA(dst, b, h) do { _Pragma("unroll") for (int m = 0; m < 4; ++m) _Pragma("unroll") for (int k = 0; k < 2; ++k) dst[m][k] = *(const PG8_LAS bf16x8*)(lds + PG8_SA(b, h) + aoff + m * 2048 + k * 1024); } while (0)
; #define PG8_LDB(dst, b, h) do { _Pragma("unroll") for (int n = 0; n < 2; ++n) _Pragma("unroll") for (int k = 0; k < 2; ++k) dst[n][k] = *(const PG8_LAS bf16x8*)(lds + PG8_SB(b, h) + boff + n * 2048 + k * 1024); } while (0)
; #define PG8_MMA(ai, bj, At, Bt) do { __builtin_amdgcn_s_setprio(1); _Pragma("unroll") for (int m = 0; m < 4; ++m) _Pragma("unroll") for (int n = 0; n < 2; ++n) _Pragma("unroll") for (int k = 0; k < 2; ++k) \
;         acc[ai][bj][m][n] = __builtin_amdgcn_mfma_f32_16x16x32_bf16(Bt[n][k], At[m][k], acc[ai][bj][m][n], 0, 0, 0); __builtin_amdgcn_s_setprio(0); } while (0)
; #define PG8_WAIT_V(n) asm volatile("s_waitcnt vmcnt(" #n ")" ::: "memory")
; #define PG8_WAIT_L(n) asm volatile("s_waitcnt lgkmcnt(" #n ")" ::: "memory")
; #define PG8_BAR __builtin_amdgcn_s_barrier()
; #define PG8_SCHED __builtin_amdgcn_sched_barrier(0)
; template <class Epi, class Sched, bool STAMP = false>
; __device__ __forceinline__ void gemm_phase(PG8_LAS unsigned char* lds, const Gemm g, const Sched& S, const Epi& E, unsigned long long* stamps) {
;     ...
;             PG8_WAIT_V(6); PG8_BAR; PG8_MMA(1, 1, At, B1); PG8_BAR;
;             PG8_LDB(B0, 1, 0); PG8_SCHED; PG8_LDA(At, 1, 0); PG8_STAGE(PG8_SA(0, 1), a2 + hstep, voffA);
;             PG8_WAIT_L(8); PG8_BAR; PG8_WAIT_L(0); PG8_MMA(0, 0, At, B0); PG8_BAR; PG8_SCHED;
;             PG8_LDB(B1, 1, 1); PG8_STAGE(PG8_SB(1, 0), b3, voffB);
;             PG8_BAR; PG8_WAIT_L(0); PG8_MMA(0, 1, At, B1); PG8_BAR;
;             PG8_LDA(At, 1, 1); PG8_STAGE(PG8_SA(1, 0), a3, voffA);
;             PG8_BAR; PG8_WAIT_L(0); PG8_MMA(1, 0, At, B0); PG8_BAR; PG8_SCHED;
;             PG8_STAGE(PG8_SB(1, 1), b3 + hstep, voffB);
;             PG8_WAIT_V(6); PG8_BAR; PG8_MMA(1, 1, At, B1); PG8_BAR;
;         }
.Lzp2_mid:
	s_add_u32 s34, s54, 0xb4000
	s_addc_u32 s35, s55, 0
	s_mov_b32 m0, s64
	s_nop 0
	global_load_lds_dwordx4 v130, s[34:35]
	s_mov_b32 m0, s65
	s_nop 0
	global_load_lds_dwordx4 v134, s[34:35]
	ds_read_b128 v[166:169], v156
	ds_read_b128 v[170:173], v157
	ds_read_b128 v[174:177], v159
	ds_read_b128 v[178:181], v160
	s_add_u32 s34, s56, 0xb4000
	s_addc_u32 s35, s57, 0
	s_mov_b32 m0, s66
	ds_read_b128 v[182:185], v146 offset:32768
	ds_read_b128 v[186:189], v146 offset:33792
	ds_read_b128 v[190:193], v146 offset:34816
	ds_read_b128 v[194:197], v146 offset:35840
	ds_read_b128 v[198:201], v146 offset:36864
	ds_read_b128 v[202:205], v146 offset:37888
	ds_read_b128 v[206:209], v146 offset:38912
	ds_read_b128 v[210:213], v146 offset:39936
	global_load_lds_dwordx4 v128, s[34:35]
	s_mov_b32 m0, s67
	s_nop 0
	global_load_lds_dwordx4 v132, s[34:35]
	ds_read_b128 v[214:217], v161
	ds_read_b128 v[218:221], v162
	ds_read_b128 v[222:225], v163
	ds_read_b128 v[226:229], v164
	s_waitcnt vmcnt(8)
	s_waitcnt lgkmcnt(0)
	s_barrier
	s_setprio 1
	v_mfma_f32_16x16x32_bf16 v[124:127], v[166:169], v[182:185], v[124:127]
	v_mfma_f32_16x16x32_bf16 v[120:123], v[174:177], v[182:185], v[120:123]
	v_mfma_f32_16x16x32_bf16 v[116:119], v[166:169], v[190:193], v[116:119]
	v_mfma_f32_16x16x32_bf16 v[112:115], v[174:177], v[190:193], v[112:115]
	v_mfma_f32_16x16x32_bf16 v[100:103], v[166:169], v[198:201], v[100:103]
	v_mfma_f32_16x16x32_bf16 v[96:99], v[174:177], v[198:201], v[96:99]
	v_mfma_f32_16x16x32_bf16 v[84:87], v[166:169], v[206:209], v[84:87]
	v_mfma_f32_16x16x32_bf16 v[80:83], v[174:177], v[206:209], v[80:83]
	v_mfma_f32_16x16x32_bf16 v[124:127], v[170:173], v[186:189], v[124:127]
	v_mfma_f32_16x16x32_bf16 v[120:123], v[178:181], v[186:189], v[120:123]
	v_mfma_f32_16x16x32_bf16 v[116:119], v[170:173], v[194:197], v[116:119]
	v_mfma_f32_16x16x32_bf16 v[112:115], v[178:181], v[194:197], v[112:115]
	v_mfma_f32_16x16x32_bf16 v[100:103], v[170:173], v[202:205], v[100:103]
	v_mfma_f32_16x16x32_bf16 v[96:99], v[178:181], v[202:205], v[96:99]
	v_mfma_f32_16x16x32_bf16 v[84:87], v[170:173], v[210:213], v[84:87]
	v_mfma_f32_16x16x32_bf16 v[80:83], v[178:181], v[210:213], v[80:83]
	v_mfma_f32_16x16x32_bf16 v[108:111], v[214:217], v[182:185], v[108:111]
	v_mfma_f32_16x16x32_bf16 v[104:107], v[222:225], v[182:185], v[104:107]
	v_mfma_f32_16x16x32_bf16 v[92:95], v[214:217], v[190:193], v[92:95]
	v_mfma_f32_16x16x32_bf16 v[88:91], v[222:225], v[190:193], v[88:91]
	v_mfma_f32_16x16x32_bf16 v[76:79], v[214:217], v[198:201], v[76:79]
	v_mfma_f32_16x16x32_bf16 v[72:75], v[222:225], v[198:201], v[72:75]
	v_mfma_f32_16x16x32_bf16 v[68:71], v[214:217], v[206:209], v[68:71]
	v_mfma_f32_16x16x32_bf16 v[64:67], v[222:225], v[206:209], v[64:67]
	v_mfma_f32_16x16x32_bf16 v[108:111], v[218:221], v[186:189], v[108:111]
	v_mfma_f32_16x16x32_bf16 v[104:107], v[226:229], v[186:189], v[104:107]
	v_mfma_f32_16x16x32_bf16 v[92:95], v[218:221], v[194:197], v[92:95]
	v_mfma_f32_16x16x32_bf16 v[88:91], v[226:229], v[194:197], v[88:91]
	v_mfma_f32_16x16x32_bf16 v[76:79], v[218:221], v[202:205], v[76:79]
	v_mfma_f32_16x16x32_bf16 v[72:75], v[226:229], v[202:205], v[72:75]
	v_mfma_f32_16x16x32_bf16 v[68:71], v[218:221], v[210:213], v[68:71]
	v_mfma_f32_16x16x32_bf16 v[64:67], v[226:229], v[210:213], v[64:67]
	s_setprio 0
	s_barrier
	s_mov_b32 m0, s68
	s_add_u32 s100, s54, 0x80
	s_addc_u32 s101, s55, 0
	global_load_lds_dwordx4 v130, s[100:101]
	s_mov_b32 m0, s69
	s_nop 0
	global_load_lds_dwordx4 v134, s[100:101]
	s_mov_b32 m0, s70
	ds_read_b128 v[182:185], v146 offset:49152
	ds_read_b128 v[186:189], v146 offset:50176
	ds_read_b128 v[190:193], v146 offset:51200
	ds_read_b128 v[194:197], v146 offset:52224
	ds_read_b128 v[198:201], v146 offset:53248
	ds_read_b128 v[202:205], v146 offset:54272
	ds_read_b128 v[206:209], v146 offset:55296
	ds_read_b128 v[210:213], v146 offset:56320
	s_add_u32 s100, s56, 0x80
	s_addc_u32 s101, s57, 0
	global_load_lds_dwordx4 v128, s[100:101]
	s_mov_b32 m0, s71
	s_nop 0
	global_load_lds_dwordx4 v132, s[100:101]
	s_waitcnt vmcnt(6)
	s_waitcnt lgkmcnt(0)
	s_barrier
	s_setprio 1
	v_mfma_f32_16x16x32_bf16 v[60:63], v[166:169], v[182:185], v[60:63]
	v_mfma_f32_16x16x32_bf16 v[56:59], v[174:177], v[182:185], v[56:59]
	v_mfma_f32_16x16x32_bf16 v[52:55], v[166:169], v[190:193], v[52:55]
	v_mfma_f32_16x16x32_bf16 v[48:51], v[174:177], v[190:193], v[48:51]
	v_mfma_f32_16x16x32_bf16 v[36:39], v[166:169], v[198:201], v[36:39]
	v_mfma_f32_16x16x32_bf16 v[32:35], v[174:177], v[198:201], v[32:35]
	v_mfma_f32_16x16x32_bf16 v[20:23], v[166:169], v[206:209], v[20:23]
	v_mfma_f32_16x16x32_bf16 v[16:19], v[174:177], v[206:209], v[16:19]
	v_mfma_f32_16x16x32_bf16 v[60:63], v[170:173], v[186:189], v[60:63]
	v_mfma_f32_16x16x32_bf16 v[56:59], v[178:181], v[186:189], v[56:59]
	v_mfma_f32_16x16x32_bf16 v[52:55], v[170:173], v[194:197], v[52:55]
	v_mfma_f32_16x16x32_bf16 v[48:51], v[178:181], v[194:197], v[48:51]
	v_mfma_f32_16x16x32_bf16 v[36:39], v[170:173], v[202:205], v[36:39]
	v_mfma_f32_16x16x32_bf16 v[32:35], v[178:181], v[202:205], v[32:35]
	v_mfma_f32_16x16x32_bf16 v[20:23], v[170:173], v[210:213], v[20:23]
	v_mfma_f32_16x16x32_bf16 v[16:19], v[178:181], v[210:213], v[16:19]
	v_mfma_f32_16x16x32_bf16 v[44:47], v[214:217], v[182:185], v[44:47]
	v_mfma_f32_16x16x32_bf16 v[40:43], v[222:225], v[182:185], v[40:43]
	v_mfma_f32_16x16x32_bf16 v[28:31], v[214:217], v[190:193], v[28:31]
	v_mfma_f32_16x16x32_bf16 v[24:27], v[222:225], v[190:193], v[24:27]
	v_mfma_f32_16x16x32_bf16 v[12:15], v[214:217], v[198:201], v[12:15]
	v_mfma_f32_16x16x32_bf16 v[8:11], v[222:225], v[198:201], v[8:11]
	v_mfma_f32_16x16x32_bf16 v[4:7], v[214:217], v[206:209], v[4:7]
	v_mfma_f32_16x16x32_bf16 v[0:3], v[222:225], v[206:209], v[0:3]
	v_mfma_f32_16x16x32_bf16 v[44:47], v[218:221], v[186:189], v[44:47]
	v_mfma_f32_16x16x32_bf16 v[40:43], v[226:229], v[186:189], v[40:43]
	v_mfma_f32_16x16x32_bf16 v[28:31], v[218:221], v[194:197], v[28:31]
	v_mfma_f32_16x16x32_bf16 v[24:27], v[226:229], v[194:197], v[24:27]
	v_mfma_f32_16x16x32_bf16 v[12:15], v[218:221], v[202:205], v[12:15]
	v_mfma_f32_16x16x32_bf16 v[8:11], v[226:229], v[202:205], v[8:11]
	v_mfma_f32_16x16x32_bf16 v[4:7], v[218:221], v[210:213], v[4:7]
	v_mfma_f32_16x16x32_bf16 v[0:3], v[226:229], v[210:213], v[0:3]
	s_setprio 0
	s_add_i32 s90, s90, 2
	s_add_u32 s88, s88, 0x100
	s_addc_u32 s89, s89, 0
	s_cmp_gt_u32 s90, 41
	s_mov_b64 s[34:35], s[52:53]
	s_barrier
; #define PG8_STAMP() do { if (STAMP && wid == 0 && nts < 64) { const unsigned long long _c = 0ull; \
;         ts_lo = (lane == nts) ? (int)(unsigned)_c : ts_lo; ts_hi = (lane == nts) ? (int)(unsigned)(_c >> 32) : ts_hi; ++nts; } } while (0)
; #define PG8_WAIT_V(n) asm volatile("s_waitcnt vmcnt(" #n ")" ::: "memory")
; #define PG8_BAR __builtin_amdgcn_s_barrier()
;     DI void operator()(const f32x4 (&acc)[2][2][4][2], const Unit& u, int wr, int wc, int fr, int fq) const {
;         const int row0 = u.pm * BM + wr * 64 + fr, col0 = u.pn * BM + wc * 32 + 8 * fq;
; #pragma unroll
;         for (int ai = 0; ai < 2; ++ai)
; #pragma unroll
;             for (int m = 0; m < 4; ++m) { u16* rowp = O + (size_t)(row0 + ai * HALF + m * 16) * ldc + col0;
; #pragma unroll
;                 for (int bj = 0; bj < 2; ++bj) { const f32x4 v0 = acc[ai][bj][m][0], v1 = acc[ai][bj][m][1];
;                     uint4 w = {pack2(v0[0], v0[1]), pack2(v0[2], v0[3]), pack2(v1[0], v1[1]), pack2(v1[2], v1[3])}; *(uint4*)(rowp + bj * HALF) = w; } }
; template <class Epi, class Sched, bool STAMP = false>
; __device__ __forceinline__ void gemm_phase(PG8_LAS unsigned char* lds, const Gemm g, const Sched& S, const Epi& E, unsigned long long* stamps) {
;     ...
;         if constexpr (!Epi::AFTER_DRAIN) { E(acc, cur, wr, wc, fr, fq); S.done(cur); }
;         PG8_STAMP();
;         if (!has_next) break;
; #pragma unroll
;         for (int a = 0; a < 2; ++a)
; #pragma unroll
;             for (int b = 0; b < 2; ++b)
; #pragma unroll
;                 for (int m = 0; m < 4; ++m)
; #pragma unroll
;                     for (int n = 0; n < 2; ++n) acc[a][b][m][n] = (f32x4){0.f, 0.f, 0.f, 0.f};
;         cur = nxt; cA = nA; cB = nB; ++ui;
;     }
;     PG8_WAIT_V(0);
;     if (wr == 0) PG8_BAR;
;     PG8_BAR;
	s_cbranch_scc0 .LBB0_97
	v_lshl_add_u32 v166, s84, 8, v145
	v_lshl_or_b32 v168, s87, 8, v147
	v_ashrrev_i32_e32 v167, 31, v166
	v_ashrrev_i32_e32 v169, 31, v168
	v_lshlrev_b64 v[170:171], 11, v[166:167]
	v_lshl_add_u64 v[170:171], s[14:15], 0, v[170:171]
	v_lshlrev_b64 v[168:169], 1, v[168:169]
	v_lshl_add_u64 v[170:171], v[170:171], 0, v[168:169]
	v_cvt_pk_bf16_f32 v60, v60, v61
	v_cvt_pk_bf16_f32 v61, v62, v63
	v_cvt_pk_bf16_f32 v62, v56, v57
	v_add_co_u32_e32 v56, vcc, s78, v170
	v_cvt_pk_bf16_f32 v68, v68, v69
	v_cvt_pk_bf16_f32 v69, v70, v71
	v_cvt_pk_bf16_f32 v70, v64, v65
	v_lshl_add_u64 v[64:65], v[170:171], 0, s[16:17]
	v_addc_co_u32_e32 v57, vcc, 0, v171, vcc
	v_cvt_pk_bf16_f32 v44, v44, v45
	v_cvt_pk_bf16_f32 v45, v46, v47
	v_cvt_pk_bf16_f32 v46, v40, v41
	v_cvt_pk_bf16_f32 v47, v42, v43
	v_cvt_pk_bf16_f32 v108, v108, v109
	v_cvt_pk_bf16_f32 v109, v110, v111
	v_cvt_pk_bf16_f32 v110, v104, v105
	v_or_b32_e32 v104, 16, v166
	global_store_dwordx4 v[64:65], v[44:47], off offset:256
	v_ashrrev_i32_e32 v105, 31, v104
	v_cvt_pk_bf16_f32 v92, v92, v93
	v_add_co_u32_e32 v46, vcc, s79, v170
	v_cvt_pk_bf16_f32 v93, v94, v95
	v_cvt_pk_bf16_f32 v94, v88, v89
	v_or_b32_e32 v88, 32, v166
	v_lshl_add_u64 v[44:45], v[170:171], 0, s[18:19]
	v_addc_co_u32_e32 v47, vcc, 0, v171, vcc
	v_cvt_pk_bf16_f32 v28, v28, v29
	v_cvt_pk_bf16_f32 v29, v30, v31
	v_cvt_pk_bf16_f32 v30, v24, v25
	v_cvt_pk_bf16_f32 v31, v26, v27
	v_lshlrev_b64 v[104:105], 11, v[104:105]
	v_ashrrev_i32_e32 v89, 31, v88
	v_cvt_pk_bf16_f32 v76, v76, v77
	v_cvt_pk_bf16_f32 v77, v78, v79
	v_cvt_pk_bf16_f32 v78, v72, v73
	v_or_b32_e32 v72, 48, v166
	global_store_dwordx4 v[44:45], v[28:31], off offset:256
	v_cvt_pk_bf16_f32 v111, v106, v107
	v_lshl_add_u64 v[104:105], s[14:15], 0, v[104:105]
	v_add_co_u32_e32 v30, vcc, s82, v170
	v_lshlrev_b64 v[88:89], 11, v[88:89]
	v_ashrrev_i32_e32 v73, 31, v72
	v_lshl_add_u64 v[28:29], v[170:171], 0, s[28:29]
	v_addc_co_u32_e32 v31, vcc, 0, v171, vcc
	v_cvt_pk_bf16_f32 v12, v12, v13
	v_cvt_pk_bf16_f32 v13, v14, v15
	v_cvt_pk_bf16_f32 v14, v8, v9
	v_cvt_pk_bf16_f32 v15, v10, v11
	global_store_dwordx4 v[170:171], v[108:111], off offset:256
	v_cvt_pk_bf16_f32 v95, v90, v91
	v_lshl_add_u64 v[88:89], s[14:15], 0, v[88:89]
	v_lshl_add_u64 v[108:109], v[104:105], 0, v[168:169]
	v_lshlrev_b64 v[72:73], 11, v[72:73]
	global_store_dwordx4 v[28:29], v[12:15], off offset:256
	global_store_dwordx4 v[108:109], v[92:95], off offset:256
	v_cvt_pk_bf16_f32 v79, v74, v75
	v_add_co_u32_e32 v14, vcc, s83, v170
	v_lshl_add_u64 v[92:93], v[88:89], 0, v[168:169]
	v_lshl_add_u64 v[72:73], s[14:15], 0, v[72:73]
	v_addc_co_u32_e32 v15, vcc, 0, v171, vcc
	v_cvt_pk_bf16_f32 v124, v124, v125
	v_cvt_pk_bf16_f32 v125, v126, v127
	v_cvt_pk_bf16_f32 v126, v120, v121
	v_cvt_pk_bf16_f32 v127, v122, v123
	v_cvt_pk_bf16_f32 v104, v116, v117
	v_cvt_pk_bf16_f32 v105, v118, v119
	v_cvt_pk_bf16_f32 v106, v112, v113
	v_cvt_pk_bf16_f32 v107, v114, v115
	v_cvt_pk_bf16_f32 v88, v100, v101
	v_cvt_pk_bf16_f32 v89, v102, v103
	v_cvt_pk_bf16_f32 v90, v96, v97
	v_cvt_pk_bf16_f32 v91, v98, v99
	global_store_dwordx4 v[92:93], v[76:79], off offset:256
	v_cvt_pk_bf16_f32 v74, v80, v81
	v_cvt_pk_bf16_f32 v75, v82, v83
	v_lshl_add_u64 v[76:77], v[72:73], 0, v[168:169]
	v_cvt_pk_bf16_f32 v72, v84, v85
	v_cvt_pk_bf16_f32 v73, v86, v87
	v_cvt_pk_bf16_f32 v71, v66, v67
	v_cvt_pk_bf16_f32 v63, v58, v59
	v_cvt_pk_bf16_f32 v40, v52, v53
	v_cvt_pk_bf16_f32 v41, v54, v55
	v_cvt_pk_bf16_f32 v42, v48, v49
	v_cvt_pk_bf16_f32 v43, v50, v51
	v_cvt_pk_bf16_f32 v24, v36, v37
	v_cvt_pk_bf16_f32 v25, v38, v39
	v_cvt_pk_bf16_f32 v26, v32, v33
	v_cvt_pk_bf16_f32 v27, v34, v35
	v_lshl_add_u64 v[12:13], v[170:171], 0, s[30:31]
	v_cvt_pk_bf16_f32 v8, v20, v21
	v_cvt_pk_bf16_f32 v9, v22, v23
	v_cvt_pk_bf16_f32 v10, v16, v17
	v_cvt_pk_bf16_f32 v11, v18, v19
	v_cvt_pk_bf16_f32 v4, v4, v5
	v_cvt_pk_bf16_f32 v5, v6, v7
	v_cvt_pk_bf16_f32 v6, v0, v1
	v_cvt_pk_bf16_f32 v7, v2, v3
	s_and_b64 vcc, exec, s[2:3]
	s_mov_b32 s87, s85
	s_mov_b32 s84, s86
	s_mov_b64 s[52:53], s[0:1]
	s_mov_b64 s[34:35], s[4:5]
	global_store_dwordx4 v[170:171], v[124:127], off
	global_store_dwordx4 v[108:109], v[104:107], off
	global_store_dwordx4 v[92:93], v[88:91], off
	global_store_dwordx4 v[76:77], v[72:75], off
	global_store_dwordx4 v[76:77], v[68:71], off offset:256
	global_store_dwordx4 v[56:57], v[60:63], off
	global_store_dwordx4 v[46:47], v[40:43], off
	global_store_dwordx4 v[30:31], v[24:27], off
	global_store_dwordx4 v[14:15], v[8:11], off
	global_store_dwordx4 v[12:13], v[4:7], off offset:256
	s_cbranch_vccz .LBB0_86
	s_waitcnt vmcnt(0)
	s_cmpk_gt_u32 s58, 0xff
	s_cbranch_scc1 .LBB0_101
	s_barrier

; #define PG8_STAGE(bufoff, gbase, voff) do { _Pragma("unroll") for (int _i = 0; _i < 2; ++_i) \
;         __builtin_amdgcn_global_load_lds((const unsigned*)((const char*)(gbase) + (voff)[_i]), (PG8_LAS unsigned*)(lds + (bufoff) + ldsw + _i * 8192), 16, 0, 0); } while (0)
; #define PG8_LDA(dst, b, h) do { _Pragma("unroll") for (int m = 0; m < 4; ++m) _Pragma("unroll") for (int k = 0; k < 2; ++k) dst[m][k] = *(const PG8_LAS bf16x8*)(lds + PG8_SA(b, h) + aoff + m * 2048 + k * 1024); } while (0)
; template <class Epi, class Sched, bool STAMP = false>
; __device__ __forceinline__ void gemm_phase(PG8_LAS unsigned char* lds, const Gemm g, const Sched& S, const Epi& E, unsigned long long* stamps) {
;     ...
;         for (int t = 0; t < nt; t += 2) {
;             const bool last = (t == nt - 2);
;             const char* a1 = cA + (size_t)(t + 1) * kstep;
;             const char* a2 = last ? nA : cA + (size_t)(t + 2) * kstep; const char* b2 = last ? nB : cB + (size_t)(t + 2) * kstep;
;             const char* a3 = a2 + kstep; const char* b3 = b2 + kstep;
;             if (last && has_next) S.a_ready(nxt);
;             PG8_LDB(B0, 0, 0); PG8_SCHED; PG8_LDA(At, 0, 0); PG8_STAGE(PG8_SA(1, 1), a1 + hstep, voffA);
;             PG8_WAIT_L(8); PG8_BAR; PG8_WAIT_L(0); PG8_MMA(0, 0, At, B0); PG8_BAR; PG8_SCHED;
;             PG8_LDB(B1, 0, 1); PG8_STAGE(PG8_SB(0, 0), b2, voffB);
;             PG8_BAR; PG8_WAIT_L(0); PG8_MMA(0, 1, At, B1); PG8_BAR;
;             PG8_LDA(At, 0, 1); PG8_STAGE(PG8_SA(0, 0), a2, voffA);
;             PG8_BAR; PG8_WAIT_L(0); PG8_MMA(1, 0, At, B0); PG8_BAR; PG8_SCHED;
;             PG8_STAGE(PG8_SB(0, 1), b2 + hstep, voffB);
;             PG8_WAIT_V(6); PG8_BAR; PG8_MMA(1, 1, At, B1); PG8_BAR;
;             PG8_LDB(B0, 1, 0); PG8_SCHED; PG8_LDA(At, 1, 0); PG8_STAGE(PG8_SA(0, 1), a2 + hstep, voffA);
;             PG8_WAIT_L(8); PG8_BAR; PG8_WAIT_L(0); PG8_MMA(0, 0, At, B0); PG8_BAR; PG8_SCHED;
;             PG8_LDB(B1, 1, 1); PG8_STAGE(PG8_SB(1, 0), b3, voffB);
;             PG8_BAR; PG8_WAIT_L(0); PG8_MMA(0, 1, At, B1); PG8_BAR;
;             PG8_LDA(At, 1, 1); PG8_STAGE(PG8_SA(1, 0), a3, voffA);
;             PG8_BAR; PG8_WAIT_L(0); PG8_MMA(1, 0, At, B0); PG8_BAR; PG8_SCHED;
;             PG8_STAGE(PG8_SB(1, 1), b3 + hstep, voffB);
;             PG8_WAIT_V(6); PG8_BAR; PG8_MMA(1, 1, At, B1); PG8_BAR;
;         }
.LBB0_137:
	s_add_u32 s83, s34, 0x100
	s_addc_u32 s84, s35, 0
	s_mov_b32 s85, -2
	s_waitcnt lgkmcnt(0)
	s_add_u32 s100, s83, 0x43f80
	s_addc_u32 s101, s84, 0
	s_mov_b32 m0, s71
	s_nop 0
	global_load_lds_dwordx4 v132, s[100:101]
	s_mov_b32 m0, s72
	s_nop 0
	global_load_lds_dwordx4 v128, s[100:101]
	ds_read_b128 v[166:169], v148
	ds_read_b128 v[170:173], v149
	ds_read_b128 v[174:177], v150
	ds_read_b128 v[178:181], v151
	s_add_u32 s34, s28, 0x100
	s_addc_u32 s35, s29, 0
	s_cmp_eq_u32 s85, 12
	s_cselect_b32 s53, s7, s35
	s_cselect_b32 s52, s6, s34
	s_cselect_b32 s37, s1, s84
	s_cselect_b32 s36, s0, s83
	s_mov_b32 m0, s74
	ds_read_b128 v[182:185], v146
	ds_read_b128 v[186:189], v146 offset:1024
	ds_read_b128 v[190:193], v146 offset:2048
	ds_read_b128 v[194:197], v146 offset:3072
	ds_read_b128 v[198:201], v146 offset:4096
	ds_read_b128 v[202:205], v146 offset:5120
	ds_read_b128 v[206:209], v146 offset:6144
	ds_read_b128 v[210:213], v146 offset:7168
	global_load_lds_dwordx4 v136, s[28:29]
	s_mov_b32 m0, s75
	s_nop 0
	global_load_lds_dwordx4 v138, s[28:29]
	ds_read_b128 v[214:217], v152
	ds_read_b128 v[218:221], v153
	ds_read_b128 v[222:225], v154
	ds_read_b128 v[226:229], v155
	s_waitcnt vmcnt(8)
	s_waitcnt lgkmcnt(0)
	s_barrier
	s_setprio 1
	v_mfma_f32_16x16x32_bf16 v[124:127], v[166:169], v[182:185], 0
	v_mfma_f32_16x16x32_bf16 v[120:123], v[174:177], v[182:185], 0
	v_mfma_f32_16x16x32_bf16 v[116:119], v[166:169], v[190:193], 0
	v_mfma_f32_16x16x32_bf16 v[112:115], v[174:177], v[190:193], 0
	v_mfma_f32_16x16x32_bf16 v[108:111], v[166:169], v[198:201], 0
	v_mfma_f32_16x16x32_bf16 v[104:107], v[174:177], v[198:201], 0
	v_mfma_f32_16x16x32_bf16 v[100:103], v[166:169], v[206:209], 0
	v_mfma_f32_16x16x32_bf16 v[96:99], v[174:177], v[206:209], 0
	v_mfma_f32_16x16x32_bf16 v[124:127], v[170:173], v[186:189], v[124:127]
	v_mfma_f32_16x16x32_bf16 v[120:123], v[178:181], v[186:189], v[120:123]
	v_mfma_f32_16x16x32_bf16 v[116:119], v[170:173], v[194:197], v[116:119]
	v_mfma_f32_16x16x32_bf16 v[112:115], v[178:181], v[194:197], v[112:115]
	v_mfma_f32_16x16x32_bf16 v[108:111], v[170:173], v[202:205], v[108:111]
	v_mfma_f32_16x16x32_bf16 v[104:107], v[178:181], v[202:205], v[104:107]
	v_mfma_f32_16x16x32_bf16 v[100:103], v[170:173], v[210:213], v[100:103]
	v_mfma_f32_16x16x32_bf16 v[96:99], v[178:181], v[210:213], v[96:99]
	v_mfma_f32_16x16x32_bf16 v[60:63], v[214:217], v[182:185], 0
	v_mfma_f32_16x16x32_bf16 v[56:59], v[222:225], v[182:185], 0
	v_mfma_f32_16x16x32_bf16 v[52:55], v[214:217], v[190:193], 0
	v_mfma_f32_16x16x32_bf16 v[48:51], v[222:225], v[190:193], 0
	v_mfma_f32_16x16x32_bf16 v[44:47], v[214:217], v[198:201], 0
	v_mfma_f32_16x16x32_bf16 v[40:43], v[222:225], v[198:201], 0
	v_mfma_f32_16x16x32_bf16 v[36:39], v[214:217], v[206:209], 0
	v_mfma_f32_16x16x32_bf16 v[32:35], v[222:225], v[206:209], 0
	v_mfma_f32_16x16x32_bf16 v[60:63], v[218:221], v[186:189], v[60:63]
	v_mfma_f32_16x16x32_bf16 v[56:59], v[226:229], v[186:189], v[56:59]
	v_mfma_f32_16x16x32_bf16 v[52:55], v[218:221], v[194:197], v[52:55]
	v_mfma_f32_16x16x32_bf16 v[48:51], v[226:229], v[194:197], v[48:51]
	v_mfma_f32_16x16x32_bf16 v[44:47], v[218:221], v[202:205], v[44:47]
	v_mfma_f32_16x16x32_bf16 v[40:43], v[226:229], v[202:205], v[40:43]
	v_mfma_f32_16x16x32_bf16 v[36:39], v[218:221], v[210:213], v[36:39]
	v_mfma_f32_16x16x32_bf16 v[32:35], v[226:229], v[210:213], v[32:35]
	s_setprio 0
	s_barrier
	s_mov_b32 m0, s58
	s_nop 0
	global_load_lds_dwordx4 v132, s[36:37]
	s_mov_b32 m0, s59
	s_nop 0
	global_load_lds_dwordx4 v128, s[36:37]
	s_mov_b32 m0, s55
	ds_read_b128 v[182:185], v146 offset:16384
	ds_read_b128 v[186:189], v146 offset:17408
	ds_read_b128 v[190:193], v146 offset:18432
	ds_read_b128 v[194:197], v146 offset:19456
	ds_read_b128 v[198:201], v146 offset:20480
	ds_read_b128 v[202:205], v146 offset:21504
	ds_read_b128 v[206:209], v146 offset:22528
	ds_read_b128 v[210:213], v146 offset:23552
	global_load_lds_dwordx4 v134, s[52:53]
	s_mov_b32 m0, s60
	s_nop 0
	global_load_lds_dwordx4 v130, s[52:53]
	s_waitcnt vmcnt(6)
	s_waitcnt lgkmcnt(0)
	s_barrier
	s_setprio 1
	v_mfma_f32_16x16x32_bf16 v[92:95], v[166:169], v[182:185], 0
	v_mfma_f32_16x16x32_bf16 v[88:91], v[174:177], v[182:185], 0
	v_mfma_f32_16x16x32_bf16 v[84:87], v[166:169], v[190:193], 0
	v_mfma_f32_16x16x32_bf16 v[80:83], v[174:177], v[190:193], 0
	v_mfma_f32_16x16x32_bf16 v[76:79], v[166:169], v[198:201], 0
	v_mfma_f32_16x16x32_bf16 v[72:75], v[174:177], v[198:201], 0
	v_mfma_f32_16x16x32_bf16 v[68:71], v[166:169], v[206:209], 0
	v_mfma_f32_16x16x32_bf16 v[64:67], v[174:177], v[206:209], 0
	v_mfma_f32_16x16x32_bf16 v[92:95], v[170:173], v[186:189], v[92:95]
	v_mfma_f32_16x16x32_bf16 v[88:91], v[178:181], v[186:189], v[88:91]
	v_mfma_f32_16x16x32_bf16 v[84:87], v[170:173], v[194:197], v[84:87]
	v_mfma_f32_16x16x32_bf16 v[80:83], v[178:181], v[194:197], v[80:83]
	v_mfma_f32_16x16x32_bf16 v[76:79], v[170:173], v[202:205], v[76:79]
	v_mfma_f32_16x16x32_bf16 v[72:75], v[178:181], v[202:205], v[72:75]
	v_mfma_f32_16x16x32_bf16 v[68:71], v[170:173], v[210:213], v[68:71]
	v_mfma_f32_16x16x32_bf16 v[64:67], v[178:181], v[210:213], v[64:67]
	v_mfma_f32_16x16x32_bf16 v[28:31], v[214:217], v[182:185], 0
	v_mfma_f32_16x16x32_bf16 v[24:27], v[222:225], v[182:185], 0
	v_mfma_f32_16x16x32_bf16 v[20:23], v[214:217], v[190:193], 0
	v_mfma_f32_16x16x32_bf16 v[16:19], v[222:225], v[190:193], 0
	v_mfma_f32_16x16x32_bf16 v[12:15], v[214:217], v[198:201], 0
	v_mfma_f32_16x16x32_bf16 v[8:11], v[222:225], v[198:201], 0
	v_mfma_f32_16x16x32_bf16 v[4:7], v[214:217], v[206:209], 0
	v_mfma_f32_16x16x32_bf16 v[0:3], v[222:225], v[206:209], 0
	v_mfma_f32_16x16x32_bf16 v[28:31], v[218:221], v[186:189], v[28:31]
	v_mfma_f32_16x16x32_bf16 v[24:27], v[226:229], v[186:189], v[24:27]
	v_mfma_f32_16x16x32_bf16 v[20:23], v[218:221], v[194:197], v[20:23]
	v_mfma_f32_16x16x32_bf16 v[16:19], v[226:229], v[194:197], v[16:19]
	v_mfma_f32_16x16x32_bf16 v[12:15], v[218:221], v[202:205], v[12:15]
	v_mfma_f32_16x16x32_bf16 v[8:11], v[226:229], v[202:205], v[8:11]
	v_mfma_f32_16x16x32_bf16 v[4:7], v[218:221], v[210:213], v[4:7]
	v_mfma_f32_16x16x32_bf16 v[0:3], v[226:229], v[210:213], v[0:3]
	s_setprio 0
	s_barrier
	s_branch .Lzp3_mid
; #define PG8_STAGE(bufoff, gbase, voff) do { _Pragma("unroll") for (int _i = 0; _i < 2; ++_i) \
;         __builtin_amdgcn_global_load_lds((const unsigned*)((const char*)(gbase) + (voff)[_i]), (PG8_LAS unsigned*)(lds + (bufoff) + ldsw + _i * 8192), 16, 0, 0); } while (0)
; #define PG8_LDA(dst, b, h) do { _Pragma("unroll") for (int m = 0; m < 4; ++m) _Pragma("unroll") for (int k = 0; k < 2; ++k) dst[m][k] = *(const PG8_LAS bf16x8*)(lds + PG8_SA(b, h) + aoff + m * 2048 + k * 1024); } while (0)
; template <class Epi, class Sched, bool STAMP = false>
; __device__ __forceinline__ void gemm_phase(PG8_LAS unsigned char* lds, const Gemm g, const Sched& S, const Epi& E, unsigned long long* stamps) {
;     ...
;         for (int t = 0; t < nt; t += 2) {
;             const bool last = (t == nt - 2);
;             const char* a1 = cA + (size_t)(t + 1) * kstep;
;             const char* a2 = last ? nA : cA + (size_t)(t + 2) * kstep; const char* b2 = last ? nB : cB + (size_t)(t + 2) * kstep;
;             const char* a3 = a2 + kstep; const char* b3 = b2 + kstep;
;             if (last && has_next) S.a_ready(nxt);
;             PG8_LDB(B0, 0, 0); PG8_SCHED; PG8_LDA(At, 0, 0); PG8_STAGE(PG8_SA(1, 1), a1 + hstep, voffA);
;             PG8_WAIT_L(8); PG8_BAR; PG8_WAIT_L(0); PG8_MMA(0, 0, At, B0); PG8_BAR; PG8_SCHED;
;             PG8_LDB(B1, 0, 1); PG8_STAGE(PG8_SB(0, 0), b2, voffB);
;             PG8_BAR; PG8_WAIT_L(0); PG8_MMA(0, 1, At, B1); PG8_BAR;
;             PG8_LDA(At, 0, 1); PG8_STAGE(PG8_SA(0, 0), a2, voffA);
;             PG8_BAR; PG8_WAIT_L(0); PG8_MMA(1, 0, At, B0); PG8_BAR; PG8_SCHED;
;             PG8_STAGE(PG8_SB(0, 1), b2 + hstep, voffB);
;             PG8_WAIT_V(6); PG8_BAR; PG8_MMA(1, 1, At, B1); PG8_BAR;
;             PG8_LDB(B0, 1, 0); PG8_SCHED; PG8_LDA(At, 1, 0); PG8_STAGE(PG8_SA(0, 1), a2 + hstep, voffA);
;             PG8_WAIT_L(8); PG8_BAR; PG8_WAIT_L(0); PG8_MMA(0, 0, At, B0); PG8_BAR; PG8_SCHED;
;             PG8_LDB(B1, 1, 1); PG8_STAGE(PG8_SB(1, 0), b3, voffB);
;             PG8_BAR; PG8_WAIT_L(0); PG8_MMA(0, 1, At, B1); PG8_BAR;
;             PG8_LDA(At, 1, 1); PG8_STAGE(PG8_SA(1, 0), a3, voffA);
;             PG8_BAR; PG8_WAIT_L(0); PG8_MMA(1, 0, At, B0); PG8_BAR; PG8_SCHED;
;             PG8_STAGE(PG8_SB(1, 1), b3 + hstep, voffB);
;             PG8_WAIT_V(6); PG8_BAR; PG8_MMA(1, 1, At, B1); PG8_BAR;
;         }
.LBB0_138:
	s_add_u32 s100, s83, 0x43f80
	s_addc_u32 s101, s84, 0
	s_mov_b32 m0, s71
	s_nop 0
	global_load_lds_dwordx4 v132, s[100:101]
	s_mov_b32 m0, s72
	s_nop 0
	global_load_lds_dwordx4 v128, s[100:101]
	ds_read_b128 v[166:169], v148
	ds_read_b128 v[170:173], v149
	ds_read_b128 v[174:177], v150
	ds_read_b128 v[178:181], v151
	s_add_u32 s34, s28, 0x100
	s_addc_u32 s35, s29, 0
	s_cmp_eq_u32 s85, 12
	s_cselect_b32 s53, s7, s35
	s_cselect_b32 s52, s6, s34
	s_cselect_b32 s37, s1, s84
	s_cselect_b32 s36, s0, s83
	s_mov_b32 m0, s74
	ds_read_b128 v[182:185], v146
	ds_read_b128 v[186:189], v146 offset:1024
	ds_read_b128 v[190:193], v146 offset:2048
	ds_read_b128 v[194:197], v146 offset:3072
	ds_read_b128 v[198:201], v146 offset:4096
	ds_read_b128 v[202:205], v146 offset:5120
	ds_read_b128 v[206:209], v146 offset:6144
	ds_read_b128 v[210:213], v146 offset:7168
	global_load_lds_dwordx4 v136, s[28:29]
	s_mov_b32 m0, s75
	s_nop 0
	global_load_lds_dwordx4 v138, s[28:29]
	ds_read_b128 v[214:217], v152
	ds_read_b128 v[218:221], v153
	ds_read_b128 v[222:225], v154
	ds_read_b128 v[226:229], v155
	s_waitcnt vmcnt(8)
	s_waitcnt lgkmcnt(0)
	s_barrier
	s_setprio 1
	v_mfma_f32_16x16x32_bf16 v[124:127], v[166:169], v[182:185], v[124:127]
	v_mfma_f32_16x16x32_bf16 v[120:123], v[174:177], v[182:185], v[120:123]
	v_mfma_f32_16x16x32_bf16 v[116:119], v[166:169], v[190:193], v[116:119]
	v_mfma_f32_16x16x32_bf16 v[112:115], v[174:177], v[190:193], v[112:115]
	v_mfma_f32_16x16x32_bf16 v[108:111], v[166:169], v[198:201], v[108:111]
	v_mfma_f32_16x16x32_bf16 v[104:107], v[174:177], v[198:201], v[104:107]
	v_mfma_f32_16x16x32_bf16 v[100:103], v[166:169], v[206:209], v[100:103]
	v_mfma_f32_16x16x32_bf16 v[96:99], v[174:177], v[206:209], v[96:99]
	v_mfma_f32_16x16x32_bf16 v[124:127], v[170:173], v[186:189], v[124:127]
	v_mfma_f32_16x16x32_bf16 v[120:123], v[178:181], v[186:189], v[120:123]
	v_mfma_f32_16x16x32_bf16 v[116:119], v[170:173], v[194:197], v[116:119]
	v_mfma_f32_16x16x32_bf16 v[112:115], v[178:181], v[194:197], v[112:115]
	v_mfma_f32_16x16x32_bf16 v[108:111], v[170:173], v[202:205], v[108:111]
	v_mfma_f32_16x16x32_bf16 v[104:107], v[178:181], v[202:205], v[104:107]
	v_mfma_f32_16x16x32_bf16 v[100:103], v[170:173], v[210:213], v[100:103]
	v_mfma_f32_16x16x32_bf16 v[96:99], v[178:181], v[210:213], v[96:99]
	v_mfma_f32_16x16x32_bf16 v[60:63], v[214:217], v[182:185], v[60:63]
	v_mfma_f32_16x16x32_bf16 v[56:59], v[222:225], v[182:185], v[56:59]
	v_mfma_f32_16x16x32_bf16 v[52:55], v[214:217], v[190:193], v[52:55]
	v_mfma_f32_16x16x32_bf16 v[48:51], v[222:225], v[190:193], v[48:51]
	v_mfma_f32_16x16x32_bf16 v[44:47], v[214:217], v[198:201], v[44:47]
	v_mfma_f32_16x16x32_bf16 v[40:43], v[222:225], v[198:201], v[40:43]
	v_mfma_f32_16x16x32_bf16 v[36:39], v[214:217], v[206:209], v[36:39]
	v_mfma_f32_16x16x32_bf16 v[32:35], v[222:225], v[206:209], v[32:35]
	v_mfma_f32_16x16x32_bf16 v[60:63], v[218:221], v[186:189], v[60:63]
	v_mfma_f32_16x16x32_bf16 v[56:59], v[226:229], v[186:189], v[56:59]
	v_mfma_f32_16x16x32_bf16 v[52:55], v[218:221], v[194:197], v[52:55]
	v_mfma_f32_16x16x32_bf16 v[48:51], v[226:229], v[194:197], v[48:51]
	v_mfma_f32_16x16x32_bf16 v[44:47], v[218:221], v[202:205], v[44:47]
	v_mfma_f32_16x16x32_bf16 v[40:43], v[226:229], v[202:205], v[40:43]
	v_mfma_f32_16x16x32_bf16 v[36:39], v[218:221], v[210:213], v[36:39]
	v_mfma_f32_16x16x32_bf16 v[32:35], v[226:229], v[210:213], v[32:35]
	s_setprio 0
	s_barrier
	s_mov_b32 m0, s58
	s_nop 0
	global_load_lds_dwordx4 v132, s[36:37]
	s_mov_b32 m0, s59
	s_nop 0
	global_load_lds_dwordx4 v128, s[36:37]
	s_mov_b32 m0, s55
	ds_read_b128 v[182:185], v146 offset:16384
	ds_read_b128 v[186:189], v146 offset:17408
	ds_read_b128 v[190:193], v146 offset:18432
	ds_read_b128 v[194:197], v146 offset:19456
	ds_read_b128 v[198:201], v146 offset:20480
	ds_read_b128 v[202:205], v146 offset:21504
	ds_read_b128 v[206:209], v146 offset:22528
	ds_read_b128 v[210:213], v146 offset:23552
	global_load_lds_dwordx4 v134, s[52:53]
	s_mov_b32 m0, s60
	s_nop 0
	global_load_lds_dwordx4 v130, s[52:53]
	s_waitcnt vmcnt(6)
	s_waitcnt lgkmcnt(0)
	s_barrier
	s_setprio 1
	v_mfma_f32_16x16x32_bf16 v[92:95], v[166:169], v[182:185], v[92:95]
	v_mfma_f32_16x16x32_bf16 v[88:91], v[174:177], v[182:185], v[88:91]
	v_mfma_f32_16x16x32_bf16 v[84:87], v[166:169], v[190:193], v[84:87]
	v_mfma_f32_16x16x32_bf16 v[80:83], v[174:177], v[190:193], v[80:83]
	v_mfma_f32_16x16x32_bf16 v[76:79], v[166:169], v[198:201], v[76:79]
	v_mfma_f32_16x16x32_bf16 v[72:75], v[174:177], v[198:201], v[72:75]
	v_mfma_f32_16x16x32_bf16 v[68:71], v[166:169], v[206:209], v[68:71]
	v_mfma_f32_16x16x32_bf16 v[64:67], v[174:177], v[206:209], v[64:67]
	v_mfma_f32_16x16x32_bf16 v[92:95], v[170:173], v[186:189], v[92:95]
	v_mfma_f32_16x16x32_bf16 v[88:91], v[178:181], v[186:189], v[88:91]
	v_mfma_f32_16x16x32_bf16 v[84:87], v[170:173], v[194:197], v[84:87]
	v_mfma_f32_16x16x32_bf16 v[80:83], v[178:181], v[194:197], v[80:83]
	v_mfma_f32_16x16x32_bf16 v[76:79], v[170:173], v[202:205], v[76:79]
	v_mfma_f32_16x16x32_bf16 v[72:75], v[178:181], v[202:205], v[72:75]
	v_mfma_f32_16x16x32_bf16 v[68:71], v[170:173], v[210:213], v[68:71]
	v_mfma_f32_16x16x32_bf16 v[64:67], v[178:181], v[210:213], v[64:67]
	v_mfma_f32_16x16x32_bf16 v[28:31], v[214:217], v[182:185], v[28:31]
	v_mfma_f32_16x16x32_bf16 v[24:27], v[222:225], v[182:185], v[24:27]
	v_mfma_f32_16x16x32_bf16 v[20:23], v[214:217], v[190:193], v[20:23]
	v_mfma_f32_16x16x32_bf16 v[16:19], v[222:225], v[190:193], v[16:19]
	v_mfma_f32_16x16x32_bf16 v[12:15], v[214:217], v[198:201], v[12:15]
	v_mfma_f32_16x16x32_bf16 v[8:11], v[222:225], v[198:201], v[8:11]
	v_mfma_f32_16x16x32_bf16 v[4:7], v[214:217], v[206:209], v[4:7]
	v_mfma_f32_16x16x32_bf16 v[0:3], v[222:225], v[206:209], v[0:3]
	v_mfma_f32_16x16x32_bf16 v[28:31], v[218:221], v[186:189], v[28:31]
	v_mfma_f32_16x16x32_bf16 v[24:27], v[226:229], v[186:189], v[24:27]
	v_mfma_f32_16x16x32_bf16 v[20:23], v[218:221], v[194:197], v[20:23]
	v_mfma_f32_16x16x32_bf16 v[16:19], v[226:229], v[194:197], v[16:19]
	v_mfma_f32_16x16x32_bf16 v[12:15], v[218:221], v[202:205], v[12:15]
	v_mfma_f32_16x16x32_bf16 v[8:11], v[226:229], v[202:205], v[8:11]
	v_mfma_f32_16x16x32_bf16 v[4:7], v[218:221], v[210:213], v[4:7]
	v_mfma_f32_16x16x32_bf16 v[0:3], v[226:229], v[210:213], v[0:3]
	s_setprio 0
	s_barrier
; #define PG8_STAGE(bufoff, gbase, voff) do { _Pragma("unroll") for (int _i = 0; _i < 2; ++_i) \
;         __builtin_amdgcn_global_load_lds((const unsigned*)((const char*)(gbase) + (voff)[_i]), (PG8_LAS unsigned*)(lds + (bufoff) + ldsw + _i * 8192), 16, 0, 0); } while (0)
; #define PG8_LDA(dst, b, h) do { _Pragma("unroll") for (int m = 0; m < 4; ++m) _Pragma("unroll") for (int k = 0; k < 2; ++k) dst[m][k] = *(const PG8_LAS bf16x8*)(lds + PG8_SA(b, h) + aoff + m * 2048 + k * 1024); } while (0)
; #define PG8_LDB(dst, b, h) do { _Pragma("unroll") for (int n = 0; n < 2; ++n) _Pragma("unroll") for (int k = 0; k < 2; ++k) dst[n][k] = *(const PG8_LAS bf16x8*)(lds + PG8_SB(b, h) + boff + n * 2048 + k * 1024); } while (0)
; #define PG8_MMA(ai, bj, At, Bt) do { __builtin_amdgcn_s_setprio(1); _Pragma("unroll") for (int m = 0; m < 4; ++m) _Pragma("unroll") for (int n = 0; n < 2; ++n) _Pragma("unroll") for (int k = 0; k < 2; ++k) \
;         acc[ai][bj][m][n] = __builtin_amdgcn_mfma_f32_16x16x32_bf16(Bt[n][k], At[m][k], acc[ai][bj][m][n], 0, 0, 0); __builtin_amdgcn_s_setprio(0); } while (0)
; #define PG8_WAIT_V(n) asm volatile("s_waitcnt vmcnt(" #n ")" ::: "memory")
; #define PG8_WAIT_L(n) asm volatile("s_waitcnt lgkmcnt(" #n ")" ::: "memory")
; #define PG8_BAR __builtin_amdgcn_s_barrier()
; #define PG8_SCHED __builtin_amdgcn_sched_barrier(0)
; template <class Epi, class Sched, bool STAMP = false>
; __device__ __forceinline__ void gemm_phase(PG8_LAS unsigned char* lds, const Gemm g, const Sched& S, const Epi& E, unsigned long long* stamps) {
;     ...
;             PG8_WAIT_V(6); PG8_BAR; PG8_MMA(1, 1, At, B1); PG8_BAR;
;             PG8_LDB(B0, 1, 0); PG8_SCHED; PG8_LDA(At, 1, 0); PG8_STAGE(PG8_SA(0, 1), a2 + hstep, voffA);
;             PG8_WAIT_L(8); PG8_BAR; PG8_WAIT_L(0); PG8_MMA(0, 0, At, B0); PG8_BAR; PG8_SCHED;
;             PG8_LDB(B1, 1, 1); PG8_STAGE(PG8_SB(1, 0), b3, voffB);
;             PG8_BAR; PG8_WAIT_L(0); PG8_MMA(0, 1, At, B1); PG8_BAR;
;             PG8_LDA(At, 1, 1); PG8_STAGE(PG8_SA(1, 0), a3, voffA);
;             PG8_BAR; PG8_WAIT_L(0); PG8_MMA(1, 0, At, B0); PG8_BAR; PG8_SCHED;
;             PG8_STAGE(PG8_SB(1, 1), b3 + hstep, voffB);
;             PG8_WAIT_V(6); PG8_BAR; PG8_MMA(1, 1, At, B1); PG8_BAR;
;         }
.Lzp3_mid:
	s_add_u32 s28, s36, 0x44000
	s_addc_u32 s29, s37, 0
	s_mov_b32 m0, s61
	s_nop 0
	global_load_lds_dwordx4 v132, s[28:29]
	s_mov_b32 m0, s62
	s_nop 0
	global_load_lds_dwordx4 v128, s[28:29]
	ds_read_b128 v[166:169], v156
	ds_read_b128 v[170:173], v157
	ds_read_b128 v[174:177], v159
	ds_read_b128 v[178:181], v160
	s_add_u32 s28, s52, 0x44000
	s_addc_u32 s29, s53, 0
	s_mov_b32 m0, s63
	ds_read_b128 v[182:185], v146 offset:32768
	ds_read_b128 v[186:189], v146 offset:33792
	ds_read_b128 v[190:193], v146 offset:34816
	ds_read_b128 v[194:197], v146 offset:35840
	ds_read_b128 v[198:201], v146 offset:36864
	ds_read_b128 v[202:205], v146 offset:37888
	ds_read_b128 v[206:209], v146 offset:38912
	ds_read_b128 v[210:213], v146 offset:39936
	global_load_lds_dwordx4 v134, s[28:29]
	s_mov_b32 m0, s64
	s_nop 0
	global_load_lds_dwordx4 v130, s[28:29]
	ds_read_b128 v[214:217], v161
	ds_read_b128 v[218:221], v162
	ds_read_b128 v[222:225], v163
	ds_read_b128 v[226:229], v164
	s_waitcnt vmcnt(8)
	s_waitcnt lgkmcnt(0)
	s_barrier
	s_setprio 1
	v_mfma_f32_16x16x32_bf16 v[124:127], v[166:169], v[182:185], v[124:127]
	v_mfma_f32_16x16x32_bf16 v[120:123], v[174:177], v[182:185], v[120:123]
	v_mfma_f32_16x16x32_bf16 v[116:119], v[166:169], v[190:193], v[116:119]
	v_mfma_f32_16x16x32_bf16 v[112:115], v[174:177], v[190:193], v[112:115]
	v_mfma_f32_16x16x32_bf16 v[108:111], v[166:169], v[198:201], v[108:111]
	v_mfma_f32_16x16x32_bf16 v[104:107], v[174:177], v[198:201], v[104:107]
	v_mfma_f32_16x16x32_bf16 v[100:103], v[166:169], v[206:209], v[100:103]
	v_mfma_f32_16x16x32_bf16 v[96:99], v[174:177], v[206:209], v[96:99]
	v_mfma_f32_16x16x32_bf16 v[124:127], v[170:173], v[186:189], v[124:127]
	v_mfma_f32_16x16x32_bf16 v[120:123], v[178:181], v[186:189], v[120:123]
	v_mfma_f32_16x16x32_bf16 v[116:119], v[170:173], v[194:197], v[116:119]
	v_mfma_f32_16x16x32_bf16 v[112:115], v[178:181], v[194:197], v[112:115]
	v_mfma_f32_16x16x32_bf16 v[108:111], v[170:173], v[202:205], v[108:111]
	v_mfma_f32_16x16x32_bf16 v[104:107], v[178:181], v[202:205], v[104:107]
	v_mfma_f32_16x16x32_bf16 v[100:103], v[170:173], v[210:213], v[100:103]
	v_mfma_f32_16x16x32_bf16 v[96:99], v[178:181], v[210:213], v[96:99]
	v_mfma_f32_16x16x32_bf16 v[60:63], v[214:217], v[182:185], v[60:63]
	v_mfma_f32_16x16x32_bf16 v[56:59], v[222:225], v[182:185], v[56:59]
	v_mfma_f32_16x16x32_bf16 v[52:55], v[214:217], v[190:193], v[52:55]
	v_mfma_f32_16x16x32_bf16 v[48:51], v[222:225], v[190:193], v[48:51]
	v_mfma_f32_16x16x32_bf16 v[44:47], v[214:217], v[198:201], v[44:47]
	v_mfma_f32_16x16x32_bf16 v[40:43], v[222:225], v[198:201], v[40:43]
	v_mfma_f32_16x16x32_bf16 v[36:39], v[214:217], v[206:209], v[36:39]
	v_mfma_f32_16x16x32_bf16 v[32:35], v[222:225], v[206:209], v[32:35]
	v_mfma_f32_16x16x32_bf16 v[60:63], v[218:221], v[186:189], v[60:63]
	v_mfma_f32_16x16x32_bf16 v[56:59], v[226:229], v[186:189], v[56:59]
	v_mfma_f32_16x16x32_bf16 v[52:55], v[218:221], v[194:197], v[52:55]
	v_mfma_f32_16x16x32_bf16 v[48:51], v[226:229], v[194:197], v[48:51]
	v_mfma_f32_16x16x32_bf16 v[44:47], v[218:221], v[202:205], v[44:47]
	v_mfma_f32_16x16x32_bf16 v[40:43], v[226:229], v[202:205], v[40:43]
	v_mfma_f32_16x16x32_bf16 v[36:39], v[218:221], v[210:213], v[36:39]
	v_mfma_f32_16x16x32_bf16 v[32:35], v[226:229], v[210:213], v[32:35]
	s_setprio 0
	s_barrier
	s_mov_b32 m0, s67
	s_add_u32 s100, s36, 0x80
	s_addc_u32 s101, s37, 0
	global_load_lds_dwordx4 v132, s[100:101]
	s_mov_b32 m0, s68
	s_nop 0
	global_load_lds_dwordx4 v128, s[100:101]
	s_mov_b32 m0, s69
	ds_read_b128 v[182:185], v146 offset:49152
	ds_read_b128 v[186:189], v146 offset:50176
	ds_read_b128 v[190:193], v146 offset:51200
	ds_read_b128 v[194:197], v146 offset:52224
	ds_read_b128 v[198:201], v146 offset:53248
	ds_read_b128 v[202:205], v146 offset:54272
	ds_read_b128 v[206:209], v146 offset:55296
	ds_read_b128 v[210:213], v146 offset:56320
	s_add_u32 s100, s52, 0x80
	s_addc_u32 s101, s53, 0
	global_load_lds_dwordx4 v134, s[100:101]
	s_mov_b32 m0, s70
	s_nop 0
	global_load_lds_dwordx4 v130, s[100:101]
	s_waitcnt vmcnt(6)
	s_waitcnt lgkmcnt(0)
	s_barrier
	s_setprio 1
	v_mfma_f32_16x16x32_bf16 v[92:95], v[166:169], v[182:185], v[92:95]
	v_mfma_f32_16x16x32_bf16 v[88:91], v[174:177], v[182:185], v[88:91]
	v_mfma_f32_16x16x32_bf16 v[84:87], v[166:169], v[190:193], v[84:87]
	v_mfma_f32_16x16x32_bf16 v[80:83], v[174:177], v[190:193], v[80:83]
	v_mfma_f32_16x16x32_bf16 v[76:79], v[166:169], v[198:201], v[76:79]
	v_mfma_f32_16x16x32_bf16 v[72:75], v[174:177], v[198:201], v[72:75]
	v_mfma_f32_16x16x32_bf16 v[68:71], v[166:169], v[206:209], v[68:71]
	v_mfma_f32_16x16x32_bf16 v[64:67], v[174:177], v[206:209], v[64:67]
	v_mfma_f32_16x16x32_bf16 v[92:95], v[170:173], v[186:189], v[92:95]
	v_mfma_f32_16x16x32_bf16 v[88:91], v[178:181], v[186:189], v[88:91]
	v_mfma_f32_16x16x32_bf16 v[84:87], v[170:173], v[194:197], v[84:87]
	v_mfma_f32_16x16x32_bf16 v[80:83], v[178:181], v[194:197], v[80:83]
	v_mfma_f32_16x16x32_bf16 v[76:79], v[170:173], v[202:205], v[76:79]
	v_mfma_f32_16x16x32_bf16 v[72:75], v[178:181], v[202:205], v[72:75]
	v_mfma_f32_16x16x32_bf16 v[68:71], v[170:173], v[210:213], v[68:71]
	v_mfma_f32_16x16x32_bf16 v[64:67], v[178:181], v[210:213], v[64:67]
	v_mfma_f32_16x16x32_bf16 v[28:31], v[214:217], v[182:185], v[28:31]
	v_mfma_f32_16x16x32_bf16 v[24:27], v[222:225], v[182:185], v[24:27]
	v_mfma_f32_16x16x32_bf16 v[20:23], v[214:217], v[190:193], v[20:23]
	v_mfma_f32_16x16x32_bf16 v[16:19], v[222:225], v[190:193], v[16:19]
	v_mfma_f32_16x16x32_bf16 v[12:15], v[214:217], v[198:201], v[12:15]
	v_mfma_f32_16x16x32_bf16 v[8:11], v[222:225], v[198:201], v[8:11]
	v_mfma_f32_16x16x32_bf16 v[4:7], v[214:217], v[206:209], v[4:7]
	v_mfma_f32_16x16x32_bf16 v[0:3], v[222:225], v[206:209], v[0:3]
	v_mfma_f32_16x16x32_bf16 v[28:31], v[218:221], v[186:189], v[28:31]
	v_mfma_f32_16x16x32_bf16 v[24:27], v[226:229], v[186:189], v[24:27]
	v_mfma_f32_16x16x32_bf16 v[20:23], v[218:221], v[194:197], v[20:23]
	v_mfma_f32_16x16x32_bf16 v[16:19], v[226:229], v[194:197], v[16:19]
	v_mfma_f32_16x16x32_bf16 v[12:15], v[218:221], v[202:205], v[12:15]
	v_mfma_f32_16x16x32_bf16 v[8:11], v[226:229], v[202:205], v[8:11]
	v_mfma_f32_16x16x32_bf16 v[4:7], v[218:221], v[210:213], v[4:7]
	v_mfma_f32_16x16x32_bf16 v[0:3], v[226:229], v[210:213], v[0:3]
	s_setprio 0
	s_add_i32 s85, s85, 2
	s_add_u32 s83, s83, 0x100
	s_addc_u32 s84, s84, 0
	s_cmp_gt_u32 s85, 13
	s_mov_b64 s[28:29], s[34:35]
	s_barrier
;     DI void operator()(const f32x4 (&acc)[2][2][4][2], const Unit& u, int wr, int wc, int fr, int fq) const {
;         const int row0 = u.pm * BM + wr * 64 + fr, col0 = u.pn * BM + wc * 32 + 8 * fq;
; #pragma unroll
;         for (int ai = 0; ai < 2; ++ai)
; #pragma unroll
;             for (int m = 0; m < 4; ++m) { u16* rowp = O + (size_t)(row0 + ai * HALF + m * 16) * ldc + col0;
; #pragma unroll
;                 for (int bj = 0; bj < 2; ++bj) { const f32x4 v0 = acc[ai][bj][m][0], v1 = acc[ai][bj][m][1];
;                     uint4 w = {pack2(v0[0], v0[1]), pack2(v0[2], v0[3]), pack2(v1[0], v1[1]), pack2(v1[2], v1[3])}; *(uint4*)(rowp + bj * HALF) = w; } }
;         if (kmaxp) {
; #pragma unroll
;             for (int bj = 0; bj < 2; ++bj) {
;                 const int cb = u.pn * BM + bj * HALF + wc * 32;
;                 const bool isA = (cb >= 384 && cb < 768), isB = (cb >= 1408 && cb < 1664);
;                 if (isA || isB) {
	s_cbranch_scc0 .LBB0_138
	s_lshl_b32 s52, s79, 8
	v_or_b32_e32 v166, s52, v147
	v_lshl_add_u32 v176, s82, 8, v145
	v_ashrrev_i32_e32 v167, 31, v166
	v_mov_b64_e32 v[170:171], s[12:13]
	v_mad_i64_i32 v[168:169], s[28:29], v176, s76, v[170:171]
	v_lshlrev_b64 v[172:173], 1, v[166:167]
	v_lshl_add_u64 v[174:175], v[168:169], 0, v[172:173]
	v_cvt_pk_bf16_f32 v166, v124, v125
	v_cvt_pk_bf16_f32 v167, v126, v127
	v_cvt_pk_bf16_f32 v168, v120, v121
	v_cvt_pk_bf16_f32 v169, v122, v123
	global_store_dwordx4 v[174:175], v[166:169], off
	s_or_b32 s10, s52, s66
	s_nop 0
	v_cvt_pk_bf16_f32 v166, v60, v61
	v_cvt_pk_bf16_f32 v167, v62, v63
	v_cvt_pk_bf16_f32 v168, v56, v57
	v_cvt_pk_bf16_f32 v169, v58, v59
	global_store_dwordx4 v[174:175], v[166:169], off offset:256
	s_nop 1
	v_or_b32_e32 v166, 16, v176
	v_mad_i64_i32 v[166:167], s[28:29], v166, s76, v[170:171]
	v_lshl_add_u64 v[174:175], v[166:167], 0, v[172:173]
	v_cvt_pk_bf16_f32 v166, v116, v117
	v_cvt_pk_bf16_f32 v167, v118, v119
	v_cvt_pk_bf16_f32 v168, v112, v113
	v_cvt_pk_bf16_f32 v169, v114, v115
	global_store_dwordx4 v[174:175], v[166:169], off
	s_nop 1
	v_cvt_pk_bf16_f32 v166, v52, v53
	v_cvt_pk_bf16_f32 v167, v54, v55
	v_cvt_pk_bf16_f32 v168, v48, v49
	v_cvt_pk_bf16_f32 v169, v50, v51
	global_store_dwordx4 v[174:175], v[166:169], off offset:256
	s_nop 1
	v_or_b32_e32 v166, 32, v176
	v_mad_i64_i32 v[166:167], s[28:29], v166, s76, v[170:171]
	v_lshl_add_u64 v[174:175], v[166:167], 0, v[172:173]
	v_cvt_pk_bf16_f32 v166, v108, v109
	v_cvt_pk_bf16_f32 v167, v110, v111
	v_cvt_pk_bf16_f32 v168, v104, v105
	v_cvt_pk_bf16_f32 v169, v106, v107
	global_store_dwordx4 v[174:175], v[166:169], off
	s_nop 1
	v_cvt_pk_bf16_f32 v166, v44, v45
	v_cvt_pk_bf16_f32 v167, v46, v47
	v_cvt_pk_bf16_f32 v168, v40, v41
	v_cvt_pk_bf16_f32 v169, v42, v43
	global_store_dwordx4 v[174:175], v[166:169], off offset:256
	s_nop 1
	v_or_b32_e32 v166, 48, v176
	v_mad_i64_i32 v[166:167], s[28:29], v166, s76, v[170:171]
	v_lshl_add_u64 v[174:175], v[166:167], 0, v[172:173]
	v_cvt_pk_bf16_f32 v166, v100, v101
	v_cvt_pk_bf16_f32 v167, v102, v103
	v_cvt_pk_bf16_f32 v168, v96, v97
	v_cvt_pk_bf16_f32 v169, v98, v99
	global_store_dwordx4 v[174:175], v[166:169], off
	s_nop 1
	v_cvt_pk_bf16_f32 v166, v36, v37
	v_cvt_pk_bf16_f32 v167, v38, v39
	v_cvt_pk_bf16_f32 v168, v32, v33
	v_cvt_pk_bf16_f32 v169, v34, v35
	global_store_dwordx4 v[174:175], v[166:169], off offset:256
	s_nop 1
	v_add_u32_e32 v166, 0x80, v176
	v_mad_i64_i32 v[166:167], s[28:29], v166, s76, v[170:171]
	v_lshl_add_u64 v[174:175], v[166:167], 0, v[172:173]
	v_cvt_pk_bf16_f32 v166, v92, v93
	v_cvt_pk_bf16_f32 v167, v94, v95
	v_cvt_pk_bf16_f32 v168, v88, v89
	v_cvt_pk_bf16_f32 v169, v90, v91
	global_store_dwordx4 v[174:175], v[166:169], off
	s_nop 1
	v_cvt_pk_bf16_f32 v166, v28, v29
	v_cvt_pk_bf16_f32 v167, v30, v31
	v_cvt_pk_bf16_f32 v168, v24, v25
	v_cvt_pk_bf16_f32 v169, v26, v27
	global_store_dwordx4 v[174:175], v[166:169], off offset:256
	s_nop 1
	v_add_u32_e32 v166, 0x90, v176
	v_mad_i64_i32 v[166:167], s[28:29], v166, s76, v[170:171]
	v_lshl_add_u64 v[174:175], v[166:167], 0, v[172:173]
	v_cvt_pk_bf16_f32 v166, v84, v85
	v_cvt_pk_bf16_f32 v167, v86, v87
	v_cvt_pk_bf16_f32 v168, v80, v81
	v_cvt_pk_bf16_f32 v169, v82, v83
	global_store_dwordx4 v[174:175], v[166:169], off
	s_nop 1
	v_cvt_pk_bf16_f32 v166, v20, v21
	v_cvt_pk_bf16_f32 v167, v22, v23
	v_cvt_pk_bf16_f32 v168, v16, v17
	v_cvt_pk_bf16_f32 v169, v18, v19
	global_store_dwordx4 v[174:175], v[166:169], off offset:256
	s_nop 1
	v_add_u32_e32 v166, 0xa0, v176
	v_mad_i64_i32 v[166:167], s[28:29], v166, s76, v[170:171]
	v_lshl_add_u64 v[174:175], v[166:167], 0, v[172:173]
	v_cvt_pk_bf16_f32 v166, v76, v77
	v_cvt_pk_bf16_f32 v167, v78, v79
	v_cvt_pk_bf16_f32 v168, v72, v73
	v_cvt_pk_bf16_f32 v169, v74, v75
	global_store_dwordx4 v[174:175], v[166:169], off
	s_nop 1
	v_cvt_pk_bf16_f32 v166, v12, v13
	v_cvt_pk_bf16_f32 v167, v14, v15
	v_cvt_pk_bf16_f32 v168, v8, v9
	v_cvt_pk_bf16_f32 v169, v10, v11
	global_store_dwordx4 v[174:175], v[166:169], off offset:256
	s_nop 1
	v_add_u32_e32 v166, 0xb0, v176
	v_mad_i64_i32 v[166:167], s[28:29], v166, s76, v[170:171]
	s_add_i32 s28, s52, 0xfffffe80
	s_cmpk_gt_u32 s28, 0x17f
	s_cselect_b64 s[28:29], -1, 0
	s_add_i32 s34, s52, 0xfffffa80
	s_cmpk_gt_u32 s34, 0xff
	s_cselect_b64 s[34:35], -1, 0
	v_lshl_add_u64 v[170:171], v[166:167], 0, v[172:173]
	v_cvt_pk_bf16_f32 v166, v68, v69
	v_cvt_pk_bf16_f32 v167, v70, v71
	v_cvt_pk_bf16_f32 v168, v64, v65
	v_cvt_pk_bf16_f32 v169, v66, v67
	s_and_b64 s[34:35], s[28:29], s[34:35]
	global_store_dwordx4 v[170:171], v[166:169], off
	s_and_b64 vcc, exec, s[34:35]
	s_nop 0
	v_cvt_pk_bf16_f32 v166, v4, v5
	v_cvt_pk_bf16_f32 v167, v6, v7
	v_cvt_pk_bf16_f32 v168, v0, v1
	v_cvt_pk_bf16_f32 v169, v2, v3
	global_store_dwordx4 v[170:171], v[166:169], off offset:256
	s_cbranch_vccnz .LBB0_150
;     DI void operator()(const f32x4 (&acc)[2][2][4][2], const Unit& u, int wr, int wc, int fr, int fq) const {
;     ...
;                     float mx = 0.f;
; #pragma unroll
;                     for (int ai = 0; ai < 2; ++ai)
; #pragma unroll
;                         for (int m = 0; m < 4; ++m) {
;                             const f32x4 a = acc[ai][bj][m][0], b = acc[ai][bj][m][1];
;                             float s0 = a[0] * a[0] + a[1] * a[1] + a[2] * a[2] + a[3] * a[3] + b[0] * b[0] + b[1] * b[1] + b[2] * b[2] + b[3] * b[3];
;                             s0 += __shfl_xor(s0, 16);
;                             s0 += __shfl_xor(s0, 32);
;                             mx = fmaxf(mx, s0);
;                         }
; #pragma unroll
;                     for (int o = 1; o <= 8; o <<= 1) mx = fmaxf(mx, __shfl_xor(mx, o));
;                     if ((threadIdx.x & 63) == 0) atomicMax((unsigned*)kmaxp + (isA ? ((cb - 384) >> 5) : (12 + ((cb - 1408) >> 5))), __float_as_uint(mx));
;                 }
;             }
	v_mul_f32_e32 v125, v125, v125
	v_mul_f32_e32 v117, v117, v117
	v_fmac_f32_e32 v125, v124, v124
	v_fmac_f32_e32 v117, v116, v116
	v_mul_f32_e32 v109, v109, v109
	v_mul_f32_e32 v101, v101, v101
	v_fmac_f32_e32 v125, v126, v126
	v_fmac_f32_e32 v117, v118, v118
	v_fmac_f32_e32 v109, v108, v108
	v_fmac_f32_e32 v101, v100, v100
	v_and_b32_e32 v167, 64, v165
	v_fmac_f32_e32 v125, v127, v127
	v_fmac_f32_e32 v117, v119, v119
	v_fmac_f32_e32 v109, v110, v110
	v_fmac_f32_e32 v101, v102, v102
	v_xor_b32_e32 v166, 16, v165
	v_add_u32_e32 v167, 64, v167
	v_fmac_f32_e32 v125, v120, v120
	v_fmac_f32_e32 v117, v112, v112
	v_fmac_f32_e32 v109, v111, v111
	v_fmac_f32_e32 v101, v103, v103
	v_cmp_lt_i32_e32 vcc, v166, v167
	v_fmac_f32_e32 v125, v121, v121
	v_fmac_f32_e32 v117, v113, v113
	v_fmac_f32_e32 v109, v104, v104
	v_fmac_f32_e32 v101, v96, v96
	v_cndmask_b32_e32 v166, v165, v166, vcc
	v_fmac_f32_e32 v125, v122, v122
	v_fmac_f32_e32 v117, v114, v114
	v_fmac_f32_e32 v109, v105, v105
	v_fmac_f32_e32 v101, v97, v97
	v_lshlrev_b32_e32 v166, 2, v166
	v_fmac_f32_e32 v125, v123, v123
	v_fmac_f32_e32 v117, v115, v115
	v_fmac_f32_e32 v109, v106, v106
	v_fmac_f32_e32 v101, v98, v98
	v_mul_f32_e32 v93, v93, v93
	v_mul_f32_e32 v85, v85, v85
	ds_bpermute_b32 v120, v166, v125
	ds_bpermute_b32 v112, v166, v117
	v_fmac_f32_e32 v109, v107, v107
	v_fmac_f32_e32 v101, v99, v99
	v_fmac_f32_e32 v93, v92, v92
	v_fmac_f32_e32 v85, v84, v84
	v_mul_f32_e32 v77, v77, v77
	v_mul_f32_e32 v69, v69, v69
	ds_bpermute_b32 v104, v166, v109
	ds_bpermute_b32 v96, v166, v101
	v_fmac_f32_e32 v93, v94, v94
	v_fmac_f32_e32 v85, v86, v86
	v_fmac_f32_e32 v77, v76, v76
	v_fmac_f32_e32 v69, v68, v68
	v_xor_b32_e32 v168, 32, v165
	v_fmac_f32_e32 v93, v95, v95
	v_fmac_f32_e32 v85, v87, v87
	v_fmac_f32_e32 v77, v78, v78
	v_fmac_f32_e32 v69, v70, v70
	v_cmp_lt_i32_e32 vcc, v168, v167
	v_fmac_f32_e32 v93, v88, v88
	v_fmac_f32_e32 v85, v80, v80
	v_fmac_f32_e32 v77, v79, v79
	v_fmac_f32_e32 v69, v71, v71
	v_cndmask_b32_e32 v113, v165, v168, vcc
	v_fmac_f32_e32 v93, v89, v89
	v_fmac_f32_e32 v85, v81, v81
	v_fmac_f32_e32 v77, v72, v72
	v_fmac_f32_e32 v69, v64, v64
	v_lshlrev_b32_e32 v113, 2, v113
	s_waitcnt lgkmcnt(0)
	v_add_f32_e32 v114, v125, v120
	v_add_f32_e32 v112, v117, v112
	v_fmac_f32_e32 v93, v90, v90
	v_fmac_f32_e32 v85, v82, v82
	v_fmac_f32_e32 v77, v73, v73
	v_fmac_f32_e32 v69, v65, v65
	ds_bpermute_b32 v115, v113, v114
	ds_bpermute_b32 v116, v113, v112
	v_add_f32_e32 v99, v109, v104
	v_add_f32_e32 v96, v101, v96
	v_fmac_f32_e32 v93, v91, v91
	v_fmac_f32_e32 v85, v83, v83
	v_fmac_f32_e32 v77, v74, v74
	v_fmac_f32_e32 v69, v66, v66
	ds_bpermute_b32 v100, v113, v99
	ds_bpermute_b32 v101, v113, v96
	ds_bpermute_b32 v88, v166, v93
	ds_bpermute_b32 v80, v166, v85
	v_fmac_f32_e32 v77, v75, v75
	v_fmac_f32_e32 v69, v67, v67
	ds_bpermute_b32 v72, v166, v77
	ds_bpermute_b32 v64, v166, v69
	s_waitcnt lgkmcnt(0)
	v_add_f32_e32 v97, v114, v115
	v_add_f32_e32 v98, v112, v116
	v_max3_f32 v89, v97, 0, v98
	v_add_f32_e32 v90, v99, v100
	v_add_f32_e32 v91, v96, v101
	v_add_f32_e32 v88, v93, v88
	v_add_f32_e32 v65, v85, v80
	v_max3_f32 v89, v89, v90, v91
	ds_bpermute_b32 v90, v113, v88
	ds_bpermute_b32 v66, v113, v65
	v_add_f32_e32 v67, v77, v72
	v_add_f32_e32 v64, v69, v64
	ds_bpermute_b32 v68, v113, v67
	ds_bpermute_b32 v69, v113, v64
	s_waitcnt lgkmcnt(0)
	v_add_f32_e32 v70, v88, v90
	v_add_f32_e32 v65, v65, v66
	v_max3_f32 v65, v89, v70, v65
	v_add_f32_e32 v66, v67, v68
	v_add_f32_e32 v64, v64, v69
	v_max3_f32 v64, v65, v66, v64
	v_xor_b32_e32 v65, 1, v165
	v_cmp_lt_i32_e32 vcc, v65, v167
	s_nop 1
	v_cndmask_b32_e32 v65, v165, v65, vcc
	v_lshlrev_b32_e32 v65, 2, v65
	ds_bpermute_b32 v65, v65, v64
	s_waitcnt lgkmcnt(0)
	v_max_f32_e32 v65, v65, v65
	v_max_f32_e32 v64, v64, v65
	v_xor_b32_e32 v65, 2, v165
	v_cmp_lt_i32_e32 vcc, v65, v167
	s_nop 1
	v_cndmask_b32_e32 v65, v165, v65, vcc
	v_lshlrev_b32_e32 v65, 2, v65
	ds_bpermute_b32 v65, v65, v64
	s_waitcnt lgkmcnt(0)
	v_max_f32_e32 v65, v65, v65
	v_max_f32_e32 v64, v64, v65
	v_xor_b32_e32 v65, 4, v165
	v_cmp_lt_i32_e32 vcc, v65, v167
	s_nop 1
	v_cndmask_b32_e32 v65, v165, v65, vcc
	v_lshlrev_b32_e32 v65, 2, v65
	ds_bpermute_b32 v65, v65, v64
	s_waitcnt lgkmcnt(0)
	v_max_f32_e32 v65, v65, v65
	v_max_f32_e32 v64, v64, v65
	v_xor_b32_e32 v65, 8, v165
	v_cmp_lt_i32_e32 vcc, v65, v167
	s_nop 1
	v_cndmask_b32_e32 v65, v165, v65, vcc
	v_lshlrev_b32_e32 v65, 2, v65
	ds_bpermute_b32 v65, v65, v64
	s_and_saveexec_b64 s[34:35], s[2:3]
	s_cbranch_execz .LBB0_149
	s_mov_b64 s[36:37], -1
	s_and_b64 vcc, exec, s[28:29]
	s_cbranch_vccz .LBB0_143
	s_add_i32 s28, s10, 0xfffffa80
	s_ashr_i32 s28, s28, 5
	s_add_i32 s28, s28, 12
	s_mov_b64 s[36:37], 0

; #define PG8_STAGE(bufoff, gbase, voff) do { _Pragma("unroll") for (int _i = 0; _i < 2; ++_i) \
;         __builtin_amdgcn_global_load_lds((const unsigned*)((const char*)(gbase) + (voff)[_i]), (PG8_LAS unsigned*)(lds + (bufoff) + ldsw + _i * 8192), 16, 0, 0); } while (0)
; #define PG8_LDA(dst, b, h) do { _Pragma("unroll") for (int m = 0; m < 4; ++m) _Pragma("unroll") for (int k = 0; k < 2; ++k) dst[m][k] = *(const PG8_LAS bf16x8*)(lds + PG8_SA(b, h) + aoff + m * 2048 + k * 1024); } while (0)
; template <class Epi, class Sched, bool STAMP = false>
; __device__ __forceinline__ void gemm_phase(PG8_LAS unsigned char* lds, const Gemm g, const Sched& S, const Epi& E, unsigned long long* stamps) {
;     ...
;         for (int t = 0; t < nt; t += 2) {
;             const bool last = (t == nt - 2);
;             const char* a1 = cA + (size_t)(t + 1) * kstep;
;             const char* a2 = last ? nA : cA + (size_t)(t + 2) * kstep; const char* b2 = last ? nB : cB + (size_t)(t + 2) * kstep;
;             const char* a3 = a2 + kstep; const char* b3 = b2 + kstep;
;             if (last && has_next) S.a_ready(nxt);
;             PG8_LDB(B0, 0, 0); PG8_SCHED; PG8_LDA(At, 0, 0); PG8_STAGE(PG8_SA(1, 1), a1 + hstep, voffA);
;             PG8_WAIT_L(8); PG8_BAR; PG8_WAIT_L(0); PG8_MMA(0, 0, At, B0); PG8_BAR; PG8_SCHED;
;             PG8_LDB(B1, 0, 1); PG8_STAGE(PG8_SB(0, 0), b2, voffB);
;             PG8_BAR; PG8_WAIT_L(0); PG8_MMA(0, 1, At, B1); PG8_BAR;
;             PG8_LDA(At, 0, 1); PG8_STAGE(PG8_SA(0, 0), a2, voffA);
;             PG8_BAR; PG8_WAIT_L(0); PG8_MMA(1, 0, At, B0); PG8_BAR; PG8_SCHED;
;             PG8_STAGE(PG8_SB(0, 1), b2 + hstep, voffB);
;             PG8_WAIT_V(6); PG8_BAR; PG8_MMA(1, 1, At, B1); PG8_BAR;
;             PG8_LDB(B0, 1, 0); PG8_SCHED; PG8_LDA(At, 1, 0); PG8_STAGE(PG8_SA(0, 1), a2 + hstep, voffA);
;             PG8_WAIT_L(8); PG8_BAR; PG8_WAIT_L(0); PG8_MMA(0, 0, At, B0); PG8_BAR; PG8_SCHED;
;             PG8_LDB(B1, 1, 1); PG8_STAGE(PG8_SB(1, 0), b3, voffB);
;             PG8_BAR; PG8_WAIT_L(0); PG8_MMA(0, 1, At, B1); PG8_BAR;
;             PG8_LDA(At, 1, 1); PG8_STAGE(PG8_SA(1, 0), a3, voffA);
;             PG8_BAR; PG8_WAIT_L(0); PG8_MMA(1, 0, At, B0); PG8_BAR; PG8_SCHED;
;             PG8_STAGE(PG8_SB(1, 1), b3 + hstep, voffB);
;             PG8_WAIT_V(6); PG8_BAR; PG8_MMA(1, 1, At, B1); PG8_BAR;
;         }
.LBB0_311:
	s_add_u32 s94, s58, 0x100
	s_addc_u32 s95, s59, 0
	s_mov_b32 s96, -2
	s_add_u32 s100, s94, 0x43f80
	s_addc_u32 s101, s95, 0
	s_mov_b32 m0, s78
	s_nop 0
	global_load_lds_dwordx4 v130, s[100:101]
	s_mov_b32 m0, s79
	s_nop 0
	global_load_lds_dwordx4 v134, s[100:101]
	ds_read_b128 v[170:173], v147
	ds_read_b128 v[174:177], v148
	ds_read_b128 v[178:181], v149
	ds_read_b128 v[182:185], v150
	s_add_u32 s58, s56, 0x100
	s_addc_u32 s59, s57, 0
	s_cmp_eq_u32 s96, 12
	s_cselect_b32 s63, s5, s59
	s_cselect_b32 s62, s4, s58
	s_cselect_b32 s61, s1, s95
	s_cselect_b32 s60, s0, s94
	s_mov_b32 m0, s84
	ds_read_b128 v[186:189], v145
	ds_read_b128 v[190:193], v145 offset:1024
	ds_read_b128 v[194:197], v145 offset:2048
	ds_read_b128 v[198:201], v145 offset:3072
	ds_read_b128 v[202:205], v145 offset:4096
	ds_read_b128 v[206:209], v145 offset:5120
	ds_read_b128 v[210:213], v145 offset:6144
	ds_read_b128 v[214:217], v145 offset:7168
	global_load_lds_dwordx4 v136, s[56:57]
	s_mov_b32 m0, s85
	s_nop 0
	global_load_lds_dwordx4 v138, s[56:57]
	ds_read_b128 v[218:221], v151
	ds_read_b128 v[222:225], v152
	ds_read_b128 v[226:229], v153
	ds_read_b128 v[230:233], v154
	s_waitcnt vmcnt(8)
	s_waitcnt lgkmcnt(0)
	s_barrier
	s_setprio 1
	v_mfma_f32_16x16x32_bf16 v[124:127], v[170:173], v[186:189], 0
	v_mfma_f32_16x16x32_bf16 v[120:123], v[178:181], v[186:189], 0
	v_mfma_f32_16x16x32_bf16 v[116:119], v[170:173], v[194:197], 0
	v_mfma_f32_16x16x32_bf16 v[112:115], v[178:181], v[194:197], 0
	v_mfma_f32_16x16x32_bf16 v[100:103], v[170:173], v[202:205], 0
	v_mfma_f32_16x16x32_bf16 v[96:99], v[178:181], v[202:205], 0
	v_mfma_f32_16x16x32_bf16 v[84:87], v[170:173], v[210:213], 0
	v_mfma_f32_16x16x32_bf16 v[80:83], v[178:181], v[210:213], 0
	v_mfma_f32_16x16x32_bf16 v[124:127], v[174:177], v[190:193], v[124:127]
	v_mfma_f32_16x16x32_bf16 v[120:123], v[182:185], v[190:193], v[120:123]
	v_mfma_f32_16x16x32_bf16 v[116:119], v[174:177], v[198:201], v[116:119]
	v_mfma_f32_16x16x32_bf16 v[112:115], v[182:185], v[198:201], v[112:115]
	v_mfma_f32_16x16x32_bf16 v[100:103], v[174:177], v[206:209], v[100:103]
	v_mfma_f32_16x16x32_bf16 v[96:99], v[182:185], v[206:209], v[96:99]
	v_mfma_f32_16x16x32_bf16 v[84:87], v[174:177], v[214:217], v[84:87]
	v_mfma_f32_16x16x32_bf16 v[80:83], v[182:185], v[214:217], v[80:83]
	v_mfma_f32_16x16x32_bf16 v[108:111], v[218:221], v[186:189], 0
	v_mfma_f32_16x16x32_bf16 v[104:107], v[226:229], v[186:189], 0
	v_mfma_f32_16x16x32_bf16 v[92:95], v[218:221], v[194:197], 0
	v_mfma_f32_16x16x32_bf16 v[88:91], v[226:229], v[194:197], 0
	v_mfma_f32_16x16x32_bf16 v[76:79], v[218:221], v[202:205], 0
	v_mfma_f32_16x16x32_bf16 v[72:75], v[226:229], v[202:205], 0
	v_mfma_f32_16x16x32_bf16 v[68:71], v[218:221], v[210:213], 0
	v_mfma_f32_16x16x32_bf16 v[64:67], v[226:229], v[210:213], 0
	v_mfma_f32_16x16x32_bf16 v[108:111], v[222:225], v[190:193], v[108:111]
	v_mfma_f32_16x16x32_bf16 v[104:107], v[230:233], v[190:193], v[104:107]
	v_mfma_f32_16x16x32_bf16 v[92:95], v[222:225], v[198:201], v[92:95]
	v_mfma_f32_16x16x32_bf16 v[88:91], v[230:233], v[198:201], v[88:91]
	v_mfma_f32_16x16x32_bf16 v[76:79], v[222:225], v[206:209], v[76:79]
	v_mfma_f32_16x16x32_bf16 v[72:75], v[230:233], v[206:209], v[72:75]
	v_mfma_f32_16x16x32_bf16 v[68:71], v[222:225], v[214:217], v[68:71]
	v_mfma_f32_16x16x32_bf16 v[64:67], v[230:233], v[214:217], v[64:67]
	s_setprio 0
	s_barrier
	s_mov_b32 m0, s67
	s_nop 0
	global_load_lds_dwordx4 v130, s[60:61]
	s_mov_b32 m0, s68
	s_nop 0
	global_load_lds_dwordx4 v134, s[60:61]
	s_mov_b32 m0, s66
	ds_read_b128 v[186:189], v145 offset:16384
	ds_read_b128 v[190:193], v145 offset:17408
	ds_read_b128 v[194:197], v145 offset:18432
	ds_read_b128 v[198:201], v145 offset:19456
	ds_read_b128 v[202:205], v145 offset:20480
	ds_read_b128 v[206:209], v145 offset:21504
	ds_read_b128 v[210:213], v145 offset:22528
	ds_read_b128 v[214:217], v145 offset:23552
	global_load_lds_dwordx4 v128, s[62:63]
	s_mov_b32 m0, s69
	s_nop 0
	global_load_lds_dwordx4 v132, s[62:63]
	s_waitcnt vmcnt(6)
	s_waitcnt lgkmcnt(0)
	s_barrier
	s_setprio 1
	v_mfma_f32_16x16x32_bf16 v[60:63], v[170:173], v[186:189], 0
	v_mfma_f32_16x16x32_bf16 v[56:59], v[178:181], v[186:189], 0
	v_mfma_f32_16x16x32_bf16 v[52:55], v[170:173], v[194:197], 0
	v_mfma_f32_16x16x32_bf16 v[48:51], v[178:181], v[194:197], 0
	v_mfma_f32_16x16x32_bf16 v[36:39], v[170:173], v[202:205], 0
	v_mfma_f32_16x16x32_bf16 v[32:35], v[178:181], v[202:205], 0
	v_mfma_f32_16x16x32_bf16 v[20:23], v[170:173], v[210:213], 0
	v_mfma_f32_16x16x32_bf16 v[16:19], v[178:181], v[210:213], 0
	v_mfma_f32_16x16x32_bf16 v[60:63], v[174:177], v[190:193], v[60:63]
	v_mfma_f32_16x16x32_bf16 v[56:59], v[182:185], v[190:193], v[56:59]
	v_mfma_f32_16x16x32_bf16 v[52:55], v[174:177], v[198:201], v[52:55]
	v_mfma_f32_16x16x32_bf16 v[48:51], v[182:185], v[198:201], v[48:51]
	v_mfma_f32_16x16x32_bf16 v[36:39], v[174:177], v[206:209], v[36:39]
	v_mfma_f32_16x16x32_bf16 v[32:35], v[182:185], v[206:209], v[32:35]
	v_mfma_f32_16x16x32_bf16 v[20:23], v[174:177], v[214:217], v[20:23]
	v_mfma_f32_16x16x32_bf16 v[16:19], v[182:185], v[214:217], v[16:19]
	v_mfma_f32_16x16x32_bf16 v[44:47], v[218:221], v[186:189], 0
	v_mfma_f32_16x16x32_bf16 v[40:43], v[226:229], v[186:189], 0
	v_mfma_f32_16x16x32_bf16 v[28:31], v[218:221], v[194:197], 0
	v_mfma_f32_16x16x32_bf16 v[24:27], v[226:229], v[194:197], 0
	v_mfma_f32_16x16x32_bf16 v[12:15], v[218:221], v[202:205], 0
	v_mfma_f32_16x16x32_bf16 v[8:11], v[226:229], v[202:205], 0
	v_mfma_f32_16x16x32_bf16 v[4:7], v[218:221], v[210:213], 0
	v_mfma_f32_16x16x32_bf16 v[0:3], v[226:229], v[210:213], 0
	v_mfma_f32_16x16x32_bf16 v[44:47], v[222:225], v[190:193], v[44:47]
	v_mfma_f32_16x16x32_bf16 v[40:43], v[230:233], v[190:193], v[40:43]
	v_mfma_f32_16x16x32_bf16 v[28:31], v[222:225], v[198:201], v[28:31]
	v_mfma_f32_16x16x32_bf16 v[24:27], v[230:233], v[198:201], v[24:27]
	v_mfma_f32_16x16x32_bf16 v[12:15], v[222:225], v[206:209], v[12:15]
	v_mfma_f32_16x16x32_bf16 v[8:11], v[230:233], v[206:209], v[8:11]
	v_mfma_f32_16x16x32_bf16 v[4:7], v[222:225], v[214:217], v[4:7]
	v_mfma_f32_16x16x32_bf16 v[0:3], v[230:233], v[214:217], v[0:3]
	s_setprio 0
	s_barrier
	s_branch .Lzp4_mid
; #define PG8_STAGE(bufoff, gbase, voff) do { _Pragma("unroll") for (int _i = 0; _i < 2; ++_i) \
;         __builtin_amdgcn_global_load_lds((const unsigned*)((const char*)(gbase) + (voff)[_i]), (PG8_LAS unsigned*)(lds + (bufoff) + ldsw + _i * 8192), 16, 0, 0); } while (0)
; #define PG8_LDA(dst, b, h) do { _Pragma("unroll") for (int m = 0; m < 4; ++m) _Pragma("unroll") for (int k = 0; k < 2; ++k) dst[m][k] = *(const PG8_LAS bf16x8*)(lds + PG8_SA(b, h) + aoff + m * 2048 + k * 1024); } while (0)
; template <class Epi, class Sched, bool STAMP = false>
; __device__ __forceinline__ void gemm_phase(PG8_LAS unsigned char* lds, const Gemm g, const Sched& S, const Epi& E, unsigned long long* stamps) {
;     ...
;         for (int t = 0; t < nt; t += 2) {
;             const bool last = (t == nt - 2);
;             const char* a1 = cA + (size_t)(t + 1) * kstep;
;             const char* a2 = last ? nA : cA + (size_t)(t + 2) * kstep; const char* b2 = last ? nB : cB + (size_t)(t + 2) * kstep;
;             const char* a3 = a2 + kstep; const char* b3 = b2 + kstep;
;             if (last && has_next) S.a_ready(nxt);
;             PG8_LDB(B0, 0, 0); PG8_SCHED; PG8_LDA(At, 0, 0); PG8_STAGE(PG8_SA(1, 1), a1 + hstep, voffA);
;             PG8_WAIT_L(8); PG8_BAR; PG8_WAIT_L(0); PG8_MMA(0, 0, At, B0); PG8_BAR; PG8_SCHED;
;             PG8_LDB(B1, 0, 1); PG8_STAGE(PG8_SB(0, 0), b2, voffB);
;             PG8_BAR; PG8_WAIT_L(0); PG8_MMA(0, 1, At, B1); PG8_BAR;
;             PG8_LDA(At, 0, 1); PG8_STAGE(PG8_SA(0, 0), a2, voffA);
;             PG8_BAR; PG8_WAIT_L(0); PG8_MMA(1, 0, At, B0); PG8_BAR; PG8_SCHED;
;             PG8_STAGE(PG8_SB(0, 1), b2 + hstep, voffB);
;             PG8_WAIT_V(6); PG8_BAR; PG8_MMA(1, 1, At, B1); PG8_BAR;
;             PG8_LDB(B0, 1, 0); PG8_SCHED; PG8_LDA(At, 1, 0); PG8_STAGE(PG8_SA(0, 1), a2 + hstep, voffA);
;             PG8_WAIT_L(8); PG8_BAR; PG8_WAIT_L(0); PG8_MMA(0, 0, At, B0); PG8_BAR; PG8_SCHED;
;             PG8_LDB(B1, 1, 1); PG8_STAGE(PG8_SB(1, 0), b3, voffB);
;             PG8_BAR; PG8_WAIT_L(0); PG8_MMA(0, 1, At, B1); PG8_BAR;
;             PG8_LDA(At, 1, 1); PG8_STAGE(PG8_SA(1, 0), a3, voffA);
;             PG8_BAR; PG8_WAIT_L(0); PG8_MMA(1, 0, At, B0); PG8_BAR; PG8_SCHED;
;             PG8_STAGE(PG8_SB(1, 1), b3 + hstep, voffB);
;             PG8_WAIT_V(6); PG8_BAR; PG8_MMA(1, 1, At, B1); PG8_BAR;
;         }
.LBB0_312:
	s_add_u32 s100, s94, 0x43f80
	s_addc_u32 s101, s95, 0
	s_mov_b32 m0, s78
	s_nop 0
	global_load_lds_dwordx4 v130, s[100:101]
	s_mov_b32 m0, s79
	s_nop 0
	global_load_lds_dwordx4 v134, s[100:101]
	ds_read_b128 v[170:173], v147
	ds_read_b128 v[174:177], v148
	ds_read_b128 v[178:181], v149
	ds_read_b128 v[182:185], v150
	s_add_u32 s58, s56, 0x100
	s_addc_u32 s59, s57, 0
	s_cmp_eq_u32 s96, 12
	s_cselect_b32 s63, s5, s59
	s_cselect_b32 s62, s4, s58
	s_cselect_b32 s61, s1, s95
	s_cselect_b32 s60, s0, s94
	s_mov_b32 m0, s84
	ds_read_b128 v[186:189], v145
	ds_read_b128 v[190:193], v145 offset:1024
	ds_read_b128 v[194:197], v145 offset:2048
	ds_read_b128 v[198:201], v145 offset:3072
	ds_read_b128 v[202:205], v145 offset:4096
	ds_read_b128 v[206:209], v145 offset:5120
	ds_read_b128 v[210:213], v145 offset:6144
	ds_read_b128 v[214:217], v145 offset:7168
	global_load_lds_dwordx4 v136, s[56:57]
	s_mov_b32 m0, s85
	s_nop 0
	global_load_lds_dwordx4 v138, s[56:57]
	ds_read_b128 v[218:221], v151
	ds_read_b128 v[222:225], v152
	ds_read_b128 v[226:229], v153
	ds_read_b128 v[230:233], v154
	s_waitcnt vmcnt(8)
	s_waitcnt lgkmcnt(0)
	s_barrier
	s_setprio 1
	v_mfma_f32_16x16x32_bf16 v[124:127], v[170:173], v[186:189], v[124:127]
	v_mfma_f32_16x16x32_bf16 v[120:123], v[178:181], v[186:189], v[120:123]
	v_mfma_f32_16x16x32_bf16 v[116:119], v[170:173], v[194:197], v[116:119]
	v_mfma_f32_16x16x32_bf16 v[112:115], v[178:181], v[194:197], v[112:115]
	v_mfma_f32_16x16x32_bf16 v[100:103], v[170:173], v[202:205], v[100:103]
	v_mfma_f32_16x16x32_bf16 v[96:99], v[178:181], v[202:205], v[96:99]
	v_mfma_f32_16x16x32_bf16 v[84:87], v[170:173], v[210:213], v[84:87]
	v_mfma_f32_16x16x32_bf16 v[80:83], v[178:181], v[210:213], v[80:83]
	v_mfma_f32_16x16x32_bf16 v[124:127], v[174:177], v[190:193], v[124:127]
	v_mfma_f32_16x16x32_bf16 v[120:123], v[182:185], v[190:193], v[120:123]
	v_mfma_f32_16x16x32_bf16 v[116:119], v[174:177], v[198:201], v[116:119]
	v_mfma_f32_16x16x32_bf16 v[112:115], v[182:185], v[198:201], v[112:115]
	v_mfma_f32_16x16x32_bf16 v[100:103], v[174:177], v[206:209], v[100:103]
	v_mfma_f32_16x16x32_bf16 v[96:99], v[182:185], v[206:209], v[96:99]
	v_mfma_f32_16x16x32_bf16 v[84:87], v[174:177], v[214:217], v[84:87]
	v_mfma_f32_16x16x32_bf16 v[80:83], v[182:185], v[214:217], v[80:83]
	v_mfma_f32_16x16x32_bf16 v[108:111], v[218:221], v[186:189], v[108:111]
	v_mfma_f32_16x16x32_bf16 v[104:107], v[226:229], v[186:189], v[104:107]
	v_mfma_f32_16x16x32_bf16 v[92:95], v[218:221], v[194:197], v[92:95]
	v_mfma_f32_16x16x32_bf16 v[88:91], v[226:229], v[194:197], v[88:91]
	v_mfma_f32_16x16x32_bf16 v[76:79], v[218:221], v[202:205], v[76:79]
	v_mfma_f32_16x16x32_bf16 v[72:75], v[226:229], v[202:205], v[72:75]
	v_mfma_f32_16x16x32_bf16 v[68:71], v[218:221], v[210:213], v[68:71]
	v_mfma_f32_16x16x32_bf16 v[64:67], v[226:229], v[210:213], v[64:67]
	v_mfma_f32_16x16x32_bf16 v[108:111], v[222:225], v[190:193], v[108:111]
	v_mfma_f32_16x16x32_bf16 v[104:107], v[230:233], v[190:193], v[104:107]
	v_mfma_f32_16x16x32_bf16 v[92:95], v[222:225], v[198:201], v[92:95]
	v_mfma_f32_16x16x32_bf16 v[88:91], v[230:233], v[198:201], v[88:91]
	v_mfma_f32_16x16x32_bf16 v[76:79], v[222:225], v[206:209], v[76:79]
	v_mfma_f32_16x16x32_bf16 v[72:75], v[230:233], v[206:209], v[72:75]
	v_mfma_f32_16x16x32_bf16 v[68:71], v[222:225], v[214:217], v[68:71]
	v_mfma_f32_16x16x32_bf16 v[64:67], v[230:233], v[214:217], v[64:67]
	s_setprio 0
	s_barrier
	s_mov_b32 m0, s67
	s_nop 0
	global_load_lds_dwordx4 v130, s[60:61]
	s_mov_b32 m0, s68
	s_nop 0
	global_load_lds_dwordx4 v134, s[60:61]
	s_mov_b32 m0, s66
	ds_read_b128 v[186:189], v145 offset:16384
	ds_read_b128 v[190:193], v145 offset:17408
	ds_read_b128 v[194:197], v145 offset:18432
	ds_read_b128 v[198:201], v145 offset:19456
	ds_read_b128 v[202:205], v145 offset:20480
	ds_read_b128 v[206:209], v145 offset:21504
	ds_read_b128 v[210:213], v145 offset:22528
	ds_read_b128 v[214:217], v145 offset:23552
	global_load_lds_dwordx4 v128, s[62:63]
	s_mov_b32 m0, s69
	s_nop 0
	global_load_lds_dwordx4 v132, s[62:63]
	s_waitcnt vmcnt(6)
	s_waitcnt lgkmcnt(0)
	s_barrier
	s_setprio 1
	v_mfma_f32_16x16x32_bf16 v[60:63], v[170:173], v[186:189], v[60:63]
	v_mfma_f32_16x16x32_bf16 v[56:59], v[178:181], v[186:189], v[56:59]
	v_mfma_f32_16x16x32_bf16 v[52:55], v[170:173], v[194:197], v[52:55]
	v_mfma_f32_16x16x32_bf16 v[48:51], v[178:181], v[194:197], v[48:51]
	v_mfma_f32_16x16x32_bf16 v[36:39], v[170:173], v[202:205], v[36:39]
	v_mfma_f32_16x16x32_bf16 v[32:35], v[178:181], v[202:205], v[32:35]
	v_mfma_f32_16x16x32_bf16 v[20:23], v[170:173], v[210:213], v[20:23]
	v_mfma_f32_16x16x32_bf16 v[16:19], v[178:181], v[210:213], v[16:19]
	v_mfma_f32_16x16x32_bf16 v[60:63], v[174:177], v[190:193], v[60:63]
	v_mfma_f32_16x16x32_bf16 v[56:59], v[182:185], v[190:193], v[56:59]
	v_mfma_f32_16x16x32_bf16 v[52:55], v[174:177], v[198:201], v[52:55]
	v_mfma_f32_16x16x32_bf16 v[48:51], v[182:185], v[198:201], v[48:51]
	v_mfma_f32_16x16x32_bf16 v[36:39], v[174:177], v[206:209], v[36:39]
	v_mfma_f32_16x16x32_bf16 v[32:35], v[182:185], v[206:209], v[32:35]
	v_mfma_f32_16x16x32_bf16 v[20:23], v[174:177], v[214:217], v[20:23]
	v_mfma_f32_16x16x32_bf16 v[16:19], v[182:185], v[214:217], v[16:19]
	v_mfma_f32_16x16x32_bf16 v[44:47], v[218:221], v[186:189], v[44:47]
	v_mfma_f32_16x16x32_bf16 v[40:43], v[226:229], v[186:189], v[40:43]
	v_mfma_f32_16x16x32_bf16 v[28:31], v[218:221], v[194:197], v[28:31]
	v_mfma_f32_16x16x32_bf16 v[24:27], v[226:229], v[194:197], v[24:27]
	v_mfma_f32_16x16x32_bf16 v[12:15], v[218:221], v[202:205], v[12:15]
	v_mfma_f32_16x16x32_bf16 v[8:11], v[226:229], v[202:205], v[8:11]
	v_mfma_f32_16x16x32_bf16 v[4:7], v[218:221], v[210:213], v[4:7]
	v_mfma_f32_16x16x32_bf16 v[0:3], v[226:229], v[210:213], v[0:3]
	v_mfma_f32_16x16x32_bf16 v[44:47], v[222:225], v[190:193], v[44:47]
	v_mfma_f32_16x16x32_bf16 v[40:43], v[230:233], v[190:193], v[40:43]
	v_mfma_f32_16x16x32_bf16 v[28:31], v[222:225], v[198:201], v[28:31]
	v_mfma_f32_16x16x32_bf16 v[24:27], v[230:233], v[198:201], v[24:27]
	v_mfma_f32_16x16x32_bf16 v[12:15], v[222:225], v[206:209], v[12:15]
	v_mfma_f32_16x16x32_bf16 v[8:11], v[230:233], v[206:209], v[8:11]
	v_mfma_f32_16x16x32_bf16 v[4:7], v[222:225], v[214:217], v[4:7]
	v_mfma_f32_16x16x32_bf16 v[0:3], v[230:233], v[214:217], v[0:3]
	s_setprio 0
	s_barrier
; #define PG8_STAGE(bufoff, gbase, voff) do { _Pragma("unroll") for (int _i = 0; _i < 2; ++_i) \
;         __builtin_amdgcn_global_load_lds((const unsigned*)((const char*)(gbase) + (voff)[_i]), (PG8_LAS unsigned*)(lds + (bufoff) + ldsw + _i * 8192), 16, 0, 0); } while (0)
; #define PG8_LDA(dst, b, h) do { _Pragma("unroll") for (int m = 0; m < 4; ++m) _Pragma("unroll") for (int k = 0; k < 2; ++k) dst[m][k] = *(const PG8_LAS bf16x8*)(lds + PG8_SA(b, h) + aoff + m * 2048 + k * 1024); } while (0)
; #define PG8_LDB(dst, b, h) do { _Pragma("unroll") for (int n = 0; n < 2; ++n) _Pragma("unroll") for (int k = 0; k < 2; ++k) dst[n][k] = *(const PG8_LAS bf16x8*)(lds + PG8_SB(b, h) + boff + n * 2048 + k * 1024); } while (0)
; #define PG8_MMA(ai, bj, At, Bt) do { __builtin_amdgcn_s_setprio(1); _Pragma("unroll") for (int m = 0; m < 4; ++m) _Pragma("unroll") for (int n = 0; n < 2; ++n) _Pragma("unroll") for (int k = 0; k < 2; ++k) \
;         acc[ai][bj][m][n] = __builtin_amdgcn_mfma_f32_16x16x32_bf16(Bt[n][k], At[m][k], acc[ai][bj][m][n], 0, 0, 0); __builtin_amdgcn_s_setprio(0); } while (0)
; #define PG8_WAIT_V(n) asm volatile("s_waitcnt vmcnt(" #n ")" ::: "memory")
; #define PG8_WAIT_L(n) asm volatile("s_waitcnt lgkmcnt(" #n ")" ::: "memory")
; #define PG8_BAR __builtin_amdgcn_s_barrier()
; #define PG8_SCHED __builtin_amdgcn_sched_barrier(0)
; template <class Epi, class Sched, bool STAMP = false>
; __device__ __forceinline__ void gemm_phase(PG8_LAS unsigned char* lds, const Gemm g, const Sched& S, const Epi& E, unsigned long long* stamps) {
;     ...
;             PG8_WAIT_V(6); PG8_BAR; PG8_MMA(1, 1, At, B1); PG8_BAR;
;             PG8_LDB(B0, 1, 0); PG8_SCHED; PG8_LDA(At, 1, 0); PG8_STAGE(PG8_SA(0, 1), a2 + hstep, voffA);
;             PG8_WAIT_L(8); PG8_BAR; PG8_WAIT_L(0); PG8_MMA(0, 0, At, B0); PG8_BAR; PG8_SCHED;
;             PG8_LDB(B1, 1, 1); PG8_STAGE(PG8_SB(1, 0), b3, voffB);
;             PG8_BAR; PG8_WAIT_L(0); PG8_MMA(0, 1, At, B1); PG8_BAR;
;             PG8_LDA(At, 1, 1); PG8_STAGE(PG8_SA(1, 0), a3, voffA);
;             PG8_BAR; PG8_WAIT_L(0); PG8_MMA(1, 0, At, B0); PG8_BAR; PG8_SCHED;
;             PG8_STAGE(PG8_SB(1, 1), b3 + hstep, voffB);
;             PG8_WAIT_V(6); PG8_BAR; PG8_MMA(1, 1, At, B1); PG8_BAR;
;         }
.Lzp4_mid:
	s_add_u32 s56, s60, 0x44000
	s_addc_u32 s57, s61, 0
	s_mov_b32 m0, s70
	s_nop 0
	global_load_lds_dwordx4 v130, s[56:57]
	s_mov_b32 m0, s71
	s_nop 0
	global_load_lds_dwordx4 v134, s[56:57]
	ds_read_b128 v[170:173], v155
	ds_read_b128 v[174:177], v156
	ds_read_b128 v[178:181], v157
	ds_read_b128 v[182:185], v165
	s_add_u32 s56, s62, 0x44000
	s_addc_u32 s57, s63, 0
	s_mov_b32 m0, s72
	ds_read_b128 v[186:189], v145 offset:32768
	ds_read_b128 v[190:193], v145 offset:33792
	ds_read_b128 v[194:197], v145 offset:34816
	ds_read_b128 v[198:201], v145 offset:35840
	ds_read_b128 v[202:205], v145 offset:36864
	ds_read_b128 v[206:209], v145 offset:37888
	ds_read_b128 v[210:213], v145 offset:38912
	ds_read_b128 v[214:217], v145 offset:39936
	global_load_lds_dwordx4 v128, s[56:57]
	s_mov_b32 m0, s73
	s_nop 0
	global_load_lds_dwordx4 v132, s[56:57]
	ds_read_b128 v[218:221], v166
	ds_read_b128 v[222:225], v167
	ds_read_b128 v[226:229], v168
	ds_read_b128 v[230:233], v169
	s_waitcnt vmcnt(8)
	s_waitcnt lgkmcnt(0)
	s_barrier
	s_setprio 1
	v_mfma_f32_16x16x32_bf16 v[124:127], v[170:173], v[186:189], v[124:127]
	v_mfma_f32_16x16x32_bf16 v[120:123], v[178:181], v[186:189], v[120:123]
	v_mfma_f32_16x16x32_bf16 v[116:119], v[170:173], v[194:197], v[116:119]
	v_mfma_f32_16x16x32_bf16 v[112:115], v[178:181], v[194:197], v[112:115]
	v_mfma_f32_16x16x32_bf16 v[100:103], v[170:173], v[202:205], v[100:103]
	v_mfma_f32_16x16x32_bf16 v[96:99], v[178:181], v[202:205], v[96:99]
	v_mfma_f32_16x16x32_bf16 v[84:87], v[170:173], v[210:213], v[84:87]
	v_mfma_f32_16x16x32_bf16 v[80:83], v[178:181], v[210:213], v[80:83]
	v_mfma_f32_16x16x32_bf16 v[124:127], v[174:177], v[190:193], v[124:127]
	v_mfma_f32_16x16x32_bf16 v[120:123], v[182:185], v[190:193], v[120:123]
	v_mfma_f32_16x16x32_bf16 v[116:119], v[174:177], v[198:201], v[116:119]
	v_mfma_f32_16x16x32_bf16 v[112:115], v[182:185], v[198:201], v[112:115]
	v_mfma_f32_16x16x32_bf16 v[100:103], v[174:177], v[206:209], v[100:103]
	v_mfma_f32_16x16x32_bf16 v[96:99], v[182:185], v[206:209], v[96:99]
	v_mfma_f32_16x16x32_bf16 v[84:87], v[174:177], v[214:217], v[84:87]
	v_mfma_f32_16x16x32_bf16 v[80:83], v[182:185], v[214:217], v[80:83]
	v_mfma_f32_16x16x32_bf16 v[108:111], v[218:221], v[186:189], v[108:111]
	v_mfma_f32_16x16x32_bf16 v[104:107], v[226:229], v[186:189], v[104:107]
	v_mfma_f32_16x16x32_bf16 v[92:95], v[218:221], v[194:197], v[92:95]
	v_mfma_f32_16x16x32_bf16 v[88:91], v[226:229], v[194:197], v[88:91]
	v_mfma_f32_16x16x32_bf16 v[76:79], v[218:221], v[202:205], v[76:79]
	v_mfma_f32_16x16x32_bf16 v[72:75], v[226:229], v[202:205], v[72:75]
	v_mfma_f32_16x16x32_bf16 v[68:71], v[218:221], v[210:213], v[68:71]
	v_mfma_f32_16x16x32_bf16 v[64:67], v[226:229], v[210:213], v[64:67]
	v_mfma_f32_16x16x32_bf16 v[108:111], v[222:225], v[190:193], v[108:111]
	v_mfma_f32_16x16x32_bf16 v[104:107], v[230:233], v[190:193], v[104:107]
	v_mfma_f32_16x16x32_bf16 v[92:95], v[222:225], v[198:201], v[92:95]
	v_mfma_f32_16x16x32_bf16 v[88:91], v[230:233], v[198:201], v[88:91]
	v_mfma_f32_16x16x32_bf16 v[76:79], v[222:225], v[206:209], v[76:79]
	v_mfma_f32_16x16x32_bf16 v[72:75], v[230:233], v[206:209], v[72:75]
	v_mfma_f32_16x16x32_bf16 v[68:71], v[222:225], v[214:217], v[68:71]
	v_mfma_f32_16x16x32_bf16 v[64:67], v[230:233], v[214:217], v[64:67]
	s_setprio 0
	s_barrier
	s_mov_b32 m0, s74
	s_add_u32 s100, s60, 0x80
	s_addc_u32 s101, s61, 0
	global_load_lds_dwordx4 v130, s[100:101]
	s_mov_b32 m0, s75
	s_nop 0
	global_load_lds_dwordx4 v134, s[100:101]
	s_mov_b32 m0, s76
	ds_read_b128 v[186:189], v145 offset:49152
	ds_read_b128 v[190:193], v145 offset:50176
	ds_read_b128 v[194:197], v145 offset:51200
	ds_read_b128 v[198:201], v145 offset:52224
	ds_read_b128 v[202:205], v145 offset:53248
	ds_read_b128 v[206:209], v145 offset:54272
	ds_read_b128 v[210:213], v145 offset:55296
	ds_read_b128 v[214:217], v145 offset:56320
	s_add_u32 s100, s62, 0x80
	s_addc_u32 s101, s63, 0
	global_load_lds_dwordx4 v128, s[100:101]
	s_mov_b32 m0, s77
	s_nop 0
	global_load_lds_dwordx4 v132, s[100:101]
	s_waitcnt vmcnt(6)
	s_waitcnt lgkmcnt(0)
	s_barrier
	s_setprio 1
	v_mfma_f32_16x16x32_bf16 v[60:63], v[170:173], v[186:189], v[60:63]
	v_mfma_f32_16x16x32_bf16 v[56:59], v[178:181], v[186:189], v[56:59]
	v_mfma_f32_16x16x32_bf16 v[52:55], v[170:173], v[194:197], v[52:55]
	v_mfma_f32_16x16x32_bf16 v[48:51], v[178:181], v[194:197], v[48:51]
	v_mfma_f32_16x16x32_bf16 v[36:39], v[170:173], v[202:205], v[36:39]
	v_mfma_f32_16x16x32_bf16 v[32:35], v[178:181], v[202:205], v[32:35]
	v_mfma_f32_16x16x32_bf16 v[20:23], v[170:173], v[210:213], v[20:23]
	v_mfma_f32_16x16x32_bf16 v[16:19], v[178:181], v[210:213], v[16:19]
	v_mfma_f32_16x16x32_bf16 v[60:63], v[174:177], v[190:193], v[60:63]
	v_mfma_f32_16x16x32_bf16 v[56:59], v[182:185], v[190:193], v[56:59]
	v_mfma_f32_16x16x32_bf16 v[52:55], v[174:177], v[198:201], v[52:55]
	v_mfma_f32_16x16x32_bf16 v[48:51], v[182:185], v[198:201], v[48:51]
	v_mfma_f32_16x16x32_bf16 v[36:39], v[174:177], v[206:209], v[36:39]
	v_mfma_f32_16x16x32_bf16 v[32:35], v[182:185], v[206:209], v[32:35]
	v_mfma_f32_16x16x32_bf16 v[20:23], v[174:177], v[214:217], v[20:23]
	v_mfma_f32_16x16x32_bf16 v[16:19], v[182:185], v[214:217], v[16:19]
	v_mfma_f32_16x16x32_bf16 v[44:47], v[218:221], v[186:189], v[44:47]
	v_mfma_f32_16x16x32_bf16 v[40:43], v[226:229], v[186:189], v[40:43]
	v_mfma_f32_16x16x32_bf16 v[28:31], v[218:221], v[194:197], v[28:31]
	v_mfma_f32_16x16x32_bf16 v[24:27], v[226:229], v[194:197], v[24:27]
	v_mfma_f32_16x16x32_bf16 v[12:15], v[218:221], v[202:205], v[12:15]
	v_mfma_f32_16x16x32_bf16 v[8:11], v[226:229], v[202:205], v[8:11]
	v_mfma_f32_16x16x32_bf16 v[4:7], v[218:221], v[210:213], v[4:7]
	v_mfma_f32_16x16x32_bf16 v[0:3], v[226:229], v[210:213], v[0:3]
	v_mfma_f32_16x16x32_bf16 v[44:47], v[222:225], v[190:193], v[44:47]
	v_mfma_f32_16x16x32_bf16 v[40:43], v[230:233], v[190:193], v[40:43]
	v_mfma_f32_16x16x32_bf16 v[28:31], v[222:225], v[198:201], v[28:31]
	v_mfma_f32_16x16x32_bf16 v[24:27], v[230:233], v[198:201], v[24:27]
	v_mfma_f32_16x16x32_bf16 v[12:15], v[222:225], v[206:209], v[12:15]
	v_mfma_f32_16x16x32_bf16 v[8:11], v[230:233], v[206:209], v[8:11]
	v_mfma_f32_16x16x32_bf16 v[4:7], v[222:225], v[214:217], v[4:7]
	v_mfma_f32_16x16x32_bf16 v[0:3], v[230:233], v[214:217], v[0:3]
	s_setprio 0
	s_add_i32 s96, s96, 2
	s_add_u32 s94, s94, 0x100
	s_addc_u32 s95, s95, 0
	s_cmp_gt_u32 s96, 13
	s_mov_b64 s[56:57], s[58:59]
	s_barrier
; #define PG8_STAMP() do { if (STAMP && wid == 0 && nts < 64) { const unsigned long long _c = 0ull; \
;         ts_lo = (lane == nts) ? (int)(unsigned)_c : ts_lo; ts_hi = (lane == nts) ? (int)(unsigned)(_c >> 32) : ts_hi; ++nts; } } while (0)
; #define PG8_WAIT_V(n) asm volatile("s_waitcnt vmcnt(" #n ")" ::: "memory")
; #define PG8_BAR __builtin_amdgcn_s_barrier()
;     DI void operator()(const f32x4 (&acc)[2][2][4][2], const Unit& u, int wr, int wc, int fr, int fq) const {
;         const int row0 = u.pm * BM + wr * 64 + fr, col0 = u.pn * BM + wc * 32 + 8 * fq;
; #pragma unroll
;         for (int ai = 0; ai < 2; ++ai)
; #pragma unroll
;             for (int m = 0; m < 4; ++m) { u16* rowp = O + (size_t)(row0 + ai * HALF + m * 16) * ldc + col0;
; #pragma unroll
;                 for (int bj = 0; bj < 2; ++bj) { const f32x4 v0 = acc[ai][bj][m][0], v1 = acc[ai][bj][m][1];
;                     uint4 w = {pack2(v0[0], v0[1]), pack2(v0[2], v0[3]), pack2(v1[0], v1[1]), pack2(v1[2], v1[3])}; *(uint4*)(rowp + bj * HALF) = w; } }
; template <class Epi, class Sched, bool STAMP = false>
; __device__ __forceinline__ void gemm_phase(PG8_LAS unsigned char* lds, const Gemm g, const Sched& S, const Epi& E, unsigned long long* stamps) {
;     ...
;         if constexpr (!Epi::AFTER_DRAIN) { E(acc, cur, wr, wc, fr, fq); S.done(cur); }
;         PG8_STAMP();
;         if (!has_next) break;
; #pragma unroll
;         for (int a = 0; a < 2; ++a)
; #pragma unroll
;             for (int b = 0; b < 2; ++b)
; #pragma unroll
;                 for (int m = 0; m < 4; ++m)
; #pragma unroll
;                     for (int n = 0; n < 2; ++n) acc[a][b][m][n] = (f32x4){0.f, 0.f, 0.f, 0.f};
;         cur = nxt; cA = nA; cB = nB; ++ui;
;     }
;     PG8_WAIT_V(0);
;     if (wr == 0) PG8_BAR;
;     PG8_BAR;
	s_cbranch_scc0 .LBB0_312
	v_lshl_add_u32 v170, s90, 8, v144
	v_lshl_or_b32 v172, s93, 8, v146
	v_ashrrev_i32_e32 v171, 31, v170
	v_ashrrev_i32_e32 v173, 31, v172
	v_lshlrev_b64 v[174:175], 11, v[170:171]
	v_lshl_add_u64 v[174:175], s[14:15], 0, v[174:175]
	v_lshlrev_b64 v[172:173], 1, v[172:173]
	v_lshl_add_u64 v[174:175], v[174:175], 0, v[172:173]
	v_cvt_pk_bf16_f32 v60, v60, v61
	v_cvt_pk_bf16_f32 v61, v62, v63
	v_cvt_pk_bf16_f32 v62, v56, v57
	v_add_co_u32_e32 v56, vcc, s86, v174
	v_cvt_pk_bf16_f32 v68, v68, v69
	v_cvt_pk_bf16_f32 v69, v70, v71
	v_cvt_pk_bf16_f32 v70, v64, v65
	v_lshl_add_u64 v[64:65], v[174:175], 0, s[34:35]
	v_addc_co_u32_e32 v57, vcc, 0, v175, vcc
	v_cvt_pk_bf16_f32 v44, v44, v45
	v_cvt_pk_bf16_f32 v45, v46, v47
	v_cvt_pk_bf16_f32 v46, v40, v41
	v_cvt_pk_bf16_f32 v47, v42, v43
	v_cvt_pk_bf16_f32 v108, v108, v109
	v_cvt_pk_bf16_f32 v109, v110, v111
	v_cvt_pk_bf16_f32 v110, v104, v105
	v_or_b32_e32 v104, 16, v170
	global_store_dwordx4 v[64:65], v[44:47], off offset:256
	v_ashrrev_i32_e32 v105, 31, v104
	v_cvt_pk_bf16_f32 v92, v92, v93
	v_add_co_u32_e32 v46, vcc, s87, v174
	v_cvt_pk_bf16_f32 v93, v94, v95
	v_cvt_pk_bf16_f32 v94, v88, v89
	v_or_b32_e32 v88, 32, v170
	v_lshl_add_u64 v[44:45], v[174:175], 0, s[36:37]
	v_addc_co_u32_e32 v47, vcc, 0, v175, vcc
	v_cvt_pk_bf16_f32 v28, v28, v29
	v_cvt_pk_bf16_f32 v29, v30, v31
	v_cvt_pk_bf16_f32 v30, v24, v25
	v_cvt_pk_bf16_f32 v31, v26, v27
	v_lshlrev_b64 v[104:105], 11, v[104:105]
	v_ashrrev_i32_e32 v89, 31, v88
	v_cvt_pk_bf16_f32 v76, v76, v77
	v_cvt_pk_bf16_f32 v77, v78, v79
	v_cvt_pk_bf16_f32 v78, v72, v73
	v_or_b32_e32 v72, 48, v170
	global_store_dwordx4 v[44:45], v[28:31], off offset:256
	v_cvt_pk_bf16_f32 v111, v106, v107
	v_lshl_add_u64 v[104:105], s[14:15], 0, v[104:105]
	v_add_co_u32_e32 v30, vcc, s88, v174
	v_lshlrev_b64 v[88:89], 11, v[88:89]
	v_ashrrev_i32_e32 v73, 31, v72
	v_lshl_add_u64 v[28:29], v[174:175], 0, s[52:53]
	v_addc_co_u32_e32 v31, vcc, 0, v175, vcc
	v_cvt_pk_bf16_f32 v12, v12, v13
	v_cvt_pk_bf16_f32 v13, v14, v15
	v_cvt_pk_bf16_f32 v14, v8, v9
	v_cvt_pk_bf16_f32 v15, v10, v11
	global_store_dwordx4 v[174:175], v[108:111], off offset:256
	v_cvt_pk_bf16_f32 v95, v90, v91
	v_lshl_add_u64 v[88:89], s[14:15], 0, v[88:89]
	v_lshl_add_u64 v[108:109], v[104:105], 0, v[172:173]
	v_lshlrev_b64 v[72:73], 11, v[72:73]
	global_store_dwordx4 v[28:29], v[12:15], off offset:256
	global_store_dwordx4 v[108:109], v[92:95], off offset:256
	v_cvt_pk_bf16_f32 v79, v74, v75
	v_add_co_u32_e32 v14, vcc, s89, v174
	v_lshl_add_u64 v[92:93], v[88:89], 0, v[172:173]
	v_lshl_add_u64 v[72:73], s[14:15], 0, v[72:73]
	v_addc_co_u32_e32 v15, vcc, 0, v175, vcc
	v_cvt_pk_bf16_f32 v124, v124, v125
	v_cvt_pk_bf16_f32 v125, v126, v127
	v_cvt_pk_bf16_f32 v126, v120, v121
	v_cvt_pk_bf16_f32 v127, v122, v123
	v_cvt_pk_bf16_f32 v104, v116, v117
	v_cvt_pk_bf16_f32 v105, v118, v119
	v_cvt_pk_bf16_f32 v106, v112, v113
	v_cvt_pk_bf16_f32 v107, v114, v115
	v_cvt_pk_bf16_f32 v88, v100, v101
	v_cvt_pk_bf16_f32 v89, v102, v103
	v_cvt_pk_bf16_f32 v90, v96, v97
	v_cvt_pk_bf16_f32 v91, v98, v99
	global_store_dwordx4 v[92:93], v[76:79], off offset:256
	v_cvt_pk_bf16_f32 v74, v80, v81
	v_cvt_pk_bf16_f32 v75, v82, v83
	v_lshl_add_u64 v[76:77], v[72:73], 0, v[172:173]
	v_cvt_pk_bf16_f32 v72, v84, v85
	v_cvt_pk_bf16_f32 v73, v86, v87
	v_cvt_pk_bf16_f32 v71, v66, v67
	v_cvt_pk_bf16_f32 v63, v58, v59
	v_cvt_pk_bf16_f32 v40, v52, v53
	v_cvt_pk_bf16_f32 v41, v54, v55
	v_cvt_pk_bf16_f32 v42, v48, v49
	v_cvt_pk_bf16_f32 v43, v50, v51
	v_cvt_pk_bf16_f32 v24, v36, v37
	v_cvt_pk_bf16_f32 v25, v38, v39
	v_cvt_pk_bf16_f32 v26, v32, v33
	v_cvt_pk_bf16_f32 v27, v34, v35
	v_lshl_add_u64 v[12:13], v[174:175], 0, s[54:55]
	v_cvt_pk_bf16_f32 v8, v20, v21
	v_cvt_pk_bf16_f32 v9, v22, v23
	v_cvt_pk_bf16_f32 v10, v16, v17
	v_cvt_pk_bf16_f32 v11, v18, v19
	v_cvt_pk_bf16_f32 v4, v4, v5
	v_cvt_pk_bf16_f32 v5, v6, v7
	v_cvt_pk_bf16_f32 v6, v0, v1
	v_cvt_pk_bf16_f32 v7, v2, v3
	s_and_b64 vcc, exec, s[2:3]
	s_mov_b32 s93, s91
	s_mov_b32 s90, s92
	s_mov_b64 s[58:59], s[0:1]
	s_mov_b64 s[56:57], s[4:5]
	global_store_dwordx4 v[174:175], v[124:127], off
	global_store_dwordx4 v[108:109], v[104:107], off
	global_store_dwordx4 v[92:93], v[88:91], off
	global_store_dwordx4 v[76:77], v[72:75], off
	global_store_dwordx4 v[76:77], v[68:71], off offset:256
	global_store_dwordx4 v[56:57], v[60:63], off
	global_store_dwordx4 v[46:47], v[40:43], off
	global_store_dwordx4 v[30:31], v[24:27], off
	global_store_dwordx4 v[14:15], v[8:11], off
	global_store_dwordx4 v[12:13], v[4:7], off offset:256
	s_cbranch_vccz .LBB0_301
	s_waitcnt vmcnt(0)
	s_cmpk_gt_u32 s64, 0xff
	s_cbranch_scc1 .LBB0_316
	s_barrier

; #define PG8_STAGE(bufoff, gbase, voff) do { _Pragma("unroll") for (int _i = 0; _i < 2; ++_i) \
;         __builtin_amdgcn_global_load_lds((const unsigned*)((const char*)(gbase) + (voff)[_i]), (PG8_LAS unsigned*)(lds + (bufoff) + ldsw + _i * 8192), 16, 0, 0); } while (0)
; #define PG8_LDA(dst, b, h) do { _Pragma("unroll") for (int m = 0; m < 4; ++m) _Pragma("unroll") for (int k = 0; k < 2; ++k) dst[m][k] = *(const PG8_LAS bf16x8*)(lds + PG8_SA(b, h) + aoff + m * 2048 + k * 1024); } while (0)
; template <class Epi, class Sched, bool STAMP = false>
; __device__ __forceinline__ void gemm_phase(PG8_LAS unsigned char* lds, const Gemm g, const Sched& S, const Epi& E, unsigned long long* stamps) {
;     ...
;         for (int t = 0; t < nt; t += 2) {
;             const bool last = (t == nt - 2);
;             const char* a1 = cA + (size_t)(t + 1) * kstep;
;             const char* a2 = last ? nA : cA + (size_t)(t + 2) * kstep; const char* b2 = last ? nB : cB + (size_t)(t + 2) * kstep;
;             const char* a3 = a2 + kstep; const char* b3 = b2 + kstep;
;             if (last && has_next) S.a_ready(nxt);
;             PG8_LDB(B0, 0, 0); PG8_SCHED; PG8_LDA(At, 0, 0); PG8_STAGE(PG8_SA(1, 1), a1 + hstep, voffA);
;             PG8_WAIT_L(8); PG8_BAR; PG8_WAIT_L(0); PG8_MMA(0, 0, At, B0); PG8_BAR; PG8_SCHED;
;             PG8_LDB(B1, 0, 1); PG8_STAGE(PG8_SB(0, 0), b2, voffB);
;             PG8_BAR; PG8_WAIT_L(0); PG8_MMA(0, 1, At, B1); PG8_BAR;
;             PG8_LDA(At, 0, 1); PG8_STAGE(PG8_SA(0, 0), a2, voffA);
;             PG8_BAR; PG8_WAIT_L(0); PG8_MMA(1, 0, At, B0); PG8_BAR; PG8_SCHED;
;             PG8_STAGE(PG8_SB(0, 1), b2 + hstep, voffB);
;             PG8_WAIT_V(6); PG8_BAR; PG8_MMA(1, 1, At, B1); PG8_BAR;
;             PG8_LDB(B0, 1, 0); PG8_SCHED; PG8_LDA(At, 1, 0); PG8_STAGE(PG8_SA(0, 1), a2 + hstep, voffA);
;             PG8_WAIT_L(8); PG8_BAR; PG8_WAIT_L(0); PG8_MMA(0, 0, At, B0); PG8_BAR; PG8_SCHED;
;             PG8_LDB(B1, 1, 1); PG8_STAGE(PG8_SB(1, 0), b3, voffB);
;             PG8_BAR; PG8_WAIT_L(0); PG8_MMA(0, 1, At, B1); PG8_BAR;
;             PG8_LDA(At, 1, 1); PG8_STAGE(PG8_SA(1, 0), a3, voffA);
;             PG8_BAR; PG8_WAIT_L(0); PG8_MMA(1, 0, At, B0); PG8_BAR; PG8_SCHED;
;             PG8_STAGE(PG8_SB(1, 1), b3 + hstep, voffB);
;             PG8_WAIT_V(6); PG8_BAR; PG8_MMA(1, 1, At, B1); PG8_BAR;
;         }
.LBB0_350:
	s_add_u32 s87, s36, 0x100
	s_addc_u32 s88, s37, 0
	s_mov_b32 s89, -2
	s_cmp_eq_u32 s68, s99
	s_cbranch_scc1 .Lgu2_half_loop_z
	s_add_u32 s100, s87, 0x43f80
	s_addc_u32 s101, s88, 0
	s_mov_b32 m0, s75
	s_nop 0
	global_load_lds_dwordx4 v130, s[100:101]
	s_mov_b32 m0, s76
	s_nop 0
	global_load_lds_dwordx4 v128, s[100:101]
	ds_read_b128 v[140:143], v147
	ds_read_b128 v[170:173], v148
	ds_read_b128 v[174:177], v149
	ds_read_b128 v[178:181], v150
	s_add_u32 s36, s34, 0x100
	s_addc_u32 s37, s35, 0
	s_cmp_eq_u32 s89, 12
	s_cselect_b32 s55, s5, s37
	s_cselect_b32 s54, s4, s36
	s_cselect_b32 s53, s1, s88
	s_cselect_b32 s52, s0, s87
	s_mov_b32 m0, s78
	ds_read_b128 v[182:185], v145
	ds_read_b128 v[186:189], v145 offset:1024
	ds_read_b128 v[190:193], v145 offset:2048
	ds_read_b128 v[194:197], v145 offset:3072
	ds_read_b128 v[198:201], v145 offset:4096
	ds_read_b128 v[202:205], v145 offset:5120
	ds_read_b128 v[206:209], v145 offset:6144
	ds_read_b128 v[210:213], v145 offset:7168
	global_load_lds_dwordx4 v132, s[34:35]
	s_mov_b32 m0, s79
	s_nop 0
	global_load_lds_dwordx4 v134, s[34:35]
	ds_read_b128 v[214:217], v151
	ds_read_b128 v[218:221], v152
	ds_read_b128 v[222:225], v153
	ds_read_b128 v[226:229], v154
	s_waitcnt vmcnt(8)
	s_waitcnt lgkmcnt(0)
	s_barrier
	s_setprio 1
	v_mfma_f32_16x16x32_bf16 v[124:127], v[140:143], v[182:185], 0
	v_mfma_f32_16x16x32_bf16 v[120:123], v[174:177], v[182:185], 0
	v_mfma_f32_16x16x32_bf16 v[108:111], v[140:143], v[190:193], 0
	v_mfma_f32_16x16x32_bf16 v[104:107], v[174:177], v[190:193], 0
	v_mfma_f32_16x16x32_bf16 v[92:95], v[140:143], v[198:201], 0
	v_mfma_f32_16x16x32_bf16 v[88:91], v[174:177], v[198:201], 0
	v_mfma_f32_16x16x32_bf16 v[76:79], v[140:143], v[206:209], 0
	v_mfma_f32_16x16x32_bf16 v[72:75], v[174:177], v[206:209], 0
	v_mfma_f32_16x16x32_bf16 v[124:127], v[170:173], v[186:189], v[124:127]
	v_mfma_f32_16x16x32_bf16 v[120:123], v[178:181], v[186:189], v[120:123]
	v_mfma_f32_16x16x32_bf16 v[108:111], v[170:173], v[194:197], v[108:111]
	v_mfma_f32_16x16x32_bf16 v[104:107], v[178:181], v[194:197], v[104:107]
	v_mfma_f32_16x16x32_bf16 v[92:95], v[170:173], v[202:205], v[92:95]
	v_mfma_f32_16x16x32_bf16 v[88:91], v[178:181], v[202:205], v[88:91]
	v_mfma_f32_16x16x32_bf16 v[76:79], v[170:173], v[210:213], v[76:79]
	v_mfma_f32_16x16x32_bf16 v[72:75], v[178:181], v[210:213], v[72:75]
	v_mfma_f32_16x16x32_bf16 v[116:119], v[214:217], v[182:185], 0
	v_mfma_f32_16x16x32_bf16 v[112:115], v[222:225], v[182:185], 0
	v_mfma_f32_16x16x32_bf16 v[100:103], v[214:217], v[190:193], 0
	v_mfma_f32_16x16x32_bf16 v[96:99], v[222:225], v[190:193], 0
	v_mfma_f32_16x16x32_bf16 v[84:87], v[214:217], v[198:201], 0
	v_mfma_f32_16x16x32_bf16 v[80:83], v[222:225], v[198:201], 0
	v_mfma_f32_16x16x32_bf16 v[68:71], v[214:217], v[206:209], 0
	v_mfma_f32_16x16x32_bf16 v[64:67], v[222:225], v[206:209], 0
	v_mfma_f32_16x16x32_bf16 v[116:119], v[218:221], v[186:189], v[116:119]
	v_mfma_f32_16x16x32_bf16 v[112:115], v[226:229], v[186:189], v[112:115]
	v_mfma_f32_16x16x32_bf16 v[100:103], v[218:221], v[194:197], v[100:103]
	v_mfma_f32_16x16x32_bf16 v[96:99], v[226:229], v[194:197], v[96:99]
	v_mfma_f32_16x16x32_bf16 v[84:87], v[218:221], v[202:205], v[84:87]
	v_mfma_f32_16x16x32_bf16 v[80:83], v[226:229], v[202:205], v[80:83]
	v_mfma_f32_16x16x32_bf16 v[68:71], v[218:221], v[210:213], v[68:71]
	v_mfma_f32_16x16x32_bf16 v[64:67], v[226:229], v[210:213], v[64:67]
	s_setprio 0
	s_barrier
	s_mov_b32 m0, s61
	s_nop 0
	global_load_lds_dwordx4 v130, s[52:53]
	s_mov_b32 m0, s62
	s_nop 0
	global_load_lds_dwordx4 v128, s[52:53]
	s_mov_b32 m0, s58
	ds_read_b128 v[182:185], v145 offset:16384
	ds_read_b128 v[186:189], v145 offset:17408
	ds_read_b128 v[190:193], v145 offset:18432
	ds_read_b128 v[194:197], v145 offset:19456
	ds_read_b128 v[198:201], v145 offset:20480
	ds_read_b128 v[202:205], v145 offset:21504
	ds_read_b128 v[206:209], v145 offset:22528
	ds_read_b128 v[210:213], v145 offset:23552
	global_load_lds_dwordx4 v130, s[54:55]
	s_mov_b32 m0, s63
	s_nop 0
	global_load_lds_dwordx4 v128, s[54:55]
	s_waitcnt vmcnt(6)
	s_waitcnt lgkmcnt(0)
	s_barrier
	s_setprio 1
	v_mfma_f32_16x16x32_bf16 v[60:63], v[140:143], v[182:185], 0
	v_mfma_f32_16x16x32_bf16 v[56:59], v[174:177], v[182:185], 0
	v_mfma_f32_16x16x32_bf16 v[44:47], v[140:143], v[190:193], 0
	v_mfma_f32_16x16x32_bf16 v[40:43], v[174:177], v[190:193], 0
	v_mfma_f32_16x16x32_bf16 v[28:31], v[140:143], v[198:201], 0
	v_mfma_f32_16x16x32_bf16 v[24:27], v[174:177], v[198:201], 0
	v_mfma_f32_16x16x32_bf16 v[12:15], v[140:143], v[206:209], 0
	v_mfma_f32_16x16x32_bf16 v[8:11], v[174:177], v[206:209], 0
	v_mfma_f32_16x16x32_bf16 v[60:63], v[170:173], v[186:189], v[60:63]
	v_mfma_f32_16x16x32_bf16 v[56:59], v[178:181], v[186:189], v[56:59]
	v_mfma_f32_16x16x32_bf16 v[44:47], v[170:173], v[194:197], v[44:47]
	v_mfma_f32_16x16x32_bf16 v[40:43], v[178:181], v[194:197], v[40:43]
	v_mfma_f32_16x16x32_bf16 v[28:31], v[170:173], v[202:205], v[28:31]
	v_mfma_f32_16x16x32_bf16 v[24:27], v[178:181], v[202:205], v[24:27]
	v_mfma_f32_16x16x32_bf16 v[12:15], v[170:173], v[210:213], v[12:15]
	v_mfma_f32_16x16x32_bf16 v[8:11], v[178:181], v[210:213], v[8:11]
	v_mfma_f32_16x16x32_bf16 v[52:55], v[214:217], v[182:185], 0
	v_mfma_f32_16x16x32_bf16 v[48:51], v[222:225], v[182:185], 0
	v_mfma_f32_16x16x32_bf16 v[36:39], v[214:217], v[190:193], 0
	v_mfma_f32_16x16x32_bf16 v[32:35], v[222:225], v[190:193], 0
	v_mfma_f32_16x16x32_bf16 v[20:23], v[214:217], v[198:201], 0
	v_mfma_f32_16x16x32_bf16 v[16:19], v[222:225], v[198:201], 0
	v_mfma_f32_16x16x32_bf16 v[4:7], v[214:217], v[206:209], 0
	v_mfma_f32_16x16x32_bf16 v[0:3], v[222:225], v[206:209], 0
	v_mfma_f32_16x16x32_bf16 v[52:55], v[218:221], v[186:189], v[52:55]
	v_mfma_f32_16x16x32_bf16 v[48:51], v[226:229], v[186:189], v[48:51]
	v_mfma_f32_16x16x32_bf16 v[36:39], v[218:221], v[194:197], v[36:39]
	v_mfma_f32_16x16x32_bf16 v[32:35], v[226:229], v[194:197], v[32:35]
	v_mfma_f32_16x16x32_bf16 v[20:23], v[218:221], v[202:205], v[20:23]
	v_mfma_f32_16x16x32_bf16 v[16:19], v[226:229], v[202:205], v[16:19]
	v_mfma_f32_16x16x32_bf16 v[4:7], v[218:221], v[210:213], v[4:7]
	v_mfma_f32_16x16x32_bf16 v[0:3], v[226:229], v[210:213], v[0:3]
	s_setprio 0
	s_barrier
	s_branch .Lzp5_mid
; #define PG8_STAGE(bufoff, gbase, voff) do { _Pragma("unroll") for (int _i = 0; _i < 2; ++_i) \
;         __builtin_amdgcn_global_load_lds((const unsigned*)((const char*)(gbase) + (voff)[_i]), (PG8_LAS unsigned*)(lds + (bufoff) + ldsw + _i * 8192), 16, 0, 0); } while (0)
; #define PG8_LDA(dst, b, h) do { _Pragma("unroll") for (int m = 0; m < 4; ++m) _Pragma("unroll") for (int k = 0; k < 2; ++k) dst[m][k] = *(const PG8_LAS bf16x8*)(lds + PG8_SA(b, h) + aoff + m * 2048 + k * 1024); } while (0)
; template <class Epi, class Sched, bool STAMP = false>
; __device__ __forceinline__ void gemm_phase(PG8_LAS unsigned char* lds, const Gemm g, const Sched& S, const Epi& E, unsigned long long* stamps) {
;     ...
;         for (int t = 0; t < nt; t += 2) {
;             const bool last = (t == nt - 2);
;             const char* a1 = cA + (size_t)(t + 1) * kstep;
;             const char* a2 = last ? nA : cA + (size_t)(t + 2) * kstep; const char* b2 = last ? nB : cB + (size_t)(t + 2) * kstep;
;             const char* a3 = a2 + kstep; const char* b3 = b2 + kstep;
;             if (last && has_next) S.a_ready(nxt);
;             PG8_LDB(B0, 0, 0); PG8_SCHED; PG8_LDA(At, 0, 0); PG8_STAGE(PG8_SA(1, 1), a1 + hstep, voffA);
;             PG8_WAIT_L(8); PG8_BAR; PG8_WAIT_L(0); PG8_MMA(0, 0, At, B0); PG8_BAR; PG8_SCHED;
;             PG8_LDB(B1, 0, 1); PG8_STAGE(PG8_SB(0, 0), b2, voffB);
;             PG8_BAR; PG8_WAIT_L(0); PG8_MMA(0, 1, At, B1); PG8_BAR;
;             PG8_LDA(At, 0, 1); PG8_STAGE(PG8_SA(0, 0), a2, voffA);
;             PG8_BAR; PG8_WAIT_L(0); PG8_MMA(1, 0, At, B0); PG8_BAR; PG8_SCHED;
;             PG8_STAGE(PG8_SB(0, 1), b2 + hstep, voffB);
;             PG8_WAIT_V(6); PG8_BAR; PG8_MMA(1, 1, At, B1); PG8_BAR;
;             PG8_LDB(B0, 1, 0); PG8_SCHED; PG8_LDA(At, 1, 0); PG8_STAGE(PG8_SA(0, 1), a2 + hstep, voffA);
;             PG8_WAIT_L(8); PG8_BAR; PG8_WAIT_L(0); PG8_MMA(0, 0, At, B0); PG8_BAR; PG8_SCHED;
;             PG8_LDB(B1, 1, 1); PG8_STAGE(PG8_SB(1, 0), b3, voffB);
;             PG8_BAR; PG8_WAIT_L(0); PG8_MMA(0, 1, At, B1); PG8_BAR;
;             PG8_LDA(At, 1, 1); PG8_STAGE(PG8_SA(1, 0), a3, voffA);
;             PG8_BAR; PG8_WAIT_L(0); PG8_MMA(1, 0, At, B0); PG8_BAR; PG8_SCHED;
;             PG8_STAGE(PG8_SB(1, 1), b3 + hstep, voffB);
;             PG8_WAIT_V(6); PG8_BAR; PG8_MMA(1, 1, At, B1); PG8_BAR;
;         }
.LBB0_351:
	s_add_u32 s100, s87, 0x43f80
	s_addc_u32 s101, s88, 0
	s_mov_b32 m0, s75
	s_nop 0
	global_load_lds_dwordx4 v130, s[100:101]
	s_mov_b32 m0, s76
	s_nop 0
	global_load_lds_dwordx4 v128, s[100:101]
	ds_read_b128 v[140:143], v147
	ds_read_b128 v[170:173], v148
	ds_read_b128 v[174:177], v149
	ds_read_b128 v[178:181], v150
	s_add_u32 s36, s34, 0x100
	s_addc_u32 s37, s35, 0
	s_cmp_eq_u32 s89, 12
	s_cselect_b32 s55, s5, s37
	s_cselect_b32 s54, s4, s36
	s_cselect_b32 s53, s1, s88
	s_cselect_b32 s52, s0, s87
	s_mov_b32 m0, s78
	ds_read_b128 v[182:185], v145
	ds_read_b128 v[186:189], v145 offset:1024
	ds_read_b128 v[190:193], v145 offset:2048
	ds_read_b128 v[194:197], v145 offset:3072
	ds_read_b128 v[198:201], v145 offset:4096
	ds_read_b128 v[202:205], v145 offset:5120
	ds_read_b128 v[206:209], v145 offset:6144
	ds_read_b128 v[210:213], v145 offset:7168
	global_load_lds_dwordx4 v132, s[34:35]
	s_mov_b32 m0, s79
	s_nop 0
	global_load_lds_dwordx4 v134, s[34:35]
	ds_read_b128 v[214:217], v151
	ds_read_b128 v[218:221], v152
	ds_read_b128 v[222:225], v153
	ds_read_b128 v[226:229], v154
	s_waitcnt vmcnt(8)
	s_waitcnt lgkmcnt(0)
	s_barrier
	s_setprio 1
	v_mfma_f32_16x16x32_bf16 v[124:127], v[140:143], v[182:185], v[124:127]
	v_mfma_f32_16x16x32_bf16 v[120:123], v[174:177], v[182:185], v[120:123]
	v_mfma_f32_16x16x32_bf16 v[108:111], v[140:143], v[190:193], v[108:111]
	v_mfma_f32_16x16x32_bf16 v[104:107], v[174:177], v[190:193], v[104:107]
	v_mfma_f32_16x16x32_bf16 v[92:95], v[140:143], v[198:201], v[92:95]
	v_mfma_f32_16x16x32_bf16 v[88:91], v[174:177], v[198:201], v[88:91]
	v_mfma_f32_16x16x32_bf16 v[76:79], v[140:143], v[206:209], v[76:79]
	v_mfma_f32_16x16x32_bf16 v[72:75], v[174:177], v[206:209], v[72:75]
	v_mfma_f32_16x16x32_bf16 v[124:127], v[170:173], v[186:189], v[124:127]
	v_mfma_f32_16x16x32_bf16 v[120:123], v[178:181], v[186:189], v[120:123]
	v_mfma_f32_16x16x32_bf16 v[108:111], v[170:173], v[194:197], v[108:111]
	v_mfma_f32_16x16x32_bf16 v[104:107], v[178:181], v[194:197], v[104:107]
	v_mfma_f32_16x16x32_bf16 v[92:95], v[170:173], v[202:205], v[92:95]
	v_mfma_f32_16x16x32_bf16 v[88:91], v[178:181], v[202:205], v[88:91]
	v_mfma_f32_16x16x32_bf16 v[76:79], v[170:173], v[210:213], v[76:79]
	v_mfma_f32_16x16x32_bf16 v[72:75], v[178:181], v[210:213], v[72:75]
	v_mfma_f32_16x16x32_bf16 v[116:119], v[214:217], v[182:185], v[116:119]
	v_mfma_f32_16x16x32_bf16 v[112:115], v[222:225], v[182:185], v[112:115]
	v_mfma_f32_16x16x32_bf16 v[100:103], v[214:217], v[190:193], v[100:103]
	v_mfma_f32_16x16x32_bf16 v[96:99], v[222:225], v[190:193], v[96:99]
	v_mfma_f32_16x16x32_bf16 v[84:87], v[214:217], v[198:201], v[84:87]
	v_mfma_f32_16x16x32_bf16 v[80:83], v[222:225], v[198:201], v[80:83]
	v_mfma_f32_16x16x32_bf16 v[68:71], v[214:217], v[206:209], v[68:71]
	v_mfma_f32_16x16x32_bf16 v[64:67], v[222:225], v[206:209], v[64:67]
	v_mfma_f32_16x16x32_bf16 v[116:119], v[218:221], v[186:189], v[116:119]
	v_mfma_f32_16x16x32_bf16 v[112:115], v[226:229], v[186:189], v[112:115]
	v_mfma_f32_16x16x32_bf16 v[100:103], v[218:221], v[194:197], v[100:103]
	v_mfma_f32_16x16x32_bf16 v[96:99], v[226:229], v[194:197], v[96:99]
	v_mfma_f32_16x16x32_bf16 v[84:87], v[218:221], v[202:205], v[84:87]
	v_mfma_f32_16x16x32_bf16 v[80:83], v[226:229], v[202:205], v[80:83]
	v_mfma_f32_16x16x32_bf16 v[68:71], v[218:221], v[210:213], v[68:71]
	v_mfma_f32_16x16x32_bf16 v[64:67], v[226:229], v[210:213], v[64:67]
	s_setprio 0
	s_barrier
	s_mov_b32 m0, s61
	s_nop 0
	global_load_lds_dwordx4 v130, s[52:53]
	s_mov_b32 m0, s62
	s_nop 0
	global_load_lds_dwordx4 v128, s[52:53]
	s_mov_b32 m0, s58
	ds_read_b128 v[182:185], v145 offset:16384
	ds_read_b128 v[186:189], v145 offset:17408
	ds_read_b128 v[190:193], v145 offset:18432
	ds_read_b128 v[194:197], v145 offset:19456
	ds_read_b128 v[198:201], v145 offset:20480
	ds_read_b128 v[202:205], v145 offset:21504
	ds_read_b128 v[206:209], v145 offset:22528
	ds_read_b128 v[210:213], v145 offset:23552
	global_load_lds_dwordx4 v130, s[54:55]
	s_mov_b32 m0, s63
	s_nop 0
	global_load_lds_dwordx4 v128, s[54:55]
	s_waitcnt vmcnt(6)
	s_waitcnt lgkmcnt(0)
	s_barrier
	s_setprio 1
	v_mfma_f32_16x16x32_bf16 v[60:63], v[140:143], v[182:185], v[60:63]
	v_mfma_f32_16x16x32_bf16 v[56:59], v[174:177], v[182:185], v[56:59]
	v_mfma_f32_16x16x32_bf16 v[44:47], v[140:143], v[190:193], v[44:47]
	v_mfma_f32_16x16x32_bf16 v[40:43], v[174:177], v[190:193], v[40:43]
	v_mfma_f32_16x16x32_bf16 v[28:31], v[140:143], v[198:201], v[28:31]
	v_mfma_f32_16x16x32_bf16 v[24:27], v[174:177], v[198:201], v[24:27]
	v_mfma_f32_16x16x32_bf16 v[12:15], v[140:143], v[206:209], v[12:15]
	v_mfma_f32_16x16x32_bf16 v[8:11], v[174:177], v[206:209], v[8:11]
	v_mfma_f32_16x16x32_bf16 v[60:63], v[170:173], v[186:189], v[60:63]
	v_mfma_f32_16x16x32_bf16 v[56:59], v[178:181], v[186:189], v[56:59]
	v_mfma_f32_16x16x32_bf16 v[44:47], v[170:173], v[194:197], v[44:47]
	v_mfma_f32_16x16x32_bf16 v[40:43], v[178:181], v[194:197], v[40:43]
	v_mfma_f32_16x16x32_bf16 v[28:31], v[170:173], v[202:205], v[28:31]
	v_mfma_f32_16x16x32_bf16 v[24:27], v[178:181], v[202:205], v[24:27]
	v_mfma_f32_16x16x32_bf16 v[12:15], v[170:173], v[210:213], v[12:15]
	v_mfma_f32_16x16x32_bf16 v[8:11], v[178:181], v[210:213], v[8:11]
	v_mfma_f32_16x16x32_bf16 v[52:55], v[214:217], v[182:185], v[52:55]
	v_mfma_f32_16x16x32_bf16 v[48:51], v[222:225], v[182:185], v[48:51]
	v_mfma_f32_16x16x32_bf16 v[36:39], v[214:217], v[190:193], v[36:39]
	v_mfma_f32_16x16x32_bf16 v[32:35], v[222:225], v[190:193], v[32:35]
	v_mfma_f32_16x16x32_bf16 v[20:23], v[214:217], v[198:201], v[20:23]
	v_mfma_f32_16x16x32_bf16 v[16:19], v[222:225], v[198:201], v[16:19]
	v_mfma_f32_16x16x32_bf16 v[4:7], v[214:217], v[206:209], v[4:7]
	v_mfma_f32_16x16x32_bf16 v[0:3], v[222:225], v[206:209], v[0:3]
	v_mfma_f32_16x16x32_bf16 v[52:55], v[218:221], v[186:189], v[52:55]
	v_mfma_f32_16x16x32_bf16 v[48:51], v[226:229], v[186:189], v[48:51]
	v_mfma_f32_16x16x32_bf16 v[36:39], v[218:221], v[194:197], v[36:39]
	v_mfma_f32_16x16x32_bf16 v[32:35], v[226:229], v[194:197], v[32:35]
	v_mfma_f32_16x16x32_bf16 v[20:23], v[218:221], v[202:205], v[20:23]
	v_mfma_f32_16x16x32_bf16 v[16:19], v[226:229], v[202:205], v[16:19]
	v_mfma_f32_16x16x32_bf16 v[4:7], v[218:221], v[210:213], v[4:7]
	v_mfma_f32_16x16x32_bf16 v[0:3], v[226:229], v[210:213], v[0:3]
	s_setprio 0
	s_barrier
; #define PG8_STAGE(bufoff, gbase, voff) do { _Pragma("unroll") for (int _i = 0; _i < 2; ++_i) \
;         __builtin_amdgcn_global_load_lds((const unsigned*)((const char*)(gbase) + (voff)[_i]), (PG8_LAS unsigned*)(lds + (bufoff) + ldsw + _i * 8192), 16, 0, 0); } while (0)
; #define PG8_LDA(dst, b, h) do { _Pragma("unroll") for (int m = 0; m < 4; ++m) _Pragma("unroll") for (int k = 0; k < 2; ++k) dst[m][k] = *(const PG8_LAS bf16x8*)(lds + PG8_SA(b, h) + aoff + m * 2048 + k * 1024); } while (0)
; #define PG8_LDB(dst, b, h) do { _Pragma("unroll") for (int n = 0; n < 2; ++n) _Pragma("unroll") for (int k = 0; k < 2; ++k) dst[n][k] = *(const PG8_LAS bf16x8*)(lds + PG8_SB(b, h) + boff + n * 2048 + k * 1024); } while (0)
; #define PG8_MMA(ai, bj, At, Bt) do { __builtin_amdgcn_s_setprio(1); _Pragma("unroll") for (int m = 0; m < 4; ++m) _Pragma("unroll") for (int n = 0; n < 2; ++n) _Pragma("unroll") for (int k = 0; k < 2; ++k) \
;         acc[ai][bj][m][n] = __builtin_amdgcn_mfma_f32_16x16x32_bf16(Bt[n][k], At[m][k], acc[ai][bj][m][n], 0, 0, 0); __builtin_amdgcn_s_setprio(0); } while (0)
; #define PG8_WAIT_V(n) asm volatile("s_waitcnt vmcnt(" #n ")" ::: "memory")
; #define PG8_WAIT_L(n) asm volatile("s_waitcnt lgkmcnt(" #n ")" ::: "memory")
; #define PG8_BAR __builtin_amdgcn_s_barrier()
; #define PG8_SCHED __builtin_amdgcn_sched_barrier(0)
; template <class Epi, class Sched, bool STAMP = false>
; __device__ __forceinline__ void gemm_phase(PG8_LAS unsigned char* lds, const Gemm g, const Sched& S, const Epi& E, unsigned long long* stamps) {
;     ...
;             PG8_WAIT_V(6); PG8_BAR; PG8_MMA(1, 1, At, B1); PG8_BAR;
;             PG8_LDB(B0, 1, 0); PG8_SCHED; PG8_LDA(At, 1, 0); PG8_STAGE(PG8_SA(0, 1), a2 + hstep, voffA);
;             PG8_WAIT_L(8); PG8_BAR; PG8_WAIT_L(0); PG8_MMA(0, 0, At, B0); PG8_BAR; PG8_SCHED;
;             PG8_LDB(B1, 1, 1); PG8_STAGE(PG8_SB(1, 0), b3, voffB);
;             PG8_BAR; PG8_WAIT_L(0); PG8_MMA(0, 1, At, B1); PG8_BAR;
;             PG8_LDA(At, 1, 1); PG8_STAGE(PG8_SA(1, 0), a3, voffA);
;             PG8_BAR; PG8_WAIT_L(0); PG8_MMA(1, 0, At, B0); PG8_BAR; PG8_SCHED;
;             PG8_STAGE(PG8_SB(1, 1), b3 + hstep, voffB);
;             PG8_WAIT_V(6); PG8_BAR; PG8_MMA(1, 1, At, B1); PG8_BAR;
;         }
.Lzp5_mid:
	s_add_u32 s34, s52, 0x44000
	s_addc_u32 s35, s53, 0
	s_mov_b32 m0, s64
	s_nop 0
	global_load_lds_dwordx4 v130, s[34:35]
	s_mov_b32 m0, s65
	s_nop 0
	global_load_lds_dwordx4 v128, s[34:35]
	ds_read_b128 v[140:143], v155
	ds_read_b128 v[170:173], v156
	ds_read_b128 v[174:177], v157
	ds_read_b128 v[178:181], v165
	s_add_u32 s34, s54, 0x44000
	s_addc_u32 s35, s55, 0
	s_mov_b32 m0, s66
	ds_read_b128 v[182:185], v145 offset:32768
	ds_read_b128 v[186:189], v145 offset:33792
	ds_read_b128 v[190:193], v145 offset:34816
	ds_read_b128 v[194:197], v145 offset:35840
	ds_read_b128 v[198:201], v145 offset:36864
	ds_read_b128 v[202:205], v145 offset:37888
	ds_read_b128 v[206:209], v145 offset:38912
	ds_read_b128 v[210:213], v145 offset:39936
	global_load_lds_dwordx4 v130, s[34:35]
	s_mov_b32 m0, s67
	s_nop 0
	global_load_lds_dwordx4 v128, s[34:35]
	ds_read_b128 v[214:217], v166
	ds_read_b128 v[218:221], v167
	ds_read_b128 v[222:225], v168
	ds_read_b128 v[226:229], v169
	s_waitcnt vmcnt(8)
	s_waitcnt lgkmcnt(0)
	s_barrier
	s_setprio 1
	v_mfma_f32_16x16x32_bf16 v[124:127], v[140:143], v[182:185], v[124:127]
	v_mfma_f32_16x16x32_bf16 v[120:123], v[174:177], v[182:185], v[120:123]
	v_mfma_f32_16x16x32_bf16 v[108:111], v[140:143], v[190:193], v[108:111]
	v_mfma_f32_16x16x32_bf16 v[104:107], v[174:177], v[190:193], v[104:107]
	v_mfma_f32_16x16x32_bf16 v[92:95], v[140:143], v[198:201], v[92:95]
	v_mfma_f32_16x16x32_bf16 v[88:91], v[174:177], v[198:201], v[88:91]
	v_mfma_f32_16x16x32_bf16 v[76:79], v[140:143], v[206:209], v[76:79]
	v_mfma_f32_16x16x32_bf16 v[72:75], v[174:177], v[206:209], v[72:75]
	v_mfma_f32_16x16x32_bf16 v[124:127], v[170:173], v[186:189], v[124:127]
	v_mfma_f32_16x16x32_bf16 v[120:123], v[178:181], v[186:189], v[120:123]
	v_mfma_f32_16x16x32_bf16 v[108:111], v[170:173], v[194:197], v[108:111]
	v_mfma_f32_16x16x32_bf16 v[104:107], v[178:181], v[194:197], v[104:107]
	v_mfma_f32_16x16x32_bf16 v[92:95], v[170:173], v[202:205], v[92:95]
	v_mfma_f32_16x16x32_bf16 v[88:91], v[178:181], v[202:205], v[88:91]
	v_mfma_f32_16x16x32_bf16 v[76:79], v[170:173], v[210:213], v[76:79]
	v_mfma_f32_16x16x32_bf16 v[72:75], v[178:181], v[210:213], v[72:75]
	v_mfma_f32_16x16x32_bf16 v[116:119], v[214:217], v[182:185], v[116:119]
	v_mfma_f32_16x16x32_bf16 v[112:115], v[222:225], v[182:185], v[112:115]
	v_mfma_f32_16x16x32_bf16 v[100:103], v[214:217], v[190:193], v[100:103]
	v_mfma_f32_16x16x32_bf16 v[96:99], v[222:225], v[190:193], v[96:99]
	v_mfma_f32_16x16x32_bf16 v[84:87], v[214:217], v[198:201], v[84:87]
	v_mfma_f32_16x16x32_bf16 v[80:83], v[222:225], v[198:201], v[80:83]
	v_mfma_f32_16x16x32_bf16 v[68:71], v[214:217], v[206:209], v[68:71]
	v_mfma_f32_16x16x32_bf16 v[64:67], v[222:225], v[206:209], v[64:67]
	v_mfma_f32_16x16x32_bf16 v[116:119], v[218:221], v[186:189], v[116:119]
	v_mfma_f32_16x16x32_bf16 v[112:115], v[226:229], v[186:189], v[112:115]
	v_mfma_f32_16x16x32_bf16 v[100:103], v[218:221], v[194:197], v[100:103]
	v_mfma_f32_16x16x32_bf16 v[96:99], v[226:229], v[194:197], v[96:99]
	v_mfma_f32_16x16x32_bf16 v[84:87], v[218:221], v[202:205], v[84:87]
	v_mfma_f32_16x16x32_bf16 v[80:83], v[226:229], v[202:205], v[80:83]
	v_mfma_f32_16x16x32_bf16 v[68:71], v[218:221], v[210:213], v[68:71]
	v_mfma_f32_16x16x32_bf16 v[64:67], v[226:229], v[210:213], v[64:67]
	s_setprio 0
	s_barrier
	s_mov_b32 m0, s70
	s_add_u32 s100, s52, 0x80
	s_addc_u32 s101, s53, 0
	global_load_lds_dwordx4 v130, s[100:101]
	s_mov_b32 m0, s71
	s_nop 0
	global_load_lds_dwordx4 v128, s[100:101]
	s_mov_b32 m0, s73
	ds_read_b128 v[182:185], v145 offset:49152
	ds_read_b128 v[186:189], v145 offset:50176
	ds_read_b128 v[190:193], v145 offset:51200
	ds_read_b128 v[194:197], v145 offset:52224
	ds_read_b128 v[198:201], v145 offset:53248
	ds_read_b128 v[202:205], v145 offset:54272
	ds_read_b128 v[206:209], v145 offset:55296
	ds_read_b128 v[210:213], v145 offset:56320
	s_add_u32 s100, s54, 0x80
	s_addc_u32 s101, s55, 0
	global_load_lds_dwordx4 v130, s[100:101]
	s_mov_b32 m0, s74
	s_nop 0
	global_load_lds_dwordx4 v128, s[100:101]
	s_waitcnt vmcnt(6)
	s_waitcnt lgkmcnt(0)
	s_barrier
	s_setprio 1
	v_mfma_f32_16x16x32_bf16 v[60:63], v[140:143], v[182:185], v[60:63]
	v_mfma_f32_16x16x32_bf16 v[56:59], v[174:177], v[182:185], v[56:59]
	v_mfma_f32_16x16x32_bf16 v[44:47], v[140:143], v[190:193], v[44:47]
	v_mfma_f32_16x16x32_bf16 v[40:43], v[174:177], v[190:193], v[40:43]
	v_mfma_f32_16x16x32_bf16 v[28:31], v[140:143], v[198:201], v[28:31]
	v_mfma_f32_16x16x32_bf16 v[24:27], v[174:177], v[198:201], v[24:27]
	v_mfma_f32_16x16x32_bf16 v[12:15], v[140:143], v[206:209], v[12:15]
	v_mfma_f32_16x16x32_bf16 v[8:11], v[174:177], v[206:209], v[8:11]
	v_mfma_f32_16x16x32_bf16 v[60:63], v[170:173], v[186:189], v[60:63]
	v_mfma_f32_16x16x32_bf16 v[56:59], v[178:181], v[186:189], v[56:59]
	v_mfma_f32_16x16x32_bf16 v[44:47], v[170:173], v[194:197], v[44:47]
	v_mfma_f32_16x16x32_bf16 v[40:43], v[178:181], v[194:197], v[40:43]
	v_mfma_f32_16x16x32_bf16 v[28:31], v[170:173], v[202:205], v[28:31]
	v_mfma_f32_16x16x32_bf16 v[24:27], v[178:181], v[202:205], v[24:27]
	v_mfma_f32_16x16x32_bf16 v[12:15], v[170:173], v[210:213], v[12:15]
	v_mfma_f32_16x16x32_bf16 v[8:11], v[178:181], v[210:213], v[8:11]
	v_mfma_f32_16x16x32_bf16 v[52:55], v[214:217], v[182:185], v[52:55]
	v_mfma_f32_16x16x32_bf16 v[48:51], v[222:225], v[182:185], v[48:51]
	v_mfma_f32_16x16x32_bf16 v[36:39], v[214:217], v[190:193], v[36:39]
	v_mfma_f32_16x16x32_bf16 v[32:35], v[222:225], v[190:193], v[32:35]
	v_mfma_f32_16x16x32_bf16 v[20:23], v[214:217], v[198:201], v[20:23]
	v_mfma_f32_16x16x32_bf16 v[16:19], v[222:225], v[198:201], v[16:19]
	v_mfma_f32_16x16x32_bf16 v[4:7], v[214:217], v[206:209], v[4:7]
	v_mfma_f32_16x16x32_bf16 v[0:3], v[222:225], v[206:209], v[0:3]
	v_mfma_f32_16x16x32_bf16 v[52:55], v[218:221], v[186:189], v[52:55]
	v_mfma_f32_16x16x32_bf16 v[48:51], v[226:229], v[186:189], v[48:51]
	v_mfma_f32_16x16x32_bf16 v[36:39], v[218:221], v[194:197], v[36:39]
	v_mfma_f32_16x16x32_bf16 v[32:35], v[226:229], v[194:197], v[32:35]
	v_mfma_f32_16x16x32_bf16 v[20:23], v[218:221], v[202:205], v[20:23]
	v_mfma_f32_16x16x32_bf16 v[16:19], v[226:229], v[202:205], v[16:19]
	v_mfma_f32_16x16x32_bf16 v[4:7], v[218:221], v[210:213], v[4:7]
	v_mfma_f32_16x16x32_bf16 v[0:3], v[226:229], v[210:213], v[0:3]
	s_setprio 0
	s_add_i32 s89, s89, 2
	s_add_u32 s87, s87, 0x100
	s_addc_u32 s88, s88, 0
	s_cmp_gt_u32 s89, 13
	s_mov_b64 s[34:35], s[36:37]
	s_barrier
; DI float ex2(float x) { return __builtin_amdgcn_exp2f(x); }
;     DI void operator()(const f32x4 (&acc)[2][2][4][2], const Unit& u, int wr, int wc, int fr, int fq) const {
;         const int row0 = u.pm * BM + wr * 64 + fr, hcol0 = ((u.pn * BM + wc * 32) >> 1) + 4 * fq;
; #pragma unroll
;         for (int ai = 0; ai < 2; ++ai)
; #pragma unroll
;             for (int m = 0; m < 4; ++m) { u16* rowp = O + (size_t)(row0 + ai * HALF + m * 16) * ldc + hcol0;
; #pragma unroll
;                 for (int bj = 0; bj < 2; ++bj) { const f32x4 g = acc[ai][bj][m][0], up = acc[ai][bj][m][1]; float r[4];
; #pragma unroll
;                     for (int j = 0; j < 4; ++j) r[j] = g[j] * up[j] * __builtin_amdgcn_rcpf(1.f + ex2(-LOG2E * g[j]));
;                     uint2 w = {pack2(r[0], r[1]), pack2(r[2], r[3])}; *(uint2*)(rowp + bj * (HALF / 2)) = w; } }
;     }
	s_cbranch_scc0 .LBB0_351
	v_exp_f32_e64 v171, -v124
	v_exp_f32_e64 v175, -v125
	s_lshl_b32 s10, s86, 8
	v_add_f32_e32 v171, 1.0, v171
	v_rcp_f32_e32 v174, v171
	v_add_f32_e32 v171, 1.0, v175
	v_exp_f32_e64 v176, -v126
	v_exp_f32_e64 v177, -v127
	v_rcp_f32_e32 v175, v171
	v_add_f32_e32 v171, 1.0, v176
	v_rcp_f32_e32 v176, v171
	v_add_f32_e32 v171, 1.0, v177
	v_rcp_f32_e32 v177, v171
	v_pk_mul_f32 v[122:123], v[126:127], v[122:123]
	v_pk_mul_f32 v[120:121], v[124:125], v[120:121]
	s_or_b32 s10, s10, s69
	v_pk_mul_f32 v[120:121], v[120:121], v[174:175]
	v_pk_mul_f32 v[122:123], v[122:123], v[176:177]
	s_ashr_i32 s10, s10, 1
	v_cvt_pk_bf16_f32 v120, v120, v121
	v_cvt_pk_bf16_f32 v121, v122, v123
	v_or_b32_e32 v140, s10, v146
	v_exp_f32_e64 v122, -v116
	v_exp_f32_e64 v123, -v117
	v_lshl_add_u32 v170, s85, 8, v144
	v_ashrrev_i32_e32 v141, 31, v140
	v_mov_b64_e32 v[142:143], s[12:13]
	v_mad_i64_i32 v[172:173], s[34:35], v170, s82, v[142:143]
	v_lshlrev_b64 v[140:141], 1, v[140:141]
	v_lshl_add_u64 v[172:173], v[172:173], 0, v[140:141]
	global_store_dwordx2 v[172:173], v[120:121], off
	v_add_f32_e32 v120, 1.0, v122
	v_add_f32_e32 v121, 1.0, v123
	v_exp_f32_e64 v122, -v118
	v_exp_f32_e64 v123, -v119
	v_rcp_f32_e32 v120, v120
	v_rcp_f32_e32 v121, v121
	v_add_f32_e32 v122, 1.0, v122
	v_add_f32_e32 v123, 1.0, v123
	v_rcp_f32_e32 v122, v122
	v_rcp_f32_e32 v123, v123
	v_pk_mul_f32 v[114:115], v[118:119], v[114:115]
	v_pk_mul_f32 v[112:113], v[116:117], v[112:113]
	v_pk_mul_f32 v[112:113], v[112:113], v[120:121]
	v_pk_mul_f32 v[114:115], v[114:115], v[122:123]
	v_cvt_pk_bf16_f32 v112, v112, v113
	v_cvt_pk_bf16_f32 v113, v114, v115
	v_exp_f32_e64 v114, -v108
	v_exp_f32_e64 v115, -v109
	v_exp_f32_e64 v116, -v110
	v_exp_f32_e64 v117, -v111
	v_add_f32_e32 v114, 1.0, v114
	v_add_f32_e32 v115, 1.0, v115
	v_add_f32_e32 v116, 1.0, v116
	v_add_f32_e32 v117, 1.0, v117
	v_rcp_f32_e32 v114, v114
	v_rcp_f32_e32 v115, v115
	v_rcp_f32_e32 v116, v116
	v_rcp_f32_e32 v117, v117
	v_pk_mul_f32 v[106:107], v[110:111], v[106:107]
	v_pk_mul_f32 v[104:105], v[108:109], v[104:105]
	global_store_dwordx2 v[172:173], v[112:113], off offset:128
	v_pk_mul_f32 v[104:105], v[104:105], v[114:115]
	v_pk_mul_f32 v[106:107], v[106:107], v[116:117]
	v_cvt_pk_bf16_f32 v104, v104, v105
	v_cvt_pk_bf16_f32 v105, v106, v107
	v_exp_f32_e64 v106, -v100
	v_exp_f32_e64 v107, -v101
	v_or_b32_e32 v112, 16, v170
	v_mad_i64_i32 v[112:113], s[34:35], v112, s82, v[142:143]
	v_lshl_add_u64 v[112:113], v[112:113], 0, v[140:141]
	global_store_dwordx2 v[112:113], v[104:105], off
	v_add_f32_e32 v104, 1.0, v106
	v_add_f32_e32 v105, 1.0, v107
	v_exp_f32_e64 v106, -v102
	v_exp_f32_e64 v107, -v103
	v_rcp_f32_e32 v104, v104
	v_rcp_f32_e32 v105, v105
	v_add_f32_e32 v106, 1.0, v106
	v_add_f32_e32 v107, 1.0, v107
	v_rcp_f32_e32 v106, v106
	v_rcp_f32_e32 v107, v107
	v_pk_mul_f32 v[98:99], v[102:103], v[98:99]
	v_pk_mul_f32 v[96:97], v[100:101], v[96:97]
	v_pk_mul_f32 v[96:97], v[96:97], v[104:105]
	v_pk_mul_f32 v[98:99], v[98:99], v[106:107]
	v_cvt_pk_bf16_f32 v96, v96, v97
	v_cvt_pk_bf16_f32 v97, v98, v99
	v_exp_f32_e64 v98, -v92
	v_exp_f32_e64 v99, -v93
	v_exp_f32_e64 v100, -v94
	v_exp_f32_e64 v101, -v95
	v_add_f32_e32 v98, 1.0, v98
	v_add_f32_e32 v99, 1.0, v99
	v_add_f32_e32 v100, 1.0, v100
	v_add_f32_e32 v101, 1.0, v101
	v_rcp_f32_e32 v98, v98
	v_rcp_f32_e32 v99, v99
	v_rcp_f32_e32 v100, v100
	v_rcp_f32_e32 v101, v101
	v_pk_mul_f32 v[90:91], v[94:95], v[90:91]
	v_pk_mul_f32 v[88:89], v[92:93], v[88:89]
	global_store_dwordx2 v[112:113], v[96:97], off offset:128
	v_pk_mul_f32 v[88:89], v[88:89], v[98:99]
	v_pk_mul_f32 v[90:91], v[90:91], v[100:101]
	v_cvt_pk_bf16_f32 v88, v88, v89
	v_cvt_pk_bf16_f32 v89, v90, v91
	v_exp_f32_e64 v90, -v84
	v_exp_f32_e64 v91, -v85
	v_or_b32_e32 v96, 32, v170
	v_mad_i64_i32 v[96:97], s[34:35], v96, s82, v[142:143]
	v_lshl_add_u64 v[96:97], v[96:97], 0, v[140:141]
	global_store_dwordx2 v[96:97], v[88:89], off
	v_add_f32_e32 v88, 1.0, v90
	v_add_f32_e32 v89, 1.0, v91
	v_exp_f32_e64 v90, -v86
	v_exp_f32_e64 v91, -v87
	v_rcp_f32_e32 v88, v88
	v_rcp_f32_e32 v89, v89
	v_add_f32_e32 v90, 1.0, v90
	v_add_f32_e32 v91, 1.0, v91
	v_rcp_f32_e32 v90, v90
	v_rcp_f32_e32 v91, v91
	v_pk_mul_f32 v[82:83], v[86:87], v[82:83]
	v_pk_mul_f32 v[80:81], v[84:85], v[80:81]
	v_pk_mul_f32 v[80:81], v[80:81], v[88:89]
	v_pk_mul_f32 v[82:83], v[82:83], v[90:91]
	v_cvt_pk_bf16_f32 v80, v80, v81
	v_cvt_pk_bf16_f32 v81, v82, v83
	v_exp_f32_e64 v82, -v76
	v_exp_f32_e64 v83, -v77
	v_exp_f32_e64 v84, -v78
	v_exp_f32_e64 v85, -v79
	v_add_f32_e32 v82, 1.0, v82
	v_add_f32_e32 v83, 1.0, v83
	v_add_f32_e32 v84, 1.0, v84
	v_add_f32_e32 v85, 1.0, v85
	v_rcp_f32_e32 v82, v82
	v_rcp_f32_e32 v83, v83
	v_rcp_f32_e32 v84, v84
	v_rcp_f32_e32 v85, v85
	v_pk_mul_f32 v[74:75], v[78:79], v[74:75]
	v_pk_mul_f32 v[72:73], v[76:77], v[72:73]
	global_store_dwordx2 v[96:97], v[80:81], off offset:128
	v_pk_mul_f32 v[72:73], v[72:73], v[82:83]
	v_pk_mul_f32 v[74:75], v[74:75], v[84:85]
	v_cvt_pk_bf16_f32 v72, v72, v73
	v_cvt_pk_bf16_f32 v73, v74, v75
	v_exp_f32_e64 v74, -v68
	v_exp_f32_e64 v75, -v69
	v_or_b32_e32 v80, 48, v170
	v_mad_i64_i32 v[80:81], s[34:35], v80, s82, v[142:143]
	v_lshl_add_u64 v[80:81], v[80:81], 0, v[140:141]
	global_store_dwordx2 v[80:81], v[72:73], off
	v_add_f32_e32 v72, 1.0, v74
	v_add_f32_e32 v73, 1.0, v75
	v_exp_f32_e64 v74, -v70
	v_exp_f32_e64 v75, -v71
	v_rcp_f32_e32 v72, v72
	v_rcp_f32_e32 v73, v73
	v_add_f32_e32 v74, 1.0, v74
	v_add_f32_e32 v75, 1.0, v75
	v_rcp_f32_e32 v74, v74
	v_rcp_f32_e32 v75, v75
	v_pk_mul_f32 v[66:67], v[70:71], v[66:67]
	v_pk_mul_f32 v[64:65], v[68:69], v[64:65]
; DI float ex2(float x) { return __builtin_amdgcn_exp2f(x); }
;     DI void operator()(const f32x4 (&acc)[2][2][4][2], const Unit& u, int wr, int wc, int fr, int fq) const {
;         const int row0 = u.pm * BM + wr * 64 + fr, hcol0 = ((u.pn * BM + wc * 32) >> 1) + 4 * fq;
; #pragma unroll
;         for (int ai = 0; ai < 2; ++ai)
; #pragma unroll
;             for (int m = 0; m < 4; ++m) { u16* rowp = O + (size_t)(row0 + ai * HALF + m * 16) * ldc + hcol0;
; #pragma unroll
;                 for (int bj = 0; bj < 2; ++bj) { const f32x4 g = acc[ai][bj][m][0], up = acc[ai][bj][m][1]; float r[4];
; #pragma unroll
;                     for (int j = 0; j < 4; ++j) r[j] = g[j] * up[j] * __builtin_amdgcn_rcpf(1.f + ex2(-LOG2E * g[j]));
;                     uint2 w = {pack2(r[0], r[1]), pack2(r[2], r[3])}; *(uint2*)(rowp + bj * (HALF / 2)) = w; } }
;     }
; template <class Epi, class Sched, bool STAMP = false>
; __device__ __forceinline__ void gemm_phase(PG8_LAS unsigned char* lds, const Gemm g, const Sched& S, const Epi& E, unsigned long long* stamps) {
;     ...
;         if (!has_next) break;
; #pragma unroll
;         for (int a = 0; a < 2; ++a)
; #pragma unroll
;             for (int b = 0; b < 2; ++b)
; #pragma unroll
;                 for (int m = 0; m < 4; ++m)
; #pragma unroll
;                     for (int n = 0; n < 2; ++n) acc[a][b][m][n] = (f32x4){0.f, 0.f, 0.f, 0.f};
;         cur = nxt; cA = nA; cB = nB; ++ui;
;     }
	v_pk_mul_f32 v[64:65], v[64:65], v[72:73]
	v_pk_mul_f32 v[66:67], v[66:67], v[74:75]
	v_cvt_pk_bf16_f32 v64, v64, v65
	v_cvt_pk_bf16_f32 v65, v66, v67
	v_exp_f32_e64 v66, -v60
	v_exp_f32_e64 v67, -v61
	v_exp_f32_e64 v68, -v62
	v_exp_f32_e64 v69, -v63
	v_add_f32_e32 v66, 1.0, v66
	v_add_f32_e32 v67, 1.0, v67
	v_add_f32_e32 v68, 1.0, v68
	v_add_f32_e32 v69, 1.0, v69
	v_rcp_f32_e32 v66, v66
	v_rcp_f32_e32 v67, v67
	v_rcp_f32_e32 v68, v68
	v_rcp_f32_e32 v69, v69
	v_pk_mul_f32 v[58:59], v[62:63], v[58:59]
	v_pk_mul_f32 v[56:57], v[60:61], v[56:57]
	global_store_dwordx2 v[80:81], v[64:65], off offset:128
	v_pk_mul_f32 v[56:57], v[56:57], v[66:67]
	v_pk_mul_f32 v[58:59], v[58:59], v[68:69]
	v_cvt_pk_bf16_f32 v56, v56, v57
	v_cvt_pk_bf16_f32 v57, v58, v59
	v_exp_f32_e64 v58, -v52
	v_exp_f32_e64 v59, -v53
	v_add_u32_e32 v64, 0x80, v170
	v_mad_i64_i32 v[64:65], s[34:35], v64, s82, v[142:143]
	v_lshl_add_u64 v[64:65], v[64:65], 0, v[140:141]
	global_store_dwordx2 v[64:65], v[56:57], off
	v_add_f32_e32 v56, 1.0, v58
	v_add_f32_e32 v57, 1.0, v59
	v_exp_f32_e64 v58, -v54
	v_exp_f32_e64 v59, -v55
	v_rcp_f32_e32 v56, v56
	v_rcp_f32_e32 v57, v57
	v_add_f32_e32 v58, 1.0, v58
	v_add_f32_e32 v59, 1.0, v59
	v_rcp_f32_e32 v58, v58
	v_rcp_f32_e32 v59, v59
	v_pk_mul_f32 v[50:51], v[54:55], v[50:51]
	v_pk_mul_f32 v[48:49], v[52:53], v[48:49]
	v_pk_mul_f32 v[48:49], v[48:49], v[56:57]
	v_pk_mul_f32 v[50:51], v[50:51], v[58:59]
	v_cvt_pk_bf16_f32 v48, v48, v49
	v_cvt_pk_bf16_f32 v49, v50, v51
	v_exp_f32_e64 v50, -v44
	v_exp_f32_e64 v51, -v45
	v_exp_f32_e64 v52, -v46
	v_exp_f32_e64 v53, -v47
	v_add_f32_e32 v50, 1.0, v50
	v_add_f32_e32 v51, 1.0, v51
	v_add_f32_e32 v52, 1.0, v52
	v_add_f32_e32 v53, 1.0, v53
	v_rcp_f32_e32 v50, v50
	v_rcp_f32_e32 v51, v51
	v_rcp_f32_e32 v52, v52
	v_rcp_f32_e32 v53, v53
	v_pk_mul_f32 v[42:43], v[46:47], v[42:43]
	v_pk_mul_f32 v[40:41], v[44:45], v[40:41]
	global_store_dwordx2 v[64:65], v[48:49], off offset:128
	v_pk_mul_f32 v[40:41], v[40:41], v[50:51]
	v_pk_mul_f32 v[42:43], v[42:43], v[52:53]
	v_cvt_pk_bf16_f32 v40, v40, v41
	v_cvt_pk_bf16_f32 v41, v42, v43
	v_exp_f32_e64 v42, -v36
	v_exp_f32_e64 v43, -v37
	v_add_u32_e32 v48, 0x90, v170
	v_mad_i64_i32 v[48:49], s[34:35], v48, s82, v[142:143]
	v_lshl_add_u64 v[48:49], v[48:49], 0, v[140:141]
	global_store_dwordx2 v[48:49], v[40:41], off
	v_add_f32_e32 v40, 1.0, v42
	v_add_f32_e32 v41, 1.0, v43
	v_exp_f32_e64 v42, -v38
	v_exp_f32_e64 v43, -v39
	v_rcp_f32_e32 v40, v40
	v_rcp_f32_e32 v41, v41
	v_add_f32_e32 v42, 1.0, v42
	v_add_f32_e32 v43, 1.0, v43
	v_rcp_f32_e32 v42, v42
	v_rcp_f32_e32 v43, v43
	v_pk_mul_f32 v[34:35], v[38:39], v[34:35]
	v_pk_mul_f32 v[32:33], v[36:37], v[32:33]
	v_pk_mul_f32 v[32:33], v[32:33], v[40:41]
	v_pk_mul_f32 v[34:35], v[34:35], v[42:43]
	v_cvt_pk_bf16_f32 v32, v32, v33
	v_cvt_pk_bf16_f32 v33, v34, v35
	v_exp_f32_e64 v34, -v28
	v_exp_f32_e64 v35, -v29
	v_exp_f32_e64 v36, -v30
	v_exp_f32_e64 v37, -v31
	v_add_f32_e32 v34, 1.0, v34
	v_add_f32_e32 v35, 1.0, v35
	v_add_f32_e32 v36, 1.0, v36
	v_add_f32_e32 v37, 1.0, v37
	v_rcp_f32_e32 v34, v34
	v_rcp_f32_e32 v35, v35
	v_rcp_f32_e32 v36, v36
	v_rcp_f32_e32 v37, v37
	v_pk_mul_f32 v[26:27], v[30:31], v[26:27]
	v_pk_mul_f32 v[24:25], v[28:29], v[24:25]
	global_store_dwordx2 v[48:49], v[32:33], off offset:128
	v_pk_mul_f32 v[24:25], v[24:25], v[34:35]
	v_pk_mul_f32 v[26:27], v[26:27], v[36:37]
	v_cvt_pk_bf16_f32 v24, v24, v25
	v_cvt_pk_bf16_f32 v25, v26, v27
	v_exp_f32_e64 v26, -v20
	v_exp_f32_e64 v27, -v21
	v_add_u32_e32 v32, 0xa0, v170
	v_mad_i64_i32 v[32:33], s[34:35], v32, s82, v[142:143]
	v_lshl_add_u64 v[32:33], v[32:33], 0, v[140:141]
	global_store_dwordx2 v[32:33], v[24:25], off
	v_add_f32_e32 v24, 1.0, v26
	v_add_f32_e32 v25, 1.0, v27
	v_exp_f32_e64 v26, -v22
	v_exp_f32_e64 v27, -v23
	v_rcp_f32_e32 v24, v24
	v_rcp_f32_e32 v25, v25
	v_add_f32_e32 v26, 1.0, v26
	v_add_f32_e32 v27, 1.0, v27
	v_rcp_f32_e32 v26, v26
	v_rcp_f32_e32 v27, v27
	v_pk_mul_f32 v[18:19], v[22:23], v[18:19]
	v_pk_mul_f32 v[16:17], v[20:21], v[16:17]
	v_pk_mul_f32 v[16:17], v[16:17], v[24:25]
	v_pk_mul_f32 v[18:19], v[18:19], v[26:27]
	v_cvt_pk_bf16_f32 v16, v16, v17
	v_cvt_pk_bf16_f32 v17, v18, v19
	v_exp_f32_e64 v18, -v12
	v_exp_f32_e64 v19, -v13
	v_exp_f32_e64 v20, -v14
	v_exp_f32_e64 v21, -v15
	v_add_f32_e32 v18, 1.0, v18
	v_add_f32_e32 v19, 1.0, v19
	v_add_f32_e32 v20, 1.0, v20
	v_add_f32_e32 v21, 1.0, v21
	v_rcp_f32_e32 v18, v18
	v_rcp_f32_e32 v19, v19
	v_rcp_f32_e32 v20, v20
	v_rcp_f32_e32 v21, v21
	v_pk_mul_f32 v[10:11], v[14:15], v[10:11]
	v_pk_mul_f32 v[8:9], v[12:13], v[8:9]
	global_store_dwordx2 v[32:33], v[16:17], off offset:128
	v_pk_mul_f32 v[8:9], v[8:9], v[18:19]
	v_pk_mul_f32 v[10:11], v[10:11], v[20:21]
	v_cvt_pk_bf16_f32 v8, v8, v9
	v_cvt_pk_bf16_f32 v9, v10, v11
	v_exp_f32_e64 v10, -v4
	v_exp_f32_e64 v11, -v5
	v_add_u32_e32 v16, 0xb0, v170
	v_mad_i64_i32 v[16:17], s[34:35], v16, s82, v[142:143]
	v_lshl_add_u64 v[16:17], v[16:17], 0, v[140:141]
	global_store_dwordx2 v[16:17], v[8:9], off
	v_add_f32_e32 v8, 1.0, v10
	v_add_f32_e32 v9, 1.0, v11
	v_exp_f32_e64 v10, -v6
	v_exp_f32_e64 v11, -v7
	v_rcp_f32_e32 v8, v8
	v_rcp_f32_e32 v9, v9
	v_add_f32_e32 v10, 1.0, v10
	v_add_f32_e32 v11, 1.0, v11
	v_rcp_f32_e32 v10, v10
	v_rcp_f32_e32 v11, v11
	v_pk_mul_f32 v[2:3], v[6:7], v[2:3]
	v_pk_mul_f32 v[0:1], v[4:5], v[0:1]
	s_and_b64 vcc, exec, s[2:3]
	v_pk_mul_f32 v[0:1], v[0:1], v[8:9]
	v_pk_mul_f32 v[2:3], v[2:3], v[10:11]
	v_cvt_pk_bf16_f32 v0, v0, v1
	v_cvt_pk_bf16_f32 v1, v2, v3
	s_mov_b32 s86, s83
	s_mov_b32 s85, s84
	s_mov_b64 s[36:37], s[0:1]
	s_mov_b64 s[34:35], s[4:5]
	global_store_dwordx2 v[16:17], v[0:1], off offset:128
	s_cbranch_vccz .LBB0_344
	s_branch .Lgu2_done

; #define PG8_STAGE(bufoff, gbase, voff) do { _Pragma("unroll") for (int _i = 0; _i < 2; ++_i) \
;         __builtin_amdgcn_global_load_lds((const unsigned*)((const char*)(gbase) + (voff)[_i]), (PG8_LAS unsigned*)(lds + (bufoff) + ldsw + _i * 8192), 16, 0, 0); } while (0)
; #define PG8_LDA(dst, b, h) do { _Pragma("unroll") for (int m = 0; m < 4; ++m) _Pragma("unroll") for (int k = 0; k < 2; ++k) dst[m][k] = *(const PG8_LAS bf16x8*)(lds + PG8_SA(b, h) + aoff + m * 2048 + k * 1024); } while (0)
; #define PG8_BAR __builtin_amdgcn_s_barrier()
; template <class Epi, class Sched, bool STAMP = false>
; __device__ __forceinline__ void gemm_phase(PG8_LAS unsigned char* lds, const Gemm g, const Sched& S, const Epi& E, unsigned long long* stamps) {
;     ...
;         for (int t = 0; t < nt; t += 2) {
;             const bool last = (t == nt - 2);
;             const char* a1 = cA + (size_t)(t + 1) * kstep;
;             const char* a2 = last ? nA : cA + (size_t)(t + 2) * kstep; const char* b2 = last ? nB : cB + (size_t)(t + 2) * kstep;
;             const char* a3 = a2 + kstep; const char* b3 = b2 + kstep;
;             if (last && has_next) S.a_ready(nxt);
;             PG8_LDB(B0, 0, 0); PG8_SCHED; PG8_LDA(At, 0, 0); PG8_STAGE(PG8_SA(1, 1), a1 + hstep, voffA);
;             PG8_WAIT_L(8); PG8_BAR; PG8_WAIT_L(0); PG8_MMA(0, 0, At, B0); PG8_BAR; PG8_SCHED;
;             PG8_LDB(B1, 0, 1); PG8_STAGE(PG8_SB(0, 0), b2, voffB);
;             PG8_BAR; PG8_WAIT_L(0); PG8_MMA(0, 1, At, B1); PG8_BAR;
;             PG8_LDA(At, 0, 1); PG8_STAGE(PG8_SA(0, 0), a2, voffA);
;             PG8_BAR; PG8_WAIT_L(0); PG8_MMA(1, 0, At, B0); PG8_BAR; PG8_SCHED;
;             PG8_STAGE(PG8_SB(0, 1), b2 + hstep, voffB);
;             PG8_WAIT_V(6); PG8_BAR; PG8_MMA(1, 1, At, B1); PG8_BAR;
;             PG8_LDB(B0, 1, 0); PG8_SCHED; PG8_LDA(At, 1, 0); PG8_STAGE(PG8_SA(0, 1), a2 + hstep, voffA);
;             PG8_WAIT_L(8); PG8_BAR; PG8_WAIT_L(0); PG8_MMA(0, 0, At, B0); PG8_BAR; PG8_SCHED;
;             PG8_LDB(B1, 1, 1); PG8_STAGE(PG8_SB(1, 0), b3, voffB);
;             PG8_BAR; PG8_WAIT_L(0); PG8_MMA(0, 1, At, B1); PG8_BAR;
;             PG8_LDA(At, 1, 1); PG8_STAGE(PG8_SA(1, 0), a3, voffA);
;             PG8_BAR; PG8_WAIT_L(0); PG8_MMA(1, 0, At, B0); PG8_BAR; PG8_SCHED;
;             PG8_STAGE(PG8_SB(1, 1), b3 + hstep, voffB);
;             PG8_WAIT_V(6); PG8_BAR; PG8_MMA(1, 1, At, B1); PG8_BAR;
.Lgu2_half_loop:
	s_add_u32 s100, s87, 0x43f80
	s_addc_u32 s101, s88, 0
	s_mov_b32 m0, s75
	s_nop 0
	global_load_lds_dwordx4 v130, s[100:101]
	s_mov_b32 m0, s76
	s_nop 0
	global_load_lds_dwordx4 v128, s[100:101]
	ds_read_b128 v[140:143], v147
	ds_read_b128 v[170:173], v148
	ds_read_b128 v[174:177], v149
	ds_read_b128 v[178:181], v150
	s_add_u32 s36, s34, 0x100
	s_addc_u32 s37, s35, 0
	s_cmp_eq_u32 s89, 12
	s_cselect_b32 s55, s5, s37
	s_cselect_b32 s54, s4, s36
	s_cselect_b32 s53, s1, s88
	s_cselect_b32 s52, s0, s87
	s_mov_b32 m0, s78
	ds_read_b128 v[182:185], v145
	ds_read_b128 v[186:189], v145 offset:1024
	ds_read_b128 v[190:193], v145 offset:2048
	ds_read_b128 v[194:197], v145 offset:3072
	ds_read_b128 v[198:201], v145 offset:4096
	ds_read_b128 v[202:205], v145 offset:5120
	ds_read_b128 v[206:209], v145 offset:6144
	ds_read_b128 v[210:213], v145 offset:7168
	global_load_lds_dwordx4 v132, s[34:35]
	s_mov_b32 m0, s79
	s_nop 0
	global_load_lds_dwordx4 v134, s[34:35]
	s_waitcnt vmcnt(8)
	s_waitcnt lgkmcnt(0)
	s_barrier
	s_setprio 1
	v_mfma_f32_16x16x32_bf16 v[124:127], v[140:143], v[182:185], v[124:127]
	v_mfma_f32_16x16x32_bf16 v[120:123], v[174:177], v[182:185], v[120:123]
	v_mfma_f32_16x16x32_bf16 v[108:111], v[140:143], v[190:193], v[108:111]
	v_mfma_f32_16x16x32_bf16 v[104:107], v[174:177], v[190:193], v[104:107]
	v_mfma_f32_16x16x32_bf16 v[92:95], v[140:143], v[198:201], v[92:95]
	v_mfma_f32_16x16x32_bf16 v[88:91], v[174:177], v[198:201], v[88:91]
	v_mfma_f32_16x16x32_bf16 v[76:79], v[140:143], v[206:209], v[76:79]
	v_mfma_f32_16x16x32_bf16 v[72:75], v[174:177], v[206:209], v[72:75]
	v_mfma_f32_16x16x32_bf16 v[124:127], v[170:173], v[186:189], v[124:127]
	v_mfma_f32_16x16x32_bf16 v[120:123], v[178:181], v[186:189], v[120:123]
	v_mfma_f32_16x16x32_bf16 v[108:111], v[170:173], v[194:197], v[108:111]
	v_mfma_f32_16x16x32_bf16 v[104:107], v[178:181], v[194:197], v[104:107]
	v_mfma_f32_16x16x32_bf16 v[92:95], v[170:173], v[202:205], v[92:95]
	v_mfma_f32_16x16x32_bf16 v[88:91], v[178:181], v[202:205], v[88:91]
	v_mfma_f32_16x16x32_bf16 v[76:79], v[170:173], v[210:213], v[76:79]
	v_mfma_f32_16x16x32_bf16 v[72:75], v[178:181], v[210:213], v[72:75]
	s_setprio 0
	s_barrier
	s_mov_b32 m0, s61
	s_nop 0
	global_load_lds_dwordx4 v130, s[52:53]
	s_mov_b32 m0, s62
	s_nop 0
	global_load_lds_dwordx4 v128, s[52:53]
	s_mov_b32 m0, s58
	ds_read_b128 v[182:185], v145 offset:16384
	ds_read_b128 v[186:189], v145 offset:17408
	ds_read_b128 v[190:193], v145 offset:18432
	ds_read_b128 v[194:197], v145 offset:19456
	ds_read_b128 v[198:201], v145 offset:20480
	ds_read_b128 v[202:205], v145 offset:21504
	ds_read_b128 v[206:209], v145 offset:22528
	ds_read_b128 v[210:213], v145 offset:23552
	global_load_lds_dwordx4 v130, s[54:55]
	s_mov_b32 m0, s63
	s_nop 0
	global_load_lds_dwordx4 v128, s[54:55]
	s_waitcnt vmcnt(6)
	s_waitcnt lgkmcnt(0)
	s_barrier
	s_setprio 1
	v_mfma_f32_16x16x32_bf16 v[60:63], v[140:143], v[182:185], v[60:63]
	v_mfma_f32_16x16x32_bf16 v[56:59], v[174:177], v[182:185], v[56:59]
	v_mfma_f32_16x16x32_bf16 v[44:47], v[140:143], v[190:193], v[44:47]
	v_mfma_f32_16x16x32_bf16 v[40:43], v[174:177], v[190:193], v[40:43]
	v_mfma_f32_16x16x32_bf16 v[28:31], v[140:143], v[198:201], v[28:31]
	v_mfma_f32_16x16x32_bf16 v[24:27], v[174:177], v[198:201], v[24:27]
	v_mfma_f32_16x16x32_bf16 v[12:15], v[140:143], v[206:209], v[12:15]
	v_mfma_f32_16x16x32_bf16 v[8:11], v[174:177], v[206:209], v[8:11]
	v_mfma_f32_16x16x32_bf16 v[60:63], v[170:173], v[186:189], v[60:63]
	v_mfma_f32_16x16x32_bf16 v[56:59], v[178:181], v[186:189], v[56:59]
	v_mfma_f32_16x16x32_bf16 v[44:47], v[170:173], v[194:197], v[44:47]
	v_mfma_f32_16x16x32_bf16 v[40:43], v[178:181], v[194:197], v[40:43]
	v_mfma_f32_16x16x32_bf16 v[28:31], v[170:173], v[202:205], v[28:31]
	v_mfma_f32_16x16x32_bf16 v[24:27], v[178:181], v[202:205], v[24:27]
	v_mfma_f32_16x16x32_bf16 v[12:15], v[170:173], v[210:213], v[12:15]
	v_mfma_f32_16x16x32_bf16 v[8:11], v[178:181], v[210:213], v[8:11]
	s_setprio 0
	s_barrier
	s_add_u32 s34, s52, 0x44000
	s_addc_u32 s35, s53, 0
	s_mov_b32 m0, s64
	s_nop 0
	global_load_lds_dwordx4 v130, s[34:35]
	s_mov_b32 m0, s65
	s_nop 0
	global_load_lds_dwordx4 v128, s[34:35]
	ds_read_b128 v[140:143], v155
	ds_read_b128 v[170:173], v156
	ds_read_b128 v[174:177], v157
	ds_read_b128 v[178:181], v165
	s_add_u32 s34, s54, 0x44000
	s_addc_u32 s35, s55, 0
	s_mov_b32 m0, s66
	ds_read_b128 v[182:185], v145 offset:32768
	ds_read_b128 v[186:189], v145 offset:33792
	ds_read_b128 v[190:193], v145 offset:34816
	ds_read_b128 v[194:197], v145 offset:35840
	ds_read_b128 v[198:201], v145 offset:36864
	ds_read_b128 v[202:205], v145 offset:37888
	ds_read_b128 v[206:209], v145 offset:38912
	ds_read_b128 v[210:213], v145 offset:39936
	global_load_lds_dwordx4 v130, s[34:35]
	s_mov_b32 m0, s67
	s_nop 0
	global_load_lds_dwordx4 v128, s[34:35]
	s_waitcnt vmcnt(8)
	s_waitcnt lgkmcnt(0)
	s_barrier
	s_setprio 1
	v_mfma_f32_16x16x32_bf16 v[124:127], v[140:143], v[182:185], v[124:127]
	v_mfma_f32_16x16x32_bf16 v[120:123], v[174:177], v[182:185], v[120:123]
	v_mfma_f32_16x16x32_bf16 v[108:111], v[140:143], v[190:193], v[108:111]
	v_mfma_f32_16x16x32_bf16 v[104:107], v[174:177], v[190:193], v[104:107]
	v_mfma_f32_16x16x32_bf16 v[92:95], v[140:143], v[198:201], v[92:95]
	v_mfma_f32_16x16x32_bf16 v[88:91], v[174:177], v[198:201], v[88:91]
	v_mfma_f32_16x16x32_bf16 v[76:79], v[140:143], v[206:209], v[76:79]
	v_mfma_f32_16x16x32_bf16 v[72:75], v[174:177], v[206:209], v[72:75]
	v_mfma_f32_16x16x32_bf16 v[124:127], v[170:173], v[186:189], v[124:127]
	v_mfma_f32_16x16x32_bf16 v[120:123], v[178:181], v[186:189], v[120:123]
	v_mfma_f32_16x16x32_bf16 v[108:111], v[170:173], v[194:197], v[108:111]
	v_mfma_f32_16x16x32_bf16 v[104:107], v[178:181], v[194:197], v[104:107]
	v_mfma_f32_16x16x32_bf16 v[92:95], v[170:173], v[202:205], v[92:95]
	v_mfma_f32_16x16x32_bf16 v[88:91], v[178:181], v[202:205], v[88:91]
	v_mfma_f32_16x16x32_bf16 v[76:79], v[170:173], v[210:213], v[76:79]
	v_mfma_f32_16x16x32_bf16 v[72:75], v[178:181], v[210:213], v[72:75]
	s_setprio 0
	s_barrier
; #define PG8_STAGE(bufoff, gbase, voff) do { _Pragma("unroll") for (int _i = 0; _i < 2; ++_i) \
;         __builtin_amdgcn_global_load_lds((const unsigned*)((const char*)(gbase) + (voff)[_i]), (PG8_LAS unsigned*)(lds + (bufoff) + ldsw + _i * 8192), 16, 0, 0); } while (0)
; #define PG8_LDA(dst, b, h) do { _Pragma("unroll") for (int m = 0; m < 4; ++m) _Pragma("unroll") for (int k = 0; k < 2; ++k) dst[m][k] = *(const PG8_LAS bf16x8*)(lds + PG8_SA(b, h) + aoff + m * 2048 + k * 1024); } while (0)
; #define PG8_MMA(ai, bj, At, Bt) do { __builtin_amdgcn_s_setprio(1); _Pragma("unroll") for (int m = 0; m < 4; ++m) _Pragma("unroll") for (int n = 0; n < 2; ++n) _Pragma("unroll") for (int k = 0; k < 2; ++k) \
;         acc[ai][bj][m][n] = __builtin_amdgcn_mfma_f32_16x16x32_bf16(Bt[n][k], At[m][k], acc[ai][bj][m][n], 0, 0, 0); __builtin_amdgcn_s_setprio(0); } while (0)
; #define PG8_WAIT_V(n) asm volatile("s_waitcnt vmcnt(" #n ")" ::: "memory")
; #define PG8_WAIT_L(n) asm volatile("s_waitcnt lgkmcnt(" #n ")" ::: "memory")
; #define PG8_BAR __builtin_amdgcn_s_barrier()
; #define PG8_SCHED __builtin_amdgcn_sched_barrier(0)
; template <class Epi, class Sched, bool STAMP = false>
; __device__ __forceinline__ void gemm_phase(PG8_LAS unsigned char* lds, const Gemm g, const Sched& S, const Epi& E, unsigned long long* stamps) {
;     ...
;             PG8_LDA(At, 1, 1); PG8_STAGE(PG8_SA(1, 0), a3, voffA);
;             PG8_BAR; PG8_WAIT_L(0); PG8_MMA(1, 0, At, B0); PG8_BAR; PG8_SCHED;
;             PG8_STAGE(PG8_SB(1, 1), b3 + hstep, voffB);
;             PG8_WAIT_V(6); PG8_BAR; PG8_MMA(1, 1, At, B1); PG8_BAR;
;         }
	s_mov_b32 m0, s70
	s_add_u32 s100, s52, 0x80
	s_addc_u32 s101, s53, 0
	global_load_lds_dwordx4 v130, s[100:101]
	s_mov_b32 m0, s71
	s_nop 0
	global_load_lds_dwordx4 v128, s[100:101]
	s_mov_b32 m0, s73
	ds_read_b128 v[182:185], v145 offset:49152
	ds_read_b128 v[186:189], v145 offset:50176
	ds_read_b128 v[190:193], v145 offset:51200
	ds_read_b128 v[194:197], v145 offset:52224
	ds_read_b128 v[198:201], v145 offset:53248
	ds_read_b128 v[202:205], v145 offset:54272
	ds_read_b128 v[206:209], v145 offset:55296
	ds_read_b128 v[210:213], v145 offset:56320
	s_add_u32 s100, s54, 0x80
	s_addc_u32 s101, s55, 0
	global_load_lds_dwordx4 v130, s[100:101]
	s_mov_b32 m0, s74
	s_nop 0
	global_load_lds_dwordx4 v128, s[100:101]
	s_waitcnt vmcnt(6)
	s_waitcnt lgkmcnt(0)
	s_barrier
	s_setprio 1
	v_mfma_f32_16x16x32_bf16 v[60:63], v[140:143], v[182:185], v[60:63]
	v_mfma_f32_16x16x32_bf16 v[56:59], v[174:177], v[182:185], v[56:59]
	v_mfma_f32_16x16x32_bf16 v[44:47], v[140:143], v[190:193], v[44:47]
	v_mfma_f32_16x16x32_bf16 v[40:43], v[174:177], v[190:193], v[40:43]
	v_mfma_f32_16x16x32_bf16 v[28:31], v[140:143], v[198:201], v[28:31]
	v_mfma_f32_16x16x32_bf16 v[24:27], v[174:177], v[198:201], v[24:27]
	v_mfma_f32_16x16x32_bf16 v[12:15], v[140:143], v[206:209], v[12:15]
	v_mfma_f32_16x16x32_bf16 v[8:11], v[174:177], v[206:209], v[8:11]
	v_mfma_f32_16x16x32_bf16 v[60:63], v[170:173], v[186:189], v[60:63]
	v_mfma_f32_16x16x32_bf16 v[56:59], v[178:181], v[186:189], v[56:59]
	v_mfma_f32_16x16x32_bf16 v[44:47], v[170:173], v[194:197], v[44:47]
	v_mfma_f32_16x16x32_bf16 v[40:43], v[178:181], v[194:197], v[40:43]
	v_mfma_f32_16x16x32_bf16 v[28:31], v[170:173], v[202:205], v[28:31]
	v_mfma_f32_16x16x32_bf16 v[24:27], v[178:181], v[202:205], v[24:27]
	v_mfma_f32_16x16x32_bf16 v[12:15], v[170:173], v[210:213], v[12:15]
	v_mfma_f32_16x16x32_bf16 v[8:11], v[178:181], v[210:213], v[8:11]
	s_setprio 0
	s_add_i32 s89, s89, 2
	s_add_u32 s87, s87, 0x100
	s_addc_u32 s88, s88, 0
	s_cmp_gt_u32 s89, 13
	s_mov_b64 s[34:35], s[36:37]
	s_barrier
	s_cbranch_scc0 .Lgu2_half_loop
; DI float ex2(float x) { return __builtin_amdgcn_exp2f(x); }
;     DI void operator()(const f32x4 (&acc)[2][2][4][2], const Unit& u, int wr, int wc, int fr, int fq) const {
;         const int row0 = u.pm * BM + wr * 64 + fr, hcol0 = ((u.pn * BM + wc * 32) >> 1) + 4 * fq;
; #pragma unroll
;         for (int ai = 0; ai < 2; ++ai)
; #pragma unroll
;             for (int m = 0; m < 4; ++m) { u16* rowp = O + (size_t)(row0 + ai * HALF + m * 16) * ldc + hcol0;
; #pragma unroll
;                 for (int bj = 0; bj < 2; ++bj) { const f32x4 g = acc[ai][bj][m][0], up = acc[ai][bj][m][1]; float r[4];
; #pragma unroll
;                     for (int j = 0; j < 4; ++j) r[j] = g[j] * up[j] * __builtin_amdgcn_rcpf(1.f + ex2(-LOG2E * g[j]));
;                     uint2 w = {pack2(r[0], r[1]), pack2(r[2], r[3])}; *(uint2*)(rowp + bj * (HALF / 2)) = w; } }
;     }
	v_exp_f32_e64 v171, -v124
	v_exp_f32_e64 v175, -v125
	s_lshl_b32 s10, s86, 8
	v_add_f32_e32 v171, 1.0, v171
	v_rcp_f32_e32 v174, v171
	v_add_f32_e32 v171, 1.0, v175
	v_exp_f32_e64 v176, -v126
	v_exp_f32_e64 v177, -v127
	v_rcp_f32_e32 v175, v171
	v_add_f32_e32 v171, 1.0, v176
	v_rcp_f32_e32 v176, v171
	v_add_f32_e32 v171, 1.0, v177
	v_rcp_f32_e32 v177, v171
	v_pk_mul_f32 v[122:123], v[126:127], v[122:123]
	v_pk_mul_f32 v[120:121], v[124:125], v[120:121]
	s_or_b32 s10, s10, s69
	s_or_b32 s10, s10, s98
	v_pk_mul_f32 v[120:121], v[120:121], v[174:175]
	v_pk_mul_f32 v[122:123], v[122:123], v[176:177]
	s_ashr_i32 s10, s10, 1
	v_cvt_pk_bf16_f32 v120, v120, v121
	v_cvt_pk_bf16_f32 v121, v122, v123
	v_or_b32_e32 v140, s10, v146
	v_lshl_add_u32 v170, s85, 8, v144
	v_ashrrev_i32_e32 v141, 31, v140
	v_mov_b64_e32 v[142:143], s[12:13]
	v_mad_i64_i32 v[172:173], s[34:35], v170, s82, v[142:143]
	v_lshlrev_b64 v[140:141], 1, v[140:141]
	v_lshl_add_u64 v[172:173], v[172:173], 0, v[140:141]
	global_store_dwordx2 v[172:173], v[120:121], off
	v_exp_f32_e64 v114, -v108
	v_exp_f32_e64 v115, -v109
	v_exp_f32_e64 v116, -v110
	v_exp_f32_e64 v117, -v111
	v_add_f32_e32 v114, 1.0, v114
	v_add_f32_e32 v115, 1.0, v115
	v_add_f32_e32 v116, 1.0, v116
	v_add_f32_e32 v117, 1.0, v117
	v_rcp_f32_e32 v114, v114
	v_rcp_f32_e32 v115, v115
	v_rcp_f32_e32 v116, v116
	v_rcp_f32_e32 v117, v117
	v_pk_mul_f32 v[106:107], v[110:111], v[106:107]
	v_pk_mul_f32 v[104:105], v[108:109], v[104:105]
	v_pk_mul_f32 v[104:105], v[104:105], v[114:115]
	v_pk_mul_f32 v[106:107], v[106:107], v[116:117]
	v_cvt_pk_bf16_f32 v104, v104, v105
	v_cvt_pk_bf16_f32 v105, v106, v107
	v_or_b32_e32 v112, 16, v170
	v_mad_i64_i32 v[112:113], s[34:35], v112, s82, v[142:143]
	v_lshl_add_u64 v[112:113], v[112:113], 0, v[140:141]
	global_store_dwordx2 v[112:113], v[104:105], off
	v_exp_f32_e64 v98, -v92
	v_exp_f32_e64 v99, -v93
	v_exp_f32_e64 v100, -v94
	v_exp_f32_e64 v101, -v95
	v_add_f32_e32 v98, 1.0, v98
	v_add_f32_e32 v99, 1.0, v99
	v_add_f32_e32 v100, 1.0, v100
	v_add_f32_e32 v101, 1.0, v101
	v_rcp_f32_e32 v98, v98
	v_rcp_f32_e32 v99, v99
	v_rcp_f32_e32 v100, v100
	v_rcp_f32_e32 v101, v101
	v_pk_mul_f32 v[90:91], v[94:95], v[90:91]
	v_pk_mul_f32 v[88:89], v[92:93], v[88:89]
	v_pk_mul_f32 v[88:89], v[88:89], v[98:99]
	v_pk_mul_f32 v[90:91], v[90:91], v[100:101]
	v_cvt_pk_bf16_f32 v88, v88, v89
	v_cvt_pk_bf16_f32 v89, v90, v91
	v_or_b32_e32 v96, 32, v170
	v_mad_i64_i32 v[96:97], s[34:35], v96, s82, v[142:143]
	v_lshl_add_u64 v[96:97], v[96:97], 0, v[140:141]
	global_store_dwordx2 v[96:97], v[88:89], off
	v_exp_f32_e64 v82, -v76
	v_exp_f32_e64 v83, -v77
	v_exp_f32_e64 v84, -v78
	v_exp_f32_e64 v85, -v79
	v_add_f32_e32 v82, 1.0, v82
	v_add_f32_e32 v83, 1.0, v83
	v_add_f32_e32 v84, 1.0, v84
	v_add_f32_e32 v85, 1.0, v85
	v_rcp_f32_e32 v82, v82
	v_rcp_f32_e32 v83, v83
	v_rcp_f32_e32 v84, v84
	v_rcp_f32_e32 v85, v85
	v_pk_mul_f32 v[74:75], v[78:79], v[74:75]
	v_pk_mul_f32 v[72:73], v[76:77], v[72:73]
	v_pk_mul_f32 v[72:73], v[72:73], v[82:83]
	v_pk_mul_f32 v[74:75], v[74:75], v[84:85]
	v_cvt_pk_bf16_f32 v72, v72, v73
	v_cvt_pk_bf16_f32 v73, v74, v75
	v_or_b32_e32 v80, 48, v170
	v_mad_i64_i32 v[80:81], s[34:35], v80, s82, v[142:143]
	v_lshl_add_u64 v[80:81], v[80:81], 0, v[140:141]
	global_store_dwordx2 v[80:81], v[72:73], off
	v_exp_f32_e64 v66, -v60
	v_exp_f32_e64 v67, -v61
	v_exp_f32_e64 v68, -v62
	v_exp_f32_e64 v69, -v63
	v_add_f32_e32 v66, 1.0, v66
	v_add_f32_e32 v67, 1.0, v67
	v_add_f32_e32 v68, 1.0, v68
	v_add_f32_e32 v69, 1.0, v69
	v_rcp_f32_e32 v66, v66
	v_rcp_f32_e32 v67, v67
	v_rcp_f32_e32 v68, v68
	v_rcp_f32_e32 v69, v69
	v_pk_mul_f32 v[58:59], v[62:63], v[58:59]
	v_pk_mul_f32 v[56:57], v[60:61], v[56:57]
	v_pk_mul_f32 v[56:57], v[56:57], v[66:67]
	v_pk_mul_f32 v[58:59], v[58:59], v[68:69]
	v_cvt_pk_bf16_f32 v56, v56, v57
	v_cvt_pk_bf16_f32 v57, v58, v59
	v_add_u32_e32 v64, 0x80, v170
	v_mad_i64_i32 v[64:65], s[34:35], v64, s82, v[142:143]
	v_lshl_add_u64 v[64:65], v[64:65], 0, v[140:141]
	global_store_dwordx2 v[64:65], v[56:57], off
	v_exp_f32_e64 v50, -v44
	v_exp_f32_e64 v51, -v45
	v_exp_f32_e64 v52, -v46
	v_exp_f32_e64 v53, -v47
	v_add_f32_e32 v50, 1.0, v50
	v_add_f32_e32 v51, 1.0, v51
	v_add_f32_e32 v52, 1.0, v52
	v_add_f32_e32 v53, 1.0, v53
	v_rcp_f32_e32 v50, v50
	v_rcp_f32_e32 v51, v51
	v_rcp_f32_e32 v52, v52
	v_rcp_f32_e32 v53, v53
	v_pk_mul_f32 v[42:43], v[46:47], v[42:43]
	v_pk_mul_f32 v[40:41], v[44:45], v[40:41]
	v_pk_mul_f32 v[40:41], v[40:41], v[50:51]
	v_pk_mul_f32 v[42:43], v[42:43], v[52:53]
	v_cvt_pk_bf16_f32 v40, v40, v41
	v_cvt_pk_bf16_f32 v41, v42, v43
	v_add_u32_e32 v48, 0x90, v170
	v_mad_i64_i32 v[48:49], s[34:35], v48, s82, v[142:143]
	v_lshl_add_u64 v[48:49], v[48:49], 0, v[140:141]
	global_store_dwordx2 v[48:49], v[40:41], off
	v_exp_f32_e64 v34, -v28
	v_exp_f32_e64 v35, -v29
	v_exp_f32_e64 v36, -v30
	v_exp_f32_e64 v37, -v31
	v_add_f32_e32 v34, 1.0, v34
	v_add_f32_e32 v35, 1.0, v35
	v_add_f32_e32 v36, 1.0, v36
	v_add_f32_e32 v37, 1.0, v37
	v_rcp_f32_e32 v34, v34
	v_rcp_f32_e32 v35, v35
	v_rcp_f32_e32 v36, v36
	v_rcp_f32_e32 v37, v37
	v_pk_mul_f32 v[26:27], v[30:31], v[26:27]
	v_pk_mul_f32 v[24:25], v[28:29], v[24:25]
	v_pk_mul_f32 v[24:25], v[24:25], v[34:35]
	v_pk_mul_f32 v[26:27], v[26:27], v[36:37]
	v_cvt_pk_bf16_f32 v24, v24, v25
	v_cvt_pk_bf16_f32 v25, v26, v27
	v_add_u32_e32 v32, 0xa0, v170
	v_mad_i64_i32 v[32:33], s[34:35], v32, s82, v[142:143]
	v_lshl_add_u64 v[32:33], v[32:33], 0, v[140:141]
	global_store_dwordx2 v[32:33], v[24:25], off
	v_exp_f32_e64 v18, -v12
	v_exp_f32_e64 v19, -v13
	v_exp_f32_e64 v20, -v14
	v_exp_f32_e64 v21, -v15
	v_add_f32_e32 v18, 1.0, v18
	v_add_f32_e32 v19, 1.0, v19
	v_add_f32_e32 v20, 1.0, v20
	v_add_f32_e32 v21, 1.0, v21
	v_rcp_f32_e32 v18, v18
	v_rcp_f32_e32 v19, v19
	v_rcp_f32_e32 v20, v20
	v_rcp_f32_e32 v21, v21
	v_pk_mul_f32 v[10:11], v[14:15], v[10:11]
	v_pk_mul_f32 v[8:9], v[12:13], v[8:9]
	v_pk_mul_f32 v[8:9], v[8:9], v[18:19]
	v_pk_mul_f32 v[10:11], v[10:11], v[20:21]
	v_cvt_pk_bf16_f32 v8, v8, v9
	v_cvt_pk_bf16_f32 v9, v10, v11
	v_add_u32_e32 v16, 0xb0, v170
	v_mad_i64_i32 v[16:17], s[34:35], v16, s82, v[142:143]
	v_lshl_add_u64 v[16:17], v[16:17], 0, v[140:141]
	global_store_dwordx2 v[16:17], v[8:9], off
	s_and_b64 vcc, exec, s[2:3]
	s_mov_b32 s86, s83
	s_mov_b32 s85, s84
	s_mov_b64 s[36:37], s[0:1]
	s_mov_b64 s[34:35], s[4:5]

; #define PG8_STAGE(bufoff, gbase, voff) do { _Pragma("unroll") for (int _i = 0; _i < 2; ++_i) \
;         __builtin_amdgcn_global_load_lds((const unsigned*)((const char*)(gbase) + (voff)[_i]), (PG8_LAS unsigned*)(lds + (bufoff) + ldsw + _i * 8192), 16, 0, 0); } while (0)
; #define PG8_LDA(dst, b, h) do { _Pragma("unroll") for (int m = 0; m < 4; ++m) _Pragma("unroll") for (int k = 0; k < 2; ++k) dst[m][k] = *(const PG8_LAS bf16x8*)(lds + PG8_SA(b, h) + aoff + m * 2048 + k * 1024); } while (0)
; #define PG8_LDB(dst, b, h) do { _Pragma("unroll") for (int n = 0; n < 2; ++n) _Pragma("unroll") for (int k = 0; k < 2; ++k) dst[n][k] = *(const PG8_LAS bf16x8*)(lds + PG8_SB(b, h) + boff + n * 2048 + k * 1024); } while (0)
; #define PG8_MMA(ai, bj, At, Bt) do { __builtin_amdgcn_s_setprio(1); _Pragma("unroll") for (int m = 0; m < 4; ++m) _Pragma("unroll") for (int n = 0; n < 2; ++n) _Pragma("unroll") for (int k = 0; k < 2; ++k) \
;         acc[ai][bj][m][n] = __builtin_amdgcn_mfma_f32_16x16x32_bf16(Bt[n][k], At[m][k], acc[ai][bj][m][n], 0, 0, 0); __builtin_amdgcn_s_setprio(0); } while (0)
; #define PG8_BAR __builtin_amdgcn_s_barrier()
; template <class Epi, class Sched, bool STAMP = false>
; __device__ __forceinline__ void gemm_phase(PG8_LAS unsigned char* lds, const Gemm g, const Sched& S, const Epi& E, unsigned long long* stamps) {
;     ...
;         for (int t = 0; t < nt; t += 2) {
;             const bool last = (t == nt - 2);
;             const char* a1 = cA + (size_t)(t + 1) * kstep;
;             const char* a2 = last ? nA : cA + (size_t)(t + 2) * kstep; const char* b2 = last ? nB : cB + (size_t)(t + 2) * kstep;
;             const char* a3 = a2 + kstep; const char* b3 = b2 + kstep;
;             if (last && has_next) S.a_ready(nxt);
;             PG8_LDB(B0, 0, 0); PG8_SCHED; PG8_LDA(At, 0, 0); PG8_STAGE(PG8_SA(1, 1), a1 + hstep, voffA);
;             PG8_WAIT_L(8); PG8_BAR; PG8_WAIT_L(0); PG8_MMA(0, 0, At, B0); PG8_BAR; PG8_SCHED;
;             PG8_LDB(B1, 0, 1); PG8_STAGE(PG8_SB(0, 0), b2, voffB);
;             PG8_BAR; PG8_WAIT_L(0); PG8_MMA(0, 1, At, B1); PG8_BAR;
;             PG8_LDA(At, 0, 1); PG8_STAGE(PG8_SA(0, 0), a2, voffA);
;             PG8_BAR; PG8_WAIT_L(0); PG8_MMA(1, 0, At, B0); PG8_BAR; PG8_SCHED;
;             PG8_STAGE(PG8_SB(0, 1), b2 + hstep, voffB);
;             PG8_WAIT_V(6); PG8_BAR; PG8_MMA(1, 1, At, B1); PG8_BAR;
.LBB0_384:
	s_add_u32 vcc_lo, s58, 0x100
	s_addc_u32 vcc_hi, s59, 0
	s_mov_b32 s10, -2
	s_add_u32 s100, vcc_lo, 0xb3f80
	s_addc_u32 s101, vcc_hi, 0
	s_mov_b32 m0, s84
	s_nop 0
	global_load_lds_dwordx4 v130, s[100:101]
	s_mov_b32 m0, s85
	s_nop 0
	global_load_lds_dwordx4 v134, s[100:101]
	ds_read_b128 v[170:173], v147
	ds_read_b128 v[174:177], v148
	ds_read_b128 v[178:181], v149
	ds_read_b128 v[182:185], v150
	s_add_u32 s58, s56, 0x100
	s_addc_u32 s59, s57, 0
	s_cmp_eq_u32 s10, 40
	s_cselect_b32 s63, s5, s59
	s_cselect_b32 s62, s4, s58
	s_cselect_b32 s61, s1, vcc_hi
	s_cselect_b32 s60, s0, vcc_lo
	s_mov_b32 m0, s88
	ds_read_b128 v[186:189], v145
	ds_read_b128 v[190:193], v145 offset:1024
	ds_read_b128 v[194:197], v145 offset:2048
	ds_read_b128 v[198:201], v145 offset:3072
	ds_read_b128 v[202:205], v145 offset:4096
	ds_read_b128 v[206:209], v145 offset:5120
	ds_read_b128 v[210:213], v145 offset:6144
	ds_read_b128 v[214:217], v145 offset:7168
	global_load_lds_dwordx4 v136, s[56:57]
	s_mov_b32 m0, s89
	s_nop 0
	global_load_lds_dwordx4 v138, s[56:57]
	ds_read_b128 v[218:221], v151
	ds_read_b128 v[222:225], v152
	ds_read_b128 v[226:229], v153
	ds_read_b128 v[230:233], v154
	s_waitcnt vmcnt(8)
	s_waitcnt lgkmcnt(0)
	s_barrier
	s_setprio 1
	v_mfma_f32_16x16x32_bf16 v[124:127], v[170:173], v[186:189], 0
	v_mfma_f32_16x16x32_bf16 v[120:123], v[178:181], v[186:189], 0
	v_mfma_f32_16x16x32_bf16 v[116:119], v[170:173], v[194:197], 0
	v_mfma_f32_16x16x32_bf16 v[112:115], v[178:181], v[194:197], 0
	v_mfma_f32_16x16x32_bf16 v[100:103], v[170:173], v[202:205], 0
	v_mfma_f32_16x16x32_bf16 v[96:99], v[178:181], v[202:205], 0
	v_mfma_f32_16x16x32_bf16 v[84:87], v[170:173], v[210:213], 0
	v_mfma_f32_16x16x32_bf16 v[80:83], v[178:181], v[210:213], 0
	v_mfma_f32_16x16x32_bf16 v[124:127], v[174:177], v[190:193], v[124:127]
	v_mfma_f32_16x16x32_bf16 v[120:123], v[182:185], v[190:193], v[120:123]
	v_mfma_f32_16x16x32_bf16 v[116:119], v[174:177], v[198:201], v[116:119]
	v_mfma_f32_16x16x32_bf16 v[112:115], v[182:185], v[198:201], v[112:115]
	v_mfma_f32_16x16x32_bf16 v[100:103], v[174:177], v[206:209], v[100:103]
	v_mfma_f32_16x16x32_bf16 v[96:99], v[182:185], v[206:209], v[96:99]
	v_mfma_f32_16x16x32_bf16 v[84:87], v[174:177], v[214:217], v[84:87]
	v_mfma_f32_16x16x32_bf16 v[80:83], v[182:185], v[214:217], v[80:83]
	v_mfma_f32_16x16x32_bf16 v[108:111], v[218:221], v[186:189], 0
	v_mfma_f32_16x16x32_bf16 v[104:107], v[226:229], v[186:189], 0
	v_mfma_f32_16x16x32_bf16 v[92:95], v[218:221], v[194:197], 0
	v_mfma_f32_16x16x32_bf16 v[88:91], v[226:229], v[194:197], 0
	v_mfma_f32_16x16x32_bf16 v[76:79], v[218:221], v[202:205], 0
	v_mfma_f32_16x16x32_bf16 v[72:75], v[226:229], v[202:205], 0
	v_mfma_f32_16x16x32_bf16 v[68:71], v[218:221], v[210:213], 0
	v_mfma_f32_16x16x32_bf16 v[64:67], v[226:229], v[210:213], 0
	v_mfma_f32_16x16x32_bf16 v[108:111], v[222:225], v[190:193], v[108:111]
	v_mfma_f32_16x16x32_bf16 v[104:107], v[230:233], v[190:193], v[104:107]
	v_mfma_f32_16x16x32_bf16 v[92:95], v[222:225], v[198:201], v[92:95]
	v_mfma_f32_16x16x32_bf16 v[88:91], v[230:233], v[198:201], v[88:91]
	v_mfma_f32_16x16x32_bf16 v[76:79], v[222:225], v[206:209], v[76:79]
	v_mfma_f32_16x16x32_bf16 v[72:75], v[230:233], v[206:209], v[72:75]
	v_mfma_f32_16x16x32_bf16 v[68:71], v[222:225], v[214:217], v[68:71]
	v_mfma_f32_16x16x32_bf16 v[64:67], v[230:233], v[214:217], v[64:67]
	s_setprio 0
	s_barrier
	s_mov_b32 m0, s68
	s_nop 0
	global_load_lds_dwordx4 v130, s[60:61]
	s_mov_b32 m0, s69
	s_nop 0
	global_load_lds_dwordx4 v134, s[60:61]
	s_mov_b32 m0, s67
	ds_read_b128 v[186:189], v145 offset:16384
	ds_read_b128 v[190:193], v145 offset:17408
	ds_read_b128 v[194:197], v145 offset:18432
	ds_read_b128 v[198:201], v145 offset:19456
	ds_read_b128 v[202:205], v145 offset:20480
	ds_read_b128 v[206:209], v145 offset:21504
	ds_read_b128 v[210:213], v145 offset:22528
	ds_read_b128 v[214:217], v145 offset:23552
	global_load_lds_dwordx4 v128, s[62:63]
	s_mov_b32 m0, s70
	s_nop 0
	global_load_lds_dwordx4 v132, s[62:63]
	s_waitcnt vmcnt(6)
	s_waitcnt lgkmcnt(0)
	s_barrier
	s_setprio 1
	v_mfma_f32_16x16x32_bf16 v[60:63], v[170:173], v[186:189], 0
	v_mfma_f32_16x16x32_bf16 v[56:59], v[178:181], v[186:189], 0
	v_mfma_f32_16x16x32_bf16 v[52:55], v[170:173], v[194:197], 0
	v_mfma_f32_16x16x32_bf16 v[48:51], v[178:181], v[194:197], 0
	v_mfma_f32_16x16x32_bf16 v[36:39], v[170:173], v[202:205], 0
	v_mfma_f32_16x16x32_bf16 v[32:35], v[178:181], v[202:205], 0
	v_mfma_f32_16x16x32_bf16 v[20:23], v[170:173], v[210:213], 0
	v_mfma_f32_16x16x32_bf16 v[16:19], v[178:181], v[210:213], 0
	v_mfma_f32_16x16x32_bf16 v[60:63], v[174:177], v[190:193], v[60:63]
	v_mfma_f32_16x16x32_bf16 v[56:59], v[182:185], v[190:193], v[56:59]
	v_mfma_f32_16x16x32_bf16 v[52:55], v[174:177], v[198:201], v[52:55]
	v_mfma_f32_16x16x32_bf16 v[48:51], v[182:185], v[198:201], v[48:51]
	v_mfma_f32_16x16x32_bf16 v[36:39], v[174:177], v[206:209], v[36:39]
	v_mfma_f32_16x16x32_bf16 v[32:35], v[182:185], v[206:209], v[32:35]
	v_mfma_f32_16x16x32_bf16 v[20:23], v[174:177], v[214:217], v[20:23]
	v_mfma_f32_16x16x32_bf16 v[16:19], v[182:185], v[214:217], v[16:19]
	v_mfma_f32_16x16x32_bf16 v[44:47], v[218:221], v[186:189], 0
	v_mfma_f32_16x16x32_bf16 v[40:43], v[226:229], v[186:189], 0
	v_mfma_f32_16x16x32_bf16 v[28:31], v[218:221], v[194:197], 0
	v_mfma_f32_16x16x32_bf16 v[24:27], v[226:229], v[194:197], 0
	v_mfma_f32_16x16x32_bf16 v[12:15], v[218:221], v[202:205], 0
	v_mfma_f32_16x16x32_bf16 v[8:11], v[226:229], v[202:205], 0
	v_mfma_f32_16x16x32_bf16 v[4:7], v[218:221], v[210:213], 0
	v_mfma_f32_16x16x32_bf16 v[0:3], v[226:229], v[210:213], 0
	v_mfma_f32_16x16x32_bf16 v[44:47], v[222:225], v[190:193], v[44:47]
	v_mfma_f32_16x16x32_bf16 v[40:43], v[230:233], v[190:193], v[40:43]
	v_mfma_f32_16x16x32_bf16 v[28:31], v[222:225], v[198:201], v[28:31]
	v_mfma_f32_16x16x32_bf16 v[24:27], v[230:233], v[198:201], v[24:27]
	v_mfma_f32_16x16x32_bf16 v[12:15], v[222:225], v[206:209], v[12:15]
	v_mfma_f32_16x16x32_bf16 v[8:11], v[230:233], v[206:209], v[8:11]
	v_mfma_f32_16x16x32_bf16 v[4:7], v[222:225], v[214:217], v[4:7]
	v_mfma_f32_16x16x32_bf16 v[0:3], v[230:233], v[214:217], v[0:3]
	s_setprio 0
	s_barrier
	s_branch .Lzp6_mid
; #define PG8_STAGE(bufoff, gbase, voff) do { _Pragma("unroll") for (int _i = 0; _i < 2; ++_i) \
;         __builtin_amdgcn_global_load_lds((const unsigned*)((const char*)(gbase) + (voff)[_i]), (PG8_LAS unsigned*)(lds + (bufoff) + ldsw + _i * 8192), 16, 0, 0); } while (0)
; #define PG8_LDA(dst, b, h) do { _Pragma("unroll") for (int m = 0; m < 4; ++m) _Pragma("unroll") for (int k = 0; k < 2; ++k) dst[m][k] = *(const PG8_LAS bf16x8*)(lds + PG8_SA(b, h) + aoff + m * 2048 + k * 1024); } while (0)
; #define PG8_LDB(dst, b, h) do { _Pragma("unroll") for (int n = 0; n < 2; ++n) _Pragma("unroll") for (int k = 0; k < 2; ++k) dst[n][k] = *(const PG8_LAS bf16x8*)(lds + PG8_SB(b, h) + boff + n * 2048 + k * 1024); } while (0)
; #define PG8_MMA(ai, bj, At, Bt) do { __builtin_amdgcn_s_setprio(1); _Pragma("unroll") for (int m = 0; m < 4; ++m) _Pragma("unroll") for (int n = 0; n < 2; ++n) _Pragma("unroll") for (int k = 0; k < 2; ++k) \
;         acc[ai][bj][m][n] = __builtin_amdgcn_mfma_f32_16x16x32_bf16(Bt[n][k], At[m][k], acc[ai][bj][m][n], 0, 0, 0); __builtin_amdgcn_s_setprio(0); } while (0)
; #define PG8_BAR __builtin_amdgcn_s_barrier()
; template <class Epi, class Sched, bool STAMP = false>
; __device__ __forceinline__ void gemm_phase(PG8_LAS unsigned char* lds, const Gemm g, const Sched& S, const Epi& E, unsigned long long* stamps) {
;     ...
;         for (int t = 0; t < nt; t += 2) {
;             const bool last = (t == nt - 2);
;             const char* a1 = cA + (size_t)(t + 1) * kstep;
;             const char* a2 = last ? nA : cA + (size_t)(t + 2) * kstep; const char* b2 = last ? nB : cB + (size_t)(t + 2) * kstep;
;             const char* a3 = a2 + kstep; const char* b3 = b2 + kstep;
;             if (last && has_next) S.a_ready(nxt);
;             PG8_LDB(B0, 0, 0); PG8_SCHED; PG8_LDA(At, 0, 0); PG8_STAGE(PG8_SA(1, 1), a1 + hstep, voffA);
;             PG8_WAIT_L(8); PG8_BAR; PG8_WAIT_L(0); PG8_MMA(0, 0, At, B0); PG8_BAR; PG8_SCHED;
;             PG8_LDB(B1, 0, 1); PG8_STAGE(PG8_SB(0, 0), b2, voffB);
;             PG8_BAR; PG8_WAIT_L(0); PG8_MMA(0, 1, At, B1); PG8_BAR;
;             PG8_LDA(At, 0, 1); PG8_STAGE(PG8_SA(0, 0), a2, voffA);
;             PG8_BAR; PG8_WAIT_L(0); PG8_MMA(1, 0, At, B0); PG8_BAR; PG8_SCHED;
;             PG8_STAGE(PG8_SB(0, 1), b2 + hstep, voffB);
;             PG8_WAIT_V(6); PG8_BAR; PG8_MMA(1, 1, At, B1); PG8_BAR;
.LBB0_385:
	s_add_u32 s100, vcc_lo, 0xb3f80
	s_addc_u32 s101, vcc_hi, 0
	s_mov_b32 m0, s84
	s_nop 0
	global_load_lds_dwordx4 v130, s[100:101]
	s_mov_b32 m0, s85
	s_nop 0
	global_load_lds_dwordx4 v134, s[100:101]
	ds_read_b128 v[170:173], v147
	ds_read_b128 v[174:177], v148
	ds_read_b128 v[178:181], v149
	ds_read_b128 v[182:185], v150
	s_add_u32 s58, s56, 0x100
	s_addc_u32 s59, s57, 0
	s_cmp_eq_u32 s10, 40
	s_cselect_b32 s63, s5, s59
	s_cselect_b32 s62, s4, s58
	s_cselect_b32 s61, s1, vcc_hi
	s_cselect_b32 s60, s0, vcc_lo
	s_mov_b32 m0, s88
	ds_read_b128 v[186:189], v145
	ds_read_b128 v[190:193], v145 offset:1024
	ds_read_b128 v[194:197], v145 offset:2048
	ds_read_b128 v[198:201], v145 offset:3072
	ds_read_b128 v[202:205], v145 offset:4096
	ds_read_b128 v[206:209], v145 offset:5120
	ds_read_b128 v[210:213], v145 offset:6144
	ds_read_b128 v[214:217], v145 offset:7168
	global_load_lds_dwordx4 v136, s[56:57]
	s_mov_b32 m0, s89
	s_nop 0
	global_load_lds_dwordx4 v138, s[56:57]
	ds_read_b128 v[218:221], v151
	ds_read_b128 v[222:225], v152
	ds_read_b128 v[226:229], v153
	ds_read_b128 v[230:233], v154
	s_waitcnt vmcnt(8)
	s_waitcnt lgkmcnt(0)
	s_barrier
	s_setprio 1
	v_mfma_f32_16x16x32_bf16 v[124:127], v[170:173], v[186:189], v[124:127]
	v_mfma_f32_16x16x32_bf16 v[120:123], v[178:181], v[186:189], v[120:123]
	v_mfma_f32_16x16x32_bf16 v[116:119], v[170:173], v[194:197], v[116:119]
	v_mfma_f32_16x16x32_bf16 v[112:115], v[178:181], v[194:197], v[112:115]
	v_mfma_f32_16x16x32_bf16 v[100:103], v[170:173], v[202:205], v[100:103]
	v_mfma_f32_16x16x32_bf16 v[96:99], v[178:181], v[202:205], v[96:99]
	v_mfma_f32_16x16x32_bf16 v[84:87], v[170:173], v[210:213], v[84:87]
	v_mfma_f32_16x16x32_bf16 v[80:83], v[178:181], v[210:213], v[80:83]
	v_mfma_f32_16x16x32_bf16 v[124:127], v[174:177], v[190:193], v[124:127]
	v_mfma_f32_16x16x32_bf16 v[120:123], v[182:185], v[190:193], v[120:123]
	v_mfma_f32_16x16x32_bf16 v[116:119], v[174:177], v[198:201], v[116:119]
	v_mfma_f32_16x16x32_bf16 v[112:115], v[182:185], v[198:201], v[112:115]
	v_mfma_f32_16x16x32_bf16 v[100:103], v[174:177], v[206:209], v[100:103]
	v_mfma_f32_16x16x32_bf16 v[96:99], v[182:185], v[206:209], v[96:99]
	v_mfma_f32_16x16x32_bf16 v[84:87], v[174:177], v[214:217], v[84:87]
	v_mfma_f32_16x16x32_bf16 v[80:83], v[182:185], v[214:217], v[80:83]
	v_mfma_f32_16x16x32_bf16 v[108:111], v[218:221], v[186:189], v[108:111]
	v_mfma_f32_16x16x32_bf16 v[104:107], v[226:229], v[186:189], v[104:107]
	v_mfma_f32_16x16x32_bf16 v[92:95], v[218:221], v[194:197], v[92:95]
	v_mfma_f32_16x16x32_bf16 v[88:91], v[226:229], v[194:197], v[88:91]
	v_mfma_f32_16x16x32_bf16 v[76:79], v[218:221], v[202:205], v[76:79]
	v_mfma_f32_16x16x32_bf16 v[72:75], v[226:229], v[202:205], v[72:75]
	v_mfma_f32_16x16x32_bf16 v[68:71], v[218:221], v[210:213], v[68:71]
	v_mfma_f32_16x16x32_bf16 v[64:67], v[226:229], v[210:213], v[64:67]
	v_mfma_f32_16x16x32_bf16 v[108:111], v[222:225], v[190:193], v[108:111]
	v_mfma_f32_16x16x32_bf16 v[104:107], v[230:233], v[190:193], v[104:107]
	v_mfma_f32_16x16x32_bf16 v[92:95], v[222:225], v[198:201], v[92:95]
	v_mfma_f32_16x16x32_bf16 v[88:91], v[230:233], v[198:201], v[88:91]
	v_mfma_f32_16x16x32_bf16 v[76:79], v[222:225], v[206:209], v[76:79]
	v_mfma_f32_16x16x32_bf16 v[72:75], v[230:233], v[206:209], v[72:75]
	v_mfma_f32_16x16x32_bf16 v[68:71], v[222:225], v[214:217], v[68:71]
	v_mfma_f32_16x16x32_bf16 v[64:67], v[230:233], v[214:217], v[64:67]
	s_setprio 0
	s_barrier
	s_mov_b32 m0, s68
	s_nop 0
	global_load_lds_dwordx4 v130, s[60:61]
	s_mov_b32 m0, s69
	s_nop 0
	global_load_lds_dwordx4 v134, s[60:61]
	s_mov_b32 m0, s67
	ds_read_b128 v[186:189], v145 offset:16384
	ds_read_b128 v[190:193], v145 offset:17408
	ds_read_b128 v[194:197], v145 offset:18432
	ds_read_b128 v[198:201], v145 offset:19456
	ds_read_b128 v[202:205], v145 offset:20480
	ds_read_b128 v[206:209], v145 offset:21504
	ds_read_b128 v[210:213], v145 offset:22528
	ds_read_b128 v[214:217], v145 offset:23552
	global_load_lds_dwordx4 v128, s[62:63]
	s_mov_b32 m0, s70
	s_nop 0
	global_load_lds_dwordx4 v132, s[62:63]
	s_waitcnt vmcnt(6)
	s_waitcnt lgkmcnt(0)
	s_barrier
	s_setprio 1
	v_mfma_f32_16x16x32_bf16 v[60:63], v[170:173], v[186:189], v[60:63]
	v_mfma_f32_16x16x32_bf16 v[56:59], v[178:181], v[186:189], v[56:59]
	v_mfma_f32_16x16x32_bf16 v[52:55], v[170:173], v[194:197], v[52:55]
	v_mfma_f32_16x16x32_bf16 v[48:51], v[178:181], v[194:197], v[48:51]
	v_mfma_f32_16x16x32_bf16 v[36:39], v[170:173], v[202:205], v[36:39]
	v_mfma_f32_16x16x32_bf16 v[32:35], v[178:181], v[202:205], v[32:35]
	v_mfma_f32_16x16x32_bf16 v[20:23], v[170:173], v[210:213], v[20:23]
	v_mfma_f32_16x16x32_bf16 v[16:19], v[178:181], v[210:213], v[16:19]
	v_mfma_f32_16x16x32_bf16 v[60:63], v[174:177], v[190:193], v[60:63]
	v_mfma_f32_16x16x32_bf16 v[56:59], v[182:185], v[190:193], v[56:59]
	v_mfma_f32_16x16x32_bf16 v[52:55], v[174:177], v[198:201], v[52:55]
	v_mfma_f32_16x16x32_bf16 v[48:51], v[182:185], v[198:201], v[48:51]
	v_mfma_f32_16x16x32_bf16 v[36:39], v[174:177], v[206:209], v[36:39]
	v_mfma_f32_16x16x32_bf16 v[32:35], v[182:185], v[206:209], v[32:35]
	v_mfma_f32_16x16x32_bf16 v[20:23], v[174:177], v[214:217], v[20:23]
	v_mfma_f32_16x16x32_bf16 v[16:19], v[182:185], v[214:217], v[16:19]
	v_mfma_f32_16x16x32_bf16 v[44:47], v[218:221], v[186:189], v[44:47]
	v_mfma_f32_16x16x32_bf16 v[40:43], v[226:229], v[186:189], v[40:43]
	v_mfma_f32_16x16x32_bf16 v[28:31], v[218:221], v[194:197], v[28:31]
	v_mfma_f32_16x16x32_bf16 v[24:27], v[226:229], v[194:197], v[24:27]
	v_mfma_f32_16x16x32_bf16 v[12:15], v[218:221], v[202:205], v[12:15]
	v_mfma_f32_16x16x32_bf16 v[8:11], v[226:229], v[202:205], v[8:11]
	v_mfma_f32_16x16x32_bf16 v[4:7], v[218:221], v[210:213], v[4:7]
	v_mfma_f32_16x16x32_bf16 v[0:3], v[226:229], v[210:213], v[0:3]
	v_mfma_f32_16x16x32_bf16 v[44:47], v[222:225], v[190:193], v[44:47]
	v_mfma_f32_16x16x32_bf16 v[40:43], v[230:233], v[190:193], v[40:43]
	v_mfma_f32_16x16x32_bf16 v[28:31], v[222:225], v[198:201], v[28:31]
	v_mfma_f32_16x16x32_bf16 v[24:27], v[230:233], v[198:201], v[24:27]
	v_mfma_f32_16x16x32_bf16 v[12:15], v[222:225], v[206:209], v[12:15]
	v_mfma_f32_16x16x32_bf16 v[8:11], v[230:233], v[206:209], v[8:11]
	v_mfma_f32_16x16x32_bf16 v[4:7], v[222:225], v[214:217], v[4:7]
	v_mfma_f32_16x16x32_bf16 v[0:3], v[230:233], v[214:217], v[0:3]
	s_setprio 0
	s_barrier
; #define PG8_STAGE(bufoff, gbase, voff) do { _Pragma("unroll") for (int _i = 0; _i < 2; ++_i) \
;         __builtin_amdgcn_global_load_lds((const unsigned*)((const char*)(gbase) + (voff)[_i]), (PG8_LAS unsigned*)(lds + (bufoff) + ldsw + _i * 8192), 16, 0, 0); } while (0)
; #define PG8_LDA(dst, b, h) do { _Pragma("unroll") for (int m = 0; m < 4; ++m) _Pragma("unroll") for (int k = 0; k < 2; ++k) dst[m][k] = *(const PG8_LAS bf16x8*)(lds + PG8_SA(b, h) + aoff + m * 2048 + k * 1024); } while (0)
; #define PG8_LDB(dst, b, h) do { _Pragma("unroll") for (int n = 0; n < 2; ++n) _Pragma("unroll") for (int k = 0; k < 2; ++k) dst[n][k] = *(const PG8_LAS bf16x8*)(lds + PG8_SB(b, h) + boff + n * 2048 + k * 1024); } while (0)
; #define PG8_MMA(ai, bj, At, Bt) do { __builtin_amdgcn_s_setprio(1); _Pragma("unroll") for (int m = 0; m < 4; ++m) _Pragma("unroll") for (int n = 0; n < 2; ++n) _Pragma("unroll") for (int k = 0; k < 2; ++k) \
;         acc[ai][bj][m][n] = __builtin_amdgcn_mfma_f32_16x16x32_bf16(Bt[n][k], At[m][k], acc[ai][bj][m][n], 0, 0, 0); __builtin_amdgcn_s_setprio(0); } while (0)
; #define PG8_WAIT_V(n) asm volatile("s_waitcnt vmcnt(" #n ")" ::: "memory")
; #define PG8_WAIT_L(n) asm volatile("s_waitcnt lgkmcnt(" #n ")" ::: "memory")
; #define PG8_BAR __builtin_amdgcn_s_barrier()
; #define PG8_SCHED __builtin_amdgcn_sched_barrier(0)
; template <class Epi, class Sched, bool STAMP = false>
; __device__ __forceinline__ void gemm_phase(PG8_LAS unsigned char* lds, const Gemm g, const Sched& S, const Epi& E, unsigned long long* stamps) {
;     ...
;             PG8_LDB(B0, 1, 0); PG8_SCHED; PG8_LDA(At, 1, 0); PG8_STAGE(PG8_SA(0, 1), a2 + hstep, voffA);
;             PG8_WAIT_L(8); PG8_BAR; PG8_WAIT_L(0); PG8_MMA(0, 0, At, B0); PG8_BAR; PG8_SCHED;
;             PG8_LDB(B1, 1, 1); PG8_STAGE(PG8_SB(1, 0), b3, voffB);
;             PG8_BAR; PG8_WAIT_L(0); PG8_MMA(0, 1, At, B1); PG8_BAR;
;             PG8_LDA(At, 1, 1); PG8_STAGE(PG8_SA(1, 0), a3, voffA);
;             PG8_BAR; PG8_WAIT_L(0); PG8_MMA(1, 0, At, B0); PG8_BAR; PG8_SCHED;
;             PG8_STAGE(PG8_SB(1, 1), b3 + hstep, voffB);
;             PG8_WAIT_V(6); PG8_BAR; PG8_MMA(1, 1, At, B1); PG8_BAR;
;         }
.Lzp6_mid:
	s_add_u32 s56, s60, 0xb4000
	s_addc_u32 s57, s61, 0
	s_mov_b32 m0, s71
	s_nop 0
	global_load_lds_dwordx4 v130, s[56:57]
	s_mov_b32 m0, s75
	s_nop 0
	global_load_lds_dwordx4 v134, s[56:57]
	ds_read_b128 v[170:173], v155
	ds_read_b128 v[174:177], v156
	ds_read_b128 v[178:181], v157
	ds_read_b128 v[182:185], v165
	s_add_u32 s56, s62, 0xb4000
	s_addc_u32 s57, s63, 0
	s_mov_b32 m0, s76
	ds_read_b128 v[186:189], v145 offset:32768
	ds_read_b128 v[190:193], v145 offset:33792
	ds_read_b128 v[194:197], v145 offset:34816
	ds_read_b128 v[198:201], v145 offset:35840
	ds_read_b128 v[202:205], v145 offset:36864
	ds_read_b128 v[206:209], v145 offset:37888
	ds_read_b128 v[210:213], v145 offset:38912
	ds_read_b128 v[214:217], v145 offset:39936
	global_load_lds_dwordx4 v128, s[56:57]
	s_mov_b32 m0, s77
	s_nop 0
	global_load_lds_dwordx4 v132, s[56:57]
	ds_read_b128 v[218:221], v166
	ds_read_b128 v[222:225], v167
	ds_read_b128 v[226:229], v168
	ds_read_b128 v[230:233], v169
	s_waitcnt vmcnt(8)
	s_waitcnt lgkmcnt(0)
	s_barrier
	s_setprio 1
	v_mfma_f32_16x16x32_bf16 v[124:127], v[170:173], v[186:189], v[124:127]
	v_mfma_f32_16x16x32_bf16 v[120:123], v[178:181], v[186:189], v[120:123]
	v_mfma_f32_16x16x32_bf16 v[116:119], v[170:173], v[194:197], v[116:119]
	v_mfma_f32_16x16x32_bf16 v[112:115], v[178:181], v[194:197], v[112:115]
	v_mfma_f32_16x16x32_bf16 v[100:103], v[170:173], v[202:205], v[100:103]
	v_mfma_f32_16x16x32_bf16 v[96:99], v[178:181], v[202:205], v[96:99]
	v_mfma_f32_16x16x32_bf16 v[84:87], v[170:173], v[210:213], v[84:87]
	v_mfma_f32_16x16x32_bf16 v[80:83], v[178:181], v[210:213], v[80:83]
	v_mfma_f32_16x16x32_bf16 v[124:127], v[174:177], v[190:193], v[124:127]
	v_mfma_f32_16x16x32_bf16 v[120:123], v[182:185], v[190:193], v[120:123]
	v_mfma_f32_16x16x32_bf16 v[116:119], v[174:177], v[198:201], v[116:119]
	v_mfma_f32_16x16x32_bf16 v[112:115], v[182:185], v[198:201], v[112:115]
	v_mfma_f32_16x16x32_bf16 v[100:103], v[174:177], v[206:209], v[100:103]
	v_mfma_f32_16x16x32_bf16 v[96:99], v[182:185], v[206:209], v[96:99]
	v_mfma_f32_16x16x32_bf16 v[84:87], v[174:177], v[214:217], v[84:87]
	v_mfma_f32_16x16x32_bf16 v[80:83], v[182:185], v[214:217], v[80:83]
	v_mfma_f32_16x16x32_bf16 v[108:111], v[218:221], v[186:189], v[108:111]
	v_mfma_f32_16x16x32_bf16 v[104:107], v[226:229], v[186:189], v[104:107]
	v_mfma_f32_16x16x32_bf16 v[92:95], v[218:221], v[194:197], v[92:95]
	v_mfma_f32_16x16x32_bf16 v[88:91], v[226:229], v[194:197], v[88:91]
	v_mfma_f32_16x16x32_bf16 v[76:79], v[218:221], v[202:205], v[76:79]
	v_mfma_f32_16x16x32_bf16 v[72:75], v[226:229], v[202:205], v[72:75]
	v_mfma_f32_16x16x32_bf16 v[68:71], v[218:221], v[210:213], v[68:71]
	v_mfma_f32_16x16x32_bf16 v[64:67], v[226:229], v[210:213], v[64:67]
	v_mfma_f32_16x16x32_bf16 v[108:111], v[222:225], v[190:193], v[108:111]
	v_mfma_f32_16x16x32_bf16 v[104:107], v[230:233], v[190:193], v[104:107]
	v_mfma_f32_16x16x32_bf16 v[92:95], v[222:225], v[198:201], v[92:95]
	v_mfma_f32_16x16x32_bf16 v[88:91], v[230:233], v[198:201], v[88:91]
	v_mfma_f32_16x16x32_bf16 v[76:79], v[222:225], v[206:209], v[76:79]
	v_mfma_f32_16x16x32_bf16 v[72:75], v[230:233], v[206:209], v[72:75]
	v_mfma_f32_16x16x32_bf16 v[68:71], v[222:225], v[214:217], v[68:71]
	v_mfma_f32_16x16x32_bf16 v[64:67], v[230:233], v[214:217], v[64:67]
	s_setprio 0
	s_barrier
	s_mov_b32 m0, s78
	s_add_u32 s100, s60, 0x80
	s_addc_u32 s101, s61, 0
	global_load_lds_dwordx4 v130, s[100:101]
	s_mov_b32 m0, s79
	s_nop 0
	global_load_lds_dwordx4 v134, s[100:101]
	s_mov_b32 m0, s82
	ds_read_b128 v[186:189], v145 offset:49152
	ds_read_b128 v[190:193], v145 offset:50176
	ds_read_b128 v[194:197], v145 offset:51200
	ds_read_b128 v[198:201], v145 offset:52224
	ds_read_b128 v[202:205], v145 offset:53248
	ds_read_b128 v[206:209], v145 offset:54272
	ds_read_b128 v[210:213], v145 offset:55296
	ds_read_b128 v[214:217], v145 offset:56320
	s_add_u32 s100, s62, 0x80
	s_addc_u32 s101, s63, 0
	global_load_lds_dwordx4 v128, s[100:101]
	s_mov_b32 m0, s83
	s_nop 0
	global_load_lds_dwordx4 v132, s[100:101]
	s_waitcnt vmcnt(6)
	s_waitcnt lgkmcnt(0)
	s_barrier
	s_setprio 1
	v_mfma_f32_16x16x32_bf16 v[60:63], v[170:173], v[186:189], v[60:63]
	v_mfma_f32_16x16x32_bf16 v[56:59], v[178:181], v[186:189], v[56:59]
	v_mfma_f32_16x16x32_bf16 v[52:55], v[170:173], v[194:197], v[52:55]
	v_mfma_f32_16x16x32_bf16 v[48:51], v[178:181], v[194:197], v[48:51]
	v_mfma_f32_16x16x32_bf16 v[36:39], v[170:173], v[202:205], v[36:39]
	v_mfma_f32_16x16x32_bf16 v[32:35], v[178:181], v[202:205], v[32:35]
	v_mfma_f32_16x16x32_bf16 v[20:23], v[170:173], v[210:213], v[20:23]
	v_mfma_f32_16x16x32_bf16 v[16:19], v[178:181], v[210:213], v[16:19]
	v_mfma_f32_16x16x32_bf16 v[60:63], v[174:177], v[190:193], v[60:63]
	v_mfma_f32_16x16x32_bf16 v[56:59], v[182:185], v[190:193], v[56:59]
	v_mfma_f32_16x16x32_bf16 v[52:55], v[174:177], v[198:201], v[52:55]
	v_mfma_f32_16x16x32_bf16 v[48:51], v[182:185], v[198:201], v[48:51]
	v_mfma_f32_16x16x32_bf16 v[36:39], v[174:177], v[206:209], v[36:39]
	v_mfma_f32_16x16x32_bf16 v[32:35], v[182:185], v[206:209], v[32:35]
	v_mfma_f32_16x16x32_bf16 v[20:23], v[174:177], v[214:217], v[20:23]
	v_mfma_f32_16x16x32_bf16 v[16:19], v[182:185], v[214:217], v[16:19]
	v_mfma_f32_16x16x32_bf16 v[44:47], v[218:221], v[186:189], v[44:47]
	v_mfma_f32_16x16x32_bf16 v[40:43], v[226:229], v[186:189], v[40:43]
	v_mfma_f32_16x16x32_bf16 v[28:31], v[218:221], v[194:197], v[28:31]
	v_mfma_f32_16x16x32_bf16 v[24:27], v[226:229], v[194:197], v[24:27]
	v_mfma_f32_16x16x32_bf16 v[12:15], v[218:221], v[202:205], v[12:15]
	v_mfma_f32_16x16x32_bf16 v[8:11], v[226:229], v[202:205], v[8:11]
	v_mfma_f32_16x16x32_bf16 v[4:7], v[218:221], v[210:213], v[4:7]
	v_mfma_f32_16x16x32_bf16 v[0:3], v[226:229], v[210:213], v[0:3]
	v_mfma_f32_16x16x32_bf16 v[44:47], v[222:225], v[190:193], v[44:47]
	v_mfma_f32_16x16x32_bf16 v[40:43], v[230:233], v[190:193], v[40:43]
	v_mfma_f32_16x16x32_bf16 v[28:31], v[222:225], v[198:201], v[28:31]
	v_mfma_f32_16x16x32_bf16 v[24:27], v[230:233], v[198:201], v[24:27]
	v_mfma_f32_16x16x32_bf16 v[12:15], v[222:225], v[206:209], v[12:15]
	v_mfma_f32_16x16x32_bf16 v[8:11], v[230:233], v[206:209], v[8:11]
	v_mfma_f32_16x16x32_bf16 v[4:7], v[222:225], v[214:217], v[4:7]
	v_mfma_f32_16x16x32_bf16 v[0:3], v[230:233], v[214:217], v[0:3]
	s_setprio 0
	s_add_i32 s10, s10, 2
	s_add_u32 vcc_lo, vcc_lo, 0x100
	s_addc_u32 vcc_hi, vcc_hi, 0
	s_cmp_gt_u32 s10, 41
	s_mov_b64 s[56:57], s[58:59]
	s_barrier
; #define PG8_STAMP() do { if (STAMP && wid == 0 && nts < 64) { const unsigned long long _c = 0ull; \
;         ts_lo = (lane == nts) ? (int)(unsigned)_c : ts_lo; ts_hi = (lane == nts) ? (int)(unsigned)(_c >> 32) : ts_hi; ++nts; } } while (0)
; #define PG8_WAIT_V(n) asm volatile("s_waitcnt vmcnt(" #n ")" ::: "memory")
; #define PG8_BAR __builtin_amdgcn_s_barrier()
;     DI void operator()(const f32x4 (&acc)[2][2][4][2], const Unit& u, int wr, int wc, int fr, int fq) const {
;         const int row0 = u.pm * BM + wr * 64 + fr, col0 = u.pn * BM + wc * 32 + 8 * fq;
; #pragma unroll
;         for (int ai = 0; ai < 2; ++ai)
; #pragma unroll
;             for (int m = 0; m < 4; ++m) { u16* rowp = O + (size_t)(row0 + ai * HALF + m * 16) * ldc + col0;
; #pragma unroll
;                 for (int bj = 0; bj < 2; ++bj) { const f32x4 v0 = acc[ai][bj][m][0], v1 = acc[ai][bj][m][1];
;                     uint4 w = {pack2(v0[0], v0[1]), pack2(v0[2], v0[3]), pack2(v1[0], v1[1]), pack2(v1[2], v1[3])}; *(uint4*)(rowp + bj * HALF) = w; } }
; template <class Epi, class Sched, bool STAMP = false>
; __device__ __forceinline__ void gemm_phase(PG8_LAS unsigned char* lds, const Gemm g, const Sched& S, const Epi& E, unsigned long long* stamps) {
;     ...
;         if constexpr (!Epi::AFTER_DRAIN) { E(acc, cur, wr, wc, fr, fq); S.done(cur); }
;         PG8_STAMP();
;         if (!has_next) break;
; #pragma unroll
;         for (int a = 0; a < 2; ++a)
; #pragma unroll
;             for (int b = 0; b < 2; ++b)
; #pragma unroll
;                 for (int m = 0; m < 4; ++m)
; #pragma unroll
;                     for (int n = 0; n < 2; ++n) acc[a][b][m][n] = (f32x4){0.f, 0.f, 0.f, 0.f};
;         cur = nxt; cA = nA; cB = nB; ++ui;
;     }
;     PG8_WAIT_V(0);
;     if (wr == 0) PG8_BAR;
;     PG8_BAR;
	s_cbranch_scc0 .LBB0_385
	v_lshl_add_u32 v170, s94, 8, v144
	v_lshl_or_b32 v172, s97, 8, v146
	v_ashrrev_i32_e32 v171, 31, v170
	v_ashrrev_i32_e32 v173, 31, v172
	v_lshlrev_b64 v[174:175], 11, v[170:171]
	v_lshl_add_u64 v[174:175], s[14:15], 0, v[174:175]
	v_lshlrev_b64 v[172:173], 1, v[172:173]
	v_lshl_add_u64 v[174:175], v[174:175], 0, v[172:173]
	v_cvt_pk_bf16_f32 v60, v60, v61
	v_cvt_pk_bf16_f32 v61, v62, v63
	v_cvt_pk_bf16_f32 v62, v56, v57
	v_add_co_u32_e32 v56, vcc, s90, v174
	v_cvt_pk_bf16_f32 v68, v68, v69
	v_cvt_pk_bf16_f32 v69, v70, v71
	v_cvt_pk_bf16_f32 v70, v64, v65
	v_lshl_add_u64 v[64:65], v[174:175], 0, s[34:35]
	v_addc_co_u32_e32 v57, vcc, 0, v175, vcc
	v_cvt_pk_bf16_f32 v44, v44, v45
	v_cvt_pk_bf16_f32 v45, v46, v47
	v_cvt_pk_bf16_f32 v46, v40, v41
	v_cvt_pk_bf16_f32 v47, v42, v43
	v_cvt_pk_bf16_f32 v108, v108, v109
	v_cvt_pk_bf16_f32 v109, v110, v111
	v_cvt_pk_bf16_f32 v110, v104, v105
	v_or_b32_e32 v104, 16, v170
	global_store_dwordx4 v[64:65], v[44:47], off offset:256
	v_ashrrev_i32_e32 v105, 31, v104
	v_cvt_pk_bf16_f32 v92, v92, v93
	v_add_co_u32_e32 v46, vcc, s91, v174
	v_cvt_pk_bf16_f32 v93, v94, v95
	v_cvt_pk_bf16_f32 v94, v88, v89
	v_or_b32_e32 v88, 32, v170
	v_lshl_add_u64 v[44:45], v[174:175], 0, s[36:37]
	v_addc_co_u32_e32 v47, vcc, 0, v175, vcc
	v_cvt_pk_bf16_f32 v28, v28, v29
	v_cvt_pk_bf16_f32 v29, v30, v31
	v_cvt_pk_bf16_f32 v30, v24, v25
	v_cvt_pk_bf16_f32 v31, v26, v27
	v_lshlrev_b64 v[104:105], 11, v[104:105]
	v_ashrrev_i32_e32 v89, 31, v88
	v_cvt_pk_bf16_f32 v76, v76, v77
	v_cvt_pk_bf16_f32 v77, v78, v79
	v_cvt_pk_bf16_f32 v78, v72, v73
	v_or_b32_e32 v72, 48, v170
	global_store_dwordx4 v[44:45], v[28:31], off offset:256
	v_cvt_pk_bf16_f32 v111, v106, v107
	v_lshl_add_u64 v[104:105], s[14:15], 0, v[104:105]
	v_add_co_u32_e32 v30, vcc, s92, v174
	v_lshlrev_b64 v[88:89], 11, v[88:89]
	v_ashrrev_i32_e32 v73, 31, v72
	v_lshl_add_u64 v[28:29], v[174:175], 0, s[52:53]
	v_addc_co_u32_e32 v31, vcc, 0, v175, vcc
	v_cvt_pk_bf16_f32 v12, v12, v13
	v_cvt_pk_bf16_f32 v13, v14, v15
	v_cvt_pk_bf16_f32 v14, v8, v9
	v_cvt_pk_bf16_f32 v15, v10, v11
	global_store_dwordx4 v[174:175], v[108:111], off offset:256
	v_cvt_pk_bf16_f32 v95, v90, v91
	v_lshl_add_u64 v[88:89], s[14:15], 0, v[88:89]
	v_lshl_add_u64 v[108:109], v[104:105], 0, v[172:173]
	v_lshlrev_b64 v[72:73], 11, v[72:73]
	global_store_dwordx4 v[28:29], v[12:15], off offset:256
	global_store_dwordx4 v[108:109], v[92:95], off offset:256
	v_cvt_pk_bf16_f32 v79, v74, v75
	v_add_co_u32_e32 v14, vcc, s93, v174
	v_lshl_add_u64 v[92:93], v[88:89], 0, v[172:173]
	v_lshl_add_u64 v[72:73], s[14:15], 0, v[72:73]
	v_addc_co_u32_e32 v15, vcc, 0, v175, vcc
	v_cvt_pk_bf16_f32 v124, v124, v125
	v_cvt_pk_bf16_f32 v125, v126, v127
	v_cvt_pk_bf16_f32 v126, v120, v121
	v_cvt_pk_bf16_f32 v127, v122, v123
	v_cvt_pk_bf16_f32 v104, v116, v117
	v_cvt_pk_bf16_f32 v105, v118, v119
	v_cvt_pk_bf16_f32 v106, v112, v113
	v_cvt_pk_bf16_f32 v107, v114, v115
	v_cvt_pk_bf16_f32 v88, v100, v101
	v_cvt_pk_bf16_f32 v89, v102, v103
	v_cvt_pk_bf16_f32 v90, v96, v97
	v_cvt_pk_bf16_f32 v91, v98, v99
	global_store_dwordx4 v[92:93], v[76:79], off offset:256
	v_cvt_pk_bf16_f32 v74, v80, v81
	v_cvt_pk_bf16_f32 v75, v82, v83
	v_lshl_add_u64 v[76:77], v[72:73], 0, v[172:173]
	v_cvt_pk_bf16_f32 v72, v84, v85
	v_cvt_pk_bf16_f32 v73, v86, v87
	v_cvt_pk_bf16_f32 v71, v66, v67
	v_cvt_pk_bf16_f32 v63, v58, v59
	v_cvt_pk_bf16_f32 v40, v52, v53
	v_cvt_pk_bf16_f32 v41, v54, v55
	v_cvt_pk_bf16_f32 v42, v48, v49
	v_cvt_pk_bf16_f32 v43, v50, v51
	v_cvt_pk_bf16_f32 v24, v36, v37
	v_cvt_pk_bf16_f32 v25, v38, v39
	v_cvt_pk_bf16_f32 v26, v32, v33
	v_cvt_pk_bf16_f32 v27, v34, v35
	v_lshl_add_u64 v[12:13], v[174:175], 0, s[54:55]
	v_cvt_pk_bf16_f32 v8, v20, v21
	v_cvt_pk_bf16_f32 v9, v22, v23
	v_cvt_pk_bf16_f32 v10, v16, v17
	v_cvt_pk_bf16_f32 v11, v18, v19
	v_cvt_pk_bf16_f32 v4, v4, v5
	v_cvt_pk_bf16_f32 v5, v6, v7
	v_cvt_pk_bf16_f32 v6, v0, v1
	v_cvt_pk_bf16_f32 v7, v2, v3
	s_and_b64 vcc, exec, s[2:3]
	s_mov_b32 s97, s95
	s_mov_b32 s94, s96
	s_mov_b64 s[58:59], s[0:1]
	s_mov_b64 s[56:57], s[4:5]
	global_store_dwordx4 v[174:175], v[124:127], off
	global_store_dwordx4 v[108:109], v[104:107], off
	global_store_dwordx4 v[92:93], v[88:91], off
	global_store_dwordx4 v[76:77], v[72:75], off
	global_store_dwordx4 v[76:77], v[68:71], off offset:256
	global_store_dwordx4 v[56:57], v[60:63], off
	global_store_dwordx4 v[46:47], v[40:43], off
	global_store_dwordx4 v[30:31], v[24:27], off
	global_store_dwordx4 v[14:15], v[8:11], off
	global_store_dwordx4 v[12:13], v[4:7], off offset:256
	s_cbranch_vccz .LBB0_374
	s_waitcnt vmcnt(0)
	s_cmpk_gt_u32 s65, 0xff
	s_cbranch_scc1 .LBB0_389
	s_barrier

; #define PG8_STAGE(bufoff, gbase, voff) do { _Pragma("unroll") for (int _i = 0; _i < 2; ++_i) \
;         __builtin_amdgcn_global_load_lds((const unsigned*)((const char*)(gbase) + (voff)[_i]), (PG8_LAS unsigned*)(lds + (bufoff) + ldsw + _i * 8192), 16, 0, 0); } while (0)
; #define PG8_LDA(dst, b, h) do { _Pragma("unroll") for (int m = 0; m < 4; ++m) _Pragma("unroll") for (int k = 0; k < 2; ++k) dst[m][k] = *(const PG8_LAS bf16x8*)(lds + PG8_SA(b, h) + aoff + m * 2048 + k * 1024); } while (0)
; #define PG8_LDB(dst, b, h) do { _Pragma("unroll") for (int n = 0; n < 2; ++n) _Pragma("unroll") for (int k = 0; k < 2; ++k) dst[n][k] = *(const PG8_LAS bf16x8*)(lds + PG8_SB(b, h) + boff + n * 2048 + k * 1024); } while (0)
; #define PG8_MMA(ai, bj, At, Bt) do { __builtin_amdgcn_s_setprio(1); _Pragma("unroll") for (int m = 0; m < 4; ++m) _Pragma("unroll") for (int n = 0; n < 2; ++n) _Pragma("unroll") for (int k = 0; k < 2; ++k) \
;         acc[ai][bj][m][n] = __builtin_amdgcn_mfma_f32_16x16x32_bf16(Bt[n][k], At[m][k], acc[ai][bj][m][n], 0, 0, 0); __builtin_amdgcn_s_setprio(0); } while (0)
; #define PG8_BAR __builtin_amdgcn_s_barrier()
; template <class Epi, class Sched, bool STAMP = false>
; __device__ __forceinline__ void gemm_phase(PG8_LAS unsigned char* lds, const Gemm g, const Sched& S, const Epi& E, unsigned long long* stamps) {
;     ...
;         for (int t = 0; t < nt; t += 2) {
;             const bool last = (t == nt - 2);
;             const char* a1 = cA + (size_t)(t + 1) * kstep;
;             const char* a2 = last ? nA : cA + (size_t)(t + 2) * kstep; const char* b2 = last ? nB : cB + (size_t)(t + 2) * kstep;
;             const char* a3 = a2 + kstep; const char* b3 = b2 + kstep;
;             if (last && has_next) S.a_ready(nxt);
;             PG8_LDB(B0, 0, 0); PG8_SCHED; PG8_LDA(At, 0, 0); PG8_STAGE(PG8_SA(1, 1), a1 + hstep, voffA);
;             PG8_WAIT_L(8); PG8_BAR; PG8_WAIT_L(0); PG8_MMA(0, 0, At, B0); PG8_BAR; PG8_SCHED;
;             PG8_LDB(B1, 0, 1); PG8_STAGE(PG8_SB(0, 0), b2, voffB);
;             PG8_BAR; PG8_WAIT_L(0); PG8_MMA(0, 1, At, B1); PG8_BAR;
;             PG8_LDA(At, 0, 1); PG8_STAGE(PG8_SA(0, 0), a2, voffA);
;             PG8_BAR; PG8_WAIT_L(0); PG8_MMA(1, 0, At, B0); PG8_BAR; PG8_SCHED;
;             PG8_STAGE(PG8_SB(0, 1), b2 + hstep, voffB);
;             PG8_WAIT_V(6); PG8_BAR; PG8_MMA(1, 1, At, B1); PG8_BAR;
.LBB0_438:
	s_add_u32 s77, s36, 0x100
	s_addc_u32 s78, s37, 0
	s_mov_b32 s10, -2
	s_cmp_eq_u32 s58, s99
	s_cbranch_scc1 .Lgu3_half_loop_z
	s_add_u32 s100, s77, 0x43f80
	s_addc_u32 s101, s78, 0
	s_mov_b32 m0, s64
	s_nop 0
	global_load_lds_dwordx4 v130, s[100:101]
	s_mov_b32 m0, s65
	s_nop 0
	global_load_lds_dwordx4 v128, s[100:101]
	ds_read_b128 v[140:143], v147
	ds_read_b128 v[170:173], v148
	ds_read_b128 v[174:177], v149
	ds_read_b128 v[178:181], v150
	s_add_u32 s36, s34, 0x100
	s_addc_u32 s37, s35, 0
	s_cmp_eq_u32 s10, 12
	s_cselect_b32 s43, s5, s37
	s_cselect_b32 s42, s4, s36
	s_cselect_b32 s41, s1, s78
	s_cselect_b32 s40, s0, s77
	s_mov_b32 m0, s67
	ds_read_b128 v[182:185], v145
	ds_read_b128 v[186:189], v145 offset:1024
	ds_read_b128 v[190:193], v145 offset:2048
	ds_read_b128 v[194:197], v145 offset:3072
	ds_read_b128 v[198:201], v145 offset:4096
	ds_read_b128 v[202:205], v145 offset:5120
	ds_read_b128 v[206:209], v145 offset:6144
	ds_read_b128 v[210:213], v145 offset:7168
	global_load_lds_dwordx4 v132, s[34:35]
	s_mov_b32 m0, s68
	s_nop 0
	global_load_lds_dwordx4 v134, s[34:35]
	ds_read_b128 v[214:217], v151
	ds_read_b128 v[218:221], v152
	ds_read_b128 v[222:225], v153
	ds_read_b128 v[226:229], v154
	s_waitcnt vmcnt(8)
	s_waitcnt lgkmcnt(0)
	s_barrier
	s_setprio 1
	v_mfma_f32_16x16x32_bf16 v[124:127], v[140:143], v[182:185], 0
	v_mfma_f32_16x16x32_bf16 v[120:123], v[174:177], v[182:185], 0
	v_mfma_f32_16x16x32_bf16 v[108:111], v[140:143], v[190:193], 0
	v_mfma_f32_16x16x32_bf16 v[104:107], v[174:177], v[190:193], 0
	v_mfma_f32_16x16x32_bf16 v[92:95], v[140:143], v[198:201], 0
	v_mfma_f32_16x16x32_bf16 v[88:91], v[174:177], v[198:201], 0
	v_mfma_f32_16x16x32_bf16 v[76:79], v[140:143], v[206:209], 0
	v_mfma_f32_16x16x32_bf16 v[72:75], v[174:177], v[206:209], 0
	v_mfma_f32_16x16x32_bf16 v[124:127], v[170:173], v[186:189], v[124:127]
	v_mfma_f32_16x16x32_bf16 v[120:123], v[178:181], v[186:189], v[120:123]
	v_mfma_f32_16x16x32_bf16 v[108:111], v[170:173], v[194:197], v[108:111]
	v_mfma_f32_16x16x32_bf16 v[104:107], v[178:181], v[194:197], v[104:107]
	v_mfma_f32_16x16x32_bf16 v[92:95], v[170:173], v[202:205], v[92:95]
	v_mfma_f32_16x16x32_bf16 v[88:91], v[178:181], v[202:205], v[88:91]
	v_mfma_f32_16x16x32_bf16 v[76:79], v[170:173], v[210:213], v[76:79]
	v_mfma_f32_16x16x32_bf16 v[72:75], v[178:181], v[210:213], v[72:75]
	v_mfma_f32_16x16x32_bf16 v[116:119], v[214:217], v[182:185], 0
	v_mfma_f32_16x16x32_bf16 v[112:115], v[222:225], v[182:185], 0
	v_mfma_f32_16x16x32_bf16 v[100:103], v[214:217], v[190:193], 0
	v_mfma_f32_16x16x32_bf16 v[96:99], v[222:225], v[190:193], 0
	v_mfma_f32_16x16x32_bf16 v[84:87], v[214:217], v[198:201], 0
	v_mfma_f32_16x16x32_bf16 v[80:83], v[222:225], v[198:201], 0
	v_mfma_f32_16x16x32_bf16 v[68:71], v[214:217], v[206:209], 0
	v_mfma_f32_16x16x32_bf16 v[64:67], v[222:225], v[206:209], 0
	v_mfma_f32_16x16x32_bf16 v[116:119], v[218:221], v[186:189], v[116:119]
	v_mfma_f32_16x16x32_bf16 v[112:115], v[226:229], v[186:189], v[112:115]
	v_mfma_f32_16x16x32_bf16 v[100:103], v[218:221], v[194:197], v[100:103]
	v_mfma_f32_16x16x32_bf16 v[96:99], v[226:229], v[194:197], v[96:99]
	v_mfma_f32_16x16x32_bf16 v[84:87], v[218:221], v[202:205], v[84:87]
	v_mfma_f32_16x16x32_bf16 v[80:83], v[226:229], v[202:205], v[80:83]
	v_mfma_f32_16x16x32_bf16 v[68:71], v[218:221], v[210:213], v[68:71]
	v_mfma_f32_16x16x32_bf16 v[64:67], v[226:229], v[210:213], v[64:67]
	s_setprio 0
	s_barrier
	s_mov_b32 m0, s49
	s_nop 0
	global_load_lds_dwordx4 v130, s[40:41]
	s_mov_b32 m0, s52
	s_nop 0
	global_load_lds_dwordx4 v128, s[40:41]
	s_mov_b32 m0, s46
	ds_read_b128 v[182:185], v145 offset:16384
	ds_read_b128 v[186:189], v145 offset:17408
	ds_read_b128 v[190:193], v145 offset:18432
	ds_read_b128 v[194:197], v145 offset:19456
	ds_read_b128 v[198:201], v145 offset:20480
	ds_read_b128 v[202:205], v145 offset:21504
	ds_read_b128 v[206:209], v145 offset:22528
	ds_read_b128 v[210:213], v145 offset:23552
	global_load_lds_dwordx4 v130, s[42:43]
	s_mov_b32 m0, s53
	s_nop 0
	global_load_lds_dwordx4 v128, s[42:43]
	s_waitcnt vmcnt(6)
	s_waitcnt lgkmcnt(0)
	s_barrier
	s_setprio 1
	v_mfma_f32_16x16x32_bf16 v[60:63], v[140:143], v[182:185], 0
	v_mfma_f32_16x16x32_bf16 v[56:59], v[174:177], v[182:185], 0
	v_mfma_f32_16x16x32_bf16 v[44:47], v[140:143], v[190:193], 0
	v_mfma_f32_16x16x32_bf16 v[40:43], v[174:177], v[190:193], 0
	v_mfma_f32_16x16x32_bf16 v[28:31], v[140:143], v[198:201], 0
	v_mfma_f32_16x16x32_bf16 v[24:27], v[174:177], v[198:201], 0
	v_mfma_f32_16x16x32_bf16 v[12:15], v[140:143], v[206:209], 0
	v_mfma_f32_16x16x32_bf16 v[8:11], v[174:177], v[206:209], 0
	v_mfma_f32_16x16x32_bf16 v[60:63], v[170:173], v[186:189], v[60:63]
	v_mfma_f32_16x16x32_bf16 v[56:59], v[178:181], v[186:189], v[56:59]
	v_mfma_f32_16x16x32_bf16 v[44:47], v[170:173], v[194:197], v[44:47]
	v_mfma_f32_16x16x32_bf16 v[40:43], v[178:181], v[194:197], v[40:43]
	v_mfma_f32_16x16x32_bf16 v[28:31], v[170:173], v[202:205], v[28:31]
	v_mfma_f32_16x16x32_bf16 v[24:27], v[178:181], v[202:205], v[24:27]
	v_mfma_f32_16x16x32_bf16 v[12:15], v[170:173], v[210:213], v[12:15]
	v_mfma_f32_16x16x32_bf16 v[8:11], v[178:181], v[210:213], v[8:11]
	v_mfma_f32_16x16x32_bf16 v[52:55], v[214:217], v[182:185], 0
	v_mfma_f32_16x16x32_bf16 v[48:51], v[222:225], v[182:185], 0
	v_mfma_f32_16x16x32_bf16 v[36:39], v[214:217], v[190:193], 0
	v_mfma_f32_16x16x32_bf16 v[32:35], v[222:225], v[190:193], 0
	v_mfma_f32_16x16x32_bf16 v[20:23], v[214:217], v[198:201], 0
	v_mfma_f32_16x16x32_bf16 v[16:19], v[222:225], v[198:201], 0
	v_mfma_f32_16x16x32_bf16 v[4:7], v[214:217], v[206:209], 0
	v_mfma_f32_16x16x32_bf16 v[0:3], v[222:225], v[206:209], 0
	v_mfma_f32_16x16x32_bf16 v[52:55], v[218:221], v[186:189], v[52:55]
	v_mfma_f32_16x16x32_bf16 v[48:51], v[226:229], v[186:189], v[48:51]
	v_mfma_f32_16x16x32_bf16 v[36:39], v[218:221], v[194:197], v[36:39]
	v_mfma_f32_16x16x32_bf16 v[32:35], v[226:229], v[194:197], v[32:35]
	v_mfma_f32_16x16x32_bf16 v[20:23], v[218:221], v[202:205], v[20:23]
	v_mfma_f32_16x16x32_bf16 v[16:19], v[226:229], v[202:205], v[16:19]
	v_mfma_f32_16x16x32_bf16 v[4:7], v[218:221], v[210:213], v[4:7]
	v_mfma_f32_16x16x32_bf16 v[0:3], v[226:229], v[210:213], v[0:3]
	s_setprio 0
	s_barrier
	s_branch .Lzp7_mid
; #define PG8_STAGE(bufoff, gbase, voff) do { _Pragma("unroll") for (int _i = 0; _i < 2; ++_i) \
;         __builtin_amdgcn_global_load_lds((const unsigned*)((const char*)(gbase) + (voff)[_i]), (PG8_LAS unsigned*)(lds + (bufoff) + ldsw + _i * 8192), 16, 0, 0); } while (0)
; #define PG8_LDA(dst, b, h) do { _Pragma("unroll") for (int m = 0; m < 4; ++m) _Pragma("unroll") for (int k = 0; k < 2; ++k) dst[m][k] = *(const PG8_LAS bf16x8*)(lds + PG8_SA(b, h) + aoff + m * 2048 + k * 1024); } while (0)
; #define PG8_LDB(dst, b, h) do { _Pragma("unroll") for (int n = 0; n < 2; ++n) _Pragma("unroll") for (int k = 0; k < 2; ++k) dst[n][k] = *(const PG8_LAS bf16x8*)(lds + PG8_SB(b, h) + boff + n * 2048 + k * 1024); } while (0)
; #define PG8_MMA(ai, bj, At, Bt) do { __builtin_amdgcn_s_setprio(1); _Pragma("unroll") for (int m = 0; m < 4; ++m) _Pragma("unroll") for (int n = 0; n < 2; ++n) _Pragma("unroll") for (int k = 0; k < 2; ++k) \
;         acc[ai][bj][m][n] = __builtin_amdgcn_mfma_f32_16x16x32_bf16(Bt[n][k], At[m][k], acc[ai][bj][m][n], 0, 0, 0); __builtin_amdgcn_s_setprio(0); } while (0)
; #define PG8_BAR __builtin_amdgcn_s_barrier()
; template <class Epi, class Sched, bool STAMP = false>
; __device__ __forceinline__ void gemm_phase(PG8_LAS unsigned char* lds, const Gemm g, const Sched& S, const Epi& E, unsigned long long* stamps) {
;     ...
;         for (int t = 0; t < nt; t += 2) {
;             const bool last = (t == nt - 2);
;             const char* a1 = cA + (size_t)(t + 1) * kstep;
;             const char* a2 = last ? nA : cA + (size_t)(t + 2) * kstep; const char* b2 = last ? nB : cB + (size_t)(t + 2) * kstep;
;             const char* a3 = a2 + kstep; const char* b3 = b2 + kstep;
;             if (last && has_next) S.a_ready(nxt);
;             PG8_LDB(B0, 0, 0); PG8_SCHED; PG8_LDA(At, 0, 0); PG8_STAGE(PG8_SA(1, 1), a1 + hstep, voffA);
;             PG8_WAIT_L(8); PG8_BAR; PG8_WAIT_L(0); PG8_MMA(0, 0, At, B0); PG8_BAR; PG8_SCHED;
;             PG8_LDB(B1, 0, 1); PG8_STAGE(PG8_SB(0, 0), b2, voffB);
;             PG8_BAR; PG8_WAIT_L(0); PG8_MMA(0, 1, At, B1); PG8_BAR;
;             PG8_LDA(At, 0, 1); PG8_STAGE(PG8_SA(0, 0), a2, voffA);
;             PG8_BAR; PG8_WAIT_L(0); PG8_MMA(1, 0, At, B0); PG8_BAR; PG8_SCHED;
;             PG8_STAGE(PG8_SB(0, 1), b2 + hstep, voffB);
;             PG8_WAIT_V(6); PG8_BAR; PG8_MMA(1, 1, At, B1); PG8_BAR;
.LBB0_439:
	s_add_u32 s100, s77, 0x43f80
	s_addc_u32 s101, s78, 0
	s_mov_b32 m0, s64
	s_nop 0
	global_load_lds_dwordx4 v130, s[100:101]
	s_mov_b32 m0, s65
	s_nop 0
	global_load_lds_dwordx4 v128, s[100:101]
	ds_read_b128 v[140:143], v147
	ds_read_b128 v[170:173], v148
	ds_read_b128 v[174:177], v149
	ds_read_b128 v[178:181], v150
	s_add_u32 s36, s34, 0x100
	s_addc_u32 s37, s35, 0
	s_cmp_eq_u32 s10, 12
	s_cselect_b32 s43, s5, s37
	s_cselect_b32 s42, s4, s36
	s_cselect_b32 s41, s1, s78
	s_cselect_b32 s40, s0, s77
	s_mov_b32 m0, s67
	ds_read_b128 v[182:185], v145
	ds_read_b128 v[186:189], v145 offset:1024
	ds_read_b128 v[190:193], v145 offset:2048
	ds_read_b128 v[194:197], v145 offset:3072
	ds_read_b128 v[198:201], v145 offset:4096
	ds_read_b128 v[202:205], v145 offset:5120
	ds_read_b128 v[206:209], v145 offset:6144
	ds_read_b128 v[210:213], v145 offset:7168
	global_load_lds_dwordx4 v132, s[34:35]
	s_mov_b32 m0, s68
	s_nop 0
	global_load_lds_dwordx4 v134, s[34:35]
	ds_read_b128 v[214:217], v151
	ds_read_b128 v[218:221], v152
	ds_read_b128 v[222:225], v153
	ds_read_b128 v[226:229], v154
	s_waitcnt vmcnt(8)
	s_waitcnt lgkmcnt(0)
	s_barrier
	s_setprio 1
	v_mfma_f32_16x16x32_bf16 v[124:127], v[140:143], v[182:185], v[124:127]
	v_mfma_f32_16x16x32_bf16 v[120:123], v[174:177], v[182:185], v[120:123]
	v_mfma_f32_16x16x32_bf16 v[108:111], v[140:143], v[190:193], v[108:111]
	v_mfma_f32_16x16x32_bf16 v[104:107], v[174:177], v[190:193], v[104:107]
	v_mfma_f32_16x16x32_bf16 v[92:95], v[140:143], v[198:201], v[92:95]
	v_mfma_f32_16x16x32_bf16 v[88:91], v[174:177], v[198:201], v[88:91]
	v_mfma_f32_16x16x32_bf16 v[76:79], v[140:143], v[206:209], v[76:79]
	v_mfma_f32_16x16x32_bf16 v[72:75], v[174:177], v[206:209], v[72:75]
	v_mfma_f32_16x16x32_bf16 v[124:127], v[170:173], v[186:189], v[124:127]
	v_mfma_f32_16x16x32_bf16 v[120:123], v[178:181], v[186:189], v[120:123]
	v_mfma_f32_16x16x32_bf16 v[108:111], v[170:173], v[194:197], v[108:111]
	v_mfma_f32_16x16x32_bf16 v[104:107], v[178:181], v[194:197], v[104:107]
	v_mfma_f32_16x16x32_bf16 v[92:95], v[170:173], v[202:205], v[92:95]
	v_mfma_f32_16x16x32_bf16 v[88:91], v[178:181], v[202:205], v[88:91]
	v_mfma_f32_16x16x32_bf16 v[76:79], v[170:173], v[210:213], v[76:79]
	v_mfma_f32_16x16x32_bf16 v[72:75], v[178:181], v[210:213], v[72:75]
	v_mfma_f32_16x16x32_bf16 v[116:119], v[214:217], v[182:185], v[116:119]
	v_mfma_f32_16x16x32_bf16 v[112:115], v[222:225], v[182:185], v[112:115]
	v_mfma_f32_16x16x32_bf16 v[100:103], v[214:217], v[190:193], v[100:103]
	v_mfma_f32_16x16x32_bf16 v[96:99], v[222:225], v[190:193], v[96:99]
	v_mfma_f32_16x16x32_bf16 v[84:87], v[214:217], v[198:201], v[84:87]
	v_mfma_f32_16x16x32_bf16 v[80:83], v[222:225], v[198:201], v[80:83]
	v_mfma_f32_16x16x32_bf16 v[68:71], v[214:217], v[206:209], v[68:71]
	v_mfma_f32_16x16x32_bf16 v[64:67], v[222:225], v[206:209], v[64:67]
	v_mfma_f32_16x16x32_bf16 v[116:119], v[218:221], v[186:189], v[116:119]
	v_mfma_f32_16x16x32_bf16 v[112:115], v[226:229], v[186:189], v[112:115]
	v_mfma_f32_16x16x32_bf16 v[100:103], v[218:221], v[194:197], v[100:103]
	v_mfma_f32_16x16x32_bf16 v[96:99], v[226:229], v[194:197], v[96:99]
	v_mfma_f32_16x16x32_bf16 v[84:87], v[218:221], v[202:205], v[84:87]
	v_mfma_f32_16x16x32_bf16 v[80:83], v[226:229], v[202:205], v[80:83]
	v_mfma_f32_16x16x32_bf16 v[68:71], v[218:221], v[210:213], v[68:71]
	v_mfma_f32_16x16x32_bf16 v[64:67], v[226:229], v[210:213], v[64:67]
	s_setprio 0
	s_barrier
	s_mov_b32 m0, s49
	s_nop 0
	global_load_lds_dwordx4 v130, s[40:41]
	s_mov_b32 m0, s52
	s_nop 0
	global_load_lds_dwordx4 v128, s[40:41]
	s_mov_b32 m0, s46
	ds_read_b128 v[182:185], v145 offset:16384
	ds_read_b128 v[186:189], v145 offset:17408
	ds_read_b128 v[190:193], v145 offset:18432
	ds_read_b128 v[194:197], v145 offset:19456
	ds_read_b128 v[198:201], v145 offset:20480
	ds_read_b128 v[202:205], v145 offset:21504
	ds_read_b128 v[206:209], v145 offset:22528
	ds_read_b128 v[210:213], v145 offset:23552
	global_load_lds_dwordx4 v130, s[42:43]
	s_mov_b32 m0, s53
	s_nop 0
	global_load_lds_dwordx4 v128, s[42:43]
	s_waitcnt vmcnt(6)
	s_waitcnt lgkmcnt(0)
	s_barrier
	s_setprio 1
	v_mfma_f32_16x16x32_bf16 v[60:63], v[140:143], v[182:185], v[60:63]
	v_mfma_f32_16x16x32_bf16 v[56:59], v[174:177], v[182:185], v[56:59]
	v_mfma_f32_16x16x32_bf16 v[44:47], v[140:143], v[190:193], v[44:47]
	v_mfma_f32_16x16x32_bf16 v[40:43], v[174:177], v[190:193], v[40:43]
	v_mfma_f32_16x16x32_bf16 v[28:31], v[140:143], v[198:201], v[28:31]
	v_mfma_f32_16x16x32_bf16 v[24:27], v[174:177], v[198:201], v[24:27]
	v_mfma_f32_16x16x32_bf16 v[12:15], v[140:143], v[206:209], v[12:15]
	v_mfma_f32_16x16x32_bf16 v[8:11], v[174:177], v[206:209], v[8:11]
	v_mfma_f32_16x16x32_bf16 v[60:63], v[170:173], v[186:189], v[60:63]
	v_mfma_f32_16x16x32_bf16 v[56:59], v[178:181], v[186:189], v[56:59]
	v_mfma_f32_16x16x32_bf16 v[44:47], v[170:173], v[194:197], v[44:47]
	v_mfma_f32_16x16x32_bf16 v[40:43], v[178:181], v[194:197], v[40:43]
	v_mfma_f32_16x16x32_bf16 v[28:31], v[170:173], v[202:205], v[28:31]
	v_mfma_f32_16x16x32_bf16 v[24:27], v[178:181], v[202:205], v[24:27]
	v_mfma_f32_16x16x32_bf16 v[12:15], v[170:173], v[210:213], v[12:15]
	v_mfma_f32_16x16x32_bf16 v[8:11], v[178:181], v[210:213], v[8:11]
	v_mfma_f32_16x16x32_bf16 v[52:55], v[214:217], v[182:185], v[52:55]
	v_mfma_f32_16x16x32_bf16 v[48:51], v[222:225], v[182:185], v[48:51]
	v_mfma_f32_16x16x32_bf16 v[36:39], v[214:217], v[190:193], v[36:39]
	v_mfma_f32_16x16x32_bf16 v[32:35], v[222:225], v[190:193], v[32:35]
	v_mfma_f32_16x16x32_bf16 v[20:23], v[214:217], v[198:201], v[20:23]
	v_mfma_f32_16x16x32_bf16 v[16:19], v[222:225], v[198:201], v[16:19]
	v_mfma_f32_16x16x32_bf16 v[4:7], v[214:217], v[206:209], v[4:7]
	v_mfma_f32_16x16x32_bf16 v[0:3], v[222:225], v[206:209], v[0:3]
	v_mfma_f32_16x16x32_bf16 v[52:55], v[218:221], v[186:189], v[52:55]
	v_mfma_f32_16x16x32_bf16 v[48:51], v[226:229], v[186:189], v[48:51]
	v_mfma_f32_16x16x32_bf16 v[36:39], v[218:221], v[194:197], v[36:39]
	v_mfma_f32_16x16x32_bf16 v[32:35], v[226:229], v[194:197], v[32:35]
	v_mfma_f32_16x16x32_bf16 v[20:23], v[218:221], v[202:205], v[20:23]
	v_mfma_f32_16x16x32_bf16 v[16:19], v[226:229], v[202:205], v[16:19]
	v_mfma_f32_16x16x32_bf16 v[4:7], v[218:221], v[210:213], v[4:7]
	v_mfma_f32_16x16x32_bf16 v[0:3], v[226:229], v[210:213], v[0:3]
	s_setprio 0
	s_barrier
; #define PG8_STAGE(bufoff, gbase, voff) do { _Pragma("unroll") for (int _i = 0; _i < 2; ++_i) \
;         __builtin_amdgcn_global_load_lds((const unsigned*)((const char*)(gbase) + (voff)[_i]), (PG8_LAS unsigned*)(lds + (bufoff) + ldsw + _i * 8192), 16, 0, 0); } while (0)
; #define PG8_LDA(dst, b, h) do { _Pragma("unroll") for (int m = 0; m < 4; ++m) _Pragma("unroll") for (int k = 0; k < 2; ++k) dst[m][k] = *(const PG8_LAS bf16x8*)(lds + PG8_SA(b, h) + aoff + m * 2048 + k * 1024); } while (0)
; #define PG8_LDB(dst, b, h) do { _Pragma("unroll") for (int n = 0; n < 2; ++n) _Pragma("unroll") for (int k = 0; k < 2; ++k) dst[n][k] = *(const PG8_LAS bf16x8*)(lds + PG8_SB(b, h) + boff + n * 2048 + k * 1024); } while (0)
; #define PG8_MMA(ai, bj, At, Bt) do { __builtin_amdgcn_s_setprio(1); _Pragma("unroll") for (int m = 0; m < 4; ++m) _Pragma("unroll") for (int n = 0; n < 2; ++n) _Pragma("unroll") for (int k = 0; k < 2; ++k) \
;         acc[ai][bj][m][n] = __builtin_amdgcn_mfma_f32_16x16x32_bf16(Bt[n][k], At[m][k], acc[ai][bj][m][n], 0, 0, 0); __builtin_amdgcn_s_setprio(0); } while (0)
; #define PG8_WAIT_V(n) asm volatile("s_waitcnt vmcnt(" #n ")" ::: "memory")
; #define PG8_WAIT_L(n) asm volatile("s_waitcnt lgkmcnt(" #n ")" ::: "memory")
; #define PG8_BAR __builtin_amdgcn_s_barrier()
; #define PG8_SCHED __builtin_amdgcn_sched_barrier(0)
; template <class Epi, class Sched, bool STAMP = false>
; __device__ __forceinline__ void gemm_phase(PG8_LAS unsigned char* lds, const Gemm g, const Sched& S, const Epi& E, unsigned long long* stamps) {
;     ...
;             PG8_LDB(B0, 1, 0); PG8_SCHED; PG8_LDA(At, 1, 0); PG8_STAGE(PG8_SA(0, 1), a2 + hstep, voffA);
;             PG8_WAIT_L(8); PG8_BAR; PG8_WAIT_L(0); PG8_MMA(0, 0, At, B0); PG8_BAR; PG8_SCHED;
;             PG8_LDB(B1, 1, 1); PG8_STAGE(PG8_SB(1, 0), b3, voffB);
;             PG8_BAR; PG8_WAIT_L(0); PG8_MMA(0, 1, At, B1); PG8_BAR;
;             PG8_LDA(At, 1, 1); PG8_STAGE(PG8_SA(1, 0), a3, voffA);
;             PG8_BAR; PG8_WAIT_L(0); PG8_MMA(1, 0, At, B0); PG8_BAR; PG8_SCHED;
;             PG8_STAGE(PG8_SB(1, 1), b3 + hstep, voffB);
;             PG8_WAIT_V(6); PG8_BAR; PG8_MMA(1, 1, At, B1); PG8_BAR;
;         }
.Lzp7_mid:
	s_add_u32 s34, s40, 0x44000
	s_addc_u32 s35, s41, 0
	s_mov_b32 m0, s54
	s_nop 0
	global_load_lds_dwordx4 v130, s[34:35]
	s_mov_b32 m0, s55
	s_nop 0
	global_load_lds_dwordx4 v128, s[34:35]
	ds_read_b128 v[140:143], v155
	ds_read_b128 v[170:173], v156
	ds_read_b128 v[174:177], v157
	ds_read_b128 v[178:181], v165
	s_add_u32 s34, s42, 0x44000
	s_addc_u32 s35, s43, 0
	s_mov_b32 m0, s56
	ds_read_b128 v[182:185], v145 offset:32768
	ds_read_b128 v[186:189], v145 offset:33792
	ds_read_b128 v[190:193], v145 offset:34816
	ds_read_b128 v[194:197], v145 offset:35840
	ds_read_b128 v[198:201], v145 offset:36864
	ds_read_b128 v[202:205], v145 offset:37888
	ds_read_b128 v[206:209], v145 offset:38912
	ds_read_b128 v[210:213], v145 offset:39936
	global_load_lds_dwordx4 v130, s[34:35]
	s_mov_b32 m0, s57
	s_nop 0
	global_load_lds_dwordx4 v128, s[34:35]
	ds_read_b128 v[214:217], v166
	ds_read_b128 v[218:221], v167
	ds_read_b128 v[222:225], v168
	ds_read_b128 v[226:229], v169
	s_waitcnt vmcnt(8)
	s_waitcnt lgkmcnt(0)
	s_barrier
	s_setprio 1
	v_mfma_f32_16x16x32_bf16 v[124:127], v[140:143], v[182:185], v[124:127]
	v_mfma_f32_16x16x32_bf16 v[120:123], v[174:177], v[182:185], v[120:123]
	v_mfma_f32_16x16x32_bf16 v[108:111], v[140:143], v[190:193], v[108:111]
	v_mfma_f32_16x16x32_bf16 v[104:107], v[174:177], v[190:193], v[104:107]
	v_mfma_f32_16x16x32_bf16 v[92:95], v[140:143], v[198:201], v[92:95]
	v_mfma_f32_16x16x32_bf16 v[88:91], v[174:177], v[198:201], v[88:91]
	v_mfma_f32_16x16x32_bf16 v[76:79], v[140:143], v[206:209], v[76:79]
	v_mfma_f32_16x16x32_bf16 v[72:75], v[174:177], v[206:209], v[72:75]
	v_mfma_f32_16x16x32_bf16 v[124:127], v[170:173], v[186:189], v[124:127]
	v_mfma_f32_16x16x32_bf16 v[120:123], v[178:181], v[186:189], v[120:123]
	v_mfma_f32_16x16x32_bf16 v[108:111], v[170:173], v[194:197], v[108:111]
	v_mfma_f32_16x16x32_bf16 v[104:107], v[178:181], v[194:197], v[104:107]
	v_mfma_f32_16x16x32_bf16 v[92:95], v[170:173], v[202:205], v[92:95]
	v_mfma_f32_16x16x32_bf16 v[88:91], v[178:181], v[202:205], v[88:91]
	v_mfma_f32_16x16x32_bf16 v[76:79], v[170:173], v[210:213], v[76:79]
	v_mfma_f32_16x16x32_bf16 v[72:75], v[178:181], v[210:213], v[72:75]
	v_mfma_f32_16x16x32_bf16 v[116:119], v[214:217], v[182:185], v[116:119]
	v_mfma_f32_16x16x32_bf16 v[112:115], v[222:225], v[182:185], v[112:115]
	v_mfma_f32_16x16x32_bf16 v[100:103], v[214:217], v[190:193], v[100:103]
	v_mfma_f32_16x16x32_bf16 v[96:99], v[222:225], v[190:193], v[96:99]
	v_mfma_f32_16x16x32_bf16 v[84:87], v[214:217], v[198:201], v[84:87]
	v_mfma_f32_16x16x32_bf16 v[80:83], v[222:225], v[198:201], v[80:83]
	v_mfma_f32_16x16x32_bf16 v[68:71], v[214:217], v[206:209], v[68:71]
	v_mfma_f32_16x16x32_bf16 v[64:67], v[222:225], v[206:209], v[64:67]
	v_mfma_f32_16x16x32_bf16 v[116:119], v[218:221], v[186:189], v[116:119]
	v_mfma_f32_16x16x32_bf16 v[112:115], v[226:229], v[186:189], v[112:115]
	v_mfma_f32_16x16x32_bf16 v[100:103], v[218:221], v[194:197], v[100:103]
	v_mfma_f32_16x16x32_bf16 v[96:99], v[226:229], v[194:197], v[96:99]
	v_mfma_f32_16x16x32_bf16 v[84:87], v[218:221], v[202:205], v[84:87]
	v_mfma_f32_16x16x32_bf16 v[80:83], v[226:229], v[202:205], v[80:83]
	v_mfma_f32_16x16x32_bf16 v[68:71], v[218:221], v[210:213], v[68:71]
	v_mfma_f32_16x16x32_bf16 v[64:67], v[226:229], v[210:213], v[64:67]
	s_setprio 0
	s_barrier
	s_mov_b32 m0, s60
	s_add_u32 s100, s40, 0x80
	s_addc_u32 s101, s41, 0
	global_load_lds_dwordx4 v130, s[100:101]
	s_mov_b32 m0, s61
	s_nop 0
	global_load_lds_dwordx4 v128, s[100:101]
	s_mov_b32 m0, s62
	ds_read_b128 v[182:185], v145 offset:49152
	ds_read_b128 v[186:189], v145 offset:50176
	ds_read_b128 v[190:193], v145 offset:51200
	ds_read_b128 v[194:197], v145 offset:52224
	ds_read_b128 v[198:201], v145 offset:53248
	ds_read_b128 v[202:205], v145 offset:54272
	ds_read_b128 v[206:209], v145 offset:55296
	ds_read_b128 v[210:213], v145 offset:56320
	s_add_u32 s100, s42, 0x80
	s_addc_u32 s101, s43, 0
	global_load_lds_dwordx4 v130, s[100:101]
	s_mov_b32 m0, s63
	s_nop 0
	global_load_lds_dwordx4 v128, s[100:101]
	s_waitcnt vmcnt(6)
	s_waitcnt lgkmcnt(0)
	s_barrier
	s_setprio 1
	v_mfma_f32_16x16x32_bf16 v[60:63], v[140:143], v[182:185], v[60:63]
	v_mfma_f32_16x16x32_bf16 v[56:59], v[174:177], v[182:185], v[56:59]
	v_mfma_f32_16x16x32_bf16 v[44:47], v[140:143], v[190:193], v[44:47]
	v_mfma_f32_16x16x32_bf16 v[40:43], v[174:177], v[190:193], v[40:43]
	v_mfma_f32_16x16x32_bf16 v[28:31], v[140:143], v[198:201], v[28:31]
	v_mfma_f32_16x16x32_bf16 v[24:27], v[174:177], v[198:201], v[24:27]
	v_mfma_f32_16x16x32_bf16 v[12:15], v[140:143], v[206:209], v[12:15]
	v_mfma_f32_16x16x32_bf16 v[8:11], v[174:177], v[206:209], v[8:11]
	v_mfma_f32_16x16x32_bf16 v[60:63], v[170:173], v[186:189], v[60:63]
	v_mfma_f32_16x16x32_bf16 v[56:59], v[178:181], v[186:189], v[56:59]
	v_mfma_f32_16x16x32_bf16 v[44:47], v[170:173], v[194:197], v[44:47]
	v_mfma_f32_16x16x32_bf16 v[40:43], v[178:181], v[194:197], v[40:43]
	v_mfma_f32_16x16x32_bf16 v[28:31], v[170:173], v[202:205], v[28:31]
	v_mfma_f32_16x16x32_bf16 v[24:27], v[178:181], v[202:205], v[24:27]
	v_mfma_f32_16x16x32_bf16 v[12:15], v[170:173], v[210:213], v[12:15]
	v_mfma_f32_16x16x32_bf16 v[8:11], v[178:181], v[210:213], v[8:11]
	v_mfma_f32_16x16x32_bf16 v[52:55], v[214:217], v[182:185], v[52:55]
	v_mfma_f32_16x16x32_bf16 v[48:51], v[222:225], v[182:185], v[48:51]
	v_mfma_f32_16x16x32_bf16 v[36:39], v[214:217], v[190:193], v[36:39]
	v_mfma_f32_16x16x32_bf16 v[32:35], v[222:225], v[190:193], v[32:35]
	v_mfma_f32_16x16x32_bf16 v[20:23], v[214:217], v[198:201], v[20:23]
	v_mfma_f32_16x16x32_bf16 v[16:19], v[222:225], v[198:201], v[16:19]
	v_mfma_f32_16x16x32_bf16 v[4:7], v[214:217], v[206:209], v[4:7]
	v_mfma_f32_16x16x32_bf16 v[0:3], v[222:225], v[206:209], v[0:3]
	v_mfma_f32_16x16x32_bf16 v[52:55], v[218:221], v[186:189], v[52:55]
	v_mfma_f32_16x16x32_bf16 v[48:51], v[226:229], v[186:189], v[48:51]
	v_mfma_f32_16x16x32_bf16 v[36:39], v[218:221], v[194:197], v[36:39]
	v_mfma_f32_16x16x32_bf16 v[32:35], v[226:229], v[194:197], v[32:35]
	v_mfma_f32_16x16x32_bf16 v[20:23], v[218:221], v[202:205], v[20:23]
	v_mfma_f32_16x16x32_bf16 v[16:19], v[226:229], v[202:205], v[16:19]
	v_mfma_f32_16x16x32_bf16 v[4:7], v[218:221], v[210:213], v[4:7]
	v_mfma_f32_16x16x32_bf16 v[0:3], v[226:229], v[210:213], v[0:3]
	s_setprio 0
	s_add_i32 s10, s10, 2
	s_add_u32 s77, s77, 0x100
	s_addc_u32 s78, s78, 0
	s_cmp_gt_u32 s10, 13
	s_mov_b64 s[34:35], s[36:37]
	s_barrier
; DI float ex2(float x) { return __builtin_amdgcn_exp2f(x); }
;     DI void operator()(const f32x4 (&acc)[2][2][4][2], const Unit& u, int wr, int wc, int fr, int fq) const {
;         const int row0 = u.pm * BM + wr * 64 + fr, hcol0 = ((u.pn * BM + wc * 32) >> 1) + 4 * fq;
; #pragma unroll
;         for (int ai = 0; ai < 2; ++ai)
; #pragma unroll
;             for (int m = 0; m < 4; ++m) { u16* rowp = O + (size_t)(row0 + ai * HALF + m * 16) * ldc + hcol0;
; #pragma unroll
;                 for (int bj = 0; bj < 2; ++bj) { const f32x4 g = acc[ai][bj][m][0], up = acc[ai][bj][m][1]; float r[4];
; #pragma unroll
;                     for (int j = 0; j < 4; ++j) r[j] = g[j] * up[j] * __builtin_amdgcn_rcpf(1.f + ex2(-LOG2E * g[j]));
;                     uint2 w = {pack2(r[0], r[1]), pack2(r[2], r[3])}; *(uint2*)(rowp + bj * (HALF / 2)) = w; } }
;     }
	s_cbranch_scc0 .LBB0_439
	v_exp_f32_e64 v171, -v124
	v_exp_f32_e64 v175, -v125
	s_lshl_b32 s10, s76, 8
	v_add_f32_e32 v171, 1.0, v171
	v_rcp_f32_e32 v174, v171
	v_add_f32_e32 v171, 1.0, v175
	v_exp_f32_e64 v176, -v126
	v_exp_f32_e64 v177, -v127
	v_rcp_f32_e32 v175, v171
	v_add_f32_e32 v171, 1.0, v176
	v_rcp_f32_e32 v176, v171
	v_add_f32_e32 v171, 1.0, v177
	v_rcp_f32_e32 v177, v171
	v_pk_mul_f32 v[122:123], v[126:127], v[122:123]
	v_pk_mul_f32 v[120:121], v[124:125], v[120:121]
	s_or_b32 s10, s10, s59
	v_pk_mul_f32 v[120:121], v[120:121], v[174:175]
	v_pk_mul_f32 v[122:123], v[122:123], v[176:177]
	s_ashr_i32 s10, s10, 1
	v_cvt_pk_bf16_f32 v120, v120, v121
	v_cvt_pk_bf16_f32 v121, v122, v123
	v_or_b32_e32 v140, s10, v146
	v_exp_f32_e64 v122, -v116
	v_exp_f32_e64 v123, -v117
	v_lshl_add_u32 v170, s75, 8, v144
	v_ashrrev_i32_e32 v141, 31, v140
	v_mov_b64_e32 v[142:143], s[12:13]
	v_mad_i64_i32 v[172:173], s[34:35], v170, s69, v[142:143]
	v_lshlrev_b64 v[140:141], 1, v[140:141]
	v_lshl_add_u64 v[172:173], v[172:173], 0, v[140:141]
	global_store_dwordx2 v[172:173], v[120:121], off
	v_add_f32_e32 v120, 1.0, v122
	v_add_f32_e32 v121, 1.0, v123
	v_exp_f32_e64 v122, -v118
	v_exp_f32_e64 v123, -v119
	v_rcp_f32_e32 v120, v120
	v_rcp_f32_e32 v121, v121
	v_add_f32_e32 v122, 1.0, v122
	v_add_f32_e32 v123, 1.0, v123
	v_rcp_f32_e32 v122, v122
	v_rcp_f32_e32 v123, v123
	v_pk_mul_f32 v[114:115], v[118:119], v[114:115]
	v_pk_mul_f32 v[112:113], v[116:117], v[112:113]
	v_pk_mul_f32 v[112:113], v[112:113], v[120:121]
	v_pk_mul_f32 v[114:115], v[114:115], v[122:123]
	v_cvt_pk_bf16_f32 v112, v112, v113
	v_cvt_pk_bf16_f32 v113, v114, v115
	v_exp_f32_e64 v114, -v108
	v_exp_f32_e64 v115, -v109
	v_exp_f32_e64 v116, -v110
	v_exp_f32_e64 v117, -v111
	v_add_f32_e32 v114, 1.0, v114
	v_add_f32_e32 v115, 1.0, v115
	v_add_f32_e32 v116, 1.0, v116
	v_add_f32_e32 v117, 1.0, v117
	v_rcp_f32_e32 v114, v114
	v_rcp_f32_e32 v115, v115
	v_rcp_f32_e32 v116, v116
	v_rcp_f32_e32 v117, v117
	v_pk_mul_f32 v[106:107], v[110:111], v[106:107]
	v_pk_mul_f32 v[104:105], v[108:109], v[104:105]
	global_store_dwordx2 v[172:173], v[112:113], off offset:128
	v_pk_mul_f32 v[104:105], v[104:105], v[114:115]
	v_pk_mul_f32 v[106:107], v[106:107], v[116:117]
	v_cvt_pk_bf16_f32 v104, v104, v105
	v_cvt_pk_bf16_f32 v105, v106, v107
	v_exp_f32_e64 v106, -v100
	v_exp_f32_e64 v107, -v101
	v_or_b32_e32 v112, 16, v170
	v_mad_i64_i32 v[112:113], s[34:35], v112, s69, v[142:143]
	v_lshl_add_u64 v[112:113], v[112:113], 0, v[140:141]
	global_store_dwordx2 v[112:113], v[104:105], off
	v_add_f32_e32 v104, 1.0, v106
	v_add_f32_e32 v105, 1.0, v107
	v_exp_f32_e64 v106, -v102
	v_exp_f32_e64 v107, -v103
	v_rcp_f32_e32 v104, v104
	v_rcp_f32_e32 v105, v105
	v_add_f32_e32 v106, 1.0, v106
	v_add_f32_e32 v107, 1.0, v107
	v_rcp_f32_e32 v106, v106
	v_rcp_f32_e32 v107, v107
	v_pk_mul_f32 v[98:99], v[102:103], v[98:99]
	v_pk_mul_f32 v[96:97], v[100:101], v[96:97]
	v_pk_mul_f32 v[96:97], v[96:97], v[104:105]
	v_pk_mul_f32 v[98:99], v[98:99], v[106:107]
	v_cvt_pk_bf16_f32 v96, v96, v97
	v_cvt_pk_bf16_f32 v97, v98, v99
	v_exp_f32_e64 v98, -v92
	v_exp_f32_e64 v99, -v93
	v_exp_f32_e64 v100, -v94
	v_exp_f32_e64 v101, -v95
	v_add_f32_e32 v98, 1.0, v98
	v_add_f32_e32 v99, 1.0, v99
	v_add_f32_e32 v100, 1.0, v100
	v_add_f32_e32 v101, 1.0, v101
	v_rcp_f32_e32 v98, v98
	v_rcp_f32_e32 v99, v99
	v_rcp_f32_e32 v100, v100
	v_rcp_f32_e32 v101, v101
	v_pk_mul_f32 v[90:91], v[94:95], v[90:91]
	v_pk_mul_f32 v[88:89], v[92:93], v[88:89]
	global_store_dwordx2 v[112:113], v[96:97], off offset:128
	v_pk_mul_f32 v[88:89], v[88:89], v[98:99]
	v_pk_mul_f32 v[90:91], v[90:91], v[100:101]
	v_cvt_pk_bf16_f32 v88, v88, v89
	v_cvt_pk_bf16_f32 v89, v90, v91
	v_exp_f32_e64 v90, -v84
	v_exp_f32_e64 v91, -v85
	v_or_b32_e32 v96, 32, v170
	v_mad_i64_i32 v[96:97], s[34:35], v96, s69, v[142:143]
	v_lshl_add_u64 v[96:97], v[96:97], 0, v[140:141]
	global_store_dwordx2 v[96:97], v[88:89], off
	v_add_f32_e32 v88, 1.0, v90
	v_add_f32_e32 v89, 1.0, v91
	v_exp_f32_e64 v90, -v86
	v_exp_f32_e64 v91, -v87
	v_rcp_f32_e32 v88, v88
	v_rcp_f32_e32 v89, v89
	v_add_f32_e32 v90, 1.0, v90
	v_add_f32_e32 v91, 1.0, v91
	v_rcp_f32_e32 v90, v90
	v_rcp_f32_e32 v91, v91
	v_pk_mul_f32 v[82:83], v[86:87], v[82:83]
	v_pk_mul_f32 v[80:81], v[84:85], v[80:81]
	v_pk_mul_f32 v[80:81], v[80:81], v[88:89]
	v_pk_mul_f32 v[82:83], v[82:83], v[90:91]
	v_cvt_pk_bf16_f32 v80, v80, v81
	v_cvt_pk_bf16_f32 v81, v82, v83
	v_exp_f32_e64 v82, -v76
	v_exp_f32_e64 v83, -v77
	v_exp_f32_e64 v84, -v78
	v_exp_f32_e64 v85, -v79
	v_add_f32_e32 v82, 1.0, v82
	v_add_f32_e32 v83, 1.0, v83
	v_add_f32_e32 v84, 1.0, v84
	v_add_f32_e32 v85, 1.0, v85
	v_rcp_f32_e32 v82, v82
	v_rcp_f32_e32 v83, v83
	v_rcp_f32_e32 v84, v84
	v_rcp_f32_e32 v85, v85
	v_pk_mul_f32 v[74:75], v[78:79], v[74:75]
	v_pk_mul_f32 v[72:73], v[76:77], v[72:73]
	global_store_dwordx2 v[96:97], v[80:81], off offset:128
	v_pk_mul_f32 v[72:73], v[72:73], v[82:83]
	v_pk_mul_f32 v[74:75], v[74:75], v[84:85]
	v_cvt_pk_bf16_f32 v72, v72, v73
	v_cvt_pk_bf16_f32 v73, v74, v75
	v_exp_f32_e64 v74, -v68
	v_exp_f32_e64 v75, -v69
	v_or_b32_e32 v80, 48, v170
	v_mad_i64_i32 v[80:81], s[34:35], v80, s69, v[142:143]
	v_lshl_add_u64 v[80:81], v[80:81], 0, v[140:141]
	global_store_dwordx2 v[80:81], v[72:73], off
	v_add_f32_e32 v72, 1.0, v74
	v_add_f32_e32 v73, 1.0, v75
	v_exp_f32_e64 v74, -v70
	v_exp_f32_e64 v75, -v71
	v_rcp_f32_e32 v72, v72
	v_rcp_f32_e32 v73, v73
	v_add_f32_e32 v74, 1.0, v74
	v_add_f32_e32 v75, 1.0, v75
	v_rcp_f32_e32 v74, v74
	v_rcp_f32_e32 v75, v75
	v_pk_mul_f32 v[66:67], v[70:71], v[66:67]
	v_pk_mul_f32 v[64:65], v[68:69], v[64:65]
; DI float ex2(float x) { return __builtin_amdgcn_exp2f(x); }
;     DI void operator()(const f32x4 (&acc)[2][2][4][2], const Unit& u, int wr, int wc, int fr, int fq) const {
;         const int row0 = u.pm * BM + wr * 64 + fr, hcol0 = ((u.pn * BM + wc * 32) >> 1) + 4 * fq;
; #pragma unroll
;         for (int ai = 0; ai < 2; ++ai)
; #pragma unroll
;             for (int m = 0; m < 4; ++m) { u16* rowp = O + (size_t)(row0 + ai * HALF + m * 16) * ldc + hcol0;
; #pragma unroll
;                 for (int bj = 0; bj < 2; ++bj) { const f32x4 g = acc[ai][bj][m][0], up = acc[ai][bj][m][1]; float r[4];
; #pragma unroll
;                     for (int j = 0; j < 4; ++j) r[j] = g[j] * up[j] * __builtin_amdgcn_rcpf(1.f + ex2(-LOG2E * g[j]));
;                     uint2 w = {pack2(r[0], r[1]), pack2(r[2], r[3])}; *(uint2*)(rowp + bj * (HALF / 2)) = w; } }
;     }
	v_pk_mul_f32 v[64:65], v[64:65], v[72:73]
	v_pk_mul_f32 v[66:67], v[66:67], v[74:75]
	v_cvt_pk_bf16_f32 v64, v64, v65
	v_cvt_pk_bf16_f32 v65, v66, v67
	v_exp_f32_e64 v66, -v60
	v_exp_f32_e64 v67, -v61
	v_exp_f32_e64 v68, -v62
	v_exp_f32_e64 v69, -v63
	v_add_f32_e32 v66, 1.0, v66
	v_add_f32_e32 v67, 1.0, v67
	v_add_f32_e32 v68, 1.0, v68
	v_add_f32_e32 v69, 1.0, v69
	v_rcp_f32_e32 v66, v66
	v_rcp_f32_e32 v67, v67
	v_rcp_f32_e32 v68, v68
	v_rcp_f32_e32 v69, v69
	v_pk_mul_f32 v[58:59], v[62:63], v[58:59]
	v_pk_mul_f32 v[56:57], v[60:61], v[56:57]
	global_store_dwordx2 v[80:81], v[64:65], off offset:128
	v_pk_mul_f32 v[56:57], v[56:57], v[66:67]
	v_pk_mul_f32 v[58:59], v[58:59], v[68:69]
	v_cvt_pk_bf16_f32 v56, v56, v57
	v_cvt_pk_bf16_f32 v57, v58, v59
	v_exp_f32_e64 v58, -v52
	v_exp_f32_e64 v59, -v53
	v_add_u32_e32 v64, 0x80, v170
	v_mad_i64_i32 v[64:65], s[34:35], v64, s69, v[142:143]
	v_lshl_add_u64 v[64:65], v[64:65], 0, v[140:141]
	global_store_dwordx2 v[64:65], v[56:57], off
	v_add_f32_e32 v56, 1.0, v58
	v_add_f32_e32 v57, 1.0, v59
	v_exp_f32_e64 v58, -v54
	v_exp_f32_e64 v59, -v55
	v_rcp_f32_e32 v56, v56
	v_rcp_f32_e32 v57, v57
	v_add_f32_e32 v58, 1.0, v58
	v_add_f32_e32 v59, 1.0, v59
	v_rcp_f32_e32 v58, v58
	v_rcp_f32_e32 v59, v59
	v_pk_mul_f32 v[50:51], v[54:55], v[50:51]
	v_pk_mul_f32 v[48:49], v[52:53], v[48:49]
	v_pk_mul_f32 v[48:49], v[48:49], v[56:57]
	v_pk_mul_f32 v[50:51], v[50:51], v[58:59]
	v_cvt_pk_bf16_f32 v48, v48, v49
	v_cvt_pk_bf16_f32 v49, v50, v51
	v_exp_f32_e64 v50, -v44
	v_exp_f32_e64 v51, -v45
	v_exp_f32_e64 v52, -v46
	v_exp_f32_e64 v53, -v47
	v_add_f32_e32 v50, 1.0, v50
	v_add_f32_e32 v51, 1.0, v51
	v_add_f32_e32 v52, 1.0, v52
	v_add_f32_e32 v53, 1.0, v53
	v_rcp_f32_e32 v50, v50
	v_rcp_f32_e32 v51, v51
	v_rcp_f32_e32 v52, v52
	v_rcp_f32_e32 v53, v53
	v_pk_mul_f32 v[42:43], v[46:47], v[42:43]
	v_pk_mul_f32 v[40:41], v[44:45], v[40:41]
	global_store_dwordx2 v[64:65], v[48:49], off offset:128
	v_pk_mul_f32 v[40:41], v[40:41], v[50:51]
	v_pk_mul_f32 v[42:43], v[42:43], v[52:53]
	v_cvt_pk_bf16_f32 v40, v40, v41
	v_cvt_pk_bf16_f32 v41, v42, v43
	v_exp_f32_e64 v42, -v36
	v_exp_f32_e64 v43, -v37
	v_add_u32_e32 v48, 0x90, v170
	v_mad_i64_i32 v[48:49], s[34:35], v48, s69, v[142:143]
	v_lshl_add_u64 v[48:49], v[48:49], 0, v[140:141]
	global_store_dwordx2 v[48:49], v[40:41], off
	v_add_f32_e32 v40, 1.0, v42
	v_add_f32_e32 v41, 1.0, v43
	v_exp_f32_e64 v42, -v38
	v_exp_f32_e64 v43, -v39
	v_rcp_f32_e32 v40, v40
	v_rcp_f32_e32 v41, v41
	v_add_f32_e32 v42, 1.0, v42
	v_add_f32_e32 v43, 1.0, v43
	v_rcp_f32_e32 v42, v42
	v_rcp_f32_e32 v43, v43
	v_pk_mul_f32 v[34:35], v[38:39], v[34:35]
	v_pk_mul_f32 v[32:33], v[36:37], v[32:33]
	v_pk_mul_f32 v[32:33], v[32:33], v[40:41]
	v_pk_mul_f32 v[34:35], v[34:35], v[42:43]
	v_cvt_pk_bf16_f32 v32, v32, v33
	v_cvt_pk_bf16_f32 v33, v34, v35
	v_exp_f32_e64 v34, -v28
	v_exp_f32_e64 v35, -v29
	v_exp_f32_e64 v36, -v30
	v_exp_f32_e64 v37, -v31
	v_add_f32_e32 v34, 1.0, v34
	v_add_f32_e32 v35, 1.0, v35
	v_add_f32_e32 v36, 1.0, v36
	v_add_f32_e32 v37, 1.0, v37
	v_rcp_f32_e32 v34, v34
	v_rcp_f32_e32 v35, v35
	v_rcp_f32_e32 v36, v36
	v_rcp_f32_e32 v37, v37
	v_pk_mul_f32 v[26:27], v[30:31], v[26:27]
	v_pk_mul_f32 v[24:25], v[28:29], v[24:25]
	global_store_dwordx2 v[48:49], v[32:33], off offset:128
	v_pk_mul_f32 v[24:25], v[24:25], v[34:35]
	v_pk_mul_f32 v[26:27], v[26:27], v[36:37]
	v_cvt_pk_bf16_f32 v24, v24, v25
	v_cvt_pk_bf16_f32 v25, v26, v27
	v_exp_f32_e64 v26, -v20
	v_exp_f32_e64 v27, -v21
	v_add_u32_e32 v32, 0xa0, v170
	v_mad_i64_i32 v[32:33], s[34:35], v32, s69, v[142:143]
	v_lshl_add_u64 v[32:33], v[32:33], 0, v[140:141]
	global_store_dwordx2 v[32:33], v[24:25], off
	v_add_f32_e32 v24, 1.0, v26
	v_add_f32_e32 v25, 1.0, v27
	v_exp_f32_e64 v26, -v22
	v_exp_f32_e64 v27, -v23
	v_rcp_f32_e32 v24, v24
	v_rcp_f32_e32 v25, v25
	v_add_f32_e32 v26, 1.0, v26
	v_add_f32_e32 v27, 1.0, v27
	v_rcp_f32_e32 v26, v26
	v_rcp_f32_e32 v27, v27
	v_pk_mul_f32 v[18:19], v[22:23], v[18:19]
	v_pk_mul_f32 v[16:17], v[20:21], v[16:17]
	v_pk_mul_f32 v[16:17], v[16:17], v[24:25]
	v_pk_mul_f32 v[18:19], v[18:19], v[26:27]
	v_cvt_pk_bf16_f32 v16, v16, v17
	v_cvt_pk_bf16_f32 v17, v18, v19
	v_exp_f32_e64 v18, -v12
	v_exp_f32_e64 v19, -v13
	v_exp_f32_e64 v20, -v14
	v_exp_f32_e64 v21, -v15
	v_add_f32_e32 v18, 1.0, v18
	v_add_f32_e32 v19, 1.0, v19
	v_add_f32_e32 v20, 1.0, v20
	v_add_f32_e32 v21, 1.0, v21
	v_rcp_f32_e32 v18, v18
	v_rcp_f32_e32 v19, v19
	v_rcp_f32_e32 v20, v20
	v_rcp_f32_e32 v21, v21
	v_pk_mul_f32 v[10:11], v[14:15], v[10:11]
	v_pk_mul_f32 v[8:9], v[12:13], v[8:9]
	global_store_dwordx2 v[32:33], v[16:17], off offset:128
	v_pk_mul_f32 v[8:9], v[8:9], v[18:19]
	v_pk_mul_f32 v[10:11], v[10:11], v[20:21]
	v_cvt_pk_bf16_f32 v8, v8, v9
	v_cvt_pk_bf16_f32 v9, v10, v11
	v_exp_f32_e64 v10, -v4
	v_exp_f32_e64 v11, -v5
	v_add_u32_e32 v16, 0xb0, v170
	v_mad_i64_i32 v[16:17], s[34:35], v16, s69, v[142:143]
	v_lshl_add_u64 v[16:17], v[16:17], 0, v[140:141]
	global_store_dwordx2 v[16:17], v[8:9], off
	v_add_f32_e32 v8, 1.0, v10
	v_add_f32_e32 v9, 1.0, v11
	v_exp_f32_e64 v10, -v6
	v_exp_f32_e64 v11, -v7
	v_rcp_f32_e32 v8, v8
	v_rcp_f32_e32 v9, v9
	v_add_f32_e32 v10, 1.0, v10
	v_add_f32_e32 v11, 1.0, v11
	v_rcp_f32_e32 v10, v10
	v_rcp_f32_e32 v11, v11
	v_pk_mul_f32 v[2:3], v[6:7], v[2:3]
	v_pk_mul_f32 v[0:1], v[4:5], v[0:1]
	s_and_b64 vcc, exec, s[2:3]
	v_pk_mul_f32 v[0:1], v[0:1], v[8:9]
	v_pk_mul_f32 v[2:3], v[2:3], v[10:11]
	v_cvt_pk_bf16_f32 v0, v0, v1
	v_cvt_pk_bf16_f32 v1, v2, v3
	s_mov_b32 s76, s70
	s_mov_b32 s75, s71
	s_mov_b64 s[36:37], s[0:1]
	s_mov_b64 s[34:35], s[4:5]
	global_store_dwordx2 v[16:17], v[0:1], off offset:128
	s_cbranch_vccz .LBB0_432
	s_branch .Lgu3_done

; #define PG8_STAGE(bufoff, gbase, voff) do { _Pragma("unroll") for (int _i = 0; _i < 2; ++_i) \
;         __builtin_amdgcn_global_load_lds((const unsigned*)((const char*)(gbase) + (voff)[_i]), (PG8_LAS unsigned*)(lds + (bufoff) + ldsw + _i * 8192), 16, 0, 0); } while (0)
; #define PG8_LDA(dst, b, h) do { _Pragma("unroll") for (int m = 0; m < 4; ++m) _Pragma("unroll") for (int k = 0; k < 2; ++k) dst[m][k] = *(const PG8_LAS bf16x8*)(lds + PG8_SA(b, h) + aoff + m * 2048 + k * 1024); } while (0)
; #define PG8_BAR __builtin_amdgcn_s_barrier()
; template <class Epi, class Sched, bool STAMP = false>
; __device__ __forceinline__ void gemm_phase(PG8_LAS unsigned char* lds, const Gemm g, const Sched& S, const Epi& E, unsigned long long* stamps) {
;     ...
;         for (int t = 0; t < nt; t += 2) {
;             const bool last = (t == nt - 2);
;             const char* a1 = cA + (size_t)(t + 1) * kstep;
;             const char* a2 = last ? nA : cA + (size_t)(t + 2) * kstep; const char* b2 = last ? nB : cB + (size_t)(t + 2) * kstep;
;             const char* a3 = a2 + kstep; const char* b3 = b2 + kstep;
;             if (last && has_next) S.a_ready(nxt);
;             PG8_LDB(B0, 0, 0); PG8_SCHED; PG8_LDA(At, 0, 0); PG8_STAGE(PG8_SA(1, 1), a1 + hstep, voffA);
;             PG8_WAIT_L(8); PG8_BAR; PG8_WAIT_L(0); PG8_MMA(0, 0, At, B0); PG8_BAR; PG8_SCHED;
;             PG8_LDB(B1, 0, 1); PG8_STAGE(PG8_SB(0, 0), b2, voffB);
;             PG8_BAR; PG8_WAIT_L(0); PG8_MMA(0, 1, At, B1); PG8_BAR;
;             PG8_LDA(At, 0, 1); PG8_STAGE(PG8_SA(0, 0), a2, voffA);
;             PG8_BAR; PG8_WAIT_L(0); PG8_MMA(1, 0, At, B0); PG8_BAR; PG8_SCHED;
;             PG8_STAGE(PG8_SB(0, 1), b2 + hstep, voffB);
;             PG8_WAIT_V(6); PG8_BAR; PG8_MMA(1, 1, At, B1); PG8_BAR;
;             PG8_LDB(B0, 1, 0); PG8_SCHED; PG8_LDA(At, 1, 0); PG8_STAGE(PG8_SA(0, 1), a2 + hstep, voffA);
;             PG8_WAIT_L(8); PG8_BAR; PG8_WAIT_L(0); PG8_MMA(0, 0, At, B0); PG8_BAR; PG8_SCHED;
;             PG8_LDB(B1, 1, 1); PG8_STAGE(PG8_SB(1, 0), b3, voffB);
;             PG8_BAR; PG8_WAIT_L(0); PG8_MMA(0, 1, At, B1); PG8_BAR;
;             PG8_LDA(At, 1, 1); PG8_STAGE(PG8_SA(1, 0), a3, voffA);
;             PG8_BAR; PG8_WAIT_L(0); PG8_MMA(1, 0, At, B0); PG8_BAR; PG8_SCHED;
;             PG8_STAGE(PG8_SB(1, 1), b3 + hstep, voffB);
;             PG8_WAIT_V(6); PG8_BAR; PG8_MMA(1, 1, At, B1); PG8_BAR;
.Lgu3_half_loop:
	s_add_u32 s100, s77, 0x43f80
	s_addc_u32 s101, s78, 0
	s_mov_b32 m0, s64
	s_nop 0
	global_load_lds_dwordx4 v130, s[100:101]
	s_mov_b32 m0, s65
	s_nop 0
	global_load_lds_dwordx4 v128, s[100:101]
	ds_read_b128 v[140:143], v147
	ds_read_b128 v[170:173], v148
	ds_read_b128 v[174:177], v149
	ds_read_b128 v[178:181], v150
	s_add_u32 s36, s34, 0x100
	s_addc_u32 s37, s35, 0
	s_cmp_eq_u32 s10, 12
	s_cselect_b32 s43, s5, s37
	s_cselect_b32 s42, s4, s36
	s_cselect_b32 s41, s1, s78
	s_cselect_b32 s40, s0, s77
	s_mov_b32 m0, s67
	ds_read_b128 v[182:185], v145
	ds_read_b128 v[186:189], v145 offset:1024
	ds_read_b128 v[190:193], v145 offset:2048
	ds_read_b128 v[194:197], v145 offset:3072
	ds_read_b128 v[198:201], v145 offset:4096
	ds_read_b128 v[202:205], v145 offset:5120
	ds_read_b128 v[206:209], v145 offset:6144
	ds_read_b128 v[210:213], v145 offset:7168
	global_load_lds_dwordx4 v132, s[34:35]
	s_mov_b32 m0, s68
	s_nop 0
	global_load_lds_dwordx4 v134, s[34:35]
	s_waitcnt vmcnt(8)
	s_waitcnt lgkmcnt(0)
	s_barrier
	s_setprio 1
	v_mfma_f32_16x16x32_bf16 v[124:127], v[140:143], v[182:185], v[124:127]
	v_mfma_f32_16x16x32_bf16 v[120:123], v[174:177], v[182:185], v[120:123]
	v_mfma_f32_16x16x32_bf16 v[108:111], v[140:143], v[190:193], v[108:111]
	v_mfma_f32_16x16x32_bf16 v[104:107], v[174:177], v[190:193], v[104:107]
	v_mfma_f32_16x16x32_bf16 v[92:95], v[140:143], v[198:201], v[92:95]
	v_mfma_f32_16x16x32_bf16 v[88:91], v[174:177], v[198:201], v[88:91]
	v_mfma_f32_16x16x32_bf16 v[76:79], v[140:143], v[206:209], v[76:79]
	v_mfma_f32_16x16x32_bf16 v[72:75], v[174:177], v[206:209], v[72:75]
	v_mfma_f32_16x16x32_bf16 v[124:127], v[170:173], v[186:189], v[124:127]
	v_mfma_f32_16x16x32_bf16 v[120:123], v[178:181], v[186:189], v[120:123]
	v_mfma_f32_16x16x32_bf16 v[108:111], v[170:173], v[194:197], v[108:111]
	v_mfma_f32_16x16x32_bf16 v[104:107], v[178:181], v[194:197], v[104:107]
	v_mfma_f32_16x16x32_bf16 v[92:95], v[170:173], v[202:205], v[92:95]
	v_mfma_f32_16x16x32_bf16 v[88:91], v[178:181], v[202:205], v[88:91]
	v_mfma_f32_16x16x32_bf16 v[76:79], v[170:173], v[210:213], v[76:79]
	v_mfma_f32_16x16x32_bf16 v[72:75], v[178:181], v[210:213], v[72:75]
	s_setprio 0
	s_barrier
	s_mov_b32 m0, s49
	s_nop 0
	global_load_lds_dwordx4 v130, s[40:41]
	s_mov_b32 m0, s52
	s_nop 0
	global_load_lds_dwordx4 v128, s[40:41]
	s_mov_b32 m0, s46
	ds_read_b128 v[182:185], v145 offset:16384
	ds_read_b128 v[186:189], v145 offset:17408
	ds_read_b128 v[190:193], v145 offset:18432
	ds_read_b128 v[194:197], v145 offset:19456
	ds_read_b128 v[198:201], v145 offset:20480
	ds_read_b128 v[202:205], v145 offset:21504
	ds_read_b128 v[206:209], v145 offset:22528
	ds_read_b128 v[210:213], v145 offset:23552
	global_load_lds_dwordx4 v130, s[42:43]
	s_mov_b32 m0, s53
	s_nop 0
	global_load_lds_dwordx4 v128, s[42:43]
	s_waitcnt vmcnt(6)
	s_waitcnt lgkmcnt(0)
	s_barrier
	s_setprio 1
	v_mfma_f32_16x16x32_bf16 v[60:63], v[140:143], v[182:185], v[60:63]
	v_mfma_f32_16x16x32_bf16 v[56:59], v[174:177], v[182:185], v[56:59]
	v_mfma_f32_16x16x32_bf16 v[44:47], v[140:143], v[190:193], v[44:47]
	v_mfma_f32_16x16x32_bf16 v[40:43], v[174:177], v[190:193], v[40:43]
	v_mfma_f32_16x16x32_bf16 v[28:31], v[140:143], v[198:201], v[28:31]
	v_mfma_f32_16x16x32_bf16 v[24:27], v[174:177], v[198:201], v[24:27]
	v_mfma_f32_16x16x32_bf16 v[12:15], v[140:143], v[206:209], v[12:15]
	v_mfma_f32_16x16x32_bf16 v[8:11], v[174:177], v[206:209], v[8:11]
	v_mfma_f32_16x16x32_bf16 v[60:63], v[170:173], v[186:189], v[60:63]
	v_mfma_f32_16x16x32_bf16 v[56:59], v[178:181], v[186:189], v[56:59]
	v_mfma_f32_16x16x32_bf16 v[44:47], v[170:173], v[194:197], v[44:47]
	v_mfma_f32_16x16x32_bf16 v[40:43], v[178:181], v[194:197], v[40:43]
	v_mfma_f32_16x16x32_bf16 v[28:31], v[170:173], v[202:205], v[28:31]
	v_mfma_f32_16x16x32_bf16 v[24:27], v[178:181], v[202:205], v[24:27]
	v_mfma_f32_16x16x32_bf16 v[12:15], v[170:173], v[210:213], v[12:15]
	v_mfma_f32_16x16x32_bf16 v[8:11], v[178:181], v[210:213], v[8:11]
	s_setprio 0
	s_barrier
	s_add_u32 s34, s40, 0x44000
	s_addc_u32 s35, s41, 0
	s_mov_b32 m0, s54
	s_nop 0
	global_load_lds_dwordx4 v130, s[34:35]
	s_mov_b32 m0, s55
	s_nop 0
	global_load_lds_dwordx4 v128, s[34:35]
	ds_read_b128 v[140:143], v155
	ds_read_b128 v[170:173], v156
	ds_read_b128 v[174:177], v157
	ds_read_b128 v[178:181], v165
	s_add_u32 s34, s42, 0x44000
	s_addc_u32 s35, s43, 0
	s_mov_b32 m0, s56
	ds_read_b128 v[182:185], v145 offset:32768
	ds_read_b128 v[186:189], v145 offset:33792
	ds_read_b128 v[190:193], v145 offset:34816
	ds_read_b128 v[194:197], v145 offset:35840
	ds_read_b128 v[198:201], v145 offset:36864
	ds_read_b128 v[202:205], v145 offset:37888
	ds_read_b128 v[206:209], v145 offset:38912
	ds_read_b128 v[210:213], v145 offset:39936
	global_load_lds_dwordx4 v130, s[34:35]
	s_mov_b32 m0, s57
	s_nop 0
	global_load_lds_dwordx4 v128, s[34:35]
	s_waitcnt vmcnt(8)
	s_waitcnt lgkmcnt(0)
	s_barrier
	s_setprio 1
	v_mfma_f32_16x16x32_bf16 v[124:127], v[140:143], v[182:185], v[124:127]
	v_mfma_f32_16x16x32_bf16 v[120:123], v[174:177], v[182:185], v[120:123]
	v_mfma_f32_16x16x32_bf16 v[108:111], v[140:143], v[190:193], v[108:111]
	v_mfma_f32_16x16x32_bf16 v[104:107], v[174:177], v[190:193], v[104:107]
	v_mfma_f32_16x16x32_bf16 v[92:95], v[140:143], v[198:201], v[92:95]
	v_mfma_f32_16x16x32_bf16 v[88:91], v[174:177], v[198:201], v[88:91]
	v_mfma_f32_16x16x32_bf16 v[76:79], v[140:143], v[206:209], v[76:79]
	v_mfma_f32_16x16x32_bf16 v[72:75], v[174:177], v[206:209], v[72:75]
	v_mfma_f32_16x16x32_bf16 v[124:127], v[170:173], v[186:189], v[124:127]
	v_mfma_f32_16x16x32_bf16 v[120:123], v[178:181], v[186:189], v[120:123]
	v_mfma_f32_16x16x32_bf16 v[108:111], v[170:173], v[194:197], v[108:111]
	v_mfma_f32_16x16x32_bf16 v[104:107], v[178:181], v[194:197], v[104:107]
	v_mfma_f32_16x16x32_bf16 v[92:95], v[170:173], v[202:205], v[92:95]
	v_mfma_f32_16x16x32_bf16 v[88:91], v[178:181], v[202:205], v[88:91]
	v_mfma_f32_16x16x32_bf16 v[76:79], v[170:173], v[210:213], v[76:79]
	v_mfma_f32_16x16x32_bf16 v[72:75], v[178:181], v[210:213], v[72:75]
	s_setprio 0
	s_barrier
; #define PG8_STAGE(bufoff, gbase, voff) do { _Pragma("unroll") for (int _i = 0; _i < 2; ++_i) \
;         __builtin_amdgcn_global_load_lds((const unsigned*)((const char*)(gbase) + (voff)[_i]), (PG8_LAS unsigned*)(lds + (bufoff) + ldsw + _i * 8192), 16, 0, 0); } while (0)
; #define PG8_LDA(dst, b, h) do { _Pragma("unroll") for (int m = 0; m < 4; ++m) _Pragma("unroll") for (int k = 0; k < 2; ++k) dst[m][k] = *(const PG8_LAS bf16x8*)(lds + PG8_SA(b, h) + aoff + m * 2048 + k * 1024); } while (0)
; #define PG8_MMA(ai, bj, At, Bt) do { __builtin_amdgcn_s_setprio(1); _Pragma("unroll") for (int m = 0; m < 4; ++m) _Pragma("unroll") for (int n = 0; n < 2; ++n) _Pragma("unroll") for (int k = 0; k < 2; ++k) \
;         acc[ai][bj][m][n] = __builtin_amdgcn_mfma_f32_16x16x32_bf16(Bt[n][k], At[m][k], acc[ai][bj][m][n], 0, 0, 0); __builtin_amdgcn_s_setprio(0); } while (0)
; #define PG8_WAIT_V(n) asm volatile("s_waitcnt vmcnt(" #n ")" ::: "memory")
; #define PG8_WAIT_L(n) asm volatile("s_waitcnt lgkmcnt(" #n ")" ::: "memory")
; #define PG8_BAR __builtin_amdgcn_s_barrier()
; #define PG8_SCHED __builtin_amdgcn_sched_barrier(0)
; template <class Epi, class Sched, bool STAMP = false>
; __device__ __forceinline__ void gemm_phase(PG8_LAS unsigned char* lds, const Gemm g, const Sched& S, const Epi& E, unsigned long long* stamps) {
;     ...
;             PG8_LDA(At, 1, 1); PG8_STAGE(PG8_SA(1, 0), a3, voffA);
;             PG8_BAR; PG8_WAIT_L(0); PG8_MMA(1, 0, At, B0); PG8_BAR; PG8_SCHED;
;             PG8_STAGE(PG8_SB(1, 1), b3 + hstep, voffB);
;             PG8_WAIT_V(6); PG8_BAR; PG8_MMA(1, 1, At, B1); PG8_BAR;
;         }
	s_mov_b32 m0, s60
	s_add_u32 s100, s40, 0x80
	s_addc_u32 s101, s41, 0
	global_load_lds_dwordx4 v130, s[100:101]
	s_mov_b32 m0, s61
	s_nop 0
	global_load_lds_dwordx4 v128, s[100:101]
	s_mov_b32 m0, s62
	ds_read_b128 v[182:185], v145 offset:49152
	ds_read_b128 v[186:189], v145 offset:50176
	ds_read_b128 v[190:193], v145 offset:51200
	ds_read_b128 v[194:197], v145 offset:52224
	ds_read_b128 v[198:201], v145 offset:53248
	ds_read_b128 v[202:205], v145 offset:54272
	ds_read_b128 v[206:209], v145 offset:55296
	ds_read_b128 v[210:213], v145 offset:56320
	s_add_u32 s100, s42, 0x80
	s_addc_u32 s101, s43, 0
	global_load_lds_dwordx4 v130, s[100:101]
	s_mov_b32 m0, s63
	s_nop 0
	global_load_lds_dwordx4 v128, s[100:101]
	s_waitcnt vmcnt(6)
	s_waitcnt lgkmcnt(0)
	s_barrier
	s_setprio 1
	v_mfma_f32_16x16x32_bf16 v[60:63], v[140:143], v[182:185], v[60:63]
	v_mfma_f32_16x16x32_bf16 v[56:59], v[174:177], v[182:185], v[56:59]
	v_mfma_f32_16x16x32_bf16 v[44:47], v[140:143], v[190:193], v[44:47]
	v_mfma_f32_16x16x32_bf16 v[40:43], v[174:177], v[190:193], v[40:43]
	v_mfma_f32_16x16x32_bf16 v[28:31], v[140:143], v[198:201], v[28:31]
	v_mfma_f32_16x16x32_bf16 v[24:27], v[174:177], v[198:201], v[24:27]
	v_mfma_f32_16x16x32_bf16 v[12:15], v[140:143], v[206:209], v[12:15]
	v_mfma_f32_16x16x32_bf16 v[8:11], v[174:177], v[206:209], v[8:11]
	v_mfma_f32_16x16x32_bf16 v[60:63], v[170:173], v[186:189], v[60:63]
	v_mfma_f32_16x16x32_bf16 v[56:59], v[178:181], v[186:189], v[56:59]
	v_mfma_f32_16x16x32_bf16 v[44:47], v[170:173], v[194:197], v[44:47]
	v_mfma_f32_16x16x32_bf16 v[40:43], v[178:181], v[194:197], v[40:43]
	v_mfma_f32_16x16x32_bf16 v[28:31], v[170:173], v[202:205], v[28:31]
	v_mfma_f32_16x16x32_bf16 v[24:27], v[178:181], v[202:205], v[24:27]
	v_mfma_f32_16x16x32_bf16 v[12:15], v[170:173], v[210:213], v[12:15]
	v_mfma_f32_16x16x32_bf16 v[8:11], v[178:181], v[210:213], v[8:11]
	s_setprio 0
	s_add_i32 s10, s10, 2
	s_add_u32 s77, s77, 0x100
	s_addc_u32 s78, s78, 0
	s_cmp_gt_u32 s10, 13
	s_mov_b64 s[34:35], s[36:37]
	s_barrier
	s_cbranch_scc0 .Lgu3_half_loop
; DI float ex2(float x) { return __builtin_amdgcn_exp2f(x); }
;     DI void operator()(const f32x4 (&acc)[2][2][4][2], const Unit& u, int wr, int wc, int fr, int fq) const {
;         const int row0 = u.pm * BM + wr * 64 + fr, hcol0 = ((u.pn * BM + wc * 32) >> 1) + 4 * fq;
; #pragma unroll
;         for (int ai = 0; ai < 2; ++ai)
; #pragma unroll
;             for (int m = 0; m < 4; ++m) { u16* rowp = O + (size_t)(row0 + ai * HALF + m * 16) * ldc + hcol0;
; #pragma unroll
;                 for (int bj = 0; bj < 2; ++bj) { const f32x4 g = acc[ai][bj][m][0], up = acc[ai][bj][m][1]; float r[4];
; #pragma unroll
;                     for (int j = 0; j < 4; ++j) r[j] = g[j] * up[j] * __builtin_amdgcn_rcpf(1.f + ex2(-LOG2E * g[j]));
;                     uint2 w = {pack2(r[0], r[1]), pack2(r[2], r[3])}; *(uint2*)(rowp + bj * (HALF / 2)) = w; } }
;     }
	v_exp_f32_e64 v171, -v124
	v_exp_f32_e64 v175, -v125
	s_lshl_b32 s10, s76, 8
	v_add_f32_e32 v171, 1.0, v171
	v_rcp_f32_e32 v174, v171
	v_add_f32_e32 v171, 1.0, v175
	v_exp_f32_e64 v176, -v126
	v_exp_f32_e64 v177, -v127
	v_rcp_f32_e32 v175, v171
	v_add_f32_e32 v171, 1.0, v176
	v_rcp_f32_e32 v176, v171
	v_add_f32_e32 v171, 1.0, v177
	v_rcp_f32_e32 v177, v171
	v_pk_mul_f32 v[122:123], v[126:127], v[122:123]
	v_pk_mul_f32 v[120:121], v[124:125], v[120:121]
	s_or_b32 s10, s10, s59
	s_or_b32 s10, s10, s98
	v_pk_mul_f32 v[120:121], v[120:121], v[174:175]
	v_pk_mul_f32 v[122:123], v[122:123], v[176:177]
	s_ashr_i32 s10, s10, 1
	v_cvt_pk_bf16_f32 v120, v120, v121
	v_cvt_pk_bf16_f32 v121, v122, v123
	v_or_b32_e32 v140, s10, v146
	v_lshl_add_u32 v170, s75, 8, v144
	v_ashrrev_i32_e32 v141, 31, v140
	v_mov_b64_e32 v[142:143], s[12:13]
	v_mad_i64_i32 v[172:173], s[34:35], v170, s69, v[142:143]
	v_lshlrev_b64 v[140:141], 1, v[140:141]
	v_lshl_add_u64 v[172:173], v[172:173], 0, v[140:141]
	global_store_dwordx2 v[172:173], v[120:121], off
	v_exp_f32_e64 v114, -v108
	v_exp_f32_e64 v115, -v109
	v_exp_f32_e64 v116, -v110
	v_exp_f32_e64 v117, -v111
	v_add_f32_e32 v114, 1.0, v114
	v_add_f32_e32 v115, 1.0, v115
	v_add_f32_e32 v116, 1.0, v116
	v_add_f32_e32 v117, 1.0, v117
	v_rcp_f32_e32 v114, v114
	v_rcp_f32_e32 v115, v115
	v_rcp_f32_e32 v116, v116
	v_rcp_f32_e32 v117, v117
	v_pk_mul_f32 v[106:107], v[110:111], v[106:107]
	v_pk_mul_f32 v[104:105], v[108:109], v[104:105]
	v_pk_mul_f32 v[104:105], v[104:105], v[114:115]
	v_pk_mul_f32 v[106:107], v[106:107], v[116:117]
	v_cvt_pk_bf16_f32 v104, v104, v105
	v_cvt_pk_bf16_f32 v105, v106, v107
	v_or_b32_e32 v112, 16, v170
	v_mad_i64_i32 v[112:113], s[34:35], v112, s69, v[142:143]
	v_lshl_add_u64 v[112:113], v[112:113], 0, v[140:141]
	global_store_dwordx2 v[112:113], v[104:105], off
	v_exp_f32_e64 v98, -v92
	v_exp_f32_e64 v99, -v93
	v_exp_f32_e64 v100, -v94
	v_exp_f32_e64 v101, -v95
	v_add_f32_e32 v98, 1.0, v98
	v_add_f32_e32 v99, 1.0, v99
	v_add_f32_e32 v100, 1.0, v100
	v_add_f32_e32 v101, 1.0, v101
	v_rcp_f32_e32 v98, v98
	v_rcp_f32_e32 v99, v99
	v_rcp_f32_e32 v100, v100
	v_rcp_f32_e32 v101, v101
	v_pk_mul_f32 v[90:91], v[94:95], v[90:91]
	v_pk_mul_f32 v[88:89], v[92:93], v[88:89]
	v_pk_mul_f32 v[88:89], v[88:89], v[98:99]
	v_pk_mul_f32 v[90:91], v[90:91], v[100:101]
	v_cvt_pk_bf16_f32 v88, v88, v89
	v_cvt_pk_bf16_f32 v89, v90, v91
	v_or_b32_e32 v96, 32, v170
	v_mad_i64_i32 v[96:97], s[34:35], v96, s69, v[142:143]
	v_lshl_add_u64 v[96:97], v[96:97], 0, v[140:141]
	global_store_dwordx2 v[96:97], v[88:89], off
	v_exp_f32_e64 v82, -v76
	v_exp_f32_e64 v83, -v77
	v_exp_f32_e64 v84, -v78
	v_exp_f32_e64 v85, -v79
	v_add_f32_e32 v82, 1.0, v82
	v_add_f32_e32 v83, 1.0, v83
	v_add_f32_e32 v84, 1.0, v84
	v_add_f32_e32 v85, 1.0, v85
	v_rcp_f32_e32 v82, v82
	v_rcp_f32_e32 v83, v83
	v_rcp_f32_e32 v84, v84
	v_rcp_f32_e32 v85, v85
	v_pk_mul_f32 v[74:75], v[78:79], v[74:75]
	v_pk_mul_f32 v[72:73], v[76:77], v[72:73]
	v_pk_mul_f32 v[72:73], v[72:73], v[82:83]
	v_pk_mul_f32 v[74:75], v[74:75], v[84:85]
	v_cvt_pk_bf16_f32 v72, v72, v73
	v_cvt_pk_bf16_f32 v73, v74, v75
	v_or_b32_e32 v80, 48, v170
	v_mad_i64_i32 v[80:81], s[34:35], v80, s69, v[142:143]
	v_lshl_add_u64 v[80:81], v[80:81], 0, v[140:141]
	global_store_dwordx2 v[80:81], v[72:73], off
	v_exp_f32_e64 v66, -v60
	v_exp_f32_e64 v67, -v61
	v_exp_f32_e64 v68, -v62
	v_exp_f32_e64 v69, -v63
	v_add_f32_e32 v66, 1.0, v66
	v_add_f32_e32 v67, 1.0, v67
	v_add_f32_e32 v68, 1.0, v68
	v_add_f32_e32 v69, 1.0, v69
	v_rcp_f32_e32 v66, v66
	v_rcp_f32_e32 v67, v67
	v_rcp_f32_e32 v68, v68
	v_rcp_f32_e32 v69, v69
	v_pk_mul_f32 v[58:59], v[62:63], v[58:59]
	v_pk_mul_f32 v[56:57], v[60:61], v[56:57]
	v_pk_mul_f32 v[56:57], v[56:57], v[66:67]
	v_pk_mul_f32 v[58:59], v[58:59], v[68:69]
	v_cvt_pk_bf16_f32 v56, v56, v57
	v_cvt_pk_bf16_f32 v57, v58, v59
	v_add_u32_e32 v64, 0x80, v170
	v_mad_i64_i32 v[64:65], s[34:35], v64, s69, v[142:143]
	v_lshl_add_u64 v[64:65], v[64:65], 0, v[140:141]
	global_store_dwordx2 v[64:65], v[56:57], off
	v_exp_f32_e64 v50, -v44
	v_exp_f32_e64 v51, -v45
	v_exp_f32_e64 v52, -v46
	v_exp_f32_e64 v53, -v47
	v_add_f32_e32 v50, 1.0, v50
	v_add_f32_e32 v51, 1.0, v51
	v_add_f32_e32 v52, 1.0, v52
	v_add_f32_e32 v53, 1.0, v53
	v_rcp_f32_e32 v50, v50
	v_rcp_f32_e32 v51, v51
	v_rcp_f32_e32 v52, v52
	v_rcp_f32_e32 v53, v53
	v_pk_mul_f32 v[42:43], v[46:47], v[42:43]
	v_pk_mul_f32 v[40:41], v[44:45], v[40:41]
	v_pk_mul_f32 v[40:41], v[40:41], v[50:51]
	v_pk_mul_f32 v[42:43], v[42:43], v[52:53]
	v_cvt_pk_bf16_f32 v40, v40, v41
	v_cvt_pk_bf16_f32 v41, v42, v43
	v_add_u32_e32 v48, 0x90, v170
	v_mad_i64_i32 v[48:49], s[34:35], v48, s69, v[142:143]
	v_lshl_add_u64 v[48:49], v[48:49], 0, v[140:141]
	global_store_dwordx2 v[48:49], v[40:41], off
	v_exp_f32_e64 v34, -v28
	v_exp_f32_e64 v35, -v29
	v_exp_f32_e64 v36, -v30
	v_exp_f32_e64 v37, -v31
	v_add_f32_e32 v34, 1.0, v34
	v_add_f32_e32 v35, 1.0, v35
	v_add_f32_e32 v36, 1.0, v36
	v_add_f32_e32 v37, 1.0, v37
	v_rcp_f32_e32 v34, v34
	v_rcp_f32_e32 v35, v35
	v_rcp_f32_e32 v36, v36
	v_rcp_f32_e32 v37, v37
	v_pk_mul_f32 v[26:27], v[30:31], v[26:27]
	v_pk_mul_f32 v[24:25], v[28:29], v[24:25]
	v_pk_mul_f32 v[24:25], v[24:25], v[34:35]
	v_pk_mul_f32 v[26:27], v[26:27], v[36:37]
	v_cvt_pk_bf16_f32 v24, v24, v25
	v_cvt_pk_bf16_f32 v25, v26, v27
	v_add_u32_e32 v32, 0xa0, v170
	v_mad_i64_i32 v[32:33], s[34:35], v32, s69, v[142:143]
	v_lshl_add_u64 v[32:33], v[32:33], 0, v[140:141]
	global_store_dwordx2 v[32:33], v[24:25], off
	v_exp_f32_e64 v18, -v12
	v_exp_f32_e64 v19, -v13
	v_exp_f32_e64 v20, -v14
	v_exp_f32_e64 v21, -v15
	v_add_f32_e32 v18, 1.0, v18
	v_add_f32_e32 v19, 1.0, v19
	v_add_f32_e32 v20, 1.0, v20
	v_add_f32_e32 v21, 1.0, v21
	v_rcp_f32_e32 v18, v18
	v_rcp_f32_e32 v19, v19
	v_rcp_f32_e32 v20, v20
	v_rcp_f32_e32 v21, v21
	v_pk_mul_f32 v[10:11], v[14:15], v[10:11]
	v_pk_mul_f32 v[8:9], v[12:13], v[8:9]
	v_pk_mul_f32 v[8:9], v[8:9], v[18:19]
	v_pk_mul_f32 v[10:11], v[10:11], v[20:21]
	v_cvt_pk_bf16_f32 v8, v8, v9
	v_cvt_pk_bf16_f32 v9, v10, v11
	v_add_u32_e32 v16, 0xb0, v170
	v_mad_i64_i32 v[16:17], s[34:35], v16, s69, v[142:143]
	v_lshl_add_u64 v[16:17], v[16:17], 0, v[140:141]
	global_store_dwordx2 v[16:17], v[8:9], off
	s_and_b64 vcc, exec, s[2:3]
	s_mov_b32 s76, s70
	s_mov_b32 s75, s71
	s_mov_b64 s[36:37], s[0:1]
	s_mov_b64 s[34:35], s[4:5]

; #define PG8_STAGE(bufoff, gbase, voff) do { _Pragma("unroll") for (int _i = 0; _i < 2; ++_i) \
;         __builtin_amdgcn_global_load_lds((const unsigned*)((const char*)(gbase) + (voff)[_i]), (PG8_LAS unsigned*)(lds + (bufoff) + ldsw + _i * 8192), 16, 0, 0); } while (0)
; #define PG8_LDA(dst, b, h) do { _Pragma("unroll") for (int m = 0; m < 4; ++m) _Pragma("unroll") for (int k = 0; k < 2; ++k) dst[m][k] = *(const PG8_LAS bf16x8*)(lds + PG8_SA(b, h) + aoff + m * 2048 + k * 1024); } while (0)
; #define PG8_LDB(dst, b, h) do { _Pragma("unroll") for (int n = 0; n < 2; ++n) _Pragma("unroll") for (int k = 0; k < 2; ++k) dst[n][k] = *(const PG8_LAS bf16x8*)(lds + PG8_SB(b, h) + boff + n * 2048 + k * 1024); } while (0)
; #define PG8_MMA(ai, bj, At, Bt) do { __builtin_amdgcn_s_setprio(1); _Pragma("unroll") for (int m = 0; m < 4; ++m) _Pragma("unroll") for (int n = 0; n < 2; ++n) _Pragma("unroll") for (int k = 0; k < 2; ++k) \
;         acc[ai][bj][m][n] = __builtin_amdgcn_mfma_f32_16x16x32_bf16(Bt[n][k], At[m][k], acc[ai][bj][m][n], 0, 0, 0); __builtin_amdgcn_s_setprio(0); } while (0)
; #define PG8_BAR __builtin_amdgcn_s_barrier()
; template <class Epi, class Sched, bool STAMP = false>
; __device__ __forceinline__ void gemm_phase(PG8_LAS unsigned char* lds, const Gemm g, const Sched& S, const Epi& E, unsigned long long* stamps) {
;     ...
;         for (int t = 0; t < nt; t += 2) {
;             const bool last = (t == nt - 2);
;             const char* a1 = cA + (size_t)(t + 1) * kstep;
;             const char* a2 = last ? nA : cA + (size_t)(t + 2) * kstep; const char* b2 = last ? nB : cB + (size_t)(t + 2) * kstep;
;             const char* a3 = a2 + kstep; const char* b3 = b2 + kstep;
;             if (last && has_next) S.a_ready(nxt);
;             PG8_LDB(B0, 0, 0); PG8_SCHED; PG8_LDA(At, 0, 0); PG8_STAGE(PG8_SA(1, 1), a1 + hstep, voffA);
;             PG8_WAIT_L(8); PG8_BAR; PG8_WAIT_L(0); PG8_MMA(0, 0, At, B0); PG8_BAR; PG8_SCHED;
;             PG8_LDB(B1, 0, 1); PG8_STAGE(PG8_SB(0, 0), b2, voffB);
;             PG8_BAR; PG8_WAIT_L(0); PG8_MMA(0, 1, At, B1); PG8_BAR;
;             PG8_LDA(At, 0, 1); PG8_STAGE(PG8_SA(0, 0), a2, voffA);
;             PG8_BAR; PG8_WAIT_L(0); PG8_MMA(1, 0, At, B0); PG8_BAR; PG8_SCHED;
;             PG8_STAGE(PG8_SB(0, 1), b2 + hstep, voffB);
;             PG8_WAIT_V(6); PG8_BAR; PG8_MMA(1, 1, At, B1); PG8_BAR;
.LBB0_472:
	s_add_u32 s88, s46, 0x100
	s_addc_u32 s89, s47, 0
	s_mov_b32 s10, -2
	s_add_u32 s100, s88, 0xb3f80
	s_addc_u32 s101, s89, 0
	s_mov_b32 m0, s69
	s_nop 0
	global_load_lds_dwordx4 v130, s[100:101]
	s_mov_b32 m0, s70
	s_nop 0
	global_load_lds_dwordx4 v134, s[100:101]
	ds_read_b128 v[170:173], v147
	ds_read_b128 v[174:177], v148
	ds_read_b128 v[178:181], v149
	ds_read_b128 v[182:185], v150
	s_add_u32 s46, s44, 0x100
	s_addc_u32 s47, s45, 0
	s_cmp_eq_u32 s10, 40
	s_cselect_b32 s53, s5, s47
	s_cselect_b32 s52, s4, s46
	s_cselect_b32 s49, s1, s89
	s_cselect_b32 s48, s0, s88
	s_mov_b32 m0, s76
	ds_read_b128 v[186:189], v145
	ds_read_b128 v[190:193], v145 offset:1024
	ds_read_b128 v[194:197], v145 offset:2048
	ds_read_b128 v[198:201], v145 offset:3072
	ds_read_b128 v[202:205], v145 offset:4096
	ds_read_b128 v[206:209], v145 offset:5120
	ds_read_b128 v[210:213], v145 offset:6144
	ds_read_b128 v[214:217], v145 offset:7168
	global_load_lds_dwordx4 v136, s[44:45]
	s_mov_b32 m0, s77
	s_nop 0
	global_load_lds_dwordx4 v138, s[44:45]
	ds_read_b128 v[218:221], v151
	ds_read_b128 v[222:225], v152
	ds_read_b128 v[226:229], v153
	ds_read_b128 v[230:233], v154
	s_waitcnt vmcnt(8)
	s_waitcnt lgkmcnt(0)
	s_barrier
	s_setprio 1
	v_mfma_f32_16x16x32_bf16 v[124:127], v[170:173], v[186:189], 0
	v_mfma_f32_16x16x32_bf16 v[120:123], v[178:181], v[186:189], 0
	v_mfma_f32_16x16x32_bf16 v[116:119], v[170:173], v[194:197], 0
	v_mfma_f32_16x16x32_bf16 v[112:115], v[178:181], v[194:197], 0
	v_mfma_f32_16x16x32_bf16 v[100:103], v[170:173], v[202:205], 0
	v_mfma_f32_16x16x32_bf16 v[96:99], v[178:181], v[202:205], 0
	v_mfma_f32_16x16x32_bf16 v[84:87], v[170:173], v[210:213], 0
	v_mfma_f32_16x16x32_bf16 v[80:83], v[178:181], v[210:213], 0
	v_mfma_f32_16x16x32_bf16 v[124:127], v[174:177], v[190:193], v[124:127]
	v_mfma_f32_16x16x32_bf16 v[120:123], v[182:185], v[190:193], v[120:123]
	v_mfma_f32_16x16x32_bf16 v[116:119], v[174:177], v[198:201], v[116:119]
	v_mfma_f32_16x16x32_bf16 v[112:115], v[182:185], v[198:201], v[112:115]
	v_mfma_f32_16x16x32_bf16 v[100:103], v[174:177], v[206:209], v[100:103]
	v_mfma_f32_16x16x32_bf16 v[96:99], v[182:185], v[206:209], v[96:99]
	v_mfma_f32_16x16x32_bf16 v[84:87], v[174:177], v[214:217], v[84:87]
	v_mfma_f32_16x16x32_bf16 v[80:83], v[182:185], v[214:217], v[80:83]
	v_mfma_f32_16x16x32_bf16 v[108:111], v[218:221], v[186:189], 0
	v_mfma_f32_16x16x32_bf16 v[104:107], v[226:229], v[186:189], 0
	v_mfma_f32_16x16x32_bf16 v[92:95], v[218:221], v[194:197], 0
	v_mfma_f32_16x16x32_bf16 v[88:91], v[226:229], v[194:197], 0
	v_mfma_f32_16x16x32_bf16 v[76:79], v[218:221], v[202:205], 0
	v_mfma_f32_16x16x32_bf16 v[72:75], v[226:229], v[202:205], 0
	v_mfma_f32_16x16x32_bf16 v[68:71], v[218:221], v[210:213], 0
	v_mfma_f32_16x16x32_bf16 v[64:67], v[226:229], v[210:213], 0
	v_mfma_f32_16x16x32_bf16 v[108:111], v[222:225], v[190:193], v[108:111]
	v_mfma_f32_16x16x32_bf16 v[104:107], v[230:233], v[190:193], v[104:107]
	v_mfma_f32_16x16x32_bf16 v[92:95], v[222:225], v[198:201], v[92:95]
	v_mfma_f32_16x16x32_bf16 v[88:91], v[230:233], v[198:201], v[88:91]
	v_mfma_f32_16x16x32_bf16 v[76:79], v[222:225], v[206:209], v[76:79]
	v_mfma_f32_16x16x32_bf16 v[72:75], v[230:233], v[206:209], v[72:75]
	v_mfma_f32_16x16x32_bf16 v[68:71], v[222:225], v[214:217], v[68:71]
	v_mfma_f32_16x16x32_bf16 v[64:67], v[230:233], v[214:217], v[64:67]
	s_setprio 0
	s_barrier
	s_mov_b32 m0, s58
	s_nop 0
	global_load_lds_dwordx4 v130, s[48:49]
	s_mov_b32 m0, s59
	s_nop 0
	global_load_lds_dwordx4 v134, s[48:49]
	s_mov_b32 m0, s57
	ds_read_b128 v[186:189], v145 offset:16384
	ds_read_b128 v[190:193], v145 offset:17408
	ds_read_b128 v[194:197], v145 offset:18432
	ds_read_b128 v[198:201], v145 offset:19456
	ds_read_b128 v[202:205], v145 offset:20480
	ds_read_b128 v[206:209], v145 offset:21504
	ds_read_b128 v[210:213], v145 offset:22528
	ds_read_b128 v[214:217], v145 offset:23552
	global_load_lds_dwordx4 v128, s[52:53]
	s_mov_b32 m0, s60
	s_nop 0
	global_load_lds_dwordx4 v132, s[52:53]
	s_waitcnt vmcnt(6)
	s_waitcnt lgkmcnt(0)
	s_barrier
	s_setprio 1
	v_mfma_f32_16x16x32_bf16 v[60:63], v[170:173], v[186:189], 0
	v_mfma_f32_16x16x32_bf16 v[56:59], v[178:181], v[186:189], 0
	v_mfma_f32_16x16x32_bf16 v[52:55], v[170:173], v[194:197], 0
	v_mfma_f32_16x16x32_bf16 v[48:51], v[178:181], v[194:197], 0
	v_mfma_f32_16x16x32_bf16 v[36:39], v[170:173], v[202:205], 0
	v_mfma_f32_16x16x32_bf16 v[32:35], v[178:181], v[202:205], 0
	v_mfma_f32_16x16x32_bf16 v[20:23], v[170:173], v[210:213], 0
	v_mfma_f32_16x16x32_bf16 v[16:19], v[178:181], v[210:213], 0
	v_mfma_f32_16x16x32_bf16 v[60:63], v[174:177], v[190:193], v[60:63]
	v_mfma_f32_16x16x32_bf16 v[56:59], v[182:185], v[190:193], v[56:59]
	v_mfma_f32_16x16x32_bf16 v[52:55], v[174:177], v[198:201], v[52:55]
	v_mfma_f32_16x16x32_bf16 v[48:51], v[182:185], v[198:201], v[48:51]
	v_mfma_f32_16x16x32_bf16 v[36:39], v[174:177], v[206:209], v[36:39]
	v_mfma_f32_16x16x32_bf16 v[32:35], v[182:185], v[206:209], v[32:35]
	v_mfma_f32_16x16x32_bf16 v[20:23], v[174:177], v[214:217], v[20:23]
	v_mfma_f32_16x16x32_bf16 v[16:19], v[182:185], v[214:217], v[16:19]
	v_mfma_f32_16x16x32_bf16 v[44:47], v[218:221], v[186:189], 0
	v_mfma_f32_16x16x32_bf16 v[40:43], v[226:229], v[186:189], 0
	v_mfma_f32_16x16x32_bf16 v[28:31], v[218:221], v[194:197], 0
	v_mfma_f32_16x16x32_bf16 v[24:27], v[226:229], v[194:197], 0
	v_mfma_f32_16x16x32_bf16 v[12:15], v[218:221], v[202:205], 0
	v_mfma_f32_16x16x32_bf16 v[8:11], v[226:229], v[202:205], 0
	v_mfma_f32_16x16x32_bf16 v[4:7], v[218:221], v[210:213], 0
	v_mfma_f32_16x16x32_bf16 v[0:3], v[226:229], v[210:213], 0
	v_mfma_f32_16x16x32_bf16 v[44:47], v[222:225], v[190:193], v[44:47]
	v_mfma_f32_16x16x32_bf16 v[40:43], v[230:233], v[190:193], v[40:43]
	v_mfma_f32_16x16x32_bf16 v[28:31], v[222:225], v[198:201], v[28:31]
	v_mfma_f32_16x16x32_bf16 v[24:27], v[230:233], v[198:201], v[24:27]
	v_mfma_f32_16x16x32_bf16 v[12:15], v[222:225], v[206:209], v[12:15]
	v_mfma_f32_16x16x32_bf16 v[8:11], v[230:233], v[206:209], v[8:11]
	v_mfma_f32_16x16x32_bf16 v[4:7], v[222:225], v[214:217], v[4:7]
	v_mfma_f32_16x16x32_bf16 v[0:3], v[230:233], v[214:217], v[0:3]
	s_setprio 0
	s_barrier
	s_branch .Lzp8_mid
; #define PG8_STAGE(bufoff, gbase, voff) do { _Pragma("unroll") for (int _i = 0; _i < 2; ++_i) \
;         __builtin_amdgcn_global_load_lds((const unsigned*)((const char*)(gbase) + (voff)[_i]), (PG8_LAS unsigned*)(lds + (bufoff) + ldsw + _i * 8192), 16, 0, 0); } while (0)
; #define PG8_LDA(dst, b, h) do { _Pragma("unroll") for (int m = 0; m < 4; ++m) _Pragma("unroll") for (int k = 0; k < 2; ++k) dst[m][k] = *(const PG8_LAS bf16x8*)(lds + PG8_SA(b, h) + aoff + m * 2048 + k * 1024); } while (0)
; #define PG8_LDB(dst, b, h) do { _Pragma("unroll") for (int n = 0; n < 2; ++n) _Pragma("unroll") for (int k = 0; k < 2; ++k) dst[n][k] = *(const PG8_LAS bf16x8*)(lds + PG8_SB(b, h) + boff + n * 2048 + k * 1024); } while (0)
; #define PG8_MMA(ai, bj, At, Bt) do { __builtin_amdgcn_s_setprio(1); _Pragma("unroll") for (int m = 0; m < 4; ++m) _Pragma("unroll") for (int n = 0; n < 2; ++n) _Pragma("unroll") for (int k = 0; k < 2; ++k) \
;         acc[ai][bj][m][n] = __builtin_amdgcn_mfma_f32_16x16x32_bf16(Bt[n][k], At[m][k], acc[ai][bj][m][n], 0, 0, 0); __builtin_amdgcn_s_setprio(0); } while (0)
; #define PG8_BAR __builtin_amdgcn_s_barrier()
; template <class Epi, class Sched, bool STAMP = false>
; __device__ __forceinline__ void gemm_phase(PG8_LAS unsigned char* lds, const Gemm g, const Sched& S, const Epi& E, unsigned long long* stamps) {
;     ...
;         for (int t = 0; t < nt; t += 2) {
;             const bool last = (t == nt - 2);
;             const char* a1 = cA + (size_t)(t + 1) * kstep;
;             const char* a2 = last ? nA : cA + (size_t)(t + 2) * kstep; const char* b2 = last ? nB : cB + (size_t)(t + 2) * kstep;
;             const char* a3 = a2 + kstep; const char* b3 = b2 + kstep;
;             if (last && has_next) S.a_ready(nxt);
;             PG8_LDB(B0, 0, 0); PG8_SCHED; PG8_LDA(At, 0, 0); PG8_STAGE(PG8_SA(1, 1), a1 + hstep, voffA);
;             PG8_WAIT_L(8); PG8_BAR; PG8_WAIT_L(0); PG8_MMA(0, 0, At, B0); PG8_BAR; PG8_SCHED;
;             PG8_LDB(B1, 0, 1); PG8_STAGE(PG8_SB(0, 0), b2, voffB);
;             PG8_BAR; PG8_WAIT_L(0); PG8_MMA(0, 1, At, B1); PG8_BAR;
;             PG8_LDA(At, 0, 1); PG8_STAGE(PG8_SA(0, 0), a2, voffA);
;             PG8_BAR; PG8_WAIT_L(0); PG8_MMA(1, 0, At, B0); PG8_BAR; PG8_SCHED;
;             PG8_STAGE(PG8_SB(0, 1), b2 + hstep, voffB);
;             PG8_WAIT_V(6); PG8_BAR; PG8_MMA(1, 1, At, B1); PG8_BAR;
.LBB0_473:
	s_add_u32 s100, s88, 0xb3f80
	s_addc_u32 s101, s89, 0
	s_mov_b32 m0, s69
	s_nop 0
	global_load_lds_dwordx4 v130, s[100:101]
	s_mov_b32 m0, s70
	s_nop 0
	global_load_lds_dwordx4 v134, s[100:101]
	ds_read_b128 v[170:173], v147
	ds_read_b128 v[174:177], v148
	ds_read_b128 v[178:181], v149
	ds_read_b128 v[182:185], v150
	s_add_u32 s46, s44, 0x100
	s_addc_u32 s47, s45, 0
	s_cmp_eq_u32 s10, 40
	s_cselect_b32 s53, s5, s47
	s_cselect_b32 s52, s4, s46
	s_cselect_b32 s49, s1, s89
	s_cselect_b32 s48, s0, s88
	s_mov_b32 m0, s76
	ds_read_b128 v[186:189], v145
	ds_read_b128 v[190:193], v145 offset:1024
	ds_read_b128 v[194:197], v145 offset:2048
	ds_read_b128 v[198:201], v145 offset:3072
	ds_read_b128 v[202:205], v145 offset:4096
	ds_read_b128 v[206:209], v145 offset:5120
	ds_read_b128 v[210:213], v145 offset:6144
	ds_read_b128 v[214:217], v145 offset:7168
	global_load_lds_dwordx4 v136, s[44:45]
	s_mov_b32 m0, s77
	s_nop 0
	global_load_lds_dwordx4 v138, s[44:45]
	ds_read_b128 v[218:221], v151
	ds_read_b128 v[222:225], v152
	ds_read_b128 v[226:229], v153
	ds_read_b128 v[230:233], v154
	s_waitcnt vmcnt(8)
	s_waitcnt lgkmcnt(0)
	s_barrier
	s_setprio 1
	v_mfma_f32_16x16x32_bf16 v[124:127], v[170:173], v[186:189], v[124:127]
	v_mfma_f32_16x16x32_bf16 v[120:123], v[178:181], v[186:189], v[120:123]
	v_mfma_f32_16x16x32_bf16 v[116:119], v[170:173], v[194:197], v[116:119]
	v_mfma_f32_16x16x32_bf16 v[112:115], v[178:181], v[194:197], v[112:115]
	v_mfma_f32_16x16x32_bf16 v[100:103], v[170:173], v[202:205], v[100:103]
	v_mfma_f32_16x16x32_bf16 v[96:99], v[178:181], v[202:205], v[96:99]
	v_mfma_f32_16x16x32_bf16 v[84:87], v[170:173], v[210:213], v[84:87]
	v_mfma_f32_16x16x32_bf16 v[80:83], v[178:181], v[210:213], v[80:83]
	v_mfma_f32_16x16x32_bf16 v[124:127], v[174:177], v[190:193], v[124:127]
	v_mfma_f32_16x16x32_bf16 v[120:123], v[182:185], v[190:193], v[120:123]
	v_mfma_f32_16x16x32_bf16 v[116:119], v[174:177], v[198:201], v[116:119]
	v_mfma_f32_16x16x32_bf16 v[112:115], v[182:185], v[198:201], v[112:115]
	v_mfma_f32_16x16x32_bf16 v[100:103], v[174:177], v[206:209], v[100:103]
	v_mfma_f32_16x16x32_bf16 v[96:99], v[182:185], v[206:209], v[96:99]
	v_mfma_f32_16x16x32_bf16 v[84:87], v[174:177], v[214:217], v[84:87]
	v_mfma_f32_16x16x32_bf16 v[80:83], v[182:185], v[214:217], v[80:83]
	v_mfma_f32_16x16x32_bf16 v[108:111], v[218:221], v[186:189], v[108:111]
	v_mfma_f32_16x16x32_bf16 v[104:107], v[226:229], v[186:189], v[104:107]
	v_mfma_f32_16x16x32_bf16 v[92:95], v[218:221], v[194:197], v[92:95]
	v_mfma_f32_16x16x32_bf16 v[88:91], v[226:229], v[194:197], v[88:91]
	v_mfma_f32_16x16x32_bf16 v[76:79], v[218:221], v[202:205], v[76:79]
	v_mfma_f32_16x16x32_bf16 v[72:75], v[226:229], v[202:205], v[72:75]
	v_mfma_f32_16x16x32_bf16 v[68:71], v[218:221], v[210:213], v[68:71]
	v_mfma_f32_16x16x32_bf16 v[64:67], v[226:229], v[210:213], v[64:67]
	v_mfma_f32_16x16x32_bf16 v[108:111], v[222:225], v[190:193], v[108:111]
	v_mfma_f32_16x16x32_bf16 v[104:107], v[230:233], v[190:193], v[104:107]
	v_mfma_f32_16x16x32_bf16 v[92:95], v[222:225], v[198:201], v[92:95]
	v_mfma_f32_16x16x32_bf16 v[88:91], v[230:233], v[198:201], v[88:91]
	v_mfma_f32_16x16x32_bf16 v[76:79], v[222:225], v[206:209], v[76:79]
	v_mfma_f32_16x16x32_bf16 v[72:75], v[230:233], v[206:209], v[72:75]
	v_mfma_f32_16x16x32_bf16 v[68:71], v[222:225], v[214:217], v[68:71]
	v_mfma_f32_16x16x32_bf16 v[64:67], v[230:233], v[214:217], v[64:67]
	s_setprio 0
	s_barrier
	s_mov_b32 m0, s58
	s_nop 0
	global_load_lds_dwordx4 v130, s[48:49]
	s_mov_b32 m0, s59
	s_nop 0
	global_load_lds_dwordx4 v134, s[48:49]
	s_mov_b32 m0, s57
	ds_read_b128 v[186:189], v145 offset:16384
	ds_read_b128 v[190:193], v145 offset:17408
	ds_read_b128 v[194:197], v145 offset:18432
	ds_read_b128 v[198:201], v145 offset:19456
	ds_read_b128 v[202:205], v145 offset:20480
	ds_read_b128 v[206:209], v145 offset:21504
	ds_read_b128 v[210:213], v145 offset:22528
	ds_read_b128 v[214:217], v145 offset:23552
	global_load_lds_dwordx4 v128, s[52:53]
	s_mov_b32 m0, s60
	s_nop 0
	global_load_lds_dwordx4 v132, s[52:53]
	s_waitcnt vmcnt(6)
	s_waitcnt lgkmcnt(0)
	s_barrier
	s_setprio 1
	v_mfma_f32_16x16x32_bf16 v[60:63], v[170:173], v[186:189], v[60:63]
	v_mfma_f32_16x16x32_bf16 v[56:59], v[178:181], v[186:189], v[56:59]
	v_mfma_f32_16x16x32_bf16 v[52:55], v[170:173], v[194:197], v[52:55]
	v_mfma_f32_16x16x32_bf16 v[48:51], v[178:181], v[194:197], v[48:51]
	v_mfma_f32_16x16x32_bf16 v[36:39], v[170:173], v[202:205], v[36:39]
	v_mfma_f32_16x16x32_bf16 v[32:35], v[178:181], v[202:205], v[32:35]
	v_mfma_f32_16x16x32_bf16 v[20:23], v[170:173], v[210:213], v[20:23]
	v_mfma_f32_16x16x32_bf16 v[16:19], v[178:181], v[210:213], v[16:19]
	v_mfma_f32_16x16x32_bf16 v[60:63], v[174:177], v[190:193], v[60:63]
	v_mfma_f32_16x16x32_bf16 v[56:59], v[182:185], v[190:193], v[56:59]
	v_mfma_f32_16x16x32_bf16 v[52:55], v[174:177], v[198:201], v[52:55]
	v_mfma_f32_16x16x32_bf16 v[48:51], v[182:185], v[198:201], v[48:51]
	v_mfma_f32_16x16x32_bf16 v[36:39], v[174:177], v[206:209], v[36:39]
	v_mfma_f32_16x16x32_bf16 v[32:35], v[182:185], v[206:209], v[32:35]
	v_mfma_f32_16x16x32_bf16 v[20:23], v[174:177], v[214:217], v[20:23]
	v_mfma_f32_16x16x32_bf16 v[16:19], v[182:185], v[214:217], v[16:19]
	v_mfma_f32_16x16x32_bf16 v[44:47], v[218:221], v[186:189], v[44:47]
	v_mfma_f32_16x16x32_bf16 v[40:43], v[226:229], v[186:189], v[40:43]
	v_mfma_f32_16x16x32_bf16 v[28:31], v[218:221], v[194:197], v[28:31]
	v_mfma_f32_16x16x32_bf16 v[24:27], v[226:229], v[194:197], v[24:27]
	v_mfma_f32_16x16x32_bf16 v[12:15], v[218:221], v[202:205], v[12:15]
	v_mfma_f32_16x16x32_bf16 v[8:11], v[226:229], v[202:205], v[8:11]
	v_mfma_f32_16x16x32_bf16 v[4:7], v[218:221], v[210:213], v[4:7]
	v_mfma_f32_16x16x32_bf16 v[0:3], v[226:229], v[210:213], v[0:3]
	v_mfma_f32_16x16x32_bf16 v[44:47], v[222:225], v[190:193], v[44:47]
	v_mfma_f32_16x16x32_bf16 v[40:43], v[230:233], v[190:193], v[40:43]
	v_mfma_f32_16x16x32_bf16 v[28:31], v[222:225], v[198:201], v[28:31]
	v_mfma_f32_16x16x32_bf16 v[24:27], v[230:233], v[198:201], v[24:27]
	v_mfma_f32_16x16x32_bf16 v[12:15], v[222:225], v[206:209], v[12:15]
	v_mfma_f32_16x16x32_bf16 v[8:11], v[230:233], v[206:209], v[8:11]
	v_mfma_f32_16x16x32_bf16 v[4:7], v[222:225], v[214:217], v[4:7]
	v_mfma_f32_16x16x32_bf16 v[0:3], v[230:233], v[214:217], v[0:3]
	s_setprio 0
	s_barrier
; #define PG8_STAGE(bufoff, gbase, voff) do { _Pragma("unroll") for (int _i = 0; _i < 2; ++_i) \
;         __builtin_amdgcn_global_load_lds((const unsigned*)((const char*)(gbase) + (voff)[_i]), (PG8_LAS unsigned*)(lds + (bufoff) + ldsw + _i * 8192), 16, 0, 0); } while (0)
; #define PG8_LDA(dst, b, h) do { _Pragma("unroll") for (int m = 0; m < 4; ++m) _Pragma("unroll") for (int k = 0; k < 2; ++k) dst[m][k] = *(const PG8_LAS bf16x8*)(lds + PG8_SA(b, h) + aoff + m * 2048 + k * 1024); } while (0)
; #define PG8_LDB(dst, b, h) do { _Pragma("unroll") for (int n = 0; n < 2; ++n) _Pragma("unroll") for (int k = 0; k < 2; ++k) dst[n][k] = *(const PG8_LAS bf16x8*)(lds + PG8_SB(b, h) + boff + n * 2048 + k * 1024); } while (0)
; #define PG8_MMA(ai, bj, At, Bt) do { __builtin_amdgcn_s_setprio(1); _Pragma("unroll") for (int m = 0; m < 4; ++m) _Pragma("unroll") for (int n = 0; n < 2; ++n) _Pragma("unroll") for (int k = 0; k < 2; ++k) \
;         acc[ai][bj][m][n] = __builtin_amdgcn_mfma_f32_16x16x32_bf16(Bt[n][k], At[m][k], acc[ai][bj][m][n], 0, 0, 0); __builtin_amdgcn_s_setprio(0); } while (0)
; #define PG8_WAIT_V(n) asm volatile("s_waitcnt vmcnt(" #n ")" ::: "memory")
; #define PG8_WAIT_L(n) asm volatile("s_waitcnt lgkmcnt(" #n ")" ::: "memory")
; #define PG8_BAR __builtin_amdgcn_s_barrier()
; #define PG8_SCHED __builtin_amdgcn_sched_barrier(0)
; template <class Epi, class Sched, bool STAMP = false>
; __device__ __forceinline__ void gemm_phase(PG8_LAS unsigned char* lds, const Gemm g, const Sched& S, const Epi& E, unsigned long long* stamps) {
;     ...
;             PG8_LDB(B0, 1, 0); PG8_SCHED; PG8_LDA(At, 1, 0); PG8_STAGE(PG8_SA(0, 1), a2 + hstep, voffA);
;             PG8_WAIT_L(8); PG8_BAR; PG8_WAIT_L(0); PG8_MMA(0, 0, At, B0); PG8_BAR; PG8_SCHED;
;             PG8_LDB(B1, 1, 1); PG8_STAGE(PG8_SB(1, 0), b3, voffB);
;             PG8_BAR; PG8_WAIT_L(0); PG8_MMA(0, 1, At, B1); PG8_BAR;
;             PG8_LDA(At, 1, 1); PG8_STAGE(PG8_SA(1, 0), a3, voffA);
;             PG8_BAR; PG8_WAIT_L(0); PG8_MMA(1, 0, At, B0); PG8_BAR; PG8_SCHED;
;             PG8_STAGE(PG8_SB(1, 1), b3 + hstep, voffB);
;             PG8_WAIT_V(6); PG8_BAR; PG8_MMA(1, 1, At, B1); PG8_BAR;
;         }
.Lzp8_mid:
	s_add_u32 s44, s48, 0xb4000
	s_addc_u32 s45, s49, 0
	s_mov_b32 m0, s61
	s_nop 0
	global_load_lds_dwordx4 v130, s[44:45]
	s_mov_b32 m0, s62
	s_nop 0
	global_load_lds_dwordx4 v134, s[44:45]
	ds_read_b128 v[170:173], v155
	ds_read_b128 v[174:177], v156
	ds_read_b128 v[178:181], v157
	ds_read_b128 v[182:185], v165
	s_add_u32 s44, s52, 0xb4000
	s_addc_u32 s45, s53, 0
	s_mov_b32 m0, s63
	ds_read_b128 v[186:189], v145 offset:32768
	ds_read_b128 v[190:193], v145 offset:33792
	ds_read_b128 v[194:197], v145 offset:34816
	ds_read_b128 v[198:201], v145 offset:35840
	ds_read_b128 v[202:205], v145 offset:36864
	ds_read_b128 v[206:209], v145 offset:37888
	ds_read_b128 v[210:213], v145 offset:38912
	ds_read_b128 v[214:217], v145 offset:39936
	global_load_lds_dwordx4 v128, s[44:45]
	s_mov_b32 m0, s64
	s_nop 0
	global_load_lds_dwordx4 v132, s[44:45]
	ds_read_b128 v[218:221], v166
	ds_read_b128 v[222:225], v167
	ds_read_b128 v[226:229], v168
	ds_read_b128 v[230:233], v169
	s_waitcnt vmcnt(8)
	s_waitcnt lgkmcnt(0)
	s_barrier
	s_setprio 1
	v_mfma_f32_16x16x32_bf16 v[124:127], v[170:173], v[186:189], v[124:127]
	v_mfma_f32_16x16x32_bf16 v[120:123], v[178:181], v[186:189], v[120:123]
	v_mfma_f32_16x16x32_bf16 v[116:119], v[170:173], v[194:197], v[116:119]
	v_mfma_f32_16x16x32_bf16 v[112:115], v[178:181], v[194:197], v[112:115]
	v_mfma_f32_16x16x32_bf16 v[100:103], v[170:173], v[202:205], v[100:103]
	v_mfma_f32_16x16x32_bf16 v[96:99], v[178:181], v[202:205], v[96:99]
	v_mfma_f32_16x16x32_bf16 v[84:87], v[170:173], v[210:213], v[84:87]
	v_mfma_f32_16x16x32_bf16 v[80:83], v[178:181], v[210:213], v[80:83]
	v_mfma_f32_16x16x32_bf16 v[124:127], v[174:177], v[190:193], v[124:127]
	v_mfma_f32_16x16x32_bf16 v[120:123], v[182:185], v[190:193], v[120:123]
	v_mfma_f32_16x16x32_bf16 v[116:119], v[174:177], v[198:201], v[116:119]
	v_mfma_f32_16x16x32_bf16 v[112:115], v[182:185], v[198:201], v[112:115]
	v_mfma_f32_16x16x32_bf16 v[100:103], v[174:177], v[206:209], v[100:103]
	v_mfma_f32_16x16x32_bf16 v[96:99], v[182:185], v[206:209], v[96:99]
	v_mfma_f32_16x16x32_bf16 v[84:87], v[174:177], v[214:217], v[84:87]
	v_mfma_f32_16x16x32_bf16 v[80:83], v[182:185], v[214:217], v[80:83]
	v_mfma_f32_16x16x32_bf16 v[108:111], v[218:221], v[186:189], v[108:111]
	v_mfma_f32_16x16x32_bf16 v[104:107], v[226:229], v[186:189], v[104:107]
	v_mfma_f32_16x16x32_bf16 v[92:95], v[218:221], v[194:197], v[92:95]
	v_mfma_f32_16x16x32_bf16 v[88:91], v[226:229], v[194:197], v[88:91]
	v_mfma_f32_16x16x32_bf16 v[76:79], v[218:221], v[202:205], v[76:79]
	v_mfma_f32_16x16x32_bf16 v[72:75], v[226:229], v[202:205], v[72:75]
	v_mfma_f32_16x16x32_bf16 v[68:71], v[218:221], v[210:213], v[68:71]
	v_mfma_f32_16x16x32_bf16 v[64:67], v[226:229], v[210:213], v[64:67]
	v_mfma_f32_16x16x32_bf16 v[108:111], v[222:225], v[190:193], v[108:111]
	v_mfma_f32_16x16x32_bf16 v[104:107], v[230:233], v[190:193], v[104:107]
	v_mfma_f32_16x16x32_bf16 v[92:95], v[222:225], v[198:201], v[92:95]
	v_mfma_f32_16x16x32_bf16 v[88:91], v[230:233], v[198:201], v[88:91]
	v_mfma_f32_16x16x32_bf16 v[76:79], v[222:225], v[206:209], v[76:79]
	v_mfma_f32_16x16x32_bf16 v[72:75], v[230:233], v[206:209], v[72:75]
	v_mfma_f32_16x16x32_bf16 v[68:71], v[222:225], v[214:217], v[68:71]
	v_mfma_f32_16x16x32_bf16 v[64:67], v[230:233], v[214:217], v[64:67]
	s_setprio 0
	s_barrier
	s_mov_b32 m0, s65
	s_add_u32 s100, s48, 0x80
	s_addc_u32 s101, s49, 0
	global_load_lds_dwordx4 v130, s[100:101]
	s_mov_b32 m0, s66
	s_nop 0
	global_load_lds_dwordx4 v134, s[100:101]
	s_mov_b32 m0, s67
	ds_read_b128 v[186:189], v145 offset:49152
	ds_read_b128 v[190:193], v145 offset:50176
	ds_read_b128 v[194:197], v145 offset:51200
	ds_read_b128 v[198:201], v145 offset:52224
	ds_read_b128 v[202:205], v145 offset:53248
	ds_read_b128 v[206:209], v145 offset:54272
	ds_read_b128 v[210:213], v145 offset:55296
	ds_read_b128 v[214:217], v145 offset:56320
	s_add_u32 s100, s52, 0x80
	s_addc_u32 s101, s53, 0
	global_load_lds_dwordx4 v128, s[100:101]
	s_mov_b32 m0, s68
	s_nop 0
	global_load_lds_dwordx4 v132, s[100:101]
	s_waitcnt vmcnt(6)
	s_waitcnt lgkmcnt(0)
	s_barrier
	s_setprio 1
	v_mfma_f32_16x16x32_bf16 v[60:63], v[170:173], v[186:189], v[60:63]
	v_mfma_f32_16x16x32_bf16 v[56:59], v[178:181], v[186:189], v[56:59]
	v_mfma_f32_16x16x32_bf16 v[52:55], v[170:173], v[194:197], v[52:55]
	v_mfma_f32_16x16x32_bf16 v[48:51], v[178:181], v[194:197], v[48:51]
	v_mfma_f32_16x16x32_bf16 v[36:39], v[170:173], v[202:205], v[36:39]
	v_mfma_f32_16x16x32_bf16 v[32:35], v[178:181], v[202:205], v[32:35]
	v_mfma_f32_16x16x32_bf16 v[20:23], v[170:173], v[210:213], v[20:23]
	v_mfma_f32_16x16x32_bf16 v[16:19], v[178:181], v[210:213], v[16:19]
	v_mfma_f32_16x16x32_bf16 v[60:63], v[174:177], v[190:193], v[60:63]
	v_mfma_f32_16x16x32_bf16 v[56:59], v[182:185], v[190:193], v[56:59]
	v_mfma_f32_16x16x32_bf16 v[52:55], v[174:177], v[198:201], v[52:55]
	v_mfma_f32_16x16x32_bf16 v[48:51], v[182:185], v[198:201], v[48:51]
	v_mfma_f32_16x16x32_bf16 v[36:39], v[174:177], v[206:209], v[36:39]
	v_mfma_f32_16x16x32_bf16 v[32:35], v[182:185], v[206:209], v[32:35]
	v_mfma_f32_16x16x32_bf16 v[20:23], v[174:177], v[214:217], v[20:23]
	v_mfma_f32_16x16x32_bf16 v[16:19], v[182:185], v[214:217], v[16:19]
	v_mfma_f32_16x16x32_bf16 v[44:47], v[218:221], v[186:189], v[44:47]
	v_mfma_f32_16x16x32_bf16 v[40:43], v[226:229], v[186:189], v[40:43]
	v_mfma_f32_16x16x32_bf16 v[28:31], v[218:221], v[194:197], v[28:31]
	v_mfma_f32_16x16x32_bf16 v[24:27], v[226:229], v[194:197], v[24:27]
	v_mfma_f32_16x16x32_bf16 v[12:15], v[218:221], v[202:205], v[12:15]
	v_mfma_f32_16x16x32_bf16 v[8:11], v[226:229], v[202:205], v[8:11]
	v_mfma_f32_16x16x32_bf16 v[4:7], v[218:221], v[210:213], v[4:7]
	v_mfma_f32_16x16x32_bf16 v[0:3], v[226:229], v[210:213], v[0:3]
	v_mfma_f32_16x16x32_bf16 v[44:47], v[222:225], v[190:193], v[44:47]
	v_mfma_f32_16x16x32_bf16 v[40:43], v[230:233], v[190:193], v[40:43]
	v_mfma_f32_16x16x32_bf16 v[28:31], v[222:225], v[198:201], v[28:31]
	v_mfma_f32_16x16x32_bf16 v[24:27], v[230:233], v[198:201], v[24:27]
	v_mfma_f32_16x16x32_bf16 v[12:15], v[222:225], v[206:209], v[12:15]
	v_mfma_f32_16x16x32_bf16 v[8:11], v[230:233], v[206:209], v[8:11]
	v_mfma_f32_16x16x32_bf16 v[4:7], v[222:225], v[214:217], v[4:7]
	v_mfma_f32_16x16x32_bf16 v[0:3], v[230:233], v[214:217], v[0:3]
	s_setprio 0
	s_add_i32 s10, s10, 2
	s_add_u32 s88, s88, 0x100
	s_addc_u32 s89, s89, 0
	s_cmp_gt_u32 s10, 41
	s_mov_b64 s[44:45], s[46:47]
	s_barrier
; #define PG8_STAMP() do { if (STAMP && wid == 0 && nts < 64) { const unsigned long long _c = 0ull; \
;         ts_lo = (lane == nts) ? (int)(unsigned)_c : ts_lo; ts_hi = (lane == nts) ? (int)(unsigned)(_c >> 32) : ts_hi; ++nts; } } while (0)
; #define PG8_WAIT_V(n) asm volatile("s_waitcnt vmcnt(" #n ")" ::: "memory")
; #define PG8_BAR __builtin_amdgcn_s_barrier()
;     DI void operator()(const f32x4 (&acc)[2][2][4][2], const Unit& u, int wr, int wc, int fr, int fq) const {
;         const int row0 = u.pm * BM + wr * 64 + fr, col0 = u.pn * BM + wc * 32 + 8 * fq;
; #pragma unroll
;         for (int ai = 0; ai < 2; ++ai)
; #pragma unroll
;             for (int m = 0; m < 4; ++m) { u16* rowp = O + (size_t)(row0 + ai * HALF + m * 16) * ldc + col0;
; #pragma unroll
;                 for (int bj = 0; bj < 2; ++bj) { const f32x4 v0 = acc[ai][bj][m][0], v1 = acc[ai][bj][m][1];
;                     uint4 w = {pack2(v0[0], v0[1]), pack2(v0[2], v0[3]), pack2(v1[0], v1[1]), pack2(v1[2], v1[3])}; *(uint4*)(rowp + bj * HALF) = w; } }
; template <class Epi, class Sched, bool STAMP = false>
; __device__ __forceinline__ void gemm_phase(PG8_LAS unsigned char* lds, const Gemm g, const Sched& S, const Epi& E, unsigned long long* stamps) {
;     ...
;         if constexpr (!Epi::AFTER_DRAIN) { E(acc, cur, wr, wc, fr, fq); S.done(cur); }
;         PG8_STAMP();
;         if (!has_next) break;
; #pragma unroll
;         for (int a = 0; a < 2; ++a)
; #pragma unroll
;             for (int b = 0; b < 2; ++b)
; #pragma unroll
;                 for (int m = 0; m < 4; ++m)
; #pragma unroll
;                     for (int n = 0; n < 2; ++n) acc[a][b][m][n] = (f32x4){0.f, 0.f, 0.f, 0.f};
;         cur = nxt; cA = nA; cB = nB; ++ui;
;     }
;     PG8_WAIT_V(0);
;     if (wr == 0) PG8_BAR;
;     PG8_BAR;
	s_cbranch_scc0 .LBB0_473
	v_lshl_add_u32 v170, s84, 8, v144
	v_lshl_or_b32 v172, s87, 8, v146
	v_ashrrev_i32_e32 v171, 31, v170
	v_ashrrev_i32_e32 v173, 31, v172
	v_lshlrev_b64 v[174:175], 11, v[170:171]
	v_lshl_add_u64 v[174:175], s[14:15], 0, v[174:175]
	v_lshlrev_b64 v[172:173], 1, v[172:173]
	v_lshl_add_u64 v[174:175], v[174:175], 0, v[172:173]
	v_cvt_pk_bf16_f32 v60, v60, v61
	v_cvt_pk_bf16_f32 v61, v62, v63
	v_cvt_pk_bf16_f32 v62, v56, v57
	v_add_co_u32_e32 v56, vcc, s78, v174
	v_cvt_pk_bf16_f32 v68, v68, v69
	v_cvt_pk_bf16_f32 v69, v70, v71
	v_cvt_pk_bf16_f32 v70, v64, v65
	v_lshl_add_u64 v[64:65], v[174:175], 0, s[34:35]
	v_addc_co_u32_e32 v57, vcc, 0, v175, vcc
	v_cvt_pk_bf16_f32 v44, v44, v45
	v_cvt_pk_bf16_f32 v45, v46, v47
	v_cvt_pk_bf16_f32 v46, v40, v41
	v_cvt_pk_bf16_f32 v47, v42, v43
	v_cvt_pk_bf16_f32 v108, v108, v109
	v_cvt_pk_bf16_f32 v109, v110, v111
	v_cvt_pk_bf16_f32 v110, v104, v105
	v_or_b32_e32 v104, 16, v170
	global_store_dwordx4 v[64:65], v[44:47], off offset:256
	v_ashrrev_i32_e32 v105, 31, v104
	v_cvt_pk_bf16_f32 v92, v92, v93
	v_add_co_u32_e32 v46, vcc, s79, v174
	v_cvt_pk_bf16_f32 v93, v94, v95
	v_cvt_pk_bf16_f32 v94, v88, v89
	v_or_b32_e32 v88, 32, v170
	v_lshl_add_u64 v[44:45], v[174:175], 0, s[36:37]
	v_addc_co_u32_e32 v47, vcc, 0, v175, vcc
	v_cvt_pk_bf16_f32 v28, v28, v29
	v_cvt_pk_bf16_f32 v29, v30, v31
	v_cvt_pk_bf16_f32 v30, v24, v25
	v_cvt_pk_bf16_f32 v31, v26, v27
	v_lshlrev_b64 v[104:105], 11, v[104:105]
	v_ashrrev_i32_e32 v89, 31, v88
	v_cvt_pk_bf16_f32 v76, v76, v77
	v_cvt_pk_bf16_f32 v77, v78, v79
	v_cvt_pk_bf16_f32 v78, v72, v73
	v_or_b32_e32 v72, 48, v170
	global_store_dwordx4 v[44:45], v[28:31], off offset:256
	v_cvt_pk_bf16_f32 v111, v106, v107
	v_lshl_add_u64 v[104:105], s[14:15], 0, v[104:105]
	v_add_co_u32_e32 v30, vcc, s82, v174
	v_lshlrev_b64 v[88:89], 11, v[88:89]
	v_ashrrev_i32_e32 v73, 31, v72
	v_lshl_add_u64 v[28:29], v[174:175], 0, s[40:41]
	v_addc_co_u32_e32 v31, vcc, 0, v175, vcc
	v_cvt_pk_bf16_f32 v12, v12, v13
	v_cvt_pk_bf16_f32 v13, v14, v15
	v_cvt_pk_bf16_f32 v14, v8, v9
	v_cvt_pk_bf16_f32 v15, v10, v11
	global_store_dwordx4 v[174:175], v[108:111], off offset:256
	v_cvt_pk_bf16_f32 v95, v90, v91
	v_lshl_add_u64 v[88:89], s[14:15], 0, v[88:89]
	v_lshl_add_u64 v[108:109], v[104:105], 0, v[172:173]
	v_lshlrev_b64 v[72:73], 11, v[72:73]
	global_store_dwordx4 v[28:29], v[12:15], off offset:256
	global_store_dwordx4 v[108:109], v[92:95], off offset:256
	v_cvt_pk_bf16_f32 v79, v74, v75
	v_add_co_u32_e32 v14, vcc, s83, v174
	v_lshl_add_u64 v[92:93], v[88:89], 0, v[172:173]
	v_lshl_add_u64 v[72:73], s[14:15], 0, v[72:73]
	v_addc_co_u32_e32 v15, vcc, 0, v175, vcc
	v_cvt_pk_bf16_f32 v124, v124, v125
	v_cvt_pk_bf16_f32 v125, v126, v127
	v_cvt_pk_bf16_f32 v126, v120, v121
	v_cvt_pk_bf16_f32 v127, v122, v123
	v_cvt_pk_bf16_f32 v104, v116, v117
	v_cvt_pk_bf16_f32 v105, v118, v119
	v_cvt_pk_bf16_f32 v106, v112, v113
	v_cvt_pk_bf16_f32 v107, v114, v115
	v_cvt_pk_bf16_f32 v88, v100, v101
	v_cvt_pk_bf16_f32 v89, v102, v103
	v_cvt_pk_bf16_f32 v90, v96, v97
	v_cvt_pk_bf16_f32 v91, v98, v99
	global_store_dwordx4 v[92:93], v[76:79], off offset:256
	v_cvt_pk_bf16_f32 v74, v80, v81
	v_cvt_pk_bf16_f32 v75, v82, v83
	v_lshl_add_u64 v[76:77], v[72:73], 0, v[172:173]
	v_cvt_pk_bf16_f32 v72, v84, v85
	v_cvt_pk_bf16_f32 v73, v86, v87
	v_cvt_pk_bf16_f32 v71, v66, v67
	v_cvt_pk_bf16_f32 v63, v58, v59
	v_cvt_pk_bf16_f32 v40, v52, v53
	v_cvt_pk_bf16_f32 v41, v54, v55
	v_cvt_pk_bf16_f32 v42, v48, v49
	v_cvt_pk_bf16_f32 v43, v50, v51
	v_cvt_pk_bf16_f32 v24, v36, v37
	v_cvt_pk_bf16_f32 v25, v38, v39
	v_cvt_pk_bf16_f32 v26, v32, v33
	v_cvt_pk_bf16_f32 v27, v34, v35
	v_lshl_add_u64 v[12:13], v[174:175], 0, s[42:43]
	v_cvt_pk_bf16_f32 v8, v20, v21
	v_cvt_pk_bf16_f32 v9, v22, v23
	v_cvt_pk_bf16_f32 v10, v16, v17
	v_cvt_pk_bf16_f32 v11, v18, v19
	v_cvt_pk_bf16_f32 v4, v4, v5
	v_cvt_pk_bf16_f32 v5, v6, v7
	v_cvt_pk_bf16_f32 v6, v0, v1
	v_cvt_pk_bf16_f32 v7, v2, v3
	s_and_b64 vcc, exec, s[2:3]
	s_mov_b32 s87, s85
	s_mov_b32 s84, s86
	s_mov_b64 s[46:47], s[0:1]
	s_mov_b64 s[44:45], s[4:5]
	global_store_dwordx4 v[174:175], v[124:127], off
	global_store_dwordx4 v[108:109], v[104:107], off
	global_store_dwordx4 v[92:93], v[88:91], off
	global_store_dwordx4 v[76:77], v[72:75], off
	global_store_dwordx4 v[76:77], v[68:71], off offset:256
	global_store_dwordx4 v[56:57], v[60:63], off
	global_store_dwordx4 v[46:47], v[40:43], off
	global_store_dwordx4 v[30:31], v[24:27], off
	global_store_dwordx4 v[14:15], v[8:11], off
	global_store_dwordx4 v[12:13], v[4:7], off offset:256
	s_cbranch_vccz .LBB0_462
	s_waitcnt vmcnt(0)
	s_cmpk_gt_u32 s55, 0xff
	s_cbranch_scc1 .LBB0_477
	s_barrier

; #define PG8_STAGE(bufoff, gbase, voff) do { _Pragma("unroll") for (int _i = 0; _i < 2; ++_i) \
;         __builtin_amdgcn_global_load_lds((const unsigned*)((const char*)(gbase) + (voff)[_i]), (PG8_LAS unsigned*)(lds + (bufoff) + ldsw + _i * 8192), 16, 0, 0); } while (0)
; #define PG8_LDA(dst, b, h) do { _Pragma("unroll") for (int m = 0; m < 4; ++m) _Pragma("unroll") for (int k = 0; k < 2; ++k) dst[m][k] = *(const PG8_LAS bf16x8*)(lds + PG8_SA(b, h) + aoff + m * 2048 + k * 1024); } while (0)
; #define PG8_LDB(dst, b, h) do { _Pragma("unroll") for (int n = 0; n < 2; ++n) _Pragma("unroll") for (int k = 0; k < 2; ++k) dst[n][k] = *(const PG8_LAS bf16x8*)(lds + PG8_SB(b, h) + boff + n * 2048 + k * 1024); } while (0)
; #define PG8_MMA(ai, bj, At, Bt) do { __builtin_amdgcn_s_setprio(1); _Pragma("unroll") for (int m = 0; m < 4; ++m) _Pragma("unroll") for (int n = 0; n < 2; ++n) _Pragma("unroll") for (int k = 0; k < 2; ++k) \
;         acc[ai][bj][m][n] = __builtin_amdgcn_mfma_f32_16x16x32_bf16(Bt[n][k], At[m][k], acc[ai][bj][m][n], 0, 0, 0); __builtin_amdgcn_s_setprio(0); } while (0)
; #define PG8_BAR __builtin_amdgcn_s_barrier()
; template <class Epi, class Sched, bool STAMP = false>
; __device__ __forceinline__ void gemm_phase(PG8_LAS unsigned char* lds, const Gemm g, const Sched& S, const Epi& E, unsigned long long* stamps) {
;     ...
;         for (int t = 0; t < nt; t += 2) {
;             const bool last = (t == nt - 2);
;             const char* a1 = cA + (size_t)(t + 1) * kstep;
;             const char* a2 = last ? nA : cA + (size_t)(t + 2) * kstep; const char* b2 = last ? nB : cB + (size_t)(t + 2) * kstep;
;             const char* a3 = a2 + kstep; const char* b3 = b2 + kstep;
;             if (last && has_next) S.a_ready(nxt);
;             PG8_LDB(B0, 0, 0); PG8_SCHED; PG8_LDA(At, 0, 0); PG8_STAGE(PG8_SA(1, 1), a1 + hstep, voffA);
;             PG8_WAIT_L(8); PG8_BAR; PG8_WAIT_L(0); PG8_MMA(0, 0, At, B0); PG8_BAR; PG8_SCHED;
;             PG8_LDB(B1, 0, 1); PG8_STAGE(PG8_SB(0, 0), b2, voffB);
;             PG8_BAR; PG8_WAIT_L(0); PG8_MMA(0, 1, At, B1); PG8_BAR;
;             PG8_LDA(At, 0, 1); PG8_STAGE(PG8_SA(0, 0), a2, voffA);
;             PG8_BAR; PG8_WAIT_L(0); PG8_MMA(1, 0, At, B0); PG8_BAR; PG8_SCHED;
;             PG8_STAGE(PG8_SB(0, 1), b2 + hstep, voffB);
;             PG8_WAIT_V(6); PG8_BAR; PG8_MMA(1, 1, At, B1); PG8_BAR;
.LBB0_513:
	s_add_u32 s81, s42, 0x100
	s_addc_u32 s82, s43, 0
	s_mov_b32 s10, -2
	s_waitcnt lgkmcnt(0)
	s_add_u32 s100, s81, 0x43f80
	s_addc_u32 s101, s82, 0
	s_mov_b32 m0, s68
	s_nop 0
	global_load_lds_dwordx4 v132, s[100:101]
	s_mov_b32 m0, s69
	s_nop 0
	global_load_lds_dwordx4 v128, s[100:101]
	ds_read_b128 v[170:173], v147
	ds_read_b128 v[174:177], v148
	ds_read_b128 v[178:181], v149
	ds_read_b128 v[182:185], v150
	s_add_u32 s42, s40, 0x100
	s_addc_u32 s43, s41, 0
	s_cmp_eq_u32 s10, 12
	s_cselect_b32 s47, s7, s43
	s_cselect_b32 s46, s6, s42
	s_cselect_b32 s45, s1, s82
	s_cselect_b32 s44, s0, s81
	s_mov_b32 m0, s71
	ds_read_b128 v[186:189], v145
	ds_read_b128 v[190:193], v145 offset:1024
	ds_read_b128 v[194:197], v145 offset:2048
	ds_read_b128 v[198:201], v145 offset:3072
	ds_read_b128 v[202:205], v145 offset:4096
	ds_read_b128 v[206:209], v145 offset:5120
	ds_read_b128 v[210:213], v145 offset:6144
	ds_read_b128 v[214:217], v145 offset:7168
	global_load_lds_dwordx4 v136, s[40:41]
	s_mov_b32 m0, s75
	s_nop 0
	global_load_lds_dwordx4 v138, s[40:41]
	ds_read_b128 v[218:221], v151
	ds_read_b128 v[222:225], v152
	ds_read_b128 v[226:229], v153
	ds_read_b128 v[230:233], v154
	s_waitcnt vmcnt(8)
	s_waitcnt lgkmcnt(0)
	s_barrier
	s_setprio 1
	v_mfma_f32_16x16x32_bf16 v[124:127], v[170:173], v[186:189], 0
	v_mfma_f32_16x16x32_bf16 v[120:123], v[178:181], v[186:189], 0
	v_mfma_f32_16x16x32_bf16 v[116:119], v[170:173], v[194:197], 0
	v_mfma_f32_16x16x32_bf16 v[112:115], v[178:181], v[194:197], 0
	v_mfma_f32_16x16x32_bf16 v[108:111], v[170:173], v[202:205], 0
	v_mfma_f32_16x16x32_bf16 v[104:107], v[178:181], v[202:205], 0
	v_mfma_f32_16x16x32_bf16 v[100:103], v[170:173], v[210:213], 0
	v_mfma_f32_16x16x32_bf16 v[96:99], v[178:181], v[210:213], 0
	v_mfma_f32_16x16x32_bf16 v[124:127], v[174:177], v[190:193], v[124:127]
	v_mfma_f32_16x16x32_bf16 v[120:123], v[182:185], v[190:193], v[120:123]
	v_mfma_f32_16x16x32_bf16 v[116:119], v[174:177], v[198:201], v[116:119]
	v_mfma_f32_16x16x32_bf16 v[112:115], v[182:185], v[198:201], v[112:115]
	v_mfma_f32_16x16x32_bf16 v[108:111], v[174:177], v[206:209], v[108:111]
	v_mfma_f32_16x16x32_bf16 v[104:107], v[182:185], v[206:209], v[104:107]
	v_mfma_f32_16x16x32_bf16 v[100:103], v[174:177], v[214:217], v[100:103]
	v_mfma_f32_16x16x32_bf16 v[96:99], v[182:185], v[214:217], v[96:99]
	v_mfma_f32_16x16x32_bf16 v[60:63], v[218:221], v[186:189], 0
	v_mfma_f32_16x16x32_bf16 v[56:59], v[226:229], v[186:189], 0
	v_mfma_f32_16x16x32_bf16 v[52:55], v[218:221], v[194:197], 0
	v_mfma_f32_16x16x32_bf16 v[48:51], v[226:229], v[194:197], 0
	v_mfma_f32_16x16x32_bf16 v[44:47], v[218:221], v[202:205], 0
	v_mfma_f32_16x16x32_bf16 v[40:43], v[226:229], v[202:205], 0
	v_mfma_f32_16x16x32_bf16 v[36:39], v[218:221], v[210:213], 0
	v_mfma_f32_16x16x32_bf16 v[32:35], v[226:229], v[210:213], 0
	v_mfma_f32_16x16x32_bf16 v[60:63], v[222:225], v[190:193], v[60:63]
	v_mfma_f32_16x16x32_bf16 v[56:59], v[230:233], v[190:193], v[56:59]
	v_mfma_f32_16x16x32_bf16 v[52:55], v[222:225], v[198:201], v[52:55]
	v_mfma_f32_16x16x32_bf16 v[48:51], v[230:233], v[198:201], v[48:51]
	v_mfma_f32_16x16x32_bf16 v[44:47], v[222:225], v[206:209], v[44:47]
	v_mfma_f32_16x16x32_bf16 v[40:43], v[230:233], v[206:209], v[40:43]
	v_mfma_f32_16x16x32_bf16 v[36:39], v[222:225], v[214:217], v[36:39]
	v_mfma_f32_16x16x32_bf16 v[32:35], v[230:233], v[214:217], v[32:35]
	s_setprio 0
	s_barrier
	s_mov_b32 m0, s55
	s_nop 0
	global_load_lds_dwordx4 v132, s[44:45]
	s_mov_b32 m0, s56
	s_nop 0
	global_load_lds_dwordx4 v128, s[44:45]
	s_mov_b32 m0, s52
	ds_read_b128 v[186:189], v145 offset:16384
	ds_read_b128 v[190:193], v145 offset:17408
	ds_read_b128 v[194:197], v145 offset:18432
	ds_read_b128 v[198:201], v145 offset:19456
	ds_read_b128 v[202:205], v145 offset:20480
	ds_read_b128 v[206:209], v145 offset:21504
	ds_read_b128 v[210:213], v145 offset:22528
	ds_read_b128 v[214:217], v145 offset:23552
	global_load_lds_dwordx4 v134, s[46:47]
	s_mov_b32 m0, s57
	s_nop 0
	global_load_lds_dwordx4 v130, s[46:47]
	s_waitcnt vmcnt(6)
	s_waitcnt lgkmcnt(0)
	s_barrier
	s_setprio 1
	v_mfma_f32_16x16x32_bf16 v[92:95], v[170:173], v[186:189], 0
	v_mfma_f32_16x16x32_bf16 v[88:91], v[178:181], v[186:189], 0
	v_mfma_f32_16x16x32_bf16 v[84:87], v[170:173], v[194:197], 0
	v_mfma_f32_16x16x32_bf16 v[80:83], v[178:181], v[194:197], 0
	v_mfma_f32_16x16x32_bf16 v[76:79], v[170:173], v[202:205], 0
	v_mfma_f32_16x16x32_bf16 v[72:75], v[178:181], v[202:205], 0
	v_mfma_f32_16x16x32_bf16 v[68:71], v[170:173], v[210:213], 0
	v_mfma_f32_16x16x32_bf16 v[64:67], v[178:181], v[210:213], 0
	v_mfma_f32_16x16x32_bf16 v[92:95], v[174:177], v[190:193], v[92:95]
	v_mfma_f32_16x16x32_bf16 v[88:91], v[182:185], v[190:193], v[88:91]
	v_mfma_f32_16x16x32_bf16 v[84:87], v[174:177], v[198:201], v[84:87]
	v_mfma_f32_16x16x32_bf16 v[80:83], v[182:185], v[198:201], v[80:83]
	v_mfma_f32_16x16x32_bf16 v[76:79], v[174:177], v[206:209], v[76:79]
	v_mfma_f32_16x16x32_bf16 v[72:75], v[182:185], v[206:209], v[72:75]
	v_mfma_f32_16x16x32_bf16 v[68:71], v[174:177], v[214:217], v[68:71]
	v_mfma_f32_16x16x32_bf16 v[64:67], v[182:185], v[214:217], v[64:67]
	v_mfma_f32_16x16x32_bf16 v[28:31], v[218:221], v[186:189], 0
	v_mfma_f32_16x16x32_bf16 v[24:27], v[226:229], v[186:189], 0
	v_mfma_f32_16x16x32_bf16 v[20:23], v[218:221], v[194:197], 0
	v_mfma_f32_16x16x32_bf16 v[16:19], v[226:229], v[194:197], 0
	v_mfma_f32_16x16x32_bf16 v[12:15], v[218:221], v[202:205], 0
	v_mfma_f32_16x16x32_bf16 v[8:11], v[226:229], v[202:205], 0
	v_mfma_f32_16x16x32_bf16 v[4:7], v[218:221], v[210:213], 0
	v_mfma_f32_16x16x32_bf16 v[0:3], v[226:229], v[210:213], 0
	v_mfma_f32_16x16x32_bf16 v[28:31], v[222:225], v[190:193], v[28:31]
	v_mfma_f32_16x16x32_bf16 v[24:27], v[230:233], v[190:193], v[24:27]
	v_mfma_f32_16x16x32_bf16 v[20:23], v[222:225], v[198:201], v[20:23]
	v_mfma_f32_16x16x32_bf16 v[16:19], v[230:233], v[198:201], v[16:19]
	v_mfma_f32_16x16x32_bf16 v[12:15], v[222:225], v[206:209], v[12:15]
	v_mfma_f32_16x16x32_bf16 v[8:11], v[230:233], v[206:209], v[8:11]
	v_mfma_f32_16x16x32_bf16 v[4:7], v[222:225], v[214:217], v[4:7]
	v_mfma_f32_16x16x32_bf16 v[0:3], v[230:233], v[214:217], v[0:3]
	s_setprio 0
	s_barrier
	s_branch .Lzp9_mid
; #define PG8_STAGE(bufoff, gbase, voff) do { _Pragma("unroll") for (int _i = 0; _i < 2; ++_i) \
;         __builtin_amdgcn_global_load_lds((const unsigned*)((const char*)(gbase) + (voff)[_i]), (PG8_LAS unsigned*)(lds + (bufoff) + ldsw + _i * 8192), 16, 0, 0); } while (0)
; #define PG8_LDA(dst, b, h) do { _Pragma("unroll") for (int m = 0; m < 4; ++m) _Pragma("unroll") for (int k = 0; k < 2; ++k) dst[m][k] = *(const PG8_LAS bf16x8*)(lds + PG8_SA(b, h) + aoff + m * 2048 + k * 1024); } while (0)
; #define PG8_LDB(dst, b, h) do { _Pragma("unroll") for (int n = 0; n < 2; ++n) _Pragma("unroll") for (int k = 0; k < 2; ++k) dst[n][k] = *(const PG8_LAS bf16x8*)(lds + PG8_SB(b, h) + boff + n * 2048 + k * 1024); } while (0)
; #define PG8_MMA(ai, bj, At, Bt) do { __builtin_amdgcn_s_setprio(1); _Pragma("unroll") for (int m = 0; m < 4; ++m) _Pragma("unroll") for (int n = 0; n < 2; ++n) _Pragma("unroll") for (int k = 0; k < 2; ++k) \
;         acc[ai][bj][m][n] = __builtin_amdgcn_mfma_f32_16x16x32_bf16(Bt[n][k], At[m][k], acc[ai][bj][m][n], 0, 0, 0); __builtin_amdgcn_s_setprio(0); } while (0)
; #define PG8_BAR __builtin_amdgcn_s_barrier()
; template <class Epi, class Sched, bool STAMP = false>
; __device__ __forceinline__ void gemm_phase(PG8_LAS unsigned char* lds, const Gemm g, const Sched& S, const Epi& E, unsigned long long* stamps) {
;     ...
;         for (int t = 0; t < nt; t += 2) {
;             const bool last = (t == nt - 2);
;             const char* a1 = cA + (size_t)(t + 1) * kstep;
;             const char* a2 = last ? nA : cA + (size_t)(t + 2) * kstep; const char* b2 = last ? nB : cB + (size_t)(t + 2) * kstep;
;             const char* a3 = a2 + kstep; const char* b3 = b2 + kstep;
;             if (last && has_next) S.a_ready(nxt);
;             PG8_LDB(B0, 0, 0); PG8_SCHED; PG8_LDA(At, 0, 0); PG8_STAGE(PG8_SA(1, 1), a1 + hstep, voffA);
;             PG8_WAIT_L(8); PG8_BAR; PG8_WAIT_L(0); PG8_MMA(0, 0, At, B0); PG8_BAR; PG8_SCHED;
;             PG8_LDB(B1, 0, 1); PG8_STAGE(PG8_SB(0, 0), b2, voffB);
;             PG8_BAR; PG8_WAIT_L(0); PG8_MMA(0, 1, At, B1); PG8_BAR;
;             PG8_LDA(At, 0, 1); PG8_STAGE(PG8_SA(0, 0), a2, voffA);
;             PG8_BAR; PG8_WAIT_L(0); PG8_MMA(1, 0, At, B0); PG8_BAR; PG8_SCHED;
;             PG8_STAGE(PG8_SB(0, 1), b2 + hstep, voffB);
;             PG8_WAIT_V(6); PG8_BAR; PG8_MMA(1, 1, At, B1); PG8_BAR;
.LBB0_514:
	s_add_u32 s100, s81, 0x43f80
	s_addc_u32 s101, s82, 0
	s_mov_b32 m0, s68
	s_nop 0
	global_load_lds_dwordx4 v132, s[100:101]
	s_mov_b32 m0, s69
	s_nop 0
	global_load_lds_dwordx4 v128, s[100:101]
	ds_read_b128 v[170:173], v147
	ds_read_b128 v[174:177], v148
	ds_read_b128 v[178:181], v149
	ds_read_b128 v[182:185], v150
	s_add_u32 s42, s40, 0x100
	s_addc_u32 s43, s41, 0
	s_cmp_eq_u32 s10, 12
	s_cselect_b32 s47, s7, s43
	s_cselect_b32 s46, s6, s42
	s_cselect_b32 s45, s1, s82
	s_cselect_b32 s44, s0, s81
	s_mov_b32 m0, s71
	ds_read_b128 v[186:189], v145
	ds_read_b128 v[190:193], v145 offset:1024
	ds_read_b128 v[194:197], v145 offset:2048
	ds_read_b128 v[198:201], v145 offset:3072
	ds_read_b128 v[202:205], v145 offset:4096
	ds_read_b128 v[206:209], v145 offset:5120
	ds_read_b128 v[210:213], v145 offset:6144
	ds_read_b128 v[214:217], v145 offset:7168
	global_load_lds_dwordx4 v136, s[40:41]
	s_mov_b32 m0, s75
	s_nop 0
	global_load_lds_dwordx4 v138, s[40:41]
	ds_read_b128 v[218:221], v151
	ds_read_b128 v[222:225], v152
	ds_read_b128 v[226:229], v153
	ds_read_b128 v[230:233], v154
	s_waitcnt vmcnt(8)
	s_waitcnt lgkmcnt(0)
	s_barrier
	s_setprio 1
	v_mfma_f32_16x16x32_bf16 v[124:127], v[170:173], v[186:189], v[124:127]
	v_mfma_f32_16x16x32_bf16 v[120:123], v[178:181], v[186:189], v[120:123]
	v_mfma_f32_16x16x32_bf16 v[116:119], v[170:173], v[194:197], v[116:119]
	v_mfma_f32_16x16x32_bf16 v[112:115], v[178:181], v[194:197], v[112:115]
	v_mfma_f32_16x16x32_bf16 v[108:111], v[170:173], v[202:205], v[108:111]
	v_mfma_f32_16x16x32_bf16 v[104:107], v[178:181], v[202:205], v[104:107]
	v_mfma_f32_16x16x32_bf16 v[100:103], v[170:173], v[210:213], v[100:103]
	v_mfma_f32_16x16x32_bf16 v[96:99], v[178:181], v[210:213], v[96:99]
	v_mfma_f32_16x16x32_bf16 v[124:127], v[174:177], v[190:193], v[124:127]
	v_mfma_f32_16x16x32_bf16 v[120:123], v[182:185], v[190:193], v[120:123]
	v_mfma_f32_16x16x32_bf16 v[116:119], v[174:177], v[198:201], v[116:119]
	v_mfma_f32_16x16x32_bf16 v[112:115], v[182:185], v[198:201], v[112:115]
	v_mfma_f32_16x16x32_bf16 v[108:111], v[174:177], v[206:209], v[108:111]
	v_mfma_f32_16x16x32_bf16 v[104:107], v[182:185], v[206:209], v[104:107]
	v_mfma_f32_16x16x32_bf16 v[100:103], v[174:177], v[214:217], v[100:103]
	v_mfma_f32_16x16x32_bf16 v[96:99], v[182:185], v[214:217], v[96:99]
	v_mfma_f32_16x16x32_bf16 v[60:63], v[218:221], v[186:189], v[60:63]
	v_mfma_f32_16x16x32_bf16 v[56:59], v[226:229], v[186:189], v[56:59]
	v_mfma_f32_16x16x32_bf16 v[52:55], v[218:221], v[194:197], v[52:55]
	v_mfma_f32_16x16x32_bf16 v[48:51], v[226:229], v[194:197], v[48:51]
	v_mfma_f32_16x16x32_bf16 v[44:47], v[218:221], v[202:205], v[44:47]
	v_mfma_f32_16x16x32_bf16 v[40:43], v[226:229], v[202:205], v[40:43]
	v_mfma_f32_16x16x32_bf16 v[36:39], v[218:221], v[210:213], v[36:39]
	v_mfma_f32_16x16x32_bf16 v[32:35], v[226:229], v[210:213], v[32:35]
	v_mfma_f32_16x16x32_bf16 v[60:63], v[222:225], v[190:193], v[60:63]
	v_mfma_f32_16x16x32_bf16 v[56:59], v[230:233], v[190:193], v[56:59]
	v_mfma_f32_16x16x32_bf16 v[52:55], v[222:225], v[198:201], v[52:55]
	v_mfma_f32_16x16x32_bf16 v[48:51], v[230:233], v[198:201], v[48:51]
	v_mfma_f32_16x16x32_bf16 v[44:47], v[222:225], v[206:209], v[44:47]
	v_mfma_f32_16x16x32_bf16 v[40:43], v[230:233], v[206:209], v[40:43]
	v_mfma_f32_16x16x32_bf16 v[36:39], v[222:225], v[214:217], v[36:39]
	v_mfma_f32_16x16x32_bf16 v[32:35], v[230:233], v[214:217], v[32:35]
	s_setprio 0
	s_barrier
	s_mov_b32 m0, s55
	s_nop 0
	global_load_lds_dwordx4 v132, s[44:45]
	s_mov_b32 m0, s56
	s_nop 0
	global_load_lds_dwordx4 v128, s[44:45]
	s_mov_b32 m0, s52
	ds_read_b128 v[186:189], v145 offset:16384
	ds_read_b128 v[190:193], v145 offset:17408
	ds_read_b128 v[194:197], v145 offset:18432
	ds_read_b128 v[198:201], v145 offset:19456
	ds_read_b128 v[202:205], v145 offset:20480
	ds_read_b128 v[206:209], v145 offset:21504
	ds_read_b128 v[210:213], v145 offset:22528
	ds_read_b128 v[214:217], v145 offset:23552
	global_load_lds_dwordx4 v134, s[46:47]
	s_mov_b32 m0, s57
	s_nop 0
	global_load_lds_dwordx4 v130, s[46:47]
	s_waitcnt vmcnt(6)
	s_waitcnt lgkmcnt(0)
	s_barrier
	s_setprio 1
	v_mfma_f32_16x16x32_bf16 v[92:95], v[170:173], v[186:189], v[92:95]
	v_mfma_f32_16x16x32_bf16 v[88:91], v[178:181], v[186:189], v[88:91]
	v_mfma_f32_16x16x32_bf16 v[84:87], v[170:173], v[194:197], v[84:87]
	v_mfma_f32_16x16x32_bf16 v[80:83], v[178:181], v[194:197], v[80:83]
	v_mfma_f32_16x16x32_bf16 v[76:79], v[170:173], v[202:205], v[76:79]
	v_mfma_f32_16x16x32_bf16 v[72:75], v[178:181], v[202:205], v[72:75]
	v_mfma_f32_16x16x32_bf16 v[68:71], v[170:173], v[210:213], v[68:71]
	v_mfma_f32_16x16x32_bf16 v[64:67], v[178:181], v[210:213], v[64:67]
	v_mfma_f32_16x16x32_bf16 v[92:95], v[174:177], v[190:193], v[92:95]
	v_mfma_f32_16x16x32_bf16 v[88:91], v[182:185], v[190:193], v[88:91]
	v_mfma_f32_16x16x32_bf16 v[84:87], v[174:177], v[198:201], v[84:87]
	v_mfma_f32_16x16x32_bf16 v[80:83], v[182:185], v[198:201], v[80:83]
	v_mfma_f32_16x16x32_bf16 v[76:79], v[174:177], v[206:209], v[76:79]
	v_mfma_f32_16x16x32_bf16 v[72:75], v[182:185], v[206:209], v[72:75]
	v_mfma_f32_16x16x32_bf16 v[68:71], v[174:177], v[214:217], v[68:71]
	v_mfma_f32_16x16x32_bf16 v[64:67], v[182:185], v[214:217], v[64:67]
	v_mfma_f32_16x16x32_bf16 v[28:31], v[218:221], v[186:189], v[28:31]
	v_mfma_f32_16x16x32_bf16 v[24:27], v[226:229], v[186:189], v[24:27]
	v_mfma_f32_16x16x32_bf16 v[20:23], v[218:221], v[194:197], v[20:23]
	v_mfma_f32_16x16x32_bf16 v[16:19], v[226:229], v[194:197], v[16:19]
	v_mfma_f32_16x16x32_bf16 v[12:15], v[218:221], v[202:205], v[12:15]
	v_mfma_f32_16x16x32_bf16 v[8:11], v[226:229], v[202:205], v[8:11]
	v_mfma_f32_16x16x32_bf16 v[4:7], v[218:221], v[210:213], v[4:7]
	v_mfma_f32_16x16x32_bf16 v[0:3], v[226:229], v[210:213], v[0:3]
	v_mfma_f32_16x16x32_bf16 v[28:31], v[222:225], v[190:193], v[28:31]
	v_mfma_f32_16x16x32_bf16 v[24:27], v[230:233], v[190:193], v[24:27]
	v_mfma_f32_16x16x32_bf16 v[20:23], v[222:225], v[198:201], v[20:23]
	v_mfma_f32_16x16x32_bf16 v[16:19], v[230:233], v[198:201], v[16:19]
	v_mfma_f32_16x16x32_bf16 v[12:15], v[222:225], v[206:209], v[12:15]
	v_mfma_f32_16x16x32_bf16 v[8:11], v[230:233], v[206:209], v[8:11]
	v_mfma_f32_16x16x32_bf16 v[4:7], v[222:225], v[214:217], v[4:7]
	v_mfma_f32_16x16x32_bf16 v[0:3], v[230:233], v[214:217], v[0:3]
	s_setprio 0
	s_barrier
; #define PG8_STAGE(bufoff, gbase, voff) do { _Pragma("unroll") for (int _i = 0; _i < 2; ++_i) \
;         __builtin_amdgcn_global_load_lds((const unsigned*)((const char*)(gbase) + (voff)[_i]), (PG8_LAS unsigned*)(lds + (bufoff) + ldsw + _i * 8192), 16, 0, 0); } while (0)
; #define PG8_LDA(dst, b, h) do { _Pragma("unroll") for (int m = 0; m < 4; ++m) _Pragma("unroll") for (int k = 0; k < 2; ++k) dst[m][k] = *(const PG8_LAS bf16x8*)(lds + PG8_SA(b, h) + aoff + m * 2048 + k * 1024); } while (0)
; #define PG8_LDB(dst, b, h) do { _Pragma("unroll") for (int n = 0; n < 2; ++n) _Pragma("unroll") for (int k = 0; k < 2; ++k) dst[n][k] = *(const PG8_LAS bf16x8*)(lds + PG8_SB(b, h) + boff + n * 2048 + k * 1024); } while (0)
; #define PG8_MMA(ai, bj, At, Bt) do { __builtin_amdgcn_s_setprio(1); _Pragma("unroll") for (int m = 0; m < 4; ++m) _Pragma("unroll") for (int n = 0; n < 2; ++n) _Pragma("unroll") for (int k = 0; k < 2; ++k) \
;         acc[ai][bj][m][n] = __builtin_amdgcn_mfma_f32_16x16x32_bf16(Bt[n][k], At[m][k], acc[ai][bj][m][n], 0, 0, 0); __builtin_amdgcn_s_setprio(0); } while (0)
; #define PG8_WAIT_V(n) asm volatile("s_waitcnt vmcnt(" #n ")" ::: "memory")
; #define PG8_WAIT_L(n) asm volatile("s_waitcnt lgkmcnt(" #n ")" ::: "memory")
; #define PG8_BAR __builtin_amdgcn_s_barrier()
; #define PG8_SCHED __builtin_amdgcn_sched_barrier(0)
; template <class Epi, class Sched, bool STAMP = false>
; __device__ __forceinline__ void gemm_phase(PG8_LAS unsigned char* lds, const Gemm g, const Sched& S, const Epi& E, unsigned long long* stamps) {
;     ...
;             PG8_LDB(B0, 1, 0); PG8_SCHED; PG8_LDA(At, 1, 0); PG8_STAGE(PG8_SA(0, 1), a2 + hstep, voffA);
;             PG8_WAIT_L(8); PG8_BAR; PG8_WAIT_L(0); PG8_MMA(0, 0, At, B0); PG8_BAR; PG8_SCHED;
;             PG8_LDB(B1, 1, 1); PG8_STAGE(PG8_SB(1, 0), b3, voffB);
;             PG8_BAR; PG8_WAIT_L(0); PG8_MMA(0, 1, At, B1); PG8_BAR;
;             PG8_LDA(At, 1, 1); PG8_STAGE(PG8_SA(1, 0), a3, voffA);
;             PG8_BAR; PG8_WAIT_L(0); PG8_MMA(1, 0, At, B0); PG8_BAR; PG8_SCHED;
;             PG8_STAGE(PG8_SB(1, 1), b3 + hstep, voffB);
;             PG8_WAIT_V(6); PG8_BAR; PG8_MMA(1, 1, At, B1); PG8_BAR;
;         }
.Lzp9_mid:
	s_add_u32 s40, s44, 0x44000
	s_addc_u32 s41, s45, 0
	s_mov_b32 m0, s58
	s_nop 0
	global_load_lds_dwordx4 v132, s[40:41]
	s_mov_b32 m0, s59
	s_nop 0
	global_load_lds_dwordx4 v128, s[40:41]
	ds_read_b128 v[170:173], v155
	ds_read_b128 v[174:177], v156
	ds_read_b128 v[178:181], v157
	ds_read_b128 v[182:185], v165
	s_add_u32 s40, s46, 0x44000
	s_addc_u32 s41, s47, 0
	s_mov_b32 m0, s60
	ds_read_b128 v[186:189], v145 offset:32768
	ds_read_b128 v[190:193], v145 offset:33792
	ds_read_b128 v[194:197], v145 offset:34816
	ds_read_b128 v[198:201], v145 offset:35840
	ds_read_b128 v[202:205], v145 offset:36864
	ds_read_b128 v[206:209], v145 offset:37888
	ds_read_b128 v[210:213], v145 offset:38912
	ds_read_b128 v[214:217], v145 offset:39936
	global_load_lds_dwordx4 v134, s[40:41]
	s_mov_b32 m0, s61
	s_nop 0
	global_load_lds_dwordx4 v130, s[40:41]
	ds_read_b128 v[218:221], v166
	ds_read_b128 v[222:225], v167
	ds_read_b128 v[226:229], v168
	ds_read_b128 v[230:233], v169
	s_waitcnt vmcnt(8)
	s_waitcnt lgkmcnt(0)
	s_barrier
	s_setprio 1
	v_mfma_f32_16x16x32_bf16 v[124:127], v[170:173], v[186:189], v[124:127]
	v_mfma_f32_16x16x32_bf16 v[120:123], v[178:181], v[186:189], v[120:123]
	v_mfma_f32_16x16x32_bf16 v[116:119], v[170:173], v[194:197], v[116:119]
	v_mfma_f32_16x16x32_bf16 v[112:115], v[178:181], v[194:197], v[112:115]
	v_mfma_f32_16x16x32_bf16 v[108:111], v[170:173], v[202:205], v[108:111]
	v_mfma_f32_16x16x32_bf16 v[104:107], v[178:181], v[202:205], v[104:107]
	v_mfma_f32_16x16x32_bf16 v[100:103], v[170:173], v[210:213], v[100:103]
	v_mfma_f32_16x16x32_bf16 v[96:99], v[178:181], v[210:213], v[96:99]
	v_mfma_f32_16x16x32_bf16 v[124:127], v[174:177], v[190:193], v[124:127]
	v_mfma_f32_16x16x32_bf16 v[120:123], v[182:185], v[190:193], v[120:123]
	v_mfma_f32_16x16x32_bf16 v[116:119], v[174:177], v[198:201], v[116:119]
	v_mfma_f32_16x16x32_bf16 v[112:115], v[182:185], v[198:201], v[112:115]
	v_mfma_f32_16x16x32_bf16 v[108:111], v[174:177], v[206:209], v[108:111]
	v_mfma_f32_16x16x32_bf16 v[104:107], v[182:185], v[206:209], v[104:107]
	v_mfma_f32_16x16x32_bf16 v[100:103], v[174:177], v[214:217], v[100:103]
	v_mfma_f32_16x16x32_bf16 v[96:99], v[182:185], v[214:217], v[96:99]
	v_mfma_f32_16x16x32_bf16 v[60:63], v[218:221], v[186:189], v[60:63]
	v_mfma_f32_16x16x32_bf16 v[56:59], v[226:229], v[186:189], v[56:59]
	v_mfma_f32_16x16x32_bf16 v[52:55], v[218:221], v[194:197], v[52:55]
	v_mfma_f32_16x16x32_bf16 v[48:51], v[226:229], v[194:197], v[48:51]
	v_mfma_f32_16x16x32_bf16 v[44:47], v[218:221], v[202:205], v[44:47]
	v_mfma_f32_16x16x32_bf16 v[40:43], v[226:229], v[202:205], v[40:43]
	v_mfma_f32_16x16x32_bf16 v[36:39], v[218:221], v[210:213], v[36:39]
	v_mfma_f32_16x16x32_bf16 v[32:35], v[226:229], v[210:213], v[32:35]
	v_mfma_f32_16x16x32_bf16 v[60:63], v[222:225], v[190:193], v[60:63]
	v_mfma_f32_16x16x32_bf16 v[56:59], v[230:233], v[190:193], v[56:59]
	v_mfma_f32_16x16x32_bf16 v[52:55], v[222:225], v[198:201], v[52:55]
	v_mfma_f32_16x16x32_bf16 v[48:51], v[230:233], v[198:201], v[48:51]
	v_mfma_f32_16x16x32_bf16 v[44:47], v[222:225], v[206:209], v[44:47]
	v_mfma_f32_16x16x32_bf16 v[40:43], v[230:233], v[206:209], v[40:43]
	v_mfma_f32_16x16x32_bf16 v[36:39], v[222:225], v[214:217], v[36:39]
	v_mfma_f32_16x16x32_bf16 v[32:35], v[230:233], v[214:217], v[32:35]
	s_setprio 0
	s_barrier
	s_mov_b32 m0, s64
	s_add_u32 s100, s44, 0x80
	s_addc_u32 s101, s45, 0
	global_load_lds_dwordx4 v132, s[100:101]
	s_mov_b32 m0, s65
	s_nop 0
	global_load_lds_dwordx4 v128, s[100:101]
	s_mov_b32 m0, s66
	ds_read_b128 v[186:189], v145 offset:49152
	ds_read_b128 v[190:193], v145 offset:50176
	ds_read_b128 v[194:197], v145 offset:51200
	ds_read_b128 v[198:201], v145 offset:52224
	ds_read_b128 v[202:205], v145 offset:53248
	ds_read_b128 v[206:209], v145 offset:54272
	ds_read_b128 v[210:213], v145 offset:55296
	ds_read_b128 v[214:217], v145 offset:56320
	s_add_u32 s100, s46, 0x80
	s_addc_u32 s101, s47, 0
	global_load_lds_dwordx4 v134, s[100:101]
	s_mov_b32 m0, s67
	s_nop 0
	global_load_lds_dwordx4 v130, s[100:101]
	s_waitcnt vmcnt(6)
	s_waitcnt lgkmcnt(0)
	s_barrier
	s_setprio 1
	v_mfma_f32_16x16x32_bf16 v[92:95], v[170:173], v[186:189], v[92:95]
	v_mfma_f32_16x16x32_bf16 v[88:91], v[178:181], v[186:189], v[88:91]
	v_mfma_f32_16x16x32_bf16 v[84:87], v[170:173], v[194:197], v[84:87]
	v_mfma_f32_16x16x32_bf16 v[80:83], v[178:181], v[194:197], v[80:83]
	v_mfma_f32_16x16x32_bf16 v[76:79], v[170:173], v[202:205], v[76:79]
	v_mfma_f32_16x16x32_bf16 v[72:75], v[178:181], v[202:205], v[72:75]
	v_mfma_f32_16x16x32_bf16 v[68:71], v[170:173], v[210:213], v[68:71]
	v_mfma_f32_16x16x32_bf16 v[64:67], v[178:181], v[210:213], v[64:67]
	v_mfma_f32_16x16x32_bf16 v[92:95], v[174:177], v[190:193], v[92:95]
	v_mfma_f32_16x16x32_bf16 v[88:91], v[182:185], v[190:193], v[88:91]
	v_mfma_f32_16x16x32_bf16 v[84:87], v[174:177], v[198:201], v[84:87]
	v_mfma_f32_16x16x32_bf16 v[80:83], v[182:185], v[198:201], v[80:83]
	v_mfma_f32_16x16x32_bf16 v[76:79], v[174:177], v[206:209], v[76:79]
	v_mfma_f32_16x16x32_bf16 v[72:75], v[182:185], v[206:209], v[72:75]
	v_mfma_f32_16x16x32_bf16 v[68:71], v[174:177], v[214:217], v[68:71]
	v_mfma_f32_16x16x32_bf16 v[64:67], v[182:185], v[214:217], v[64:67]
	v_mfma_f32_16x16x32_bf16 v[28:31], v[218:221], v[186:189], v[28:31]
	v_mfma_f32_16x16x32_bf16 v[24:27], v[226:229], v[186:189], v[24:27]
	v_mfma_f32_16x16x32_bf16 v[20:23], v[218:221], v[194:197], v[20:23]
	v_mfma_f32_16x16x32_bf16 v[16:19], v[226:229], v[194:197], v[16:19]
	v_mfma_f32_16x16x32_bf16 v[12:15], v[218:221], v[202:205], v[12:15]
	v_mfma_f32_16x16x32_bf16 v[8:11], v[226:229], v[202:205], v[8:11]
	v_mfma_f32_16x16x32_bf16 v[4:7], v[218:221], v[210:213], v[4:7]
	v_mfma_f32_16x16x32_bf16 v[0:3], v[226:229], v[210:213], v[0:3]
	v_mfma_f32_16x16x32_bf16 v[28:31], v[222:225], v[190:193], v[28:31]
	v_mfma_f32_16x16x32_bf16 v[24:27], v[230:233], v[190:193], v[24:27]
	v_mfma_f32_16x16x32_bf16 v[20:23], v[222:225], v[198:201], v[20:23]
	v_mfma_f32_16x16x32_bf16 v[16:19], v[230:233], v[198:201], v[16:19]
	v_mfma_f32_16x16x32_bf16 v[12:15], v[222:225], v[206:209], v[12:15]
	v_mfma_f32_16x16x32_bf16 v[8:11], v[230:233], v[206:209], v[8:11]
	v_mfma_f32_16x16x32_bf16 v[4:7], v[222:225], v[214:217], v[4:7]
	v_mfma_f32_16x16x32_bf16 v[0:3], v[230:233], v[214:217], v[0:3]
	s_setprio 0
	s_add_i32 s10, s10, 2
	s_add_u32 s81, s81, 0x100
	s_addc_u32 s82, s82, 0
	s_cmp_gt_u32 s10, 13
	s_mov_b64 s[40:41], s[42:43]
	s_barrier
;     DI void operator()(const f32x4 (&acc)[2][2][4][2], const Unit& u, int wr, int wc, int fr, int fq) const {
;         const int row0 = u.pm * BM + wr * 64 + fr, col0 = u.pn * BM + wc * 32 + 8 * fq;
; #pragma unroll
;         for (int ai = 0; ai < 2; ++ai)
; #pragma unroll
;             for (int m = 0; m < 4; ++m) { u16* rowp = O + (size_t)(row0 + ai * HALF + m * 16) * ldc + col0;
; #pragma unroll
;                 for (int bj = 0; bj < 2; ++bj) { const f32x4 v0 = acc[ai][bj][m][0], v1 = acc[ai][bj][m][1];
;                     uint4 w = {pack2(v0[0], v0[1]), pack2(v0[2], v0[3]), pack2(v1[0], v1[1]), pack2(v1[2], v1[3])}; *(uint4*)(rowp + bj * HALF) = w; } }
;         if (kmaxp) {
; #pragma unroll
;             for (int bj = 0; bj < 2; ++bj) {
;                 const int cb = u.pn * BM + bj * HALF + wc * 32;
;                 const bool isA = (cb >= 384 && cb < 768), isB = (cb >= 1408 && cb < 1664);
	s_cbranch_scc0 .LBB0_514
	s_lshl_b32 s46, s79, 8
	v_or_b32_e32 v170, s46, v146
	v_lshl_add_u32 v180, s80, 8, v144
	v_ashrrev_i32_e32 v171, 31, v170
	v_mov_b64_e32 v[174:175], s[12:13]
	v_mad_i64_i32 v[172:173], s[40:41], v180, s76, v[174:175]
	v_lshlrev_b64 v[176:177], 1, v[170:171]
	v_lshl_add_u64 v[178:179], v[172:173], 0, v[176:177]
	v_cvt_pk_bf16_f32 v170, v124, v125
	v_cvt_pk_bf16_f32 v171, v126, v127
	v_cvt_pk_bf16_f32 v172, v120, v121
	v_cvt_pk_bf16_f32 v173, v122, v123
	global_store_dwordx4 v[178:179], v[170:173], off
	s_or_b32 s10, s46, s63
	s_nop 0
	v_cvt_pk_bf16_f32 v170, v60, v61
	v_cvt_pk_bf16_f32 v171, v62, v63
	v_cvt_pk_bf16_f32 v172, v56, v57
	v_cvt_pk_bf16_f32 v173, v58, v59
	global_store_dwordx4 v[178:179], v[170:173], off offset:256
	s_nop 1
	v_or_b32_e32 v170, 16, v180
	v_mad_i64_i32 v[170:171], s[40:41], v170, s76, v[174:175]
	v_lshl_add_u64 v[178:179], v[170:171], 0, v[176:177]
	v_cvt_pk_bf16_f32 v170, v116, v117
	v_cvt_pk_bf16_f32 v171, v118, v119
	v_cvt_pk_bf16_f32 v172, v112, v113
	v_cvt_pk_bf16_f32 v173, v114, v115
	global_store_dwordx4 v[178:179], v[170:173], off
	s_nop 1
	v_cvt_pk_bf16_f32 v170, v52, v53
	v_cvt_pk_bf16_f32 v171, v54, v55
	v_cvt_pk_bf16_f32 v172, v48, v49
	v_cvt_pk_bf16_f32 v173, v50, v51
	global_store_dwordx4 v[178:179], v[170:173], off offset:256
	s_nop 1
	v_or_b32_e32 v170, 32, v180
	v_mad_i64_i32 v[170:171], s[40:41], v170, s76, v[174:175]
	v_lshl_add_u64 v[178:179], v[170:171], 0, v[176:177]
	v_cvt_pk_bf16_f32 v170, v108, v109
	v_cvt_pk_bf16_f32 v171, v110, v111
	v_cvt_pk_bf16_f32 v172, v104, v105
	v_cvt_pk_bf16_f32 v173, v106, v107
	global_store_dwordx4 v[178:179], v[170:173], off
	s_nop 1
	v_cvt_pk_bf16_f32 v170, v44, v45
	v_cvt_pk_bf16_f32 v171, v46, v47
	v_cvt_pk_bf16_f32 v172, v40, v41
	v_cvt_pk_bf16_f32 v173, v42, v43
	global_store_dwordx4 v[178:179], v[170:173], off offset:256
	s_nop 1
	v_or_b32_e32 v170, 48, v180
	v_mad_i64_i32 v[170:171], s[40:41], v170, s76, v[174:175]
	v_lshl_add_u64 v[178:179], v[170:171], 0, v[176:177]
	v_cvt_pk_bf16_f32 v170, v100, v101
	v_cvt_pk_bf16_f32 v171, v102, v103
	v_cvt_pk_bf16_f32 v172, v96, v97
	v_cvt_pk_bf16_f32 v173, v98, v99
	global_store_dwordx4 v[178:179], v[170:173], off
	s_nop 1
	v_cvt_pk_bf16_f32 v170, v36, v37
	v_cvt_pk_bf16_f32 v171, v38, v39
	v_cvt_pk_bf16_f32 v172, v32, v33
	v_cvt_pk_bf16_f32 v173, v34, v35
	global_store_dwordx4 v[178:179], v[170:173], off offset:256
	s_nop 1
	v_add_u32_e32 v170, 0x80, v180
	v_mad_i64_i32 v[170:171], s[40:41], v170, s76, v[174:175]
	v_lshl_add_u64 v[178:179], v[170:171], 0, v[176:177]
	v_cvt_pk_bf16_f32 v170, v92, v93
	v_cvt_pk_bf16_f32 v171, v94, v95
	v_cvt_pk_bf16_f32 v172, v88, v89
	v_cvt_pk_bf16_f32 v173, v90, v91
	global_store_dwordx4 v[178:179], v[170:173], off
	s_nop 1
	v_cvt_pk_bf16_f32 v170, v28, v29
	v_cvt_pk_bf16_f32 v171, v30, v31
	v_cvt_pk_bf16_f32 v172, v24, v25
	v_cvt_pk_bf16_f32 v173, v26, v27
	global_store_dwordx4 v[178:179], v[170:173], off offset:256
	s_nop 1
	v_add_u32_e32 v170, 0x90, v180
	v_mad_i64_i32 v[170:171], s[40:41], v170, s76, v[174:175]
	v_lshl_add_u64 v[178:179], v[170:171], 0, v[176:177]
	v_cvt_pk_bf16_f32 v170, v84, v85
	v_cvt_pk_bf16_f32 v171, v86, v87
	v_cvt_pk_bf16_f32 v172, v80, v81
	v_cvt_pk_bf16_f32 v173, v82, v83
	global_store_dwordx4 v[178:179], v[170:173], off
	s_nop 1
	v_cvt_pk_bf16_f32 v170, v20, v21
	v_cvt_pk_bf16_f32 v171, v22, v23
	v_cvt_pk_bf16_f32 v172, v16, v17
	v_cvt_pk_bf16_f32 v173, v18, v19
	global_store_dwordx4 v[178:179], v[170:173], off offset:256
	s_nop 1
	v_add_u32_e32 v170, 0xa0, v180
	v_mad_i64_i32 v[170:171], s[40:41], v170, s76, v[174:175]
	v_lshl_add_u64 v[178:179], v[170:171], 0, v[176:177]
	v_cvt_pk_bf16_f32 v170, v76, v77
	v_cvt_pk_bf16_f32 v171, v78, v79
	v_cvt_pk_bf16_f32 v172, v72, v73
	v_cvt_pk_bf16_f32 v173, v74, v75
	global_store_dwordx4 v[178:179], v[170:173], off
	s_nop 1
	v_cvt_pk_bf16_f32 v170, v12, v13
	v_cvt_pk_bf16_f32 v171, v14, v15
	v_cvt_pk_bf16_f32 v172, v8, v9
	v_cvt_pk_bf16_f32 v173, v10, v11
	global_store_dwordx4 v[178:179], v[170:173], off offset:256
	s_nop 1
	v_add_u32_e32 v170, 0xb0, v180
	v_mad_i64_i32 v[170:171], s[40:41], v170, s76, v[174:175]
	s_add_i32 s40, s46, 0xfffffe80
	s_cmpk_gt_u32 s40, 0x17f
	s_cselect_b64 s[40:41], -1, 0
	s_add_i32 s42, s46, 0xfffffa80
	s_cmpk_gt_u32 s42, 0xff
	s_cselect_b64 s[42:43], -1, 0
	v_lshl_add_u64 v[174:175], v[170:171], 0, v[176:177]
	v_cvt_pk_bf16_f32 v170, v68, v69
	v_cvt_pk_bf16_f32 v171, v70, v71
	v_cvt_pk_bf16_f32 v172, v64, v65
	v_cvt_pk_bf16_f32 v173, v66, v67
	s_and_b64 s[42:43], s[40:41], s[42:43]
	global_store_dwordx4 v[174:175], v[170:173], off
	s_and_b64 vcc, exec, s[42:43]
	s_nop 0
	v_cvt_pk_bf16_f32 v170, v4, v5
	v_cvt_pk_bf16_f32 v171, v6, v7
	v_cvt_pk_bf16_f32 v172, v0, v1
	v_cvt_pk_bf16_f32 v173, v2, v3
	global_store_dwordx4 v[174:175], v[170:173], off offset:256
	s_cbranch_vccnz .LBB0_526
;     DI void operator()(const f32x4 (&acc)[2][2][4][2], const Unit& u, int wr, int wc, int fr, int fq) const {
;     ...
;                 if (isA || isB) {
;                     float mx = 0.f;
; #pragma unroll
;                     for (int ai = 0; ai < 2; ++ai)
; #pragma unroll
;                         for (int m = 0; m < 4; ++m) {
;                             const f32x4 a = acc[ai][bj][m][0], b = acc[ai][bj][m][1];
;                             float s0 = a[0] * a[0] + a[1] * a[1] + a[2] * a[2] + a[3] * a[3] + b[0] * b[0] + b[1] * b[1] + b[2] * b[2] + b[3] * b[3];
;                             s0 += __shfl_xor(s0, 16);
;                             s0 += __shfl_xor(s0, 32);
;                             mx = fmaxf(mx, s0);
;                         }
; #pragma unroll
;                     for (int o = 1; o <= 8; o <<= 1) mx = fmaxf(mx, __shfl_xor(mx, o));
;                     if ((threadIdx.x & 63) == 0) atomicMax((unsigned*)kmaxp + (isA ? ((cb - 384) >> 5) : (12 + ((cb - 1408) >> 5))), __float_as_uint(mx));
	v_mul_f32_e32 v125, v125, v125
	v_mul_f32_e32 v117, v117, v117
	v_fmac_f32_e32 v125, v124, v124
	v_fmac_f32_e32 v117, v116, v116
	v_mul_f32_e32 v109, v109, v109
	v_mul_f32_e32 v101, v101, v101
	v_fmac_f32_e32 v125, v126, v126
	v_fmac_f32_e32 v117, v118, v118
	v_fmac_f32_e32 v109, v108, v108
	v_fmac_f32_e32 v101, v100, v100
	v_fmac_f32_e32 v125, v127, v127
	v_fmac_f32_e32 v117, v119, v119
	v_fmac_f32_e32 v109, v110, v110
	v_fmac_f32_e32 v101, v102, v102
	v_fmac_f32_e32 v125, v120, v120
	v_fmac_f32_e32 v117, v112, v112
	v_fmac_f32_e32 v109, v111, v111
	v_fmac_f32_e32 v101, v103, v103
	v_fmac_f32_e32 v125, v121, v121
	v_fmac_f32_e32 v117, v113, v113
	v_fmac_f32_e32 v109, v104, v104
	v_fmac_f32_e32 v101, v96, v96
	v_fmac_f32_e32 v125, v122, v122
	v_fmac_f32_e32 v117, v114, v114
	v_fmac_f32_e32 v109, v105, v105
	v_fmac_f32_e32 v101, v97, v97
	v_fmac_f32_e32 v125, v123, v123
	v_fmac_f32_e32 v117, v115, v115
	v_fmac_f32_e32 v109, v106, v106
	v_fmac_f32_e32 v101, v98, v98
	v_mul_f32_e32 v93, v93, v93
	v_mul_f32_e32 v85, v85, v85
	ds_bpermute_b32 v120, v160, v125
	ds_bpermute_b32 v112, v160, v117
	v_fmac_f32_e32 v109, v107, v107
	v_fmac_f32_e32 v101, v99, v99
	v_fmac_f32_e32 v93, v92, v92
	v_fmac_f32_e32 v85, v84, v84
	v_mul_f32_e32 v77, v77, v77
	v_mul_f32_e32 v69, v69, v69
	ds_bpermute_b32 v104, v160, v109
	ds_bpermute_b32 v96, v160, v101
	v_fmac_f32_e32 v93, v94, v94
	v_fmac_f32_e32 v85, v86, v86
	v_fmac_f32_e32 v77, v76, v76
	v_fmac_f32_e32 v69, v68, v68
	v_fmac_f32_e32 v93, v95, v95
	v_fmac_f32_e32 v85, v87, v87
	v_fmac_f32_e32 v77, v78, v78
	v_fmac_f32_e32 v69, v70, v70
	v_fmac_f32_e32 v93, v88, v88
	v_fmac_f32_e32 v85, v80, v80
	v_fmac_f32_e32 v77, v79, v79
	v_fmac_f32_e32 v69, v71, v71
	v_fmac_f32_e32 v93, v89, v89
	v_fmac_f32_e32 v85, v81, v81
	v_fmac_f32_e32 v77, v72, v72
	v_fmac_f32_e32 v69, v64, v64
	s_waitcnt lgkmcnt(0)
	v_add_f32_e32 v113, v125, v120
	v_add_f32_e32 v112, v117, v112
	v_fmac_f32_e32 v93, v90, v90
	v_fmac_f32_e32 v85, v82, v82
	v_fmac_f32_e32 v77, v73, v73
	v_fmac_f32_e32 v69, v65, v65
	ds_bpermute_b32 v114, v159, v113
	ds_bpermute_b32 v115, v159, v112
	v_add_f32_e32 v99, v109, v104
	v_add_f32_e32 v96, v101, v96
	v_fmac_f32_e32 v93, v91, v91
	v_fmac_f32_e32 v85, v83, v83
	v_fmac_f32_e32 v77, v74, v74
	v_fmac_f32_e32 v69, v66, v66
	ds_bpermute_b32 v100, v159, v99
	ds_bpermute_b32 v101, v159, v96
	ds_bpermute_b32 v88, v160, v93
	ds_bpermute_b32 v80, v160, v85
	v_fmac_f32_e32 v77, v75, v75
	v_fmac_f32_e32 v69, v67, v67
	ds_bpermute_b32 v72, v160, v77
	ds_bpermute_b32 v64, v160, v69
	s_waitcnt lgkmcnt(0)
	v_add_f32_e32 v97, v113, v114
	v_add_f32_e32 v98, v112, v115
	v_max3_f32 v89, v97, 0, v98
	v_add_f32_e32 v90, v99, v100
	v_add_f32_e32 v91, v96, v101
	v_add_f32_e32 v88, v93, v88
	v_add_f32_e32 v65, v85, v80
	v_max3_f32 v89, v89, v90, v91
	ds_bpermute_b32 v90, v159, v88
	ds_bpermute_b32 v66, v159, v65
	v_add_f32_e32 v67, v77, v72
	v_add_f32_e32 v64, v69, v64
	ds_bpermute_b32 v68, v159, v67
	ds_bpermute_b32 v69, v159, v64
	s_waitcnt lgkmcnt(0)
	v_add_f32_e32 v70, v88, v90
	v_add_f32_e32 v65, v65, v66
	v_max3_f32 v65, v89, v70, v65
	v_add_f32_e32 v66, v67, v68
	v_add_f32_e32 v64, v64, v69
	v_max3_f32 v64, v65, v66, v64
	ds_bpermute_b32 v65, v164, v64
	s_waitcnt lgkmcnt(0)
	v_max_f32_e32 v65, v65, v65
	v_max_f32_e32 v64, v64, v65
	ds_bpermute_b32 v65, v163, v64
	s_waitcnt lgkmcnt(0)
	v_max_f32_e32 v65, v65, v65
	v_max_f32_e32 v64, v64, v65
	ds_bpermute_b32 v65, v162, v64
	s_waitcnt lgkmcnt(0)
	v_max_f32_e32 v65, v65, v65
	v_max_f32_e32 v64, v64, v65
	ds_bpermute_b32 v65, v161, v64
	s_and_saveexec_b64 s[42:43], s[2:3]
	s_cbranch_execz .LBB0_525
	s_mov_b64 s[44:45], -1
	s_and_b64 vcc, exec, s[40:41]
	s_cbranch_vccz .LBB0_519
	s_add_i32 s40, s10, 0xfffffa80
	s_ashr_i32 s40, s40, 5
	s_add_i32 s40, s40, 12
	s_mov_b64 s[44:45], 0

; #define PG8_STAGE(bufoff, gbase, voff) do { _Pragma("unroll") for (int _i = 0; _i < 2; ++_i) \
;         __builtin_amdgcn_global_load_lds((const unsigned*)((const char*)(gbase) + (voff)[_i]), (PG8_LAS unsigned*)(lds + (bufoff) + ldsw + _i * 8192), 16, 0, 0); } while (0)
; #define PG8_LDA(dst, b, h) do { _Pragma("unroll") for (int m = 0; m < 4; ++m) _Pragma("unroll") for (int k = 0; k < 2; ++k) dst[m][k] = *(const PG8_LAS bf16x8*)(lds + PG8_SA(b, h) + aoff + m * 2048 + k * 1024); } while (0)
; #define PG8_LDB(dst, b, h) do { _Pragma("unroll") for (int n = 0; n < 2; ++n) _Pragma("unroll") for (int k = 0; k < 2; ++k) dst[n][k] = *(const PG8_LAS bf16x8*)(lds + PG8_SB(b, h) + boff + n * 2048 + k * 1024); } while (0)
; #define PG8_MMA(ai, bj, At, Bt) do { __builtin_amdgcn_s_setprio(1); _Pragma("unroll") for (int m = 0; m < 4; ++m) _Pragma("unroll") for (int n = 0; n < 2; ++n) _Pragma("unroll") for (int k = 0; k < 2; ++k) \
;         acc[ai][bj][m][n] = __builtin_amdgcn_mfma_f32_16x16x32_bf16(Bt[n][k], At[m][k], acc[ai][bj][m][n], 0, 0, 0); __builtin_amdgcn_s_setprio(0); } while (0)
; #define PG8_BAR __builtin_amdgcn_s_barrier()
; template <class Epi, class Sched, bool STAMP = false>
; __device__ __forceinline__ void gemm_phase(PG8_LAS unsigned char* lds, const Gemm g, const Sched& S, const Epi& E, unsigned long long* stamps) {
;     ...
;         for (int t = 0; t < nt; t += 2) {
;             const bool last = (t == nt - 2);
;             const char* a1 = cA + (size_t)(t + 1) * kstep;
;             const char* a2 = last ? nA : cA + (size_t)(t + 2) * kstep; const char* b2 = last ? nB : cB + (size_t)(t + 2) * kstep;
;             const char* a3 = a2 + kstep; const char* b3 = b2 + kstep;
;             if (last && has_next) S.a_ready(nxt);
;             PG8_LDB(B0, 0, 0); PG8_SCHED; PG8_LDA(At, 0, 0); PG8_STAGE(PG8_SA(1, 1), a1 + hstep, voffA);
;             PG8_WAIT_L(8); PG8_BAR; PG8_WAIT_L(0); PG8_MMA(0, 0, At, B0); PG8_BAR; PG8_SCHED;
;             PG8_LDB(B1, 0, 1); PG8_STAGE(PG8_SB(0, 0), b2, voffB);
;             PG8_BAR; PG8_WAIT_L(0); PG8_MMA(0, 1, At, B1); PG8_BAR;
;             PG8_LDA(At, 0, 1); PG8_STAGE(PG8_SA(0, 0), a2, voffA);
;             PG8_BAR; PG8_WAIT_L(0); PG8_MMA(1, 0, At, B0); PG8_BAR; PG8_SCHED;
;             PG8_STAGE(PG8_SB(0, 1), b2 + hstep, voffB);
;             PG8_WAIT_V(6); PG8_BAR; PG8_MMA(1, 1, At, B1); PG8_BAR;
.LBB0_687:
	s_add_u32 s76, s36, 0x100
	s_addc_u32 s77, s37, 0
	s_mov_b32 s10, -2
	s_add_u32 s100, s76, 0x43f80
	s_addc_u32 s101, s77, 0
	s_mov_b32 m0, s59
	s_nop 0
	global_load_lds_dwordx4 v130, s[100:101]
	s_mov_b32 m0, s60
	s_nop 0
	global_load_lds_dwordx4 v134, s[100:101]
	ds_read_b128 v[170:173], v147
	ds_read_b128 v[174:177], v148
	ds_read_b128 v[178:181], v149
	ds_read_b128 v[182:185], v150
	s_add_u32 s36, s34, 0x100
	s_addc_u32 s37, s35, 0
	s_cmp_eq_u32 s10, 12
	s_cselect_b32 s43, s5, s37
	s_cselect_b32 s42, s4, s36
	s_cselect_b32 s41, s1, s77
	s_cselect_b32 s40, s0, s76
	s_mov_b32 m0, s63
	ds_read_b128 v[186:189], v145
	ds_read_b128 v[190:193], v145 offset:1024
	ds_read_b128 v[194:197], v145 offset:2048
	ds_read_b128 v[198:201], v145 offset:3072
	ds_read_b128 v[202:205], v145 offset:4096
	ds_read_b128 v[206:209], v145 offset:5120
	ds_read_b128 v[210:213], v145 offset:6144
	ds_read_b128 v[214:217], v145 offset:7168
	global_load_lds_dwordx4 v136, s[34:35]
	s_mov_b32 m0, s64
	s_nop 0
	global_load_lds_dwordx4 v138, s[34:35]
	ds_read_b128 v[218:221], v151
	ds_read_b128 v[222:225], v152
	ds_read_b128 v[226:229], v153
	ds_read_b128 v[230:233], v154
	s_waitcnt vmcnt(8)
	s_waitcnt lgkmcnt(0)
	s_barrier
	s_setprio 1
	v_mfma_f32_16x16x32_bf16 v[124:127], v[170:173], v[186:189], 0
	v_mfma_f32_16x16x32_bf16 v[120:123], v[178:181], v[186:189], 0
	v_mfma_f32_16x16x32_bf16 v[116:119], v[170:173], v[194:197], 0
	v_mfma_f32_16x16x32_bf16 v[112:115], v[178:181], v[194:197], 0
	v_mfma_f32_16x16x32_bf16 v[100:103], v[170:173], v[202:205], 0
	v_mfma_f32_16x16x32_bf16 v[96:99], v[178:181], v[202:205], 0
	v_mfma_f32_16x16x32_bf16 v[84:87], v[170:173], v[210:213], 0
	v_mfma_f32_16x16x32_bf16 v[80:83], v[178:181], v[210:213], 0
	v_mfma_f32_16x16x32_bf16 v[124:127], v[174:177], v[190:193], v[124:127]
	v_mfma_f32_16x16x32_bf16 v[120:123], v[182:185], v[190:193], v[120:123]
	v_mfma_f32_16x16x32_bf16 v[116:119], v[174:177], v[198:201], v[116:119]
	v_mfma_f32_16x16x32_bf16 v[112:115], v[182:185], v[198:201], v[112:115]
	v_mfma_f32_16x16x32_bf16 v[100:103], v[174:177], v[206:209], v[100:103]
	v_mfma_f32_16x16x32_bf16 v[96:99], v[182:185], v[206:209], v[96:99]
	v_mfma_f32_16x16x32_bf16 v[84:87], v[174:177], v[214:217], v[84:87]
	v_mfma_f32_16x16x32_bf16 v[80:83], v[182:185], v[214:217], v[80:83]
	v_mfma_f32_16x16x32_bf16 v[108:111], v[218:221], v[186:189], 0
	v_mfma_f32_16x16x32_bf16 v[104:107], v[226:229], v[186:189], 0
	v_mfma_f32_16x16x32_bf16 v[92:95], v[218:221], v[194:197], 0
	v_mfma_f32_16x16x32_bf16 v[88:91], v[226:229], v[194:197], 0
	v_mfma_f32_16x16x32_bf16 v[76:79], v[218:221], v[202:205], 0
	v_mfma_f32_16x16x32_bf16 v[72:75], v[226:229], v[202:205], 0
	v_mfma_f32_16x16x32_bf16 v[68:71], v[218:221], v[210:213], 0
	v_mfma_f32_16x16x32_bf16 v[64:67], v[226:229], v[210:213], 0
	v_mfma_f32_16x16x32_bf16 v[108:111], v[222:225], v[190:193], v[108:111]
	v_mfma_f32_16x16x32_bf16 v[104:107], v[230:233], v[190:193], v[104:107]
	v_mfma_f32_16x16x32_bf16 v[92:95], v[222:225], v[198:201], v[92:95]
	v_mfma_f32_16x16x32_bf16 v[88:91], v[230:233], v[198:201], v[88:91]
	v_mfma_f32_16x16x32_bf16 v[76:79], v[222:225], v[206:209], v[76:79]
	v_mfma_f32_16x16x32_bf16 v[72:75], v[230:233], v[206:209], v[72:75]
	v_mfma_f32_16x16x32_bf16 v[68:71], v[222:225], v[214:217], v[68:71]
	v_mfma_f32_16x16x32_bf16 v[64:67], v[230:233], v[214:217], v[64:67]
	s_setprio 0
	s_barrier
	s_mov_b32 m0, s48
	s_nop 0
	global_load_lds_dwordx4 v130, s[40:41]
	s_mov_b32 m0, s49
	s_nop 0
	global_load_lds_dwordx4 v134, s[40:41]
	s_mov_b32 m0, s47
	ds_read_b128 v[186:189], v145 offset:16384
	ds_read_b128 v[190:193], v145 offset:17408
	ds_read_b128 v[194:197], v145 offset:18432
	ds_read_b128 v[198:201], v145 offset:19456
	ds_read_b128 v[202:205], v145 offset:20480
	ds_read_b128 v[206:209], v145 offset:21504
	ds_read_b128 v[210:213], v145 offset:22528
	ds_read_b128 v[214:217], v145 offset:23552
	global_load_lds_dwordx4 v128, s[42:43]
	s_mov_b32 m0, s50
	s_nop 0
	global_load_lds_dwordx4 v132, s[42:43]
	s_waitcnt vmcnt(6)
	s_waitcnt lgkmcnt(0)
	s_barrier
	s_setprio 1
	v_mfma_f32_16x16x32_bf16 v[60:63], v[170:173], v[186:189], 0
	v_mfma_f32_16x16x32_bf16 v[56:59], v[178:181], v[186:189], 0
	v_mfma_f32_16x16x32_bf16 v[52:55], v[170:173], v[194:197], 0
	v_mfma_f32_16x16x32_bf16 v[48:51], v[178:181], v[194:197], 0
	v_mfma_f32_16x16x32_bf16 v[36:39], v[170:173], v[202:205], 0
	v_mfma_f32_16x16x32_bf16 v[32:35], v[178:181], v[202:205], 0
	v_mfma_f32_16x16x32_bf16 v[20:23], v[170:173], v[210:213], 0
	v_mfma_f32_16x16x32_bf16 v[16:19], v[178:181], v[210:213], 0
	v_mfma_f32_16x16x32_bf16 v[60:63], v[174:177], v[190:193], v[60:63]
	v_mfma_f32_16x16x32_bf16 v[56:59], v[182:185], v[190:193], v[56:59]
	v_mfma_f32_16x16x32_bf16 v[52:55], v[174:177], v[198:201], v[52:55]
	v_mfma_f32_16x16x32_bf16 v[48:51], v[182:185], v[198:201], v[48:51]
	v_mfma_f32_16x16x32_bf16 v[36:39], v[174:177], v[206:209], v[36:39]
	v_mfma_f32_16x16x32_bf16 v[32:35], v[182:185], v[206:209], v[32:35]
	v_mfma_f32_16x16x32_bf16 v[20:23], v[174:177], v[214:217], v[20:23]
	v_mfma_f32_16x16x32_bf16 v[16:19], v[182:185], v[214:217], v[16:19]
	v_mfma_f32_16x16x32_bf16 v[44:47], v[218:221], v[186:189], 0
	v_mfma_f32_16x16x32_bf16 v[40:43], v[226:229], v[186:189], 0
	v_mfma_f32_16x16x32_bf16 v[28:31], v[218:221], v[194:197], 0
	v_mfma_f32_16x16x32_bf16 v[24:27], v[226:229], v[194:197], 0
	v_mfma_f32_16x16x32_bf16 v[12:15], v[218:221], v[202:205], 0
	v_mfma_f32_16x16x32_bf16 v[8:11], v[226:229], v[202:205], 0
	v_mfma_f32_16x16x32_bf16 v[4:7], v[218:221], v[210:213], 0
	v_mfma_f32_16x16x32_bf16 v[0:3], v[226:229], v[210:213], 0
	v_mfma_f32_16x16x32_bf16 v[44:47], v[222:225], v[190:193], v[44:47]
	v_mfma_f32_16x16x32_bf16 v[40:43], v[230:233], v[190:193], v[40:43]
	v_mfma_f32_16x16x32_bf16 v[28:31], v[222:225], v[198:201], v[28:31]
	v_mfma_f32_16x16x32_bf16 v[24:27], v[230:233], v[198:201], v[24:27]
	v_mfma_f32_16x16x32_bf16 v[12:15], v[222:225], v[206:209], v[12:15]
	v_mfma_f32_16x16x32_bf16 v[8:11], v[230:233], v[206:209], v[8:11]
	v_mfma_f32_16x16x32_bf16 v[4:7], v[222:225], v[214:217], v[4:7]
	v_mfma_f32_16x16x32_bf16 v[0:3], v[230:233], v[214:217], v[0:3]
	s_setprio 0
	s_barrier
	s_branch .Lzp10_mid
; #define PG8_STAGE(bufoff, gbase, voff) do { _Pragma("unroll") for (int _i = 0; _i < 2; ++_i) \
;         __builtin_amdgcn_global_load_lds((const unsigned*)((const char*)(gbase) + (voff)[_i]), (PG8_LAS unsigned*)(lds + (bufoff) + ldsw + _i * 8192), 16, 0, 0); } while (0)
; #define PG8_LDA(dst, b, h) do { _Pragma("unroll") for (int m = 0; m < 4; ++m) _Pragma("unroll") for (int k = 0; k < 2; ++k) dst[m][k] = *(const PG8_LAS bf16x8*)(lds + PG8_SA(b, h) + aoff + m * 2048 + k * 1024); } while (0)
; #define PG8_LDB(dst, b, h) do { _Pragma("unroll") for (int n = 0; n < 2; ++n) _Pragma("unroll") for (int k = 0; k < 2; ++k) dst[n][k] = *(const PG8_LAS bf16x8*)(lds + PG8_SB(b, h) + boff + n * 2048 + k * 1024); } while (0)
; #define PG8_MMA(ai, bj, At, Bt) do { __builtin_amdgcn_s_setprio(1); _Pragma("unroll") for (int m = 0; m < 4; ++m) _Pragma("unroll") for (int n = 0; n < 2; ++n) _Pragma("unroll") for (int k = 0; k < 2; ++k) \
;         acc[ai][bj][m][n] = __builtin_amdgcn_mfma_f32_16x16x32_bf16(Bt[n][k], At[m][k], acc[ai][bj][m][n], 0, 0, 0); __builtin_amdgcn_s_setprio(0); } while (0)
; #define PG8_BAR __builtin_amdgcn_s_barrier()
; template <class Epi, class Sched, bool STAMP = false>
; __device__ __forceinline__ void gemm_phase(PG8_LAS unsigned char* lds, const Gemm g, const Sched& S, const Epi& E, unsigned long long* stamps) {
;     ...
;         for (int t = 0; t < nt; t += 2) {
;             const bool last = (t == nt - 2);
;             const char* a1 = cA + (size_t)(t + 1) * kstep;
;             const char* a2 = last ? nA : cA + (size_t)(t + 2) * kstep; const char* b2 = last ? nB : cB + (size_t)(t + 2) * kstep;
;             const char* a3 = a2 + kstep; const char* b3 = b2 + kstep;
;             if (last && has_next) S.a_ready(nxt);
;             PG8_LDB(B0, 0, 0); PG8_SCHED; PG8_LDA(At, 0, 0); PG8_STAGE(PG8_SA(1, 1), a1 + hstep, voffA);
;             PG8_WAIT_L(8); PG8_BAR; PG8_WAIT_L(0); PG8_MMA(0, 0, At, B0); PG8_BAR; PG8_SCHED;
;             PG8_LDB(B1, 0, 1); PG8_STAGE(PG8_SB(0, 0), b2, voffB);
;             PG8_BAR; PG8_WAIT_L(0); PG8_MMA(0, 1, At, B1); PG8_BAR;
;             PG8_LDA(At, 0, 1); PG8_STAGE(PG8_SA(0, 0), a2, voffA);
;             PG8_BAR; PG8_WAIT_L(0); PG8_MMA(1, 0, At, B0); PG8_BAR; PG8_SCHED;
;             PG8_STAGE(PG8_SB(0, 1), b2 + hstep, voffB);
;             PG8_WAIT_V(6); PG8_BAR; PG8_MMA(1, 1, At, B1); PG8_BAR;
.LBB0_688:
	s_add_u32 s100, s76, 0x43f80
	s_addc_u32 s101, s77, 0
	s_mov_b32 m0, s59
	s_nop 0
	global_load_lds_dwordx4 v130, s[100:101]
	s_mov_b32 m0, s60
	s_nop 0
	global_load_lds_dwordx4 v134, s[100:101]
	ds_read_b128 v[170:173], v147
	ds_read_b128 v[174:177], v148
	ds_read_b128 v[178:181], v149
	ds_read_b128 v[182:185], v150
	s_add_u32 s36, s34, 0x100
	s_addc_u32 s37, s35, 0
	s_cmp_eq_u32 s10, 12
	s_cselect_b32 s43, s5, s37
	s_cselect_b32 s42, s4, s36
	s_cselect_b32 s41, s1, s77
	s_cselect_b32 s40, s0, s76
	s_mov_b32 m0, s63
	ds_read_b128 v[186:189], v145
	ds_read_b128 v[190:193], v145 offset:1024
	ds_read_b128 v[194:197], v145 offset:2048
	ds_read_b128 v[198:201], v145 offset:3072
	ds_read_b128 v[202:205], v145 offset:4096
	ds_read_b128 v[206:209], v145 offset:5120
	ds_read_b128 v[210:213], v145 offset:6144
	ds_read_b128 v[214:217], v145 offset:7168
	global_load_lds_dwordx4 v136, s[34:35]
	s_mov_b32 m0, s64
	s_nop 0
	global_load_lds_dwordx4 v138, s[34:35]
	ds_read_b128 v[218:221], v151
	ds_read_b128 v[222:225], v152
	ds_read_b128 v[226:229], v153
	ds_read_b128 v[230:233], v154
	s_waitcnt vmcnt(8)
	s_waitcnt lgkmcnt(0)
	s_barrier
	s_setprio 1
	v_mfma_f32_16x16x32_bf16 v[124:127], v[170:173], v[186:189], v[124:127]
	v_mfma_f32_16x16x32_bf16 v[120:123], v[178:181], v[186:189], v[120:123]
	v_mfma_f32_16x16x32_bf16 v[116:119], v[170:173], v[194:197], v[116:119]
	v_mfma_f32_16x16x32_bf16 v[112:115], v[178:181], v[194:197], v[112:115]
	v_mfma_f32_16x16x32_bf16 v[100:103], v[170:173], v[202:205], v[100:103]
	v_mfma_f32_16x16x32_bf16 v[96:99], v[178:181], v[202:205], v[96:99]
	v_mfma_f32_16x16x32_bf16 v[84:87], v[170:173], v[210:213], v[84:87]
	v_mfma_f32_16x16x32_bf16 v[80:83], v[178:181], v[210:213], v[80:83]
	v_mfma_f32_16x16x32_bf16 v[124:127], v[174:177], v[190:193], v[124:127]
	v_mfma_f32_16x16x32_bf16 v[120:123], v[182:185], v[190:193], v[120:123]
	v_mfma_f32_16x16x32_bf16 v[116:119], v[174:177], v[198:201], v[116:119]
	v_mfma_f32_16x16x32_bf16 v[112:115], v[182:185], v[198:201], v[112:115]
	v_mfma_f32_16x16x32_bf16 v[100:103], v[174:177], v[206:209], v[100:103]
	v_mfma_f32_16x16x32_bf16 v[96:99], v[182:185], v[206:209], v[96:99]
	v_mfma_f32_16x16x32_bf16 v[84:87], v[174:177], v[214:217], v[84:87]
	v_mfma_f32_16x16x32_bf16 v[80:83], v[182:185], v[214:217], v[80:83]
	v_mfma_f32_16x16x32_bf16 v[108:111], v[218:221], v[186:189], v[108:111]
	v_mfma_f32_16x16x32_bf16 v[104:107], v[226:229], v[186:189], v[104:107]
	v_mfma_f32_16x16x32_bf16 v[92:95], v[218:221], v[194:197], v[92:95]
	v_mfma_f32_16x16x32_bf16 v[88:91], v[226:229], v[194:197], v[88:91]
	v_mfma_f32_16x16x32_bf16 v[76:79], v[218:221], v[202:205], v[76:79]
	v_mfma_f32_16x16x32_bf16 v[72:75], v[226:229], v[202:205], v[72:75]
	v_mfma_f32_16x16x32_bf16 v[68:71], v[218:221], v[210:213], v[68:71]
	v_mfma_f32_16x16x32_bf16 v[64:67], v[226:229], v[210:213], v[64:67]
	v_mfma_f32_16x16x32_bf16 v[108:111], v[222:225], v[190:193], v[108:111]
	v_mfma_f32_16x16x32_bf16 v[104:107], v[230:233], v[190:193], v[104:107]
	v_mfma_f32_16x16x32_bf16 v[92:95], v[222:225], v[198:201], v[92:95]
	v_mfma_f32_16x16x32_bf16 v[88:91], v[230:233], v[198:201], v[88:91]
	v_mfma_f32_16x16x32_bf16 v[76:79], v[222:225], v[206:209], v[76:79]
	v_mfma_f32_16x16x32_bf16 v[72:75], v[230:233], v[206:209], v[72:75]
	v_mfma_f32_16x16x32_bf16 v[68:71], v[222:225], v[214:217], v[68:71]
	v_mfma_f32_16x16x32_bf16 v[64:67], v[230:233], v[214:217], v[64:67]
	s_setprio 0
	s_barrier
	s_mov_b32 m0, s48
	s_nop 0
	global_load_lds_dwordx4 v130, s[40:41]
	s_mov_b32 m0, s49
	s_nop 0
	global_load_lds_dwordx4 v134, s[40:41]
	s_mov_b32 m0, s47
	ds_read_b128 v[186:189], v145 offset:16384
	ds_read_b128 v[190:193], v145 offset:17408
	ds_read_b128 v[194:197], v145 offset:18432
	ds_read_b128 v[198:201], v145 offset:19456
	ds_read_b128 v[202:205], v145 offset:20480
	ds_read_b128 v[206:209], v145 offset:21504
	ds_read_b128 v[210:213], v145 offset:22528
	ds_read_b128 v[214:217], v145 offset:23552
	global_load_lds_dwordx4 v128, s[42:43]
	s_mov_b32 m0, s50
	s_nop 0
	global_load_lds_dwordx4 v132, s[42:43]
	s_waitcnt vmcnt(6)
	s_waitcnt lgkmcnt(0)
	s_barrier
	s_setprio 1
	v_mfma_f32_16x16x32_bf16 v[60:63], v[170:173], v[186:189], v[60:63]
	v_mfma_f32_16x16x32_bf16 v[56:59], v[178:181], v[186:189], v[56:59]
	v_mfma_f32_16x16x32_bf16 v[52:55], v[170:173], v[194:197], v[52:55]
	v_mfma_f32_16x16x32_bf16 v[48:51], v[178:181], v[194:197], v[48:51]
	v_mfma_f32_16x16x32_bf16 v[36:39], v[170:173], v[202:205], v[36:39]
	v_mfma_f32_16x16x32_bf16 v[32:35], v[178:181], v[202:205], v[32:35]
	v_mfma_f32_16x16x32_bf16 v[20:23], v[170:173], v[210:213], v[20:23]
	v_mfma_f32_16x16x32_bf16 v[16:19], v[178:181], v[210:213], v[16:19]
	v_mfma_f32_16x16x32_bf16 v[60:63], v[174:177], v[190:193], v[60:63]
	v_mfma_f32_16x16x32_bf16 v[56:59], v[182:185], v[190:193], v[56:59]
	v_mfma_f32_16x16x32_bf16 v[52:55], v[174:177], v[198:201], v[52:55]
	v_mfma_f32_16x16x32_bf16 v[48:51], v[182:185], v[198:201], v[48:51]
	v_mfma_f32_16x16x32_bf16 v[36:39], v[174:177], v[206:209], v[36:39]
	v_mfma_f32_16x16x32_bf16 v[32:35], v[182:185], v[206:209], v[32:35]
	v_mfma_f32_16x16x32_bf16 v[20:23], v[174:177], v[214:217], v[20:23]
	v_mfma_f32_16x16x32_bf16 v[16:19], v[182:185], v[214:217], v[16:19]
	v_mfma_f32_16x16x32_bf16 v[44:47], v[218:221], v[186:189], v[44:47]
	v_mfma_f32_16x16x32_bf16 v[40:43], v[226:229], v[186:189], v[40:43]
	v_mfma_f32_16x16x32_bf16 v[28:31], v[218:221], v[194:197], v[28:31]
	v_mfma_f32_16x16x32_bf16 v[24:27], v[226:229], v[194:197], v[24:27]
	v_mfma_f32_16x16x32_bf16 v[12:15], v[218:221], v[202:205], v[12:15]
	v_mfma_f32_16x16x32_bf16 v[8:11], v[226:229], v[202:205], v[8:11]
	v_mfma_f32_16x16x32_bf16 v[4:7], v[218:221], v[210:213], v[4:7]
	v_mfma_f32_16x16x32_bf16 v[0:3], v[226:229], v[210:213], v[0:3]
	v_mfma_f32_16x16x32_bf16 v[44:47], v[222:225], v[190:193], v[44:47]
	v_mfma_f32_16x16x32_bf16 v[40:43], v[230:233], v[190:193], v[40:43]
	v_mfma_f32_16x16x32_bf16 v[28:31], v[222:225], v[198:201], v[28:31]
	v_mfma_f32_16x16x32_bf16 v[24:27], v[230:233], v[198:201], v[24:27]
	v_mfma_f32_16x16x32_bf16 v[12:15], v[222:225], v[206:209], v[12:15]
	v_mfma_f32_16x16x32_bf16 v[8:11], v[230:233], v[206:209], v[8:11]
	v_mfma_f32_16x16x32_bf16 v[4:7], v[222:225], v[214:217], v[4:7]
	v_mfma_f32_16x16x32_bf16 v[0:3], v[230:233], v[214:217], v[0:3]
	s_setprio 0
	s_barrier
; #define PG8_STAGE(bufoff, gbase, voff) do { _Pragma("unroll") for (int _i = 0; _i < 2; ++_i) \
;         __builtin_amdgcn_global_load_lds((const unsigned*)((const char*)(gbase) + (voff)[_i]), (PG8_LAS unsigned*)(lds + (bufoff) + ldsw + _i * 8192), 16, 0, 0); } while (0)
; #define PG8_LDA(dst, b, h) do { _Pragma("unroll") for (int m = 0; m < 4; ++m) _Pragma("unroll") for (int k = 0; k < 2; ++k) dst[m][k] = *(const PG8_LAS bf16x8*)(lds + PG8_SA(b, h) + aoff + m * 2048 + k * 1024); } while (0)
; #define PG8_LDB(dst, b, h) do { _Pragma("unroll") for (int n = 0; n < 2; ++n) _Pragma("unroll") for (int k = 0; k < 2; ++k) dst[n][k] = *(const PG8_LAS bf16x8*)(lds + PG8_SB(b, h) + boff + n * 2048 + k * 1024); } while (0)
; #define PG8_MMA(ai, bj, At, Bt) do { __builtin_amdgcn_s_setprio(1); _Pragma("unroll") for (int m = 0; m < 4; ++m) _Pragma("unroll") for (int n = 0; n < 2; ++n) _Pragma("unroll") for (int k = 0; k < 2; ++k) \
;         acc[ai][bj][m][n] = __builtin_amdgcn_mfma_f32_16x16x32_bf16(Bt[n][k], At[m][k], acc[ai][bj][m][n], 0, 0, 0); __builtin_amdgcn_s_setprio(0); } while (0)
; #define PG8_WAIT_V(n) asm volatile("s_waitcnt vmcnt(" #n ")" ::: "memory")
; #define PG8_WAIT_L(n) asm volatile("s_waitcnt lgkmcnt(" #n ")" ::: "memory")
; #define PG8_BAR __builtin_amdgcn_s_barrier()
; #define PG8_SCHED __builtin_amdgcn_sched_barrier(0)
; template <class Epi, class Sched, bool STAMP = false>
; __device__ __forceinline__ void gemm_phase(PG8_LAS unsigned char* lds, const Gemm g, const Sched& S, const Epi& E, unsigned long long* stamps) {
;     ...
;             PG8_LDB(B0, 1, 0); PG8_SCHED; PG8_LDA(At, 1, 0); PG8_STAGE(PG8_SA(0, 1), a2 + hstep, voffA);
;             PG8_WAIT_L(8); PG8_BAR; PG8_WAIT_L(0); PG8_MMA(0, 0, At, B0); PG8_BAR; PG8_SCHED;
;             PG8_LDB(B1, 1, 1); PG8_STAGE(PG8_SB(1, 0), b3, voffB);
;             PG8_BAR; PG8_WAIT_L(0); PG8_MMA(0, 1, At, B1); PG8_BAR;
;             PG8_LDA(At, 1, 1); PG8_STAGE(PG8_SA(1, 0), a3, voffA);
;             PG8_BAR; PG8_WAIT_L(0); PG8_MMA(1, 0, At, B0); PG8_BAR; PG8_SCHED;
;             PG8_STAGE(PG8_SB(1, 1), b3 + hstep, voffB);
;             PG8_WAIT_V(6); PG8_BAR; PG8_MMA(1, 1, At, B1); PG8_BAR;
;         }
.Lzp10_mid:
	s_add_u32 s34, s40, 0x44000
	s_addc_u32 s35, s41, 0
	s_mov_b32 m0, s51
	s_nop 0
	global_load_lds_dwordx4 v130, s[34:35]
	s_mov_b32 m0, s52
	s_nop 0
	global_load_lds_dwordx4 v134, s[34:35]
	ds_read_b128 v[170:173], v155
	ds_read_b128 v[174:177], v156
	ds_read_b128 v[178:181], v157
	ds_read_b128 v[182:185], v165
	s_add_u32 s34, s42, 0x44000
	s_addc_u32 s35, s43, 0
	s_mov_b32 m0, s53
	ds_read_b128 v[186:189], v145 offset:32768
	ds_read_b128 v[190:193], v145 offset:33792
	ds_read_b128 v[194:197], v145 offset:34816
	ds_read_b128 v[198:201], v145 offset:35840
	ds_read_b128 v[202:205], v145 offset:36864
	ds_read_b128 v[206:209], v145 offset:37888
	ds_read_b128 v[210:213], v145 offset:38912
	ds_read_b128 v[214:217], v145 offset:39936
	global_load_lds_dwordx4 v128, s[34:35]
	s_mov_b32 m0, s54
	s_nop 0
	global_load_lds_dwordx4 v132, s[34:35]
	ds_read_b128 v[218:221], v166
	ds_read_b128 v[222:225], v167
	ds_read_b128 v[226:229], v168
	ds_read_b128 v[230:233], v169
	s_waitcnt vmcnt(8)
	s_waitcnt lgkmcnt(0)
	s_barrier
	s_setprio 1
	v_mfma_f32_16x16x32_bf16 v[124:127], v[170:173], v[186:189], v[124:127]
	v_mfma_f32_16x16x32_bf16 v[120:123], v[178:181], v[186:189], v[120:123]
	v_mfma_f32_16x16x32_bf16 v[116:119], v[170:173], v[194:197], v[116:119]
	v_mfma_f32_16x16x32_bf16 v[112:115], v[178:181], v[194:197], v[112:115]
	v_mfma_f32_16x16x32_bf16 v[100:103], v[170:173], v[202:205], v[100:103]
	v_mfma_f32_16x16x32_bf16 v[96:99], v[178:181], v[202:205], v[96:99]
	v_mfma_f32_16x16x32_bf16 v[84:87], v[170:173], v[210:213], v[84:87]
	v_mfma_f32_16x16x32_bf16 v[80:83], v[178:181], v[210:213], v[80:83]
	v_mfma_f32_16x16x32_bf16 v[124:127], v[174:177], v[190:193], v[124:127]
	v_mfma_f32_16x16x32_bf16 v[120:123], v[182:185], v[190:193], v[120:123]
	v_mfma_f32_16x16x32_bf16 v[116:119], v[174:177], v[198:201], v[116:119]
	v_mfma_f32_16x16x32_bf16 v[112:115], v[182:185], v[198:201], v[112:115]
	v_mfma_f32_16x16x32_bf16 v[100:103], v[174:177], v[206:209], v[100:103]
	v_mfma_f32_16x16x32_bf16 v[96:99], v[182:185], v[206:209], v[96:99]
	v_mfma_f32_16x16x32_bf16 v[84:87], v[174:177], v[214:217], v[84:87]
	v_mfma_f32_16x16x32_bf16 v[80:83], v[182:185], v[214:217], v[80:83]
	v_mfma_f32_16x16x32_bf16 v[108:111], v[218:221], v[186:189], v[108:111]
	v_mfma_f32_16x16x32_bf16 v[104:107], v[226:229], v[186:189], v[104:107]
	v_mfma_f32_16x16x32_bf16 v[92:95], v[218:221], v[194:197], v[92:95]
	v_mfma_f32_16x16x32_bf16 v[88:91], v[226:229], v[194:197], v[88:91]
	v_mfma_f32_16x16x32_bf16 v[76:79], v[218:221], v[202:205], v[76:79]
	v_mfma_f32_16x16x32_bf16 v[72:75], v[226:229], v[202:205], v[72:75]
	v_mfma_f32_16x16x32_bf16 v[68:71], v[218:221], v[210:213], v[68:71]
	v_mfma_f32_16x16x32_bf16 v[64:67], v[226:229], v[210:213], v[64:67]
	v_mfma_f32_16x16x32_bf16 v[108:111], v[222:225], v[190:193], v[108:111]
	v_mfma_f32_16x16x32_bf16 v[104:107], v[230:233], v[190:193], v[104:107]
	v_mfma_f32_16x16x32_bf16 v[92:95], v[222:225], v[198:201], v[92:95]
	v_mfma_f32_16x16x32_bf16 v[88:91], v[230:233], v[198:201], v[88:91]
	v_mfma_f32_16x16x32_bf16 v[76:79], v[222:225], v[206:209], v[76:79]
	v_mfma_f32_16x16x32_bf16 v[72:75], v[230:233], v[206:209], v[72:75]
	v_mfma_f32_16x16x32_bf16 v[68:71], v[222:225], v[214:217], v[68:71]
	v_mfma_f32_16x16x32_bf16 v[64:67], v[230:233], v[214:217], v[64:67]
	s_setprio 0
	s_barrier
	s_mov_b32 m0, s55
	s_add_u32 s100, s40, 0x80
	s_addc_u32 s101, s41, 0
	global_load_lds_dwordx4 v130, s[100:101]
	s_mov_b32 m0, s56
	s_nop 0
	global_load_lds_dwordx4 v134, s[100:101]
	s_mov_b32 m0, s57
	ds_read_b128 v[186:189], v145 offset:49152
	ds_read_b128 v[190:193], v145 offset:50176
	ds_read_b128 v[194:197], v145 offset:51200
	ds_read_b128 v[198:201], v145 offset:52224
	ds_read_b128 v[202:205], v145 offset:53248
	ds_read_b128 v[206:209], v145 offset:54272
	ds_read_b128 v[210:213], v145 offset:55296
	ds_read_b128 v[214:217], v145 offset:56320
	s_add_u32 s100, s42, 0x80
	s_addc_u32 s101, s43, 0
	global_load_lds_dwordx4 v128, s[100:101]
	s_mov_b32 m0, s58
	s_nop 0
	global_load_lds_dwordx4 v132, s[100:101]
	s_waitcnt vmcnt(6)
	s_waitcnt lgkmcnt(0)
	s_barrier
	s_setprio 1
	v_mfma_f32_16x16x32_bf16 v[60:63], v[170:173], v[186:189], v[60:63]
	v_mfma_f32_16x16x32_bf16 v[56:59], v[178:181], v[186:189], v[56:59]
	v_mfma_f32_16x16x32_bf16 v[52:55], v[170:173], v[194:197], v[52:55]
	v_mfma_f32_16x16x32_bf16 v[48:51], v[178:181], v[194:197], v[48:51]
	v_mfma_f32_16x16x32_bf16 v[36:39], v[170:173], v[202:205], v[36:39]
	v_mfma_f32_16x16x32_bf16 v[32:35], v[178:181], v[202:205], v[32:35]
	v_mfma_f32_16x16x32_bf16 v[20:23], v[170:173], v[210:213], v[20:23]
	v_mfma_f32_16x16x32_bf16 v[16:19], v[178:181], v[210:213], v[16:19]
	v_mfma_f32_16x16x32_bf16 v[60:63], v[174:177], v[190:193], v[60:63]
	v_mfma_f32_16x16x32_bf16 v[56:59], v[182:185], v[190:193], v[56:59]
	v_mfma_f32_16x16x32_bf16 v[52:55], v[174:177], v[198:201], v[52:55]
	v_mfma_f32_16x16x32_bf16 v[48:51], v[182:185], v[198:201], v[48:51]
	v_mfma_f32_16x16x32_bf16 v[36:39], v[174:177], v[206:209], v[36:39]
	v_mfma_f32_16x16x32_bf16 v[32:35], v[182:185], v[206:209], v[32:35]
	v_mfma_f32_16x16x32_bf16 v[20:23], v[174:177], v[214:217], v[20:23]
	v_mfma_f32_16x16x32_bf16 v[16:19], v[182:185], v[214:217], v[16:19]
	v_mfma_f32_16x16x32_bf16 v[44:47], v[218:221], v[186:189], v[44:47]
	v_mfma_f32_16x16x32_bf16 v[40:43], v[226:229], v[186:189], v[40:43]
	v_mfma_f32_16x16x32_bf16 v[28:31], v[218:221], v[194:197], v[28:31]
	v_mfma_f32_16x16x32_bf16 v[24:27], v[226:229], v[194:197], v[24:27]
	v_mfma_f32_16x16x32_bf16 v[12:15], v[218:221], v[202:205], v[12:15]
	v_mfma_f32_16x16x32_bf16 v[8:11], v[226:229], v[202:205], v[8:11]
	v_mfma_f32_16x16x32_bf16 v[4:7], v[218:221], v[210:213], v[4:7]
	v_mfma_f32_16x16x32_bf16 v[0:3], v[226:229], v[210:213], v[0:3]
	v_mfma_f32_16x16x32_bf16 v[44:47], v[222:225], v[190:193], v[44:47]
	v_mfma_f32_16x16x32_bf16 v[40:43], v[230:233], v[190:193], v[40:43]
	v_mfma_f32_16x16x32_bf16 v[28:31], v[222:225], v[198:201], v[28:31]
	v_mfma_f32_16x16x32_bf16 v[24:27], v[230:233], v[198:201], v[24:27]
	v_mfma_f32_16x16x32_bf16 v[12:15], v[222:225], v[206:209], v[12:15]
	v_mfma_f32_16x16x32_bf16 v[8:11], v[230:233], v[206:209], v[8:11]
	v_mfma_f32_16x16x32_bf16 v[4:7], v[222:225], v[214:217], v[4:7]
	v_mfma_f32_16x16x32_bf16 v[0:3], v[230:233], v[214:217], v[0:3]
	s_setprio 0
	s_add_i32 s10, s10, 2
	s_add_u32 s76, s76, 0x100
	s_addc_u32 s77, s77, 0
	s_cmp_gt_u32 s10, 13
	s_mov_b64 s[34:35], s[36:37]
	s_barrier
;     DI void operator()(const f32x4 (&acc)[2][2][4][2], const Unit& u, int wr, int wc, int fr, int fq) const {
;         const int row0 = u.pm * BM + wr * 64 + fr, col0 = u.pn * BM + wc * 32 + 8 * fq;
; #pragma unroll
;         for (int ai = 0; ai < 2; ++ai)
; #pragma unroll
;             for (int m = 0; m < 4; ++m) { u16* rowp = O + (size_t)(row0 + ai * HALF + m * 16) * ldc + col0;
; #pragma unroll
;                 for (int bj = 0; bj < 2; ++bj) { const f32x4 v0 = acc[ai][bj][m][0], v1 = acc[ai][bj][m][1];
;                     uint4 w = {pack2(v0[0], v0[1]), pack2(v0[2], v0[3]), pack2(v1[0], v1[1]), pack2(v1[2], v1[3])}; *(uint4*)(rowp + bj * HALF) = w; } }
	s_cbranch_scc0 .LBB0_688
	v_lshl_add_u32 v170, s69, 8, v144
	v_lshl_or_b32 v172, s75, 8, v146
	v_ashrrev_i32_e32 v171, 31, v170
	v_ashrrev_i32_e32 v173, 31, v172
	v_lshlrev_b64 v[174:175], 11, v[170:171]
	v_lshl_add_u64 v[174:175], s[14:15], 0, v[174:175]
	v_lshlrev_b64 v[172:173], 1, v[172:173]
	v_lshl_add_u64 v[174:175], v[174:175], 0, v[172:173]
	v_cvt_pk_bf16_f32 v60, v60, v61
	v_cvt_pk_bf16_f32 v61, v62, v63
	v_cvt_pk_bf16_f32 v62, v56, v57
	v_add_co_u32_e32 v56, vcc, s65, v174
	v_cvt_pk_bf16_f32 v68, v68, v69
	v_cvt_pk_bf16_f32 v69, v70, v71
	v_cvt_pk_bf16_f32 v70, v64, v65
	v_lshl_add_u64 v[64:65], v[174:175], 0, s[16:17]
	v_addc_co_u32_e32 v57, vcc, 0, v175, vcc
	v_cvt_pk_bf16_f32 v44, v44, v45
	v_cvt_pk_bf16_f32 v45, v46, v47
	v_cvt_pk_bf16_f32 v46, v40, v41
	v_cvt_pk_bf16_f32 v47, v42, v43
	v_cvt_pk_bf16_f32 v108, v108, v109
	v_cvt_pk_bf16_f32 v109, v110, v111
	v_cvt_pk_bf16_f32 v110, v104, v105
	v_or_b32_e32 v104, 16, v170
	global_store_dwordx4 v[64:65], v[44:47], off offset:256
	v_ashrrev_i32_e32 v105, 31, v104
	v_cvt_pk_bf16_f32 v92, v92, v93
	v_add_co_u32_e32 v46, vcc, s66, v174
	v_cvt_pk_bf16_f32 v93, v94, v95
	v_cvt_pk_bf16_f32 v94, v88, v89
	v_or_b32_e32 v88, 32, v170
	v_lshl_add_u64 v[44:45], v[174:175], 0, s[18:19]
	v_addc_co_u32_e32 v47, vcc, 0, v175, vcc
	v_cvt_pk_bf16_f32 v28, v28, v29
	v_cvt_pk_bf16_f32 v29, v30, v31
	v_cvt_pk_bf16_f32 v30, v24, v25
	v_cvt_pk_bf16_f32 v31, v26, v27
	v_lshlrev_b64 v[104:105], 11, v[104:105]
	v_ashrrev_i32_e32 v89, 31, v88
	v_cvt_pk_bf16_f32 v76, v76, v77
	v_cvt_pk_bf16_f32 v77, v78, v79
	v_cvt_pk_bf16_f32 v78, v72, v73
	v_or_b32_e32 v72, 48, v170
	global_store_dwordx4 v[44:45], v[28:31], off offset:256
	v_cvt_pk_bf16_f32 v111, v106, v107
	v_lshl_add_u64 v[104:105], s[14:15], 0, v[104:105]
	v_add_co_u32_e32 v30, vcc, s67, v174
	v_lshlrev_b64 v[88:89], 11, v[88:89]
	v_ashrrev_i32_e32 v73, 31, v72
	v_lshl_add_u64 v[28:29], v[174:175], 0, s[20:21]
	v_addc_co_u32_e32 v31, vcc, 0, v175, vcc
	v_cvt_pk_bf16_f32 v12, v12, v13
	v_cvt_pk_bf16_f32 v13, v14, v15
	v_cvt_pk_bf16_f32 v14, v8, v9
	v_cvt_pk_bf16_f32 v15, v10, v11
	global_store_dwordx4 v[174:175], v[108:111], off offset:256
	v_cvt_pk_bf16_f32 v95, v90, v91
	v_lshl_add_u64 v[88:89], s[14:15], 0, v[88:89]
	v_lshl_add_u64 v[108:109], v[104:105], 0, v[172:173]
	v_lshlrev_b64 v[72:73], 11, v[72:73]
	global_store_dwordx4 v[28:29], v[12:15], off offset:256
	global_store_dwordx4 v[108:109], v[92:95], off offset:256
	v_cvt_pk_bf16_f32 v79, v74, v75
	v_add_co_u32_e32 v14, vcc, s68, v174
	v_lshl_add_u64 v[92:93], v[88:89], 0, v[172:173]
	v_lshl_add_u64 v[72:73], s[14:15], 0, v[72:73]
	v_addc_co_u32_e32 v15, vcc, 0, v175, vcc
	v_cvt_pk_bf16_f32 v124, v124, v125
	v_cvt_pk_bf16_f32 v125, v126, v127
	v_cvt_pk_bf16_f32 v126, v120, v121
	v_cvt_pk_bf16_f32 v127, v122, v123
	v_cvt_pk_bf16_f32 v104, v116, v117
	v_cvt_pk_bf16_f32 v105, v118, v119
	v_cvt_pk_bf16_f32 v106, v112, v113
	v_cvt_pk_bf16_f32 v107, v114, v115
	v_cvt_pk_bf16_f32 v88, v100, v101
	v_cvt_pk_bf16_f32 v89, v102, v103
	v_cvt_pk_bf16_f32 v90, v96, v97
	v_cvt_pk_bf16_f32 v91, v98, v99
	global_store_dwordx4 v[92:93], v[76:79], off offset:256
	v_cvt_pk_bf16_f32 v74, v80, v81
	v_cvt_pk_bf16_f32 v75, v82, v83
	v_lshl_add_u64 v[76:77], v[72:73], 0, v[172:173]
	v_cvt_pk_bf16_f32 v72, v84, v85
	v_cvt_pk_bf16_f32 v73, v86, v87
	v_cvt_pk_bf16_f32 v71, v66, v67
	v_cvt_pk_bf16_f32 v63, v58, v59
	v_cvt_pk_bf16_f32 v40, v52, v53
	v_cvt_pk_bf16_f32 v41, v54, v55
	v_cvt_pk_bf16_f32 v42, v48, v49
	v_cvt_pk_bf16_f32 v43, v50, v51
	v_cvt_pk_bf16_f32 v24, v36, v37
	v_cvt_pk_bf16_f32 v25, v38, v39
	v_cvt_pk_bf16_f32 v26, v32, v33
	v_cvt_pk_bf16_f32 v27, v34, v35
	v_lshl_add_u64 v[12:13], v[174:175], 0, s[28:29]
	v_cvt_pk_bf16_f32 v8, v20, v21
	v_cvt_pk_bf16_f32 v9, v22, v23
	v_cvt_pk_bf16_f32 v10, v16, v17
	v_cvt_pk_bf16_f32 v11, v18, v19
	v_cvt_pk_bf16_f32 v4, v4, v5
	v_cvt_pk_bf16_f32 v5, v6, v7
	v_cvt_pk_bf16_f32 v6, v0, v1
	v_cvt_pk_bf16_f32 v7, v2, v3
	s_and_b64 vcc, exec, s[2:3]
	s_mov_b32 s75, s70
	s_mov_b32 s69, s71
	s_mov_b64 s[36:37], s[0:1]
	s_mov_b64 s[34:35], s[4:5]
	global_store_dwordx4 v[174:175], v[124:127], off
	global_store_dwordx4 v[108:109], v[104:107], off
	global_store_dwordx4 v[92:93], v[88:91], off
	global_store_dwordx4 v[76:77], v[72:75], off
	global_store_dwordx4 v[76:77], v[68:71], off offset:256
	global_store_dwordx4 v[56:57], v[60:63], off
	global_store_dwordx4 v[46:47], v[40:43], off
	global_store_dwordx4 v[30:31], v[24:27], off
	global_store_dwordx4 v[14:15], v[8:11], off
	global_store_dwordx4 v[12:13], v[4:7], off offset:256
	s_cbranch_vccz .LBB0_677
	s_waitcnt vmcnt(0)
	s_cmpk_gt_u32 s45, 0xff
	s_cbranch_scc1 .LBB0_692
	s_barrier

; #define PG8_STAGE(bufoff, gbase, voff) do { _Pragma("unroll") for (int _i = 0; _i < 2; ++_i) \
;         __builtin_amdgcn_global_load_lds((const unsigned*)((const char*)(gbase) + (voff)[_i]), (PG8_LAS unsigned*)(lds + (bufoff) + ldsw + _i * 8192), 16, 0, 0); } while (0)
; #define PG8_LDA(dst, b, h) do { _Pragma("unroll") for (int m = 0; m < 4; ++m) _Pragma("unroll") for (int k = 0; k < 2; ++k) dst[m][k] = *(const PG8_LAS bf16x8*)(lds + PG8_SA(b, h) + aoff + m * 2048 + k * 1024); } while (0)
; #define PG8_LDB(dst, b, h) do { _Pragma("unroll") for (int n = 0; n < 2; ++n) _Pragma("unroll") for (int k = 0; k < 2; ++k) dst[n][k] = *(const PG8_LAS bf16x8*)(lds + PG8_SB(b, h) + boff + n * 2048 + k * 1024); } while (0)
; #define PG8_MMA(ai, bj, At, Bt) do { __builtin_amdgcn_s_setprio(1); _Pragma("unroll") for (int m = 0; m < 4; ++m) _Pragma("unroll") for (int n = 0; n < 2; ++n) _Pragma("unroll") for (int k = 0; k < 2; ++k) \
;         acc[ai][bj][m][n] = __builtin_amdgcn_mfma_f32_16x16x32_bf16(Bt[n][k], At[m][k], acc[ai][bj][m][n], 0, 0, 0); __builtin_amdgcn_s_setprio(0); } while (0)
; #define PG8_BAR __builtin_amdgcn_s_barrier()
; template <class Epi, class Sched, bool STAMP = false>
; __device__ __forceinline__ void gemm_phase(PG8_LAS unsigned char* lds, const Gemm g, const Sched& S, const Epi& E, unsigned long long* stamps) {
;     ...
;         for (int t = 0; t < nt; t += 2) {
;             const bool last = (t == nt - 2);
;             const char* a1 = cA + (size_t)(t + 1) * kstep;
;             const char* a2 = last ? nA : cA + (size_t)(t + 2) * kstep; const char* b2 = last ? nB : cB + (size_t)(t + 2) * kstep;
;             const char* a3 = a2 + kstep; const char* b3 = b2 + kstep;
;             if (last && has_next) S.a_ready(nxt);
;             PG8_LDB(B0, 0, 0); PG8_SCHED; PG8_LDA(At, 0, 0); PG8_STAGE(PG8_SA(1, 1), a1 + hstep, voffA);
;             PG8_WAIT_L(8); PG8_BAR; PG8_WAIT_L(0); PG8_MMA(0, 0, At, B0); PG8_BAR; PG8_SCHED;
;             PG8_LDB(B1, 0, 1); PG8_STAGE(PG8_SB(0, 0), b2, voffB);
;             PG8_BAR; PG8_WAIT_L(0); PG8_MMA(0, 1, At, B1); PG8_BAR;
;             PG8_LDA(At, 0, 1); PG8_STAGE(PG8_SA(0, 0), a2, voffA);
;             PG8_BAR; PG8_WAIT_L(0); PG8_MMA(1, 0, At, B0); PG8_BAR; PG8_SCHED;
;             PG8_STAGE(PG8_SB(0, 1), b2 + hstep, voffB);
;             PG8_WAIT_V(6); PG8_BAR; PG8_MMA(1, 1, At, B1); PG8_BAR;
.LBB0_726:
	s_add_u32 s62, s18, 0x100
	s_addc_u32 s63, s19, 0
	s_mov_b32 s10, -2
	s_cmp_eq_u32 s46, s99
	s_cbranch_scc1 .Lgu4_half_loop_z
	s_add_u32 s100, s62, 0x43f80
	s_addc_u32 s101, s63, 0
	s_mov_b32 m0, s52
	s_nop 0
	global_load_lds_dwordx4 v130, s[100:101]
	s_mov_b32 m0, s53
	s_nop 0
	global_load_lds_dwordx4 v128, s[100:101]
	ds_read_b128 v[140:143], v147
	ds_read_b128 v[170:173], v148
	ds_read_b128 v[174:177], v149
	ds_read_b128 v[178:181], v150
	s_add_u32 s18, s16, 0x100
	s_addc_u32 s19, s17, 0
	s_cmp_eq_u32 s10, 12
	s_cselect_b32 s29, s5, s19
	s_cselect_b32 s28, s4, s18
	s_cselect_b32 s21, s1, s63
	s_cselect_b32 s20, s0, s62
	s_mov_b32 m0, s55
	ds_read_b128 v[182:185], v145
	ds_read_b128 v[186:189], v145 offset:1024
	ds_read_b128 v[190:193], v145 offset:2048
	ds_read_b128 v[194:197], v145 offset:3072
	ds_read_b128 v[198:201], v145 offset:4096
	ds_read_b128 v[202:205], v145 offset:5120
	ds_read_b128 v[206:209], v145 offset:6144
	ds_read_b128 v[210:213], v145 offset:7168
	global_load_lds_dwordx4 v132, s[16:17]
	s_mov_b32 m0, s56
	s_nop 0
	global_load_lds_dwordx4 v134, s[16:17]
	ds_read_b128 v[214:217], v151
	ds_read_b128 v[218:221], v152
	ds_read_b128 v[222:225], v153
	ds_read_b128 v[226:229], v154
	s_waitcnt vmcnt(8)
	s_waitcnt lgkmcnt(0)
	s_barrier
	s_setprio 1
	v_mfma_f32_16x16x32_bf16 v[124:127], v[140:143], v[182:185], 0
	v_mfma_f32_16x16x32_bf16 v[120:123], v[174:177], v[182:185], 0
	v_mfma_f32_16x16x32_bf16 v[108:111], v[140:143], v[190:193], 0
	v_mfma_f32_16x16x32_bf16 v[104:107], v[174:177], v[190:193], 0
	v_mfma_f32_16x16x32_bf16 v[92:95], v[140:143], v[198:201], 0
	v_mfma_f32_16x16x32_bf16 v[88:91], v[174:177], v[198:201], 0
	v_mfma_f32_16x16x32_bf16 v[76:79], v[140:143], v[206:209], 0
	v_mfma_f32_16x16x32_bf16 v[72:75], v[174:177], v[206:209], 0
	v_mfma_f32_16x16x32_bf16 v[124:127], v[170:173], v[186:189], v[124:127]
	v_mfma_f32_16x16x32_bf16 v[120:123], v[178:181], v[186:189], v[120:123]
	v_mfma_f32_16x16x32_bf16 v[108:111], v[170:173], v[194:197], v[108:111]
	v_mfma_f32_16x16x32_bf16 v[104:107], v[178:181], v[194:197], v[104:107]
	v_mfma_f32_16x16x32_bf16 v[92:95], v[170:173], v[202:205], v[92:95]
	v_mfma_f32_16x16x32_bf16 v[88:91], v[178:181], v[202:205], v[88:91]
	v_mfma_f32_16x16x32_bf16 v[76:79], v[170:173], v[210:213], v[76:79]
	v_mfma_f32_16x16x32_bf16 v[72:75], v[178:181], v[210:213], v[72:75]
	v_mfma_f32_16x16x32_bf16 v[116:119], v[214:217], v[182:185], 0
	v_mfma_f32_16x16x32_bf16 v[112:115], v[222:225], v[182:185], 0
	v_mfma_f32_16x16x32_bf16 v[100:103], v[214:217], v[190:193], 0
	v_mfma_f32_16x16x32_bf16 v[96:99], v[222:225], v[190:193], 0
	v_mfma_f32_16x16x32_bf16 v[84:87], v[214:217], v[198:201], 0
	v_mfma_f32_16x16x32_bf16 v[80:83], v[222:225], v[198:201], 0
	v_mfma_f32_16x16x32_bf16 v[68:71], v[214:217], v[206:209], 0
	v_mfma_f32_16x16x32_bf16 v[64:67], v[222:225], v[206:209], 0
	v_mfma_f32_16x16x32_bf16 v[116:119], v[218:221], v[186:189], v[116:119]
	v_mfma_f32_16x16x32_bf16 v[112:115], v[226:229], v[186:189], v[112:115]
	v_mfma_f32_16x16x32_bf16 v[100:103], v[218:221], v[194:197], v[100:103]
	v_mfma_f32_16x16x32_bf16 v[96:99], v[226:229], v[194:197], v[96:99]
	v_mfma_f32_16x16x32_bf16 v[84:87], v[218:221], v[202:205], v[84:87]
	v_mfma_f32_16x16x32_bf16 v[80:83], v[226:229], v[202:205], v[80:83]
	v_mfma_f32_16x16x32_bf16 v[68:71], v[218:221], v[210:213], v[68:71]
	v_mfma_f32_16x16x32_bf16 v[64:67], v[226:229], v[210:213], v[64:67]
	s_setprio 0
	s_barrier
	s_mov_b32 m0, s37
	s_nop 0
	global_load_lds_dwordx4 v130, s[20:21]
	s_mov_b32 m0, s40
	s_nop 0
	global_load_lds_dwordx4 v128, s[20:21]
	s_mov_b32 m0, s34
	ds_read_b128 v[182:185], v145 offset:16384
	ds_read_b128 v[186:189], v145 offset:17408
	ds_read_b128 v[190:193], v145 offset:18432
	ds_read_b128 v[194:197], v145 offset:19456
	ds_read_b128 v[198:201], v145 offset:20480
	ds_read_b128 v[202:205], v145 offset:21504
	ds_read_b128 v[206:209], v145 offset:22528
	ds_read_b128 v[210:213], v145 offset:23552
	global_load_lds_dwordx4 v130, s[28:29]
	s_mov_b32 m0, s41
	s_nop 0
	global_load_lds_dwordx4 v128, s[28:29]
	s_waitcnt vmcnt(6)
	s_waitcnt lgkmcnt(0)
	s_barrier
	s_setprio 1
	v_mfma_f32_16x16x32_bf16 v[60:63], v[140:143], v[182:185], 0
	v_mfma_f32_16x16x32_bf16 v[56:59], v[174:177], v[182:185], 0
	v_mfma_f32_16x16x32_bf16 v[44:47], v[140:143], v[190:193], 0
	v_mfma_f32_16x16x32_bf16 v[40:43], v[174:177], v[190:193], 0
	v_mfma_f32_16x16x32_bf16 v[28:31], v[140:143], v[198:201], 0
	v_mfma_f32_16x16x32_bf16 v[24:27], v[174:177], v[198:201], 0
	v_mfma_f32_16x16x32_bf16 v[12:15], v[140:143], v[206:209], 0
	v_mfma_f32_16x16x32_bf16 v[8:11], v[174:177], v[206:209], 0
	v_mfma_f32_16x16x32_bf16 v[60:63], v[170:173], v[186:189], v[60:63]
	v_mfma_f32_16x16x32_bf16 v[56:59], v[178:181], v[186:189], v[56:59]
	v_mfma_f32_16x16x32_bf16 v[44:47], v[170:173], v[194:197], v[44:47]
	v_mfma_f32_16x16x32_bf16 v[40:43], v[178:181], v[194:197], v[40:43]
	v_mfma_f32_16x16x32_bf16 v[28:31], v[170:173], v[202:205], v[28:31]
	v_mfma_f32_16x16x32_bf16 v[24:27], v[178:181], v[202:205], v[24:27]
	v_mfma_f32_16x16x32_bf16 v[12:15], v[170:173], v[210:213], v[12:15]
	v_mfma_f32_16x16x32_bf16 v[8:11], v[178:181], v[210:213], v[8:11]
	v_mfma_f32_16x16x32_bf16 v[52:55], v[214:217], v[182:185], 0
	v_mfma_f32_16x16x32_bf16 v[48:51], v[222:225], v[182:185], 0
	v_mfma_f32_16x16x32_bf16 v[36:39], v[214:217], v[190:193], 0
	v_mfma_f32_16x16x32_bf16 v[32:35], v[222:225], v[190:193], 0
	v_mfma_f32_16x16x32_bf16 v[20:23], v[214:217], v[198:201], 0
	v_mfma_f32_16x16x32_bf16 v[16:19], v[222:225], v[198:201], 0
	v_mfma_f32_16x16x32_bf16 v[4:7], v[214:217], v[206:209], 0
	v_mfma_f32_16x16x32_bf16 v[0:3], v[222:225], v[206:209], 0
	v_mfma_f32_16x16x32_bf16 v[52:55], v[218:221], v[186:189], v[52:55]
	v_mfma_f32_16x16x32_bf16 v[48:51], v[226:229], v[186:189], v[48:51]
	v_mfma_f32_16x16x32_bf16 v[36:39], v[218:221], v[194:197], v[36:39]
	v_mfma_f32_16x16x32_bf16 v[32:35], v[226:229], v[194:197], v[32:35]
	v_mfma_f32_16x16x32_bf16 v[20:23], v[218:221], v[202:205], v[20:23]
	v_mfma_f32_16x16x32_bf16 v[16:19], v[226:229], v[202:205], v[16:19]
	v_mfma_f32_16x16x32_bf16 v[4:7], v[218:221], v[210:213], v[4:7]
	v_mfma_f32_16x16x32_bf16 v[0:3], v[226:229], v[210:213], v[0:3]
	s_setprio 0
	s_barrier
	s_branch .Lzp11_mid
; #define PG8_STAGE(bufoff, gbase, voff) do { _Pragma("unroll") for (int _i = 0; _i < 2; ++_i) \
;         __builtin_amdgcn_global_load_lds((const unsigned*)((const char*)(gbase) + (voff)[_i]), (PG8_LAS unsigned*)(lds + (bufoff) + ldsw + _i * 8192), 16, 0, 0); } while (0)
; #define PG8_LDA(dst, b, h) do { _Pragma("unroll") for (int m = 0; m < 4; ++m) _Pragma("unroll") for (int k = 0; k < 2; ++k) dst[m][k] = *(const PG8_LAS bf16x8*)(lds + PG8_SA(b, h) + aoff + m * 2048 + k * 1024); } while (0)
; #define PG8_LDB(dst, b, h) do { _Pragma("unroll") for (int n = 0; n < 2; ++n) _Pragma("unroll") for (int k = 0; k < 2; ++k) dst[n][k] = *(const PG8_LAS bf16x8*)(lds + PG8_SB(b, h) + boff + n * 2048 + k * 1024); } while (0)
; #define PG8_MMA(ai, bj, At, Bt) do { __builtin_amdgcn_s_setprio(1); _Pragma("unroll") for (int m = 0; m < 4; ++m) _Pragma("unroll") for (int n = 0; n < 2; ++n) _Pragma("unroll") for (int k = 0; k < 2; ++k) \
;         acc[ai][bj][m][n] = __builtin_amdgcn_mfma_f32_16x16x32_bf16(Bt[n][k], At[m][k], acc[ai][bj][m][n], 0, 0, 0); __builtin_amdgcn_s_setprio(0); } while (0)
; #define PG8_BAR __builtin_amdgcn_s_barrier()
; template <class Epi, class Sched, bool STAMP = false>
; __device__ __forceinline__ void gemm_phase(PG8_LAS unsigned char* lds, const Gemm g, const Sched& S, const Epi& E, unsigned long long* stamps) {
;     ...
;         for (int t = 0; t < nt; t += 2) {
;             const bool last = (t == nt - 2);
;             const char* a1 = cA + (size_t)(t + 1) * kstep;
;             const char* a2 = last ? nA : cA + (size_t)(t + 2) * kstep; const char* b2 = last ? nB : cB + (size_t)(t + 2) * kstep;
;             const char* a3 = a2 + kstep; const char* b3 = b2 + kstep;
;             if (last && has_next) S.a_ready(nxt);
;             PG8_LDB(B0, 0, 0); PG8_SCHED; PG8_LDA(At, 0, 0); PG8_STAGE(PG8_SA(1, 1), a1 + hstep, voffA);
;             PG8_WAIT_L(8); PG8_BAR; PG8_WAIT_L(0); PG8_MMA(0, 0, At, B0); PG8_BAR; PG8_SCHED;
;             PG8_LDB(B1, 0, 1); PG8_STAGE(PG8_SB(0, 0), b2, voffB);
;             PG8_BAR; PG8_WAIT_L(0); PG8_MMA(0, 1, At, B1); PG8_BAR;
;             PG8_LDA(At, 0, 1); PG8_STAGE(PG8_SA(0, 0), a2, voffA);
;             PG8_BAR; PG8_WAIT_L(0); PG8_MMA(1, 0, At, B0); PG8_BAR; PG8_SCHED;
;             PG8_STAGE(PG8_SB(0, 1), b2 + hstep, voffB);
;             PG8_WAIT_V(6); PG8_BAR; PG8_MMA(1, 1, At, B1); PG8_BAR;
.LBB0_727:
	s_add_u32 s100, s62, 0x43f80
	s_addc_u32 s101, s63, 0
	s_mov_b32 m0, s52
	s_nop 0
	global_load_lds_dwordx4 v130, s[100:101]
	s_mov_b32 m0, s53
	s_nop 0
	global_load_lds_dwordx4 v128, s[100:101]
	ds_read_b128 v[140:143], v147
	ds_read_b128 v[170:173], v148
	ds_read_b128 v[174:177], v149
	ds_read_b128 v[178:181], v150
	s_add_u32 s18, s16, 0x100
	s_addc_u32 s19, s17, 0
	s_cmp_eq_u32 s10, 12
	s_cselect_b32 s29, s5, s19
	s_cselect_b32 s28, s4, s18
	s_cselect_b32 s21, s1, s63
	s_cselect_b32 s20, s0, s62
	s_mov_b32 m0, s55
	ds_read_b128 v[182:185], v145
	ds_read_b128 v[186:189], v145 offset:1024
	ds_read_b128 v[190:193], v145 offset:2048
	ds_read_b128 v[194:197], v145 offset:3072
	ds_read_b128 v[198:201], v145 offset:4096
	ds_read_b128 v[202:205], v145 offset:5120
	ds_read_b128 v[206:209], v145 offset:6144
	ds_read_b128 v[210:213], v145 offset:7168
	global_load_lds_dwordx4 v132, s[16:17]
	s_mov_b32 m0, s56
	s_nop 0
	global_load_lds_dwordx4 v134, s[16:17]
	ds_read_b128 v[214:217], v151
	ds_read_b128 v[218:221], v152
	ds_read_b128 v[222:225], v153
	ds_read_b128 v[226:229], v154
	s_waitcnt vmcnt(8)
	s_waitcnt lgkmcnt(0)
	s_barrier
	s_setprio 1
	v_mfma_f32_16x16x32_bf16 v[124:127], v[140:143], v[182:185], v[124:127]
	v_mfma_f32_16x16x32_bf16 v[120:123], v[174:177], v[182:185], v[120:123]
	v_mfma_f32_16x16x32_bf16 v[108:111], v[140:143], v[190:193], v[108:111]
	v_mfma_f32_16x16x32_bf16 v[104:107], v[174:177], v[190:193], v[104:107]
	v_mfma_f32_16x16x32_bf16 v[92:95], v[140:143], v[198:201], v[92:95]
	v_mfma_f32_16x16x32_bf16 v[88:91], v[174:177], v[198:201], v[88:91]
	v_mfma_f32_16x16x32_bf16 v[76:79], v[140:143], v[206:209], v[76:79]
	v_mfma_f32_16x16x32_bf16 v[72:75], v[174:177], v[206:209], v[72:75]
	v_mfma_f32_16x16x32_bf16 v[124:127], v[170:173], v[186:189], v[124:127]
	v_mfma_f32_16x16x32_bf16 v[120:123], v[178:181], v[186:189], v[120:123]
	v_mfma_f32_16x16x32_bf16 v[108:111], v[170:173], v[194:197], v[108:111]
	v_mfma_f32_16x16x32_bf16 v[104:107], v[178:181], v[194:197], v[104:107]
	v_mfma_f32_16x16x32_bf16 v[92:95], v[170:173], v[202:205], v[92:95]
	v_mfma_f32_16x16x32_bf16 v[88:91], v[178:181], v[202:205], v[88:91]
	v_mfma_f32_16x16x32_bf16 v[76:79], v[170:173], v[210:213], v[76:79]
	v_mfma_f32_16x16x32_bf16 v[72:75], v[178:181], v[210:213], v[72:75]
	v_mfma_f32_16x16x32_bf16 v[116:119], v[214:217], v[182:185], v[116:119]
	v_mfma_f32_16x16x32_bf16 v[112:115], v[222:225], v[182:185], v[112:115]
	v_mfma_f32_16x16x32_bf16 v[100:103], v[214:217], v[190:193], v[100:103]
	v_mfma_f32_16x16x32_bf16 v[96:99], v[222:225], v[190:193], v[96:99]
	v_mfma_f32_16x16x32_bf16 v[84:87], v[214:217], v[198:201], v[84:87]
	v_mfma_f32_16x16x32_bf16 v[80:83], v[222:225], v[198:201], v[80:83]
	v_mfma_f32_16x16x32_bf16 v[68:71], v[214:217], v[206:209], v[68:71]
	v_mfma_f32_16x16x32_bf16 v[64:67], v[222:225], v[206:209], v[64:67]
	v_mfma_f32_16x16x32_bf16 v[116:119], v[218:221], v[186:189], v[116:119]
	v_mfma_f32_16x16x32_bf16 v[112:115], v[226:229], v[186:189], v[112:115]
	v_mfma_f32_16x16x32_bf16 v[100:103], v[218:221], v[194:197], v[100:103]
	v_mfma_f32_16x16x32_bf16 v[96:99], v[226:229], v[194:197], v[96:99]
	v_mfma_f32_16x16x32_bf16 v[84:87], v[218:221], v[202:205], v[84:87]
	v_mfma_f32_16x16x32_bf16 v[80:83], v[226:229], v[202:205], v[80:83]
	v_mfma_f32_16x16x32_bf16 v[68:71], v[218:221], v[210:213], v[68:71]
	v_mfma_f32_16x16x32_bf16 v[64:67], v[226:229], v[210:213], v[64:67]
	s_setprio 0
	s_barrier
	s_mov_b32 m0, s37
	s_nop 0
	global_load_lds_dwordx4 v130, s[20:21]
	s_mov_b32 m0, s40
	s_nop 0
	global_load_lds_dwordx4 v128, s[20:21]
	s_mov_b32 m0, s34
	ds_read_b128 v[182:185], v145 offset:16384
	ds_read_b128 v[186:189], v145 offset:17408
	ds_read_b128 v[190:193], v145 offset:18432
	ds_read_b128 v[194:197], v145 offset:19456
	ds_read_b128 v[198:201], v145 offset:20480
	ds_read_b128 v[202:205], v145 offset:21504
	ds_read_b128 v[206:209], v145 offset:22528
	ds_read_b128 v[210:213], v145 offset:23552
	global_load_lds_dwordx4 v130, s[28:29]
	s_mov_b32 m0, s41
	s_nop 0
	global_load_lds_dwordx4 v128, s[28:29]
	s_waitcnt vmcnt(6)
	s_waitcnt lgkmcnt(0)
	s_barrier
	s_setprio 1
	v_mfma_f32_16x16x32_bf16 v[60:63], v[140:143], v[182:185], v[60:63]
	v_mfma_f32_16x16x32_bf16 v[56:59], v[174:177], v[182:185], v[56:59]
	v_mfma_f32_16x16x32_bf16 v[44:47], v[140:143], v[190:193], v[44:47]
	v_mfma_f32_16x16x32_bf16 v[40:43], v[174:177], v[190:193], v[40:43]
	v_mfma_f32_16x16x32_bf16 v[28:31], v[140:143], v[198:201], v[28:31]
	v_mfma_f32_16x16x32_bf16 v[24:27], v[174:177], v[198:201], v[24:27]
	v_mfma_f32_16x16x32_bf16 v[12:15], v[140:143], v[206:209], v[12:15]
	v_mfma_f32_16x16x32_bf16 v[8:11], v[174:177], v[206:209], v[8:11]
	v_mfma_f32_16x16x32_bf16 v[60:63], v[170:173], v[186:189], v[60:63]
	v_mfma_f32_16x16x32_bf16 v[56:59], v[178:181], v[186:189], v[56:59]
	v_mfma_f32_16x16x32_bf16 v[44:47], v[170:173], v[194:197], v[44:47]
	v_mfma_f32_16x16x32_bf16 v[40:43], v[178:181], v[194:197], v[40:43]
	v_mfma_f32_16x16x32_bf16 v[28:31], v[170:173], v[202:205], v[28:31]
	v_mfma_f32_16x16x32_bf16 v[24:27], v[178:181], v[202:205], v[24:27]
	v_mfma_f32_16x16x32_bf16 v[12:15], v[170:173], v[210:213], v[12:15]
	v_mfma_f32_16x16x32_bf16 v[8:11], v[178:181], v[210:213], v[8:11]
	v_mfma_f32_16x16x32_bf16 v[52:55], v[214:217], v[182:185], v[52:55]
	v_mfma_f32_16x16x32_bf16 v[48:51], v[222:225], v[182:185], v[48:51]
	v_mfma_f32_16x16x32_bf16 v[36:39], v[214:217], v[190:193], v[36:39]
	v_mfma_f32_16x16x32_bf16 v[32:35], v[222:225], v[190:193], v[32:35]
	v_mfma_f32_16x16x32_bf16 v[20:23], v[214:217], v[198:201], v[20:23]
	v_mfma_f32_16x16x32_bf16 v[16:19], v[222:225], v[198:201], v[16:19]
	v_mfma_f32_16x16x32_bf16 v[4:7], v[214:217], v[206:209], v[4:7]
	v_mfma_f32_16x16x32_bf16 v[0:3], v[222:225], v[206:209], v[0:3]
	v_mfma_f32_16x16x32_bf16 v[52:55], v[218:221], v[186:189], v[52:55]
	v_mfma_f32_16x16x32_bf16 v[48:51], v[226:229], v[186:189], v[48:51]
	v_mfma_f32_16x16x32_bf16 v[36:39], v[218:221], v[194:197], v[36:39]
	v_mfma_f32_16x16x32_bf16 v[32:35], v[226:229], v[194:197], v[32:35]
	v_mfma_f32_16x16x32_bf16 v[20:23], v[218:221], v[202:205], v[20:23]
	v_mfma_f32_16x16x32_bf16 v[16:19], v[226:229], v[202:205], v[16:19]
	v_mfma_f32_16x16x32_bf16 v[4:7], v[218:221], v[210:213], v[4:7]
	v_mfma_f32_16x16x32_bf16 v[0:3], v[226:229], v[210:213], v[0:3]
	s_setprio 0
	s_barrier
; #define PG8_STAGE(bufoff, gbase, voff) do { _Pragma("unroll") for (int _i = 0; _i < 2; ++_i) \
;         __builtin_amdgcn_global_load_lds((const unsigned*)((const char*)(gbase) + (voff)[_i]), (PG8_LAS unsigned*)(lds + (bufoff) + ldsw + _i * 8192), 16, 0, 0); } while (0)
; #define PG8_LDA(dst, b, h) do { _Pragma("unroll") for (int m = 0; m < 4; ++m) _Pragma("unroll") for (int k = 0; k < 2; ++k) dst[m][k] = *(const PG8_LAS bf16x8*)(lds + PG8_SA(b, h) + aoff + m * 2048 + k * 1024); } while (0)
; #define PG8_LDB(dst, b, h) do { _Pragma("unroll") for (int n = 0; n < 2; ++n) _Pragma("unroll") for (int k = 0; k < 2; ++k) dst[n][k] = *(const PG8_LAS bf16x8*)(lds + PG8_SB(b, h) + boff + n * 2048 + k * 1024); } while (0)
; #define PG8_MMA(ai, bj, At, Bt) do { __builtin_amdgcn_s_setprio(1); _Pragma("unroll") for (int m = 0; m < 4; ++m) _Pragma("unroll") for (int n = 0; n < 2; ++n) _Pragma("unroll") for (int k = 0; k < 2; ++k) \
;         acc[ai][bj][m][n] = __builtin_amdgcn_mfma_f32_16x16x32_bf16(Bt[n][k], At[m][k], acc[ai][bj][m][n], 0, 0, 0); __builtin_amdgcn_s_setprio(0); } while (0)
; #define PG8_WAIT_V(n) asm volatile("s_waitcnt vmcnt(" #n ")" ::: "memory")
; #define PG8_WAIT_L(n) asm volatile("s_waitcnt lgkmcnt(" #n ")" ::: "memory")
; #define PG8_BAR __builtin_amdgcn_s_barrier()
; #define PG8_SCHED __builtin_amdgcn_sched_barrier(0)
; template <class Epi, class Sched, bool STAMP = false>
; __device__ __forceinline__ void gemm_phase(PG8_LAS unsigned char* lds, const Gemm g, const Sched& S, const Epi& E, unsigned long long* stamps) {
;     ...
;             PG8_LDB(B0, 1, 0); PG8_SCHED; PG8_LDA(At, 1, 0); PG8_STAGE(PG8_SA(0, 1), a2 + hstep, voffA);
;             PG8_WAIT_L(8); PG8_BAR; PG8_WAIT_L(0); PG8_MMA(0, 0, At, B0); PG8_BAR; PG8_SCHED;
;             PG8_LDB(B1, 1, 1); PG8_STAGE(PG8_SB(1, 0), b3, voffB);
;             PG8_BAR; PG8_WAIT_L(0); PG8_MMA(0, 1, At, B1); PG8_BAR;
;             PG8_LDA(At, 1, 1); PG8_STAGE(PG8_SA(1, 0), a3, voffA);
;             PG8_BAR; PG8_WAIT_L(0); PG8_MMA(1, 0, At, B0); PG8_BAR; PG8_SCHED;
;             PG8_STAGE(PG8_SB(1, 1), b3 + hstep, voffB);
;             PG8_WAIT_V(6); PG8_BAR; PG8_MMA(1, 1, At, B1); PG8_BAR;
;         }
.Lzp11_mid:
	s_add_u32 s16, s20, 0x44000
	s_addc_u32 s17, s21, 0
	s_mov_b32 m0, s42
	s_nop 0
	global_load_lds_dwordx4 v130, s[16:17]
	s_mov_b32 m0, s43
	s_nop 0
	global_load_lds_dwordx4 v128, s[16:17]
	ds_read_b128 v[140:143], v155
	ds_read_b128 v[170:173], v156
	ds_read_b128 v[174:177], v157
	ds_read_b128 v[178:181], v165
	s_add_u32 s16, s28, 0x44000
	s_addc_u32 s17, s29, 0
	s_mov_b32 m0, s44
	ds_read_b128 v[182:185], v145 offset:32768
	ds_read_b128 v[186:189], v145 offset:33792
	ds_read_b128 v[190:193], v145 offset:34816
	ds_read_b128 v[194:197], v145 offset:35840
	ds_read_b128 v[198:201], v145 offset:36864
	ds_read_b128 v[202:205], v145 offset:37888
	ds_read_b128 v[206:209], v145 offset:38912
	ds_read_b128 v[210:213], v145 offset:39936
	global_load_lds_dwordx4 v130, s[16:17]
	s_mov_b32 m0, s45
	s_nop 0
	global_load_lds_dwordx4 v128, s[16:17]
	ds_read_b128 v[214:217], v166
	ds_read_b128 v[218:221], v167
	ds_read_b128 v[222:225], v168
	ds_read_b128 v[226:229], v169
	s_waitcnt vmcnt(8)
	s_waitcnt lgkmcnt(0)
	s_barrier
	s_setprio 1
	v_mfma_f32_16x16x32_bf16 v[124:127], v[140:143], v[182:185], v[124:127]
	v_mfma_f32_16x16x32_bf16 v[120:123], v[174:177], v[182:185], v[120:123]
	v_mfma_f32_16x16x32_bf16 v[108:111], v[140:143], v[190:193], v[108:111]
	v_mfma_f32_16x16x32_bf16 v[104:107], v[174:177], v[190:193], v[104:107]
	v_mfma_f32_16x16x32_bf16 v[92:95], v[140:143], v[198:201], v[92:95]
	v_mfma_f32_16x16x32_bf16 v[88:91], v[174:177], v[198:201], v[88:91]
	v_mfma_f32_16x16x32_bf16 v[76:79], v[140:143], v[206:209], v[76:79]
	v_mfma_f32_16x16x32_bf16 v[72:75], v[174:177], v[206:209], v[72:75]
	v_mfma_f32_16x16x32_bf16 v[124:127], v[170:173], v[186:189], v[124:127]
	v_mfma_f32_16x16x32_bf16 v[120:123], v[178:181], v[186:189], v[120:123]
	v_mfma_f32_16x16x32_bf16 v[108:111], v[170:173], v[194:197], v[108:111]
	v_mfma_f32_16x16x32_bf16 v[104:107], v[178:181], v[194:197], v[104:107]
	v_mfma_f32_16x16x32_bf16 v[92:95], v[170:173], v[202:205], v[92:95]
	v_mfma_f32_16x16x32_bf16 v[88:91], v[178:181], v[202:205], v[88:91]
	v_mfma_f32_16x16x32_bf16 v[76:79], v[170:173], v[210:213], v[76:79]
	v_mfma_f32_16x16x32_bf16 v[72:75], v[178:181], v[210:213], v[72:75]
	v_mfma_f32_16x16x32_bf16 v[116:119], v[214:217], v[182:185], v[116:119]
	v_mfma_f32_16x16x32_bf16 v[112:115], v[222:225], v[182:185], v[112:115]
	v_mfma_f32_16x16x32_bf16 v[100:103], v[214:217], v[190:193], v[100:103]
	v_mfma_f32_16x16x32_bf16 v[96:99], v[222:225], v[190:193], v[96:99]
	v_mfma_f32_16x16x32_bf16 v[84:87], v[214:217], v[198:201], v[84:87]
	v_mfma_f32_16x16x32_bf16 v[80:83], v[222:225], v[198:201], v[80:83]
	v_mfma_f32_16x16x32_bf16 v[68:71], v[214:217], v[206:209], v[68:71]
	v_mfma_f32_16x16x32_bf16 v[64:67], v[222:225], v[206:209], v[64:67]
	v_mfma_f32_16x16x32_bf16 v[116:119], v[218:221], v[186:189], v[116:119]
	v_mfma_f32_16x16x32_bf16 v[112:115], v[226:229], v[186:189], v[112:115]
	v_mfma_f32_16x16x32_bf16 v[100:103], v[218:221], v[194:197], v[100:103]
	v_mfma_f32_16x16x32_bf16 v[96:99], v[226:229], v[194:197], v[96:99]
	v_mfma_f32_16x16x32_bf16 v[84:87], v[218:221], v[202:205], v[84:87]
	v_mfma_f32_16x16x32_bf16 v[80:83], v[226:229], v[202:205], v[80:83]
	v_mfma_f32_16x16x32_bf16 v[68:71], v[218:221], v[210:213], v[68:71]
	v_mfma_f32_16x16x32_bf16 v[64:67], v[226:229], v[210:213], v[64:67]
	s_setprio 0
	s_barrier
	s_mov_b32 m0, s48
	s_add_u32 s100, s20, 0x80
	s_addc_u32 s101, s21, 0
	global_load_lds_dwordx4 v130, s[100:101]
	s_mov_b32 m0, s49
	s_nop 0
	global_load_lds_dwordx4 v128, s[100:101]
	s_mov_b32 m0, s50
	ds_read_b128 v[182:185], v145 offset:49152
	ds_read_b128 v[186:189], v145 offset:50176
	ds_read_b128 v[190:193], v145 offset:51200
	ds_read_b128 v[194:197], v145 offset:52224
	ds_read_b128 v[198:201], v145 offset:53248
	ds_read_b128 v[202:205], v145 offset:54272
	ds_read_b128 v[206:209], v145 offset:55296
	ds_read_b128 v[210:213], v145 offset:56320
	s_add_u32 s100, s28, 0x80
	s_addc_u32 s101, s29, 0
	global_load_lds_dwordx4 v130, s[100:101]
	s_mov_b32 m0, s51
	s_nop 0
	global_load_lds_dwordx4 v128, s[100:101]
	s_waitcnt vmcnt(6)
	s_waitcnt lgkmcnt(0)
	s_barrier
	s_setprio 1
	v_mfma_f32_16x16x32_bf16 v[60:63], v[140:143], v[182:185], v[60:63]
	v_mfma_f32_16x16x32_bf16 v[56:59], v[174:177], v[182:185], v[56:59]
	v_mfma_f32_16x16x32_bf16 v[44:47], v[140:143], v[190:193], v[44:47]
	v_mfma_f32_16x16x32_bf16 v[40:43], v[174:177], v[190:193], v[40:43]
	v_mfma_f32_16x16x32_bf16 v[28:31], v[140:143], v[198:201], v[28:31]
	v_mfma_f32_16x16x32_bf16 v[24:27], v[174:177], v[198:201], v[24:27]
	v_mfma_f32_16x16x32_bf16 v[12:15], v[140:143], v[206:209], v[12:15]
	v_mfma_f32_16x16x32_bf16 v[8:11], v[174:177], v[206:209], v[8:11]
	v_mfma_f32_16x16x32_bf16 v[60:63], v[170:173], v[186:189], v[60:63]
	v_mfma_f32_16x16x32_bf16 v[56:59], v[178:181], v[186:189], v[56:59]
	v_mfma_f32_16x16x32_bf16 v[44:47], v[170:173], v[194:197], v[44:47]
	v_mfma_f32_16x16x32_bf16 v[40:43], v[178:181], v[194:197], v[40:43]
	v_mfma_f32_16x16x32_bf16 v[28:31], v[170:173], v[202:205], v[28:31]
	v_mfma_f32_16x16x32_bf16 v[24:27], v[178:181], v[202:205], v[24:27]
	v_mfma_f32_16x16x32_bf16 v[12:15], v[170:173], v[210:213], v[12:15]
	v_mfma_f32_16x16x32_bf16 v[8:11], v[178:181], v[210:213], v[8:11]
	v_mfma_f32_16x16x32_bf16 v[52:55], v[214:217], v[182:185], v[52:55]
	v_mfma_f32_16x16x32_bf16 v[48:51], v[222:225], v[182:185], v[48:51]
	v_mfma_f32_16x16x32_bf16 v[36:39], v[214:217], v[190:193], v[36:39]
	v_mfma_f32_16x16x32_bf16 v[32:35], v[222:225], v[190:193], v[32:35]
	v_mfma_f32_16x16x32_bf16 v[20:23], v[214:217], v[198:201], v[20:23]
	v_mfma_f32_16x16x32_bf16 v[16:19], v[222:225], v[198:201], v[16:19]
	v_mfma_f32_16x16x32_bf16 v[4:7], v[214:217], v[206:209], v[4:7]
	v_mfma_f32_16x16x32_bf16 v[0:3], v[222:225], v[206:209], v[0:3]
	v_mfma_f32_16x16x32_bf16 v[52:55], v[218:221], v[186:189], v[52:55]
	v_mfma_f32_16x16x32_bf16 v[48:51], v[226:229], v[186:189], v[48:51]
	v_mfma_f32_16x16x32_bf16 v[36:39], v[218:221], v[194:197], v[36:39]
	v_mfma_f32_16x16x32_bf16 v[32:35], v[226:229], v[194:197], v[32:35]
	v_mfma_f32_16x16x32_bf16 v[20:23], v[218:221], v[202:205], v[20:23]
	v_mfma_f32_16x16x32_bf16 v[16:19], v[226:229], v[202:205], v[16:19]
	v_mfma_f32_16x16x32_bf16 v[4:7], v[218:221], v[210:213], v[4:7]
	v_mfma_f32_16x16x32_bf16 v[0:3], v[226:229], v[210:213], v[0:3]
	s_setprio 0
	s_add_i32 s10, s10, 2
	s_add_u32 s62, s62, 0x100
	s_addc_u32 s63, s63, 0
	s_cmp_gt_u32 s10, 13
	s_mov_b64 s[16:17], s[18:19]
	s_barrier
; DI float ex2(float x) { return __builtin_amdgcn_exp2f(x); }
;     DI void operator()(const f32x4 (&acc)[2][2][4][2], const Unit& u, int wr, int wc, int fr, int fq) const {
;         const int row0 = u.pm * BM + wr * 64 + fr, hcol0 = ((u.pn * BM + wc * 32) >> 1) + 4 * fq;
; #pragma unroll
;         for (int ai = 0; ai < 2; ++ai)
; #pragma unroll
;             for (int m = 0; m < 4; ++m) { u16* rowp = O + (size_t)(row0 + ai * HALF + m * 16) * ldc + hcol0;
; #pragma unroll
;                 for (int bj = 0; bj < 2; ++bj) { const f32x4 g = acc[ai][bj][m][0], up = acc[ai][bj][m][1]; float r[4];
; #pragma unroll
;                     for (int j = 0; j < 4; ++j) r[j] = g[j] * up[j] * __builtin_amdgcn_rcpf(1.f + ex2(-LOG2E * g[j]));
;                     uint2 w = {pack2(r[0], r[1]), pack2(r[2], r[3])}; *(uint2*)(rowp + bj * (HALF / 2)) = w; } }
	s_cbranch_scc0 .LBB0_727
	v_exp_f32_e64 v171, -v124
	v_exp_f32_e64 v175, -v125
	s_lshl_b32 s10, s61, 8
	v_add_f32_e32 v171, 1.0, v171
	v_rcp_f32_e32 v174, v171
	v_add_f32_e32 v171, 1.0, v175
	v_exp_f32_e64 v176, -v126
	v_exp_f32_e64 v177, -v127
	v_rcp_f32_e32 v175, v171
	v_add_f32_e32 v171, 1.0, v176
	v_rcp_f32_e32 v176, v171
	v_add_f32_e32 v171, 1.0, v177
	v_rcp_f32_e32 v177, v171
	v_pk_mul_f32 v[122:123], v[126:127], v[122:123]
	v_pk_mul_f32 v[120:121], v[124:125], v[120:121]
	s_or_b32 s10, s10, s47
	v_pk_mul_f32 v[120:121], v[120:121], v[174:175]
	v_pk_mul_f32 v[122:123], v[122:123], v[176:177]
	s_ashr_i32 s10, s10, 1
	v_cvt_pk_bf16_f32 v120, v120, v121
	v_cvt_pk_bf16_f32 v121, v122, v123
	v_or_b32_e32 v140, s10, v146
	v_exp_f32_e64 v122, -v116
	v_exp_f32_e64 v123, -v117
	v_lshl_add_u32 v170, s60, 8, v144
	v_ashrrev_i32_e32 v141, 31, v140
	v_mov_b64_e32 v[142:143], s[12:13]
	v_mad_i64_i32 v[172:173], s[16:17], v170, s57, v[142:143]
	v_lshlrev_b64 v[140:141], 1, v[140:141]
	v_lshl_add_u64 v[172:173], v[172:173], 0, v[140:141]
	global_store_dwordx2 v[172:173], v[120:121], off
	v_add_f32_e32 v120, 1.0, v122
	v_add_f32_e32 v121, 1.0, v123
	v_exp_f32_e64 v122, -v118
	v_exp_f32_e64 v123, -v119
	v_rcp_f32_e32 v120, v120
	v_rcp_f32_e32 v121, v121
	v_add_f32_e32 v122, 1.0, v122
	v_add_f32_e32 v123, 1.0, v123
	v_rcp_f32_e32 v122, v122
	v_rcp_f32_e32 v123, v123
	v_pk_mul_f32 v[114:115], v[118:119], v[114:115]
	v_pk_mul_f32 v[112:113], v[116:117], v[112:113]
	v_pk_mul_f32 v[112:113], v[112:113], v[120:121]
	v_pk_mul_f32 v[114:115], v[114:115], v[122:123]
	v_cvt_pk_bf16_f32 v112, v112, v113
	v_cvt_pk_bf16_f32 v113, v114, v115
	v_exp_f32_e64 v114, -v108
	v_exp_f32_e64 v115, -v109
	v_exp_f32_e64 v116, -v110
	v_exp_f32_e64 v117, -v111
	v_add_f32_e32 v114, 1.0, v114
	v_add_f32_e32 v115, 1.0, v115
	v_add_f32_e32 v116, 1.0, v116
	v_add_f32_e32 v117, 1.0, v117
	v_rcp_f32_e32 v114, v114
	v_rcp_f32_e32 v115, v115
	v_rcp_f32_e32 v116, v116
	v_rcp_f32_e32 v117, v117
	v_pk_mul_f32 v[106:107], v[110:111], v[106:107]
	v_pk_mul_f32 v[104:105], v[108:109], v[104:105]
	global_store_dwordx2 v[172:173], v[112:113], off offset:128
	v_pk_mul_f32 v[104:105], v[104:105], v[114:115]
	v_pk_mul_f32 v[106:107], v[106:107], v[116:117]
	v_cvt_pk_bf16_f32 v104, v104, v105
	v_cvt_pk_bf16_f32 v105, v106, v107
	v_exp_f32_e64 v106, -v100
	v_exp_f32_e64 v107, -v101
	v_or_b32_e32 v112, 16, v170
	v_mad_i64_i32 v[112:113], s[16:17], v112, s57, v[142:143]
	v_lshl_add_u64 v[112:113], v[112:113], 0, v[140:141]
	global_store_dwordx2 v[112:113], v[104:105], off
	v_add_f32_e32 v104, 1.0, v106
	v_add_f32_e32 v105, 1.0, v107
	v_exp_f32_e64 v106, -v102
	v_exp_f32_e64 v107, -v103
	v_rcp_f32_e32 v104, v104
	v_rcp_f32_e32 v105, v105
	v_add_f32_e32 v106, 1.0, v106
	v_add_f32_e32 v107, 1.0, v107
	v_rcp_f32_e32 v106, v106
	v_rcp_f32_e32 v107, v107
	v_pk_mul_f32 v[98:99], v[102:103], v[98:99]
	v_pk_mul_f32 v[96:97], v[100:101], v[96:97]
	v_pk_mul_f32 v[96:97], v[96:97], v[104:105]
	v_pk_mul_f32 v[98:99], v[98:99], v[106:107]
	v_cvt_pk_bf16_f32 v96, v96, v97
	v_cvt_pk_bf16_f32 v97, v98, v99
	v_exp_f32_e64 v98, -v92
	v_exp_f32_e64 v99, -v93
	v_exp_f32_e64 v100, -v94
	v_exp_f32_e64 v101, -v95
	v_add_f32_e32 v98, 1.0, v98
	v_add_f32_e32 v99, 1.0, v99
	v_add_f32_e32 v100, 1.0, v100
	v_add_f32_e32 v101, 1.0, v101
	v_rcp_f32_e32 v98, v98
	v_rcp_f32_e32 v99, v99
	v_rcp_f32_e32 v100, v100
	v_rcp_f32_e32 v101, v101
	v_pk_mul_f32 v[90:91], v[94:95], v[90:91]
	v_pk_mul_f32 v[88:89], v[92:93], v[88:89]
	global_store_dwordx2 v[112:113], v[96:97], off offset:128
	v_pk_mul_f32 v[88:89], v[88:89], v[98:99]
	v_pk_mul_f32 v[90:91], v[90:91], v[100:101]
	v_cvt_pk_bf16_f32 v88, v88, v89
	v_cvt_pk_bf16_f32 v89, v90, v91
	v_exp_f32_e64 v90, -v84
	v_exp_f32_e64 v91, -v85
	v_or_b32_e32 v96, 32, v170
	v_mad_i64_i32 v[96:97], s[16:17], v96, s57, v[142:143]
	v_lshl_add_u64 v[96:97], v[96:97], 0, v[140:141]
	global_store_dwordx2 v[96:97], v[88:89], off
	v_add_f32_e32 v88, 1.0, v90
	v_add_f32_e32 v89, 1.0, v91
	v_exp_f32_e64 v90, -v86
	v_exp_f32_e64 v91, -v87
	v_rcp_f32_e32 v88, v88
	v_rcp_f32_e32 v89, v89
	v_add_f32_e32 v90, 1.0, v90
	v_add_f32_e32 v91, 1.0, v91
	v_rcp_f32_e32 v90, v90
	v_rcp_f32_e32 v91, v91
	v_pk_mul_f32 v[82:83], v[86:87], v[82:83]
	v_pk_mul_f32 v[80:81], v[84:85], v[80:81]
	v_pk_mul_f32 v[80:81], v[80:81], v[88:89]
	v_pk_mul_f32 v[82:83], v[82:83], v[90:91]
	v_cvt_pk_bf16_f32 v80, v80, v81
	v_cvt_pk_bf16_f32 v81, v82, v83
	v_exp_f32_e64 v82, -v76
	v_exp_f32_e64 v83, -v77
	v_exp_f32_e64 v84, -v78
	v_exp_f32_e64 v85, -v79
	v_add_f32_e32 v82, 1.0, v82
	v_add_f32_e32 v83, 1.0, v83
	v_add_f32_e32 v84, 1.0, v84
	v_add_f32_e32 v85, 1.0, v85
	v_rcp_f32_e32 v82, v82
	v_rcp_f32_e32 v83, v83
	v_rcp_f32_e32 v84, v84
	v_rcp_f32_e32 v85, v85
	v_pk_mul_f32 v[74:75], v[78:79], v[74:75]
	v_pk_mul_f32 v[72:73], v[76:77], v[72:73]
	global_store_dwordx2 v[96:97], v[80:81], off offset:128
	v_pk_mul_f32 v[72:73], v[72:73], v[82:83]
	v_pk_mul_f32 v[74:75], v[74:75], v[84:85]
	v_cvt_pk_bf16_f32 v72, v72, v73
	v_cvt_pk_bf16_f32 v73, v74, v75
	v_exp_f32_e64 v74, -v68
	v_exp_f32_e64 v75, -v69
	v_or_b32_e32 v80, 48, v170
	v_mad_i64_i32 v[80:81], s[16:17], v80, s57, v[142:143]
	v_lshl_add_u64 v[80:81], v[80:81], 0, v[140:141]
	global_store_dwordx2 v[80:81], v[72:73], off
	v_add_f32_e32 v72, 1.0, v74
	v_add_f32_e32 v73, 1.0, v75
	v_exp_f32_e64 v74, -v70
	v_exp_f32_e64 v75, -v71
	v_rcp_f32_e32 v72, v72
	v_rcp_f32_e32 v73, v73
	v_add_f32_e32 v74, 1.0, v74
	v_add_f32_e32 v75, 1.0, v75
	v_rcp_f32_e32 v74, v74
	v_rcp_f32_e32 v75, v75
	v_pk_mul_f32 v[66:67], v[70:71], v[66:67]
	v_pk_mul_f32 v[64:65], v[68:69], v[64:65]
; DI float ex2(float x) { return __builtin_amdgcn_exp2f(x); }
;     DI void operator()(const f32x4 (&acc)[2][2][4][2], const Unit& u, int wr, int wc, int fr, int fq) const {
;         const int row0 = u.pm * BM + wr * 64 + fr, hcol0 = ((u.pn * BM + wc * 32) >> 1) + 4 * fq;
; #pragma unroll
;         for (int ai = 0; ai < 2; ++ai)
; #pragma unroll
;             for (int m = 0; m < 4; ++m) { u16* rowp = O + (size_t)(row0 + ai * HALF + m * 16) * ldc + hcol0;
; #pragma unroll
;                 for (int bj = 0; bj < 2; ++bj) { const f32x4 g = acc[ai][bj][m][0], up = acc[ai][bj][m][1]; float r[4];
; #pragma unroll
;                     for (int j = 0; j < 4; ++j) r[j] = g[j] * up[j] * __builtin_amdgcn_rcpf(1.f + ex2(-LOG2E * g[j]));
;                     uint2 w = {pack2(r[0], r[1]), pack2(r[2], r[3])}; *(uint2*)(rowp + bj * (HALF / 2)) = w; } }
	v_pk_mul_f32 v[64:65], v[64:65], v[72:73]
	v_pk_mul_f32 v[66:67], v[66:67], v[74:75]
	v_cvt_pk_bf16_f32 v64, v64, v65
	v_cvt_pk_bf16_f32 v65, v66, v67
	v_exp_f32_e64 v66, -v60
	v_exp_f32_e64 v67, -v61
	v_exp_f32_e64 v68, -v62
	v_exp_f32_e64 v69, -v63
	v_add_f32_e32 v66, 1.0, v66
	v_add_f32_e32 v67, 1.0, v67
	v_add_f32_e32 v68, 1.0, v68
	v_add_f32_e32 v69, 1.0, v69
	v_rcp_f32_e32 v66, v66
	v_rcp_f32_e32 v67, v67
	v_rcp_f32_e32 v68, v68
	v_rcp_f32_e32 v69, v69
	v_pk_mul_f32 v[58:59], v[62:63], v[58:59]
	v_pk_mul_f32 v[56:57], v[60:61], v[56:57]
	global_store_dwordx2 v[80:81], v[64:65], off offset:128
	v_pk_mul_f32 v[56:57], v[56:57], v[66:67]
	v_pk_mul_f32 v[58:59], v[58:59], v[68:69]
	v_cvt_pk_bf16_f32 v56, v56, v57
	v_cvt_pk_bf16_f32 v57, v58, v59
	v_exp_f32_e64 v58, -v52
	v_exp_f32_e64 v59, -v53
	v_add_u32_e32 v64, 0x80, v170
	v_mad_i64_i32 v[64:65], s[16:17], v64, s57, v[142:143]
	v_lshl_add_u64 v[64:65], v[64:65], 0, v[140:141]
	global_store_dwordx2 v[64:65], v[56:57], off
	v_add_f32_e32 v56, 1.0, v58
	v_add_f32_e32 v57, 1.0, v59
	v_exp_f32_e64 v58, -v54
	v_exp_f32_e64 v59, -v55
	v_rcp_f32_e32 v56, v56
	v_rcp_f32_e32 v57, v57
	v_add_f32_e32 v58, 1.0, v58
	v_add_f32_e32 v59, 1.0, v59
	v_rcp_f32_e32 v58, v58
	v_rcp_f32_e32 v59, v59
	v_pk_mul_f32 v[50:51], v[54:55], v[50:51]
	v_pk_mul_f32 v[48:49], v[52:53], v[48:49]
	v_pk_mul_f32 v[48:49], v[48:49], v[56:57]
	v_pk_mul_f32 v[50:51], v[50:51], v[58:59]
	v_cvt_pk_bf16_f32 v48, v48, v49
	v_cvt_pk_bf16_f32 v49, v50, v51
	v_exp_f32_e64 v50, -v44
	v_exp_f32_e64 v51, -v45
	v_exp_f32_e64 v52, -v46
	v_exp_f32_e64 v53, -v47
	v_add_f32_e32 v50, 1.0, v50
	v_add_f32_e32 v51, 1.0, v51
	v_add_f32_e32 v52, 1.0, v52
	v_add_f32_e32 v53, 1.0, v53
	v_rcp_f32_e32 v50, v50
	v_rcp_f32_e32 v51, v51
	v_rcp_f32_e32 v52, v52
	v_rcp_f32_e32 v53, v53
	v_pk_mul_f32 v[42:43], v[46:47], v[42:43]
	v_pk_mul_f32 v[40:41], v[44:45], v[40:41]
	global_store_dwordx2 v[64:65], v[48:49], off offset:128
	v_pk_mul_f32 v[40:41], v[40:41], v[50:51]
	v_pk_mul_f32 v[42:43], v[42:43], v[52:53]
	v_cvt_pk_bf16_f32 v40, v40, v41
	v_cvt_pk_bf16_f32 v41, v42, v43
	v_exp_f32_e64 v42, -v36
	v_exp_f32_e64 v43, -v37
	v_add_u32_e32 v48, 0x90, v170
	v_mad_i64_i32 v[48:49], s[16:17], v48, s57, v[142:143]
	v_lshl_add_u64 v[48:49], v[48:49], 0, v[140:141]
	global_store_dwordx2 v[48:49], v[40:41], off
	v_add_f32_e32 v40, 1.0, v42
	v_add_f32_e32 v41, 1.0, v43
	v_exp_f32_e64 v42, -v38
	v_exp_f32_e64 v43, -v39
	v_rcp_f32_e32 v40, v40
	v_rcp_f32_e32 v41, v41
	v_add_f32_e32 v42, 1.0, v42
	v_add_f32_e32 v43, 1.0, v43
	v_rcp_f32_e32 v42, v42
	v_rcp_f32_e32 v43, v43
	v_pk_mul_f32 v[34:35], v[38:39], v[34:35]
	v_pk_mul_f32 v[32:33], v[36:37], v[32:33]
	v_pk_mul_f32 v[32:33], v[32:33], v[40:41]
	v_pk_mul_f32 v[34:35], v[34:35], v[42:43]
	v_cvt_pk_bf16_f32 v32, v32, v33
	v_cvt_pk_bf16_f32 v33, v34, v35
	v_exp_f32_e64 v34, -v28
	v_exp_f32_e64 v35, -v29
	v_exp_f32_e64 v36, -v30
	v_exp_f32_e64 v37, -v31
	v_add_f32_e32 v34, 1.0, v34
	v_add_f32_e32 v35, 1.0, v35
	v_add_f32_e32 v36, 1.0, v36
	v_add_f32_e32 v37, 1.0, v37
	v_rcp_f32_e32 v34, v34
	v_rcp_f32_e32 v35, v35
	v_rcp_f32_e32 v36, v36
	v_rcp_f32_e32 v37, v37
	v_pk_mul_f32 v[26:27], v[30:31], v[26:27]
	v_pk_mul_f32 v[24:25], v[28:29], v[24:25]
	global_store_dwordx2 v[48:49], v[32:33], off offset:128
	v_pk_mul_f32 v[24:25], v[24:25], v[34:35]
	v_pk_mul_f32 v[26:27], v[26:27], v[36:37]
	v_cvt_pk_bf16_f32 v24, v24, v25
	v_cvt_pk_bf16_f32 v25, v26, v27
	v_exp_f32_e64 v26, -v20
	v_exp_f32_e64 v27, -v21
	v_add_u32_e32 v32, 0xa0, v170
	v_mad_i64_i32 v[32:33], s[16:17], v32, s57, v[142:143]
	v_lshl_add_u64 v[32:33], v[32:33], 0, v[140:141]
	global_store_dwordx2 v[32:33], v[24:25], off
	v_add_f32_e32 v24, 1.0, v26
	v_add_f32_e32 v25, 1.0, v27
	v_exp_f32_e64 v26, -v22
	v_exp_f32_e64 v27, -v23
	v_rcp_f32_e32 v24, v24
	v_rcp_f32_e32 v25, v25
	v_add_f32_e32 v26, 1.0, v26
	v_add_f32_e32 v27, 1.0, v27
	v_rcp_f32_e32 v26, v26
	v_rcp_f32_e32 v27, v27
	v_pk_mul_f32 v[18:19], v[22:23], v[18:19]
	v_pk_mul_f32 v[16:17], v[20:21], v[16:17]
	v_pk_mul_f32 v[16:17], v[16:17], v[24:25]
	v_pk_mul_f32 v[18:19], v[18:19], v[26:27]
	v_cvt_pk_bf16_f32 v16, v16, v17
	v_cvt_pk_bf16_f32 v17, v18, v19
	v_exp_f32_e64 v18, -v12
	v_exp_f32_e64 v19, -v13
	v_exp_f32_e64 v20, -v14
	v_exp_f32_e64 v21, -v15
	v_add_f32_e32 v18, 1.0, v18
	v_add_f32_e32 v19, 1.0, v19
	v_add_f32_e32 v20, 1.0, v20
	v_add_f32_e32 v21, 1.0, v21
	v_rcp_f32_e32 v18, v18
	v_rcp_f32_e32 v19, v19
	v_rcp_f32_e32 v20, v20
	v_rcp_f32_e32 v21, v21
	v_pk_mul_f32 v[10:11], v[14:15], v[10:11]
	v_pk_mul_f32 v[8:9], v[12:13], v[8:9]
	global_store_dwordx2 v[32:33], v[16:17], off offset:128
	v_pk_mul_f32 v[8:9], v[8:9], v[18:19]
	v_pk_mul_f32 v[10:11], v[10:11], v[20:21]
	v_cvt_pk_bf16_f32 v8, v8, v9
	v_cvt_pk_bf16_f32 v9, v10, v11
	v_exp_f32_e64 v10, -v4
	v_exp_f32_e64 v11, -v5
	v_add_u32_e32 v16, 0xb0, v170
	v_mad_i64_i32 v[16:17], s[16:17], v16, s57, v[142:143]
	v_lshl_add_u64 v[16:17], v[16:17], 0, v[140:141]
	global_store_dwordx2 v[16:17], v[8:9], off
	v_add_f32_e32 v8, 1.0, v10
	v_add_f32_e32 v9, 1.0, v11
	v_exp_f32_e64 v10, -v6
	v_exp_f32_e64 v11, -v7
	v_rcp_f32_e32 v8, v8
	v_rcp_f32_e32 v9, v9
	v_add_f32_e32 v10, 1.0, v10
	v_add_f32_e32 v11, 1.0, v11
	v_rcp_f32_e32 v10, v10
	v_rcp_f32_e32 v11, v11
	v_pk_mul_f32 v[2:3], v[6:7], v[2:3]
	v_pk_mul_f32 v[0:1], v[4:5], v[0:1]
	s_and_b64 vcc, exec, s[2:3]
	v_pk_mul_f32 v[0:1], v[0:1], v[8:9]
	v_pk_mul_f32 v[2:3], v[2:3], v[10:11]
	v_cvt_pk_bf16_f32 v0, v0, v1
	v_cvt_pk_bf16_f32 v1, v2, v3
	s_mov_b32 s61, s58
	s_mov_b32 s60, s59
	s_mov_b64 s[18:19], s[0:1]
	s_mov_b64 s[16:17], s[4:5]
	global_store_dwordx2 v[16:17], v[0:1], off offset:128
	s_cbranch_vccz .LBB0_720
	s_branch .Lgu4_done

; #define PG8_STAGE(bufoff, gbase, voff) do { _Pragma("unroll") for (int _i = 0; _i < 2; ++_i) \
;         __builtin_amdgcn_global_load_lds((const unsigned*)((const char*)(gbase) + (voff)[_i]), (PG8_LAS unsigned*)(lds + (bufoff) + ldsw + _i * 8192), 16, 0, 0); } while (0)
; #define PG8_LDA(dst, b, h) do { _Pragma("unroll") for (int m = 0; m < 4; ++m) _Pragma("unroll") for (int k = 0; k < 2; ++k) dst[m][k] = *(const PG8_LAS bf16x8*)(lds + PG8_SA(b, h) + aoff + m * 2048 + k * 1024); } while (0)
; #define PG8_BAR __builtin_amdgcn_s_barrier()
; template <class Epi, class Sched, bool STAMP = false>
; __device__ __forceinline__ void gemm_phase(PG8_LAS unsigned char* lds, const Gemm g, const Sched& S, const Epi& E, unsigned long long* stamps) {
;     ...
;         for (int t = 0; t < nt; t += 2) {
;             const bool last = (t == nt - 2);
;             const char* a1 = cA + (size_t)(t + 1) * kstep;
;             const char* a2 = last ? nA : cA + (size_t)(t + 2) * kstep; const char* b2 = last ? nB : cB + (size_t)(t + 2) * kstep;
;             const char* a3 = a2 + kstep; const char* b3 = b2 + kstep;
;             if (last && has_next) S.a_ready(nxt);
;             PG8_LDB(B0, 0, 0); PG8_SCHED; PG8_LDA(At, 0, 0); PG8_STAGE(PG8_SA(1, 1), a1 + hstep, voffA);
;             PG8_WAIT_L(8); PG8_BAR; PG8_WAIT_L(0); PG8_MMA(0, 0, At, B0); PG8_BAR; PG8_SCHED;
;             PG8_LDB(B1, 0, 1); PG8_STAGE(PG8_SB(0, 0), b2, voffB);
;             PG8_BAR; PG8_WAIT_L(0); PG8_MMA(0, 1, At, B1); PG8_BAR;
;             PG8_LDA(At, 0, 1); PG8_STAGE(PG8_SA(0, 0), a2, voffA);
;             PG8_BAR; PG8_WAIT_L(0); PG8_MMA(1, 0, At, B0); PG8_BAR; PG8_SCHED;
;             PG8_STAGE(PG8_SB(0, 1), b2 + hstep, voffB);
;             PG8_WAIT_V(6); PG8_BAR; PG8_MMA(1, 1, At, B1); PG8_BAR;
;             PG8_LDB(B0, 1, 0); PG8_SCHED; PG8_LDA(At, 1, 0); PG8_STAGE(PG8_SA(0, 1), a2 + hstep, voffA);
;             PG8_WAIT_L(8); PG8_BAR; PG8_WAIT_L(0); PG8_MMA(0, 0, At, B0); PG8_BAR; PG8_SCHED;
;             PG8_LDB(B1, 1, 1); PG8_STAGE(PG8_SB(1, 0), b3, voffB);
;             PG8_BAR; PG8_WAIT_L(0); PG8_MMA(0, 1, At, B1); PG8_BAR;
;             PG8_LDA(At, 1, 1); PG8_STAGE(PG8_SA(1, 0), a3, voffA);
;             PG8_BAR; PG8_WAIT_L(0); PG8_MMA(1, 0, At, B0); PG8_BAR; PG8_SCHED;
;             PG8_STAGE(PG8_SB(1, 1), b3 + hstep, voffB);
;             PG8_WAIT_V(6); PG8_BAR; PG8_MMA(1, 1, At, B1); PG8_BAR;
.Lgu4_half_loop:
	s_add_u32 s100, s62, 0x43f80
	s_addc_u32 s101, s63, 0
	s_mov_b32 m0, s52
	s_nop 0
	global_load_lds_dwordx4 v130, s[100:101]
	s_mov_b32 m0, s53
	s_nop 0
	global_load_lds_dwordx4 v128, s[100:101]
	ds_read_b128 v[140:143], v147
	ds_read_b128 v[170:173], v148
	ds_read_b128 v[174:177], v149
	ds_read_b128 v[178:181], v150
	s_add_u32 s18, s16, 0x100
	s_addc_u32 s19, s17, 0
	s_cmp_eq_u32 s10, 12
	s_cselect_b32 s29, s5, s19
	s_cselect_b32 s28, s4, s18
	s_cselect_b32 s21, s1, s63
	s_cselect_b32 s20, s0, s62
	s_mov_b32 m0, s55
	ds_read_b128 v[182:185], v145
	ds_read_b128 v[186:189], v145 offset:1024
	ds_read_b128 v[190:193], v145 offset:2048
	ds_read_b128 v[194:197], v145 offset:3072
	ds_read_b128 v[198:201], v145 offset:4096
	ds_read_b128 v[202:205], v145 offset:5120
	ds_read_b128 v[206:209], v145 offset:6144
	ds_read_b128 v[210:213], v145 offset:7168
	global_load_lds_dwordx4 v132, s[16:17]
	s_mov_b32 m0, s56
	s_nop 0
	global_load_lds_dwordx4 v134, s[16:17]
	s_waitcnt vmcnt(8)
	s_waitcnt lgkmcnt(0)
	s_barrier
	s_setprio 1
	v_mfma_f32_16x16x32_bf16 v[124:127], v[140:143], v[182:185], v[124:127]
	v_mfma_f32_16x16x32_bf16 v[120:123], v[174:177], v[182:185], v[120:123]
	v_mfma_f32_16x16x32_bf16 v[108:111], v[140:143], v[190:193], v[108:111]
	v_mfma_f32_16x16x32_bf16 v[104:107], v[174:177], v[190:193], v[104:107]
	v_mfma_f32_16x16x32_bf16 v[92:95], v[140:143], v[198:201], v[92:95]
	v_mfma_f32_16x16x32_bf16 v[88:91], v[174:177], v[198:201], v[88:91]
	v_mfma_f32_16x16x32_bf16 v[76:79], v[140:143], v[206:209], v[76:79]
	v_mfma_f32_16x16x32_bf16 v[72:75], v[174:177], v[206:209], v[72:75]
	v_mfma_f32_16x16x32_bf16 v[124:127], v[170:173], v[186:189], v[124:127]
	v_mfma_f32_16x16x32_bf16 v[120:123], v[178:181], v[186:189], v[120:123]
	v_mfma_f32_16x16x32_bf16 v[108:111], v[170:173], v[194:197], v[108:111]
	v_mfma_f32_16x16x32_bf16 v[104:107], v[178:181], v[194:197], v[104:107]
	v_mfma_f32_16x16x32_bf16 v[92:95], v[170:173], v[202:205], v[92:95]
	v_mfma_f32_16x16x32_bf16 v[88:91], v[178:181], v[202:205], v[88:91]
	v_mfma_f32_16x16x32_bf16 v[76:79], v[170:173], v[210:213], v[76:79]
	v_mfma_f32_16x16x32_bf16 v[72:75], v[178:181], v[210:213], v[72:75]
	s_setprio 0
	s_barrier
	s_mov_b32 m0, s37
	s_nop 0
	global_load_lds_dwordx4 v130, s[20:21]
	s_mov_b32 m0, s40
	s_nop 0
	global_load_lds_dwordx4 v128, s[20:21]
	s_mov_b32 m0, s34
	ds_read_b128 v[182:185], v145 offset:16384
	ds_read_b128 v[186:189], v145 offset:17408
	ds_read_b128 v[190:193], v145 offset:18432
	ds_read_b128 v[194:197], v145 offset:19456
	ds_read_b128 v[198:201], v145 offset:20480
	ds_read_b128 v[202:205], v145 offset:21504
	ds_read_b128 v[206:209], v145 offset:22528
	ds_read_b128 v[210:213], v145 offset:23552
	global_load_lds_dwordx4 v130, s[28:29]
	s_mov_b32 m0, s41
	s_nop 0
	global_load_lds_dwordx4 v128, s[28:29]
	s_waitcnt vmcnt(6)
	s_waitcnt lgkmcnt(0)
	s_barrier
	s_setprio 1
	v_mfma_f32_16x16x32_bf16 v[60:63], v[140:143], v[182:185], v[60:63]
	v_mfma_f32_16x16x32_bf16 v[56:59], v[174:177], v[182:185], v[56:59]
	v_mfma_f32_16x16x32_bf16 v[44:47], v[140:143], v[190:193], v[44:47]
	v_mfma_f32_16x16x32_bf16 v[40:43], v[174:177], v[190:193], v[40:43]
	v_mfma_f32_16x16x32_bf16 v[28:31], v[140:143], v[198:201], v[28:31]
	v_mfma_f32_16x16x32_bf16 v[24:27], v[174:177], v[198:201], v[24:27]
	v_mfma_f32_16x16x32_bf16 v[12:15], v[140:143], v[206:209], v[12:15]
	v_mfma_f32_16x16x32_bf16 v[8:11], v[174:177], v[206:209], v[8:11]
	v_mfma_f32_16x16x32_bf16 v[60:63], v[170:173], v[186:189], v[60:63]
	v_mfma_f32_16x16x32_bf16 v[56:59], v[178:181], v[186:189], v[56:59]
	v_mfma_f32_16x16x32_bf16 v[44:47], v[170:173], v[194:197], v[44:47]
	v_mfma_f32_16x16x32_bf16 v[40:43], v[178:181], v[194:197], v[40:43]
	v_mfma_f32_16x16x32_bf16 v[28:31], v[170:173], v[202:205], v[28:31]
	v_mfma_f32_16x16x32_bf16 v[24:27], v[178:181], v[202:205], v[24:27]
	v_mfma_f32_16x16x32_bf16 v[12:15], v[170:173], v[210:213], v[12:15]
	v_mfma_f32_16x16x32_bf16 v[8:11], v[178:181], v[210:213], v[8:11]
	s_setprio 0
	s_barrier
	s_add_u32 s16, s20, 0x44000
	s_addc_u32 s17, s21, 0
	s_mov_b32 m0, s42
	s_nop 0
	global_load_lds_dwordx4 v130, s[16:17]
	s_mov_b32 m0, s43
	s_nop 0
	global_load_lds_dwordx4 v128, s[16:17]
	ds_read_b128 v[140:143], v155
	ds_read_b128 v[170:173], v156
	ds_read_b128 v[174:177], v157
	ds_read_b128 v[178:181], v165
	s_add_u32 s16, s28, 0x44000
	s_addc_u32 s17, s29, 0
	s_mov_b32 m0, s44
	ds_read_b128 v[182:185], v145 offset:32768
	ds_read_b128 v[186:189], v145 offset:33792
	ds_read_b128 v[190:193], v145 offset:34816
	ds_read_b128 v[194:197], v145 offset:35840
	ds_read_b128 v[198:201], v145 offset:36864
	ds_read_b128 v[202:205], v145 offset:37888
	ds_read_b128 v[206:209], v145 offset:38912
	ds_read_b128 v[210:213], v145 offset:39936
	global_load_lds_dwordx4 v130, s[16:17]
	s_mov_b32 m0, s45
	s_nop 0
	global_load_lds_dwordx4 v128, s[16:17]
	s_waitcnt vmcnt(8)
	s_waitcnt lgkmcnt(0)
	s_barrier
	s_setprio 1
	v_mfma_f32_16x16x32_bf16 v[124:127], v[140:143], v[182:185], v[124:127]
	v_mfma_f32_16x16x32_bf16 v[120:123], v[174:177], v[182:185], v[120:123]
	v_mfma_f32_16x16x32_bf16 v[108:111], v[140:143], v[190:193], v[108:111]
	v_mfma_f32_16x16x32_bf16 v[104:107], v[174:177], v[190:193], v[104:107]
	v_mfma_f32_16x16x32_bf16 v[92:95], v[140:143], v[198:201], v[92:95]
	v_mfma_f32_16x16x32_bf16 v[88:91], v[174:177], v[198:201], v[88:91]
	v_mfma_f32_16x16x32_bf16 v[76:79], v[140:143], v[206:209], v[76:79]
	v_mfma_f32_16x16x32_bf16 v[72:75], v[174:177], v[206:209], v[72:75]
	v_mfma_f32_16x16x32_bf16 v[124:127], v[170:173], v[186:189], v[124:127]
	v_mfma_f32_16x16x32_bf16 v[120:123], v[178:181], v[186:189], v[120:123]
	v_mfma_f32_16x16x32_bf16 v[108:111], v[170:173], v[194:197], v[108:111]
	v_mfma_f32_16x16x32_bf16 v[104:107], v[178:181], v[194:197], v[104:107]
	v_mfma_f32_16x16x32_bf16 v[92:95], v[170:173], v[202:205], v[92:95]
	v_mfma_f32_16x16x32_bf16 v[88:91], v[178:181], v[202:205], v[88:91]
	v_mfma_f32_16x16x32_bf16 v[76:79], v[170:173], v[210:213], v[76:79]
	v_mfma_f32_16x16x32_bf16 v[72:75], v[178:181], v[210:213], v[72:75]
	s_setprio 0
	s_barrier
; #define PG8_STAGE(bufoff, gbase, voff) do { _Pragma("unroll") for (int _i = 0; _i < 2; ++_i) \
;         __builtin_amdgcn_global_load_lds((const unsigned*)((const char*)(gbase) + (voff)[_i]), (PG8_LAS unsigned*)(lds + (bufoff) + ldsw + _i * 8192), 16, 0, 0); } while (0)
; #define PG8_LDA(dst, b, h) do { _Pragma("unroll") for (int m = 0; m < 4; ++m) _Pragma("unroll") for (int k = 0; k < 2; ++k) dst[m][k] = *(const PG8_LAS bf16x8*)(lds + PG8_SA(b, h) + aoff + m * 2048 + k * 1024); } while (0)
; #define PG8_LDB(dst, b, h) do { _Pragma("unroll") for (int n = 0; n < 2; ++n) _Pragma("unroll") for (int k = 0; k < 2; ++k) dst[n][k] = *(const PG8_LAS bf16x8*)(lds + PG8_SB(b, h) + boff + n * 2048 + k * 1024); } while (0)
; #define PG8_MMA(ai, bj, At, Bt) do { __builtin_amdgcn_s_setprio(1); _Pragma("unroll") for (int m = 0; m < 4; ++m) _Pragma("unroll") for (int n = 0; n < 2; ++n) _Pragma("unroll") for (int k = 0; k < 2; ++k) \
;         acc[ai][bj][m][n] = __builtin_amdgcn_mfma_f32_16x16x32_bf16(Bt[n][k], At[m][k], acc[ai][bj][m][n], 0, 0, 0); __builtin_amdgcn_s_setprio(0); } while (0)
; #define PG8_WAIT_V(n) asm volatile("s_waitcnt vmcnt(" #n ")" ::: "memory")
; #define PG8_WAIT_L(n) asm volatile("s_waitcnt lgkmcnt(" #n ")" ::: "memory")
; #define PG8_BAR __builtin_amdgcn_s_barrier()
; #define PG8_SCHED __builtin_amdgcn_sched_barrier(0)
; template <class Epi, class Sched, bool STAMP = false>
; __device__ __forceinline__ void gemm_phase(PG8_LAS unsigned char* lds, const Gemm g, const Sched& S, const Epi& E, unsigned long long* stamps) {
;     ...
;             PG8_LDB(B1, 1, 1); PG8_STAGE(PG8_SB(1, 0), b3, voffB);
;             PG8_BAR; PG8_WAIT_L(0); PG8_MMA(0, 1, At, B1); PG8_BAR;
;             PG8_LDA(At, 1, 1); PG8_STAGE(PG8_SA(1, 0), a3, voffA);
;             PG8_BAR; PG8_WAIT_L(0); PG8_MMA(1, 0, At, B0); PG8_BAR; PG8_SCHED;
;             PG8_STAGE(PG8_SB(1, 1), b3 + hstep, voffB);
;             PG8_WAIT_V(6); PG8_BAR; PG8_MMA(1, 1, At, B1); PG8_BAR;
;         }
	s_mov_b32 m0, s48
	s_add_u32 s100, s20, 0x80
	s_addc_u32 s101, s21, 0
	global_load_lds_dwordx4 v130, s[100:101]
	s_mov_b32 m0, s49
	s_nop 0
	global_load_lds_dwordx4 v128, s[100:101]
	s_mov_b32 m0, s50
	ds_read_b128 v[182:185], v145 offset:49152
	ds_read_b128 v[186:189], v145 offset:50176
	ds_read_b128 v[190:193], v145 offset:51200
	ds_read_b128 v[194:197], v145 offset:52224
	ds_read_b128 v[198:201], v145 offset:53248
	ds_read_b128 v[202:205], v145 offset:54272
	ds_read_b128 v[206:209], v145 offset:55296
	ds_read_b128 v[210:213], v145 offset:56320
	s_add_u32 s100, s28, 0x80
	s_addc_u32 s101, s29, 0
	global_load_lds_dwordx4 v130, s[100:101]
	s_mov_b32 m0, s51
	s_nop 0
	global_load_lds_dwordx4 v128, s[100:101]
	s_waitcnt vmcnt(6)
	s_waitcnt lgkmcnt(0)
	s_barrier
	s_setprio 1
	v_mfma_f32_16x16x32_bf16 v[60:63], v[140:143], v[182:185], v[60:63]
	v_mfma_f32_16x16x32_bf16 v[56:59], v[174:177], v[182:185], v[56:59]
	v_mfma_f32_16x16x32_bf16 v[44:47], v[140:143], v[190:193], v[44:47]
	v_mfma_f32_16x16x32_bf16 v[40:43], v[174:177], v[190:193], v[40:43]
	v_mfma_f32_16x16x32_bf16 v[28:31], v[140:143], v[198:201], v[28:31]
	v_mfma_f32_16x16x32_bf16 v[24:27], v[174:177], v[198:201], v[24:27]
	v_mfma_f32_16x16x32_bf16 v[12:15], v[140:143], v[206:209], v[12:15]
	v_mfma_f32_16x16x32_bf16 v[8:11], v[174:177], v[206:209], v[8:11]
	v_mfma_f32_16x16x32_bf16 v[60:63], v[170:173], v[186:189], v[60:63]
	v_mfma_f32_16x16x32_bf16 v[56:59], v[178:181], v[186:189], v[56:59]
	v_mfma_f32_16x16x32_bf16 v[44:47], v[170:173], v[194:197], v[44:47]
	v_mfma_f32_16x16x32_bf16 v[40:43], v[178:181], v[194:197], v[40:43]
	v_mfma_f32_16x16x32_bf16 v[28:31], v[170:173], v[202:205], v[28:31]
	v_mfma_f32_16x16x32_bf16 v[24:27], v[178:181], v[202:205], v[24:27]
	v_mfma_f32_16x16x32_bf16 v[12:15], v[170:173], v[210:213], v[12:15]
	v_mfma_f32_16x16x32_bf16 v[8:11], v[178:181], v[210:213], v[8:11]
	s_setprio 0
	s_add_i32 s10, s10, 2
	s_add_u32 s62, s62, 0x100
	s_addc_u32 s63, s63, 0
	s_cmp_gt_u32 s10, 13
	s_mov_b64 s[16:17], s[18:19]
	s_barrier
	s_cbranch_scc0 .Lgu4_half_loop
; DI float ex2(float x) { return __builtin_amdgcn_exp2f(x); }
;     DI void operator()(const f32x4 (&acc)[2][2][4][2], const Unit& u, int wr, int wc, int fr, int fq) const {
;         const int row0 = u.pm * BM + wr * 64 + fr, hcol0 = ((u.pn * BM + wc * 32) >> 1) + 4 * fq;
; #pragma unroll
;         for (int ai = 0; ai < 2; ++ai)
; #pragma unroll
;             for (int m = 0; m < 4; ++m) { u16* rowp = O + (size_t)(row0 + ai * HALF + m * 16) * ldc + hcol0;
; #pragma unroll
;                 for (int bj = 0; bj < 2; ++bj) { const f32x4 g = acc[ai][bj][m][0], up = acc[ai][bj][m][1]; float r[4];
; #pragma unroll
;                     for (int j = 0; j < 4; ++j) r[j] = g[j] * up[j] * __builtin_amdgcn_rcpf(1.f + ex2(-LOG2E * g[j]));
;                     uint2 w = {pack2(r[0], r[1]), pack2(r[2], r[3])}; *(uint2*)(rowp + bj * (HALF / 2)) = w; } }
	v_exp_f32_e64 v171, -v124
	v_exp_f32_e64 v175, -v125
	s_lshl_b32 s10, s61, 8
	v_add_f32_e32 v171, 1.0, v171
	v_rcp_f32_e32 v174, v171
	v_add_f32_e32 v171, 1.0, v175
	v_exp_f32_e64 v176, -v126
	v_exp_f32_e64 v177, -v127
	v_rcp_f32_e32 v175, v171
	v_add_f32_e32 v171, 1.0, v176
	v_rcp_f32_e32 v176, v171
	v_add_f32_e32 v171, 1.0, v177
	v_rcp_f32_e32 v177, v171
	v_pk_mul_f32 v[122:123], v[126:127], v[122:123]
	v_pk_mul_f32 v[120:121], v[124:125], v[120:121]
	s_or_b32 s10, s10, s47
	s_or_b32 s10, s10, s98
	v_pk_mul_f32 v[120:121], v[120:121], v[174:175]
	v_pk_mul_f32 v[122:123], v[122:123], v[176:177]
	s_ashr_i32 s10, s10, 1
	v_cvt_pk_bf16_f32 v120, v120, v121
	v_cvt_pk_bf16_f32 v121, v122, v123
	v_or_b32_e32 v140, s10, v146
	v_lshl_add_u32 v170, s60, 8, v144
	v_ashrrev_i32_e32 v141, 31, v140
	v_mov_b64_e32 v[142:143], s[12:13]
	v_mad_i64_i32 v[172:173], s[16:17], v170, s57, v[142:143]
	v_lshlrev_b64 v[140:141], 1, v[140:141]
	v_lshl_add_u64 v[172:173], v[172:173], 0, v[140:141]
	global_store_dwordx2 v[172:173], v[120:121], off
	v_exp_f32_e64 v114, -v108
	v_exp_f32_e64 v115, -v109
	v_exp_f32_e64 v116, -v110
	v_exp_f32_e64 v117, -v111
	v_add_f32_e32 v114, 1.0, v114
	v_add_f32_e32 v115, 1.0, v115
	v_add_f32_e32 v116, 1.0, v116
	v_add_f32_e32 v117, 1.0, v117
	v_rcp_f32_e32 v114, v114
	v_rcp_f32_e32 v115, v115
	v_rcp_f32_e32 v116, v116
	v_rcp_f32_e32 v117, v117
	v_pk_mul_f32 v[106:107], v[110:111], v[106:107]
	v_pk_mul_f32 v[104:105], v[108:109], v[104:105]
	v_pk_mul_f32 v[104:105], v[104:105], v[114:115]
	v_pk_mul_f32 v[106:107], v[106:107], v[116:117]
	v_cvt_pk_bf16_f32 v104, v104, v105
	v_cvt_pk_bf16_f32 v105, v106, v107
	v_or_b32_e32 v112, 16, v170
	v_mad_i64_i32 v[112:113], s[16:17], v112, s57, v[142:143]
	v_lshl_add_u64 v[112:113], v[112:113], 0, v[140:141]
	global_store_dwordx2 v[112:113], v[104:105], off
	v_exp_f32_e64 v98, -v92
	v_exp_f32_e64 v99, -v93
	v_exp_f32_e64 v100, -v94
	v_exp_f32_e64 v101, -v95
	v_add_f32_e32 v98, 1.0, v98
	v_add_f32_e32 v99, 1.0, v99
	v_add_f32_e32 v100, 1.0, v100
	v_add_f32_e32 v101, 1.0, v101
	v_rcp_f32_e32 v98, v98
	v_rcp_f32_e32 v99, v99
	v_rcp_f32_e32 v100, v100
	v_rcp_f32_e32 v101, v101
	v_pk_mul_f32 v[90:91], v[94:95], v[90:91]
	v_pk_mul_f32 v[88:89], v[92:93], v[88:89]
	v_pk_mul_f32 v[88:89], v[88:89], v[98:99]
	v_pk_mul_f32 v[90:91], v[90:91], v[100:101]
	v_cvt_pk_bf16_f32 v88, v88, v89
	v_cvt_pk_bf16_f32 v89, v90, v91
	v_or_b32_e32 v96, 32, v170
	v_mad_i64_i32 v[96:97], s[16:17], v96, s57, v[142:143]
	v_lshl_add_u64 v[96:97], v[96:97], 0, v[140:141]
	global_store_dwordx2 v[96:97], v[88:89], off
	v_exp_f32_e64 v82, -v76
	v_exp_f32_e64 v83, -v77
	v_exp_f32_e64 v84, -v78
	v_exp_f32_e64 v85, -v79
	v_add_f32_e32 v82, 1.0, v82
	v_add_f32_e32 v83, 1.0, v83
	v_add_f32_e32 v84, 1.0, v84
	v_add_f32_e32 v85, 1.0, v85
	v_rcp_f32_e32 v82, v82
	v_rcp_f32_e32 v83, v83
	v_rcp_f32_e32 v84, v84
	v_rcp_f32_e32 v85, v85
	v_pk_mul_f32 v[74:75], v[78:79], v[74:75]
	v_pk_mul_f32 v[72:73], v[76:77], v[72:73]
	v_pk_mul_f32 v[72:73], v[72:73], v[82:83]
	v_pk_mul_f32 v[74:75], v[74:75], v[84:85]
	v_cvt_pk_bf16_f32 v72, v72, v73
	v_cvt_pk_bf16_f32 v73, v74, v75
	v_or_b32_e32 v80, 48, v170
	v_mad_i64_i32 v[80:81], s[16:17], v80, s57, v[142:143]
	v_lshl_add_u64 v[80:81], v[80:81], 0, v[140:141]
	global_store_dwordx2 v[80:81], v[72:73], off
	v_exp_f32_e64 v66, -v60
	v_exp_f32_e64 v67, -v61
	v_exp_f32_e64 v68, -v62
	v_exp_f32_e64 v69, -v63
	v_add_f32_e32 v66, 1.0, v66
	v_add_f32_e32 v67, 1.0, v67
	v_add_f32_e32 v68, 1.0, v68
	v_add_f32_e32 v69, 1.0, v69
	v_rcp_f32_e32 v66, v66
	v_rcp_f32_e32 v67, v67
	v_rcp_f32_e32 v68, v68
	v_rcp_f32_e32 v69, v69
	v_pk_mul_f32 v[58:59], v[62:63], v[58:59]
	v_pk_mul_f32 v[56:57], v[60:61], v[56:57]
	v_pk_mul_f32 v[56:57], v[56:57], v[66:67]
	v_pk_mul_f32 v[58:59], v[58:59], v[68:69]
	v_cvt_pk_bf16_f32 v56, v56, v57
	v_cvt_pk_bf16_f32 v57, v58, v59
	v_add_u32_e32 v64, 0x80, v170
	v_mad_i64_i32 v[64:65], s[16:17], v64, s57, v[142:143]
	v_lshl_add_u64 v[64:65], v[64:65], 0, v[140:141]
	global_store_dwordx2 v[64:65], v[56:57], off
	v_exp_f32_e64 v50, -v44
	v_exp_f32_e64 v51, -v45
	v_exp_f32_e64 v52, -v46
	v_exp_f32_e64 v53, -v47
	v_add_f32_e32 v50, 1.0, v50
	v_add_f32_e32 v51, 1.0, v51
	v_add_f32_e32 v52, 1.0, v52
	v_add_f32_e32 v53, 1.0, v53
	v_rcp_f32_e32 v50, v50
	v_rcp_f32_e32 v51, v51
	v_rcp_f32_e32 v52, v52
	v_rcp_f32_e32 v53, v53
	v_pk_mul_f32 v[42:43], v[46:47], v[42:43]
	v_pk_mul_f32 v[40:41], v[44:45], v[40:41]
	v_pk_mul_f32 v[40:41], v[40:41], v[50:51]
	v_pk_mul_f32 v[42:43], v[42:43], v[52:53]
	v_cvt_pk_bf16_f32 v40, v40, v41
	v_cvt_pk_bf16_f32 v41, v42, v43
	v_add_u32_e32 v48, 0x90, v170
	v_mad_i64_i32 v[48:49], s[16:17], v48, s57, v[142:143]
	v_lshl_add_u64 v[48:49], v[48:49], 0, v[140:141]
	global_store_dwordx2 v[48:49], v[40:41], off
	v_exp_f32_e64 v34, -v28
	v_exp_f32_e64 v35, -v29
	v_exp_f32_e64 v36, -v30
	v_exp_f32_e64 v37, -v31
	v_add_f32_e32 v34, 1.0, v34
	v_add_f32_e32 v35, 1.0, v35
	v_add_f32_e32 v36, 1.0, v36
	v_add_f32_e32 v37, 1.0, v37
	v_rcp_f32_e32 v34, v34
	v_rcp_f32_e32 v35, v35
	v_rcp_f32_e32 v36, v36
	v_rcp_f32_e32 v37, v37
	v_pk_mul_f32 v[26:27], v[30:31], v[26:27]
	v_pk_mul_f32 v[24:25], v[28:29], v[24:25]
	v_pk_mul_f32 v[24:25], v[24:25], v[34:35]
	v_pk_mul_f32 v[26:27], v[26:27], v[36:37]
	v_cvt_pk_bf16_f32 v24, v24, v25
	v_cvt_pk_bf16_f32 v25, v26, v27
	v_add_u32_e32 v32, 0xa0, v170
	v_mad_i64_i32 v[32:33], s[16:17], v32, s57, v[142:143]
	v_lshl_add_u64 v[32:33], v[32:33], 0, v[140:141]
	global_store_dwordx2 v[32:33], v[24:25], off
	v_exp_f32_e64 v18, -v12
	v_exp_f32_e64 v19, -v13
	v_exp_f32_e64 v20, -v14
	v_exp_f32_e64 v21, -v15
	v_add_f32_e32 v18, 1.0, v18
	v_add_f32_e32 v19, 1.0, v19
	v_add_f32_e32 v20, 1.0, v20
	v_add_f32_e32 v21, 1.0, v21
	v_rcp_f32_e32 v18, v18
	v_rcp_f32_e32 v19, v19
	v_rcp_f32_e32 v20, v20
	v_rcp_f32_e32 v21, v21
	v_pk_mul_f32 v[10:11], v[14:15], v[10:11]
	v_pk_mul_f32 v[8:9], v[12:13], v[8:9]
	v_pk_mul_f32 v[8:9], v[8:9], v[18:19]
	v_pk_mul_f32 v[10:11], v[10:11], v[20:21]
	v_cvt_pk_bf16_f32 v8, v8, v9
	v_cvt_pk_bf16_f32 v9, v10, v11
	v_add_u32_e32 v16, 0xb0, v170
	v_mad_i64_i32 v[16:17], s[16:17], v16, s57, v[142:143]
	v_lshl_add_u64 v[16:17], v[16:17], 0, v[140:141]
	global_store_dwordx2 v[16:17], v[8:9], off
	s_and_b64 vcc, exec, s[2:3]
	s_mov_b32 s61, s58
	s_mov_b32 s60, s59
	s_mov_b64 s[18:19], s[0:1]
	s_mov_b64 s[16:17], s[4:5]

; #define PG8_STAGE(bufoff, gbase, voff) do { _Pragma("unroll") for (int _i = 0; _i < 2; ++_i) \
;         __builtin_amdgcn_global_load_lds((const unsigned*)((const char*)(gbase) + (voff)[_i]), (PG8_LAS unsigned*)(lds + (bufoff) + ldsw + _i * 8192), 16, 0, 0); } while (0)
; #define PG8_LDA(dst, b, h) do { _Pragma("unroll") for (int m = 0; m < 4; ++m) _Pragma("unroll") for (int k = 0; k < 2; ++k) dst[m][k] = *(const PG8_LAS bf16x8*)(lds + PG8_SA(b, h) + aoff + m * 2048 + k * 1024); } while (0)
; #define PG8_LDB(dst, b, h) do { _Pragma("unroll") for (int n = 0; n < 2; ++n) _Pragma("unroll") for (int k = 0; k < 2; ++k) dst[n][k] = *(const PG8_LAS bf16x8*)(lds + PG8_SB(b, h) + boff + n * 2048 + k * 1024); } while (0)
; #define PG8_MMA(ai, bj, At, Bt) do { __builtin_amdgcn_s_setprio(1); _Pragma("unroll") for (int m = 0; m < 4; ++m) _Pragma("unroll") for (int n = 0; n < 2; ++n) _Pragma("unroll") for (int k = 0; k < 2; ++k) \
;         acc[ai][bj][m][n] = __builtin_amdgcn_mfma_f32_16x16x32_bf16(Bt[n][k], At[m][k], acc[ai][bj][m][n], 0, 0, 0); __builtin_amdgcn_s_setprio(0); } while (0)
; #define PG8_BAR __builtin_amdgcn_s_barrier()
; template <class Epi, class Sched, bool STAMP = false>
; __device__ __forceinline__ void gemm_phase(PG8_LAS unsigned char* lds, const Gemm g, const Sched& S, const Epi& E, unsigned long long* stamps) {
;     ...
;         for (int t = 0; t < nt; t += 2) {
;             const bool last = (t == nt - 2);
;             const char* a1 = cA + (size_t)(t + 1) * kstep;
;             const char* a2 = last ? nA : cA + (size_t)(t + 2) * kstep; const char* b2 = last ? nB : cB + (size_t)(t + 2) * kstep;
;             const char* a3 = a2 + kstep; const char* b3 = b2 + kstep;
;             if (last && has_next) S.a_ready(nxt);
;             PG8_LDB(B0, 0, 0); PG8_SCHED; PG8_LDA(At, 0, 0); PG8_STAGE(PG8_SA(1, 1), a1 + hstep, voffA);
;             PG8_WAIT_L(8); PG8_BAR; PG8_WAIT_L(0); PG8_MMA(0, 0, At, B0); PG8_BAR; PG8_SCHED;
;             PG8_LDB(B1, 0, 1); PG8_STAGE(PG8_SB(0, 0), b2, voffB);
;             PG8_BAR; PG8_WAIT_L(0); PG8_MMA(0, 1, At, B1); PG8_BAR;
;             PG8_LDA(At, 0, 1); PG8_STAGE(PG8_SA(0, 0), a2, voffA);
;             PG8_BAR; PG8_WAIT_L(0); PG8_MMA(1, 0, At, B0); PG8_BAR; PG8_SCHED;
;             PG8_STAGE(PG8_SB(0, 1), b2 + hstep, voffB);
;             PG8_WAIT_V(6); PG8_BAR; PG8_MMA(1, 1, At, B1); PG8_BAR;
.LBB0_760:
	s_add_u32 s68, s30, 0x100
	s_addc_u32 s69, s31, 0
	s_mov_b32 s10, -2
	s_add_u32 s100, s68, 0xb3f80
	s_addc_u32 s101, s69, 0
	s_mov_b32 m0, s54
	s_nop 0
	global_load_lds_dwordx4 v130, s[100:101]
	s_mov_b32 m0, s55
	s_nop 0
	global_load_lds_dwordx4 v134, s[100:101]
	ds_read_b128 v[170:173], v147
	ds_read_b128 v[174:177], v148
	ds_read_b128 v[178:181], v149
	ds_read_b128 v[182:185], v150
	s_add_u32 s30, s28, 0x100
	s_addc_u32 s31, s29, 0
	s_cmp_eq_u32 s10, 40
	s_cselect_b32 s37, s5, s31
	s_cselect_b32 s36, s4, s30
	s_cselect_b32 s35, s1, s69
	s_cselect_b32 s34, s0, s68
	s_mov_b32 m0, s58
	ds_read_b128 v[186:189], v145
	ds_read_b128 v[190:193], v145 offset:1024
	ds_read_b128 v[194:197], v145 offset:2048
	ds_read_b128 v[198:201], v145 offset:3072
	ds_read_b128 v[202:205], v145 offset:4096
	ds_read_b128 v[206:209], v145 offset:5120
	ds_read_b128 v[210:213], v145 offset:6144
	ds_read_b128 v[214:217], v145 offset:7168
	global_load_lds_dwordx4 v136, s[28:29]
	s_mov_b32 m0, s59
	s_nop 0
	global_load_lds_dwordx4 v138, s[28:29]
	ds_read_b128 v[218:221], v151
	ds_read_b128 v[222:225], v152
	ds_read_b128 v[226:229], v153
	ds_read_b128 v[230:233], v154
	s_waitcnt vmcnt(8)
	s_waitcnt lgkmcnt(0)
	s_barrier
	s_setprio 1
	v_mfma_f32_16x16x32_bf16 v[124:127], v[170:173], v[186:189], 0
	v_mfma_f32_16x16x32_bf16 v[120:123], v[178:181], v[186:189], 0
	v_mfma_f32_16x16x32_bf16 v[116:119], v[170:173], v[194:197], 0
	v_mfma_f32_16x16x32_bf16 v[112:115], v[178:181], v[194:197], 0
	v_mfma_f32_16x16x32_bf16 v[100:103], v[170:173], v[202:205], 0
	v_mfma_f32_16x16x32_bf16 v[96:99], v[178:181], v[202:205], 0
	v_mfma_f32_16x16x32_bf16 v[84:87], v[170:173], v[210:213], 0
	v_mfma_f32_16x16x32_bf16 v[80:83], v[178:181], v[210:213], 0
	v_mfma_f32_16x16x32_bf16 v[124:127], v[174:177], v[190:193], v[124:127]
	v_mfma_f32_16x16x32_bf16 v[120:123], v[182:185], v[190:193], v[120:123]
	v_mfma_f32_16x16x32_bf16 v[116:119], v[174:177], v[198:201], v[116:119]
	v_mfma_f32_16x16x32_bf16 v[112:115], v[182:185], v[198:201], v[112:115]
	v_mfma_f32_16x16x32_bf16 v[100:103], v[174:177], v[206:209], v[100:103]
	v_mfma_f32_16x16x32_bf16 v[96:99], v[182:185], v[206:209], v[96:99]
	v_mfma_f32_16x16x32_bf16 v[84:87], v[174:177], v[214:217], v[84:87]
	v_mfma_f32_16x16x32_bf16 v[80:83], v[182:185], v[214:217], v[80:83]
	v_mfma_f32_16x16x32_bf16 v[108:111], v[218:221], v[186:189], 0
	v_mfma_f32_16x16x32_bf16 v[104:107], v[226:229], v[186:189], 0
	v_mfma_f32_16x16x32_bf16 v[92:95], v[218:221], v[194:197], 0
	v_mfma_f32_16x16x32_bf16 v[88:91], v[226:229], v[194:197], 0
	v_mfma_f32_16x16x32_bf16 v[76:79], v[218:221], v[202:205], 0
	v_mfma_f32_16x16x32_bf16 v[72:75], v[226:229], v[202:205], 0
	v_mfma_f32_16x16x32_bf16 v[68:71], v[218:221], v[210:213], 0
	v_mfma_f32_16x16x32_bf16 v[64:67], v[226:229], v[210:213], 0
	v_mfma_f32_16x16x32_bf16 v[108:111], v[222:225], v[190:193], v[108:111]
	v_mfma_f32_16x16x32_bf16 v[104:107], v[230:233], v[190:193], v[104:107]
	v_mfma_f32_16x16x32_bf16 v[92:95], v[222:225], v[198:201], v[92:95]
	v_mfma_f32_16x16x32_bf16 v[88:91], v[230:233], v[198:201], v[88:91]
	v_mfma_f32_16x16x32_bf16 v[76:79], v[222:225], v[206:209], v[76:79]
	v_mfma_f32_16x16x32_bf16 v[72:75], v[230:233], v[206:209], v[72:75]
	v_mfma_f32_16x16x32_bf16 v[68:71], v[222:225], v[214:217], v[68:71]
	v_mfma_f32_16x16x32_bf16 v[64:67], v[230:233], v[214:217], v[64:67]
	s_setprio 0
	s_barrier
	s_mov_b32 m0, s43
	s_nop 0
	global_load_lds_dwordx4 v130, s[34:35]
	s_mov_b32 m0, s44
	s_nop 0
	global_load_lds_dwordx4 v134, s[34:35]
	s_mov_b32 m0, s42
	ds_read_b128 v[186:189], v145 offset:16384
	ds_read_b128 v[190:193], v145 offset:17408
	ds_read_b128 v[194:197], v145 offset:18432
	ds_read_b128 v[198:201], v145 offset:19456
	ds_read_b128 v[202:205], v145 offset:20480
	ds_read_b128 v[206:209], v145 offset:21504
	ds_read_b128 v[210:213], v145 offset:22528
	ds_read_b128 v[214:217], v145 offset:23552
	global_load_lds_dwordx4 v128, s[36:37]
	s_mov_b32 m0, s45
	s_nop 0
	global_load_lds_dwordx4 v132, s[36:37]
	s_waitcnt vmcnt(6)
	s_waitcnt lgkmcnt(0)
	s_barrier
	s_setprio 1
	v_mfma_f32_16x16x32_bf16 v[60:63], v[170:173], v[186:189], 0
	v_mfma_f32_16x16x32_bf16 v[56:59], v[178:181], v[186:189], 0
	v_mfma_f32_16x16x32_bf16 v[52:55], v[170:173], v[194:197], 0
	v_mfma_f32_16x16x32_bf16 v[48:51], v[178:181], v[194:197], 0
	v_mfma_f32_16x16x32_bf16 v[36:39], v[170:173], v[202:205], 0
	v_mfma_f32_16x16x32_bf16 v[32:35], v[178:181], v[202:205], 0
	v_mfma_f32_16x16x32_bf16 v[20:23], v[170:173], v[210:213], 0
	v_mfma_f32_16x16x32_bf16 v[16:19], v[178:181], v[210:213], 0
	v_mfma_f32_16x16x32_bf16 v[60:63], v[174:177], v[190:193], v[60:63]
	v_mfma_f32_16x16x32_bf16 v[56:59], v[182:185], v[190:193], v[56:59]
	v_mfma_f32_16x16x32_bf16 v[52:55], v[174:177], v[198:201], v[52:55]
	v_mfma_f32_16x16x32_bf16 v[48:51], v[182:185], v[198:201], v[48:51]
	v_mfma_f32_16x16x32_bf16 v[36:39], v[174:177], v[206:209], v[36:39]
	v_mfma_f32_16x16x32_bf16 v[32:35], v[182:185], v[206:209], v[32:35]
	v_mfma_f32_16x16x32_bf16 v[20:23], v[174:177], v[214:217], v[20:23]
	v_mfma_f32_16x16x32_bf16 v[16:19], v[182:185], v[214:217], v[16:19]
	v_mfma_f32_16x16x32_bf16 v[44:47], v[218:221], v[186:189], 0
	v_mfma_f32_16x16x32_bf16 v[40:43], v[226:229], v[186:189], 0
	v_mfma_f32_16x16x32_bf16 v[28:31], v[218:221], v[194:197], 0
	v_mfma_f32_16x16x32_bf16 v[24:27], v[226:229], v[194:197], 0
	v_mfma_f32_16x16x32_bf16 v[12:15], v[218:221], v[202:205], 0
	v_mfma_f32_16x16x32_bf16 v[8:11], v[226:229], v[202:205], 0
	v_mfma_f32_16x16x32_bf16 v[4:7], v[218:221], v[210:213], 0
	v_mfma_f32_16x16x32_bf16 v[0:3], v[226:229], v[210:213], 0
	v_mfma_f32_16x16x32_bf16 v[44:47], v[222:225], v[190:193], v[44:47]
	v_mfma_f32_16x16x32_bf16 v[40:43], v[230:233], v[190:193], v[40:43]
	v_mfma_f32_16x16x32_bf16 v[28:31], v[222:225], v[198:201], v[28:31]
	v_mfma_f32_16x16x32_bf16 v[24:27], v[230:233], v[198:201], v[24:27]
	v_mfma_f32_16x16x32_bf16 v[12:15], v[222:225], v[206:209], v[12:15]
	v_mfma_f32_16x16x32_bf16 v[8:11], v[230:233], v[206:209], v[8:11]
	v_mfma_f32_16x16x32_bf16 v[4:7], v[222:225], v[214:217], v[4:7]
	v_mfma_f32_16x16x32_bf16 v[0:3], v[230:233], v[214:217], v[0:3]
	s_setprio 0
	s_barrier
	s_branch .Lzp12_mid
; #define PG8_STAGE(bufoff, gbase, voff) do { _Pragma("unroll") for (int _i = 0; _i < 2; ++_i) \
;         __builtin_amdgcn_global_load_lds((const unsigned*)((const char*)(gbase) + (voff)[_i]), (PG8_LAS unsigned*)(lds + (bufoff) + ldsw + _i * 8192), 16, 0, 0); } while (0)
; #define PG8_LDA(dst, b, h) do { _Pragma("unroll") for (int m = 0; m < 4; ++m) _Pragma("unroll") for (int k = 0; k < 2; ++k) dst[m][k] = *(const PG8_LAS bf16x8*)(lds + PG8_SA(b, h) + aoff + m * 2048 + k * 1024); } while (0)
; #define PG8_LDB(dst, b, h) do { _Pragma("unroll") for (int n = 0; n < 2; ++n) _Pragma("unroll") for (int k = 0; k < 2; ++k) dst[n][k] = *(const PG8_LAS bf16x8*)(lds + PG8_SB(b, h) + boff + n * 2048 + k * 1024); } while (0)
; #define PG8_MMA(ai, bj, At, Bt) do { __builtin_amdgcn_s_setprio(1); _Pragma("unroll") for (int m = 0; m < 4; ++m) _Pragma("unroll") for (int n = 0; n < 2; ++n) _Pragma("unroll") for (int k = 0; k < 2; ++k) \
;         acc[ai][bj][m][n] = __builtin_amdgcn_mfma_f32_16x16x32_bf16(Bt[n][k], At[m][k], acc[ai][bj][m][n], 0, 0, 0); __builtin_amdgcn_s_setprio(0); } while (0)
; #define PG8_BAR __builtin_amdgcn_s_barrier()
; template <class Epi, class Sched, bool STAMP = false>
; __device__ __forceinline__ void gemm_phase(PG8_LAS unsigned char* lds, const Gemm g, const Sched& S, const Epi& E, unsigned long long* stamps) {
;     ...
;         for (int t = 0; t < nt; t += 2) {
;             const bool last = (t == nt - 2);
;             const char* a1 = cA + (size_t)(t + 1) * kstep;
;             const char* a2 = last ? nA : cA + (size_t)(t + 2) * kstep; const char* b2 = last ? nB : cB + (size_t)(t + 2) * kstep;
;             const char* a3 = a2 + kstep; const char* b3 = b2 + kstep;
;             if (last && has_next) S.a_ready(nxt);
;             PG8_LDB(B0, 0, 0); PG8_SCHED; PG8_LDA(At, 0, 0); PG8_STAGE(PG8_SA(1, 1), a1 + hstep, voffA);
;             PG8_WAIT_L(8); PG8_BAR; PG8_WAIT_L(0); PG8_MMA(0, 0, At, B0); PG8_BAR; PG8_SCHED;
;             PG8_LDB(B1, 0, 1); PG8_STAGE(PG8_SB(0, 0), b2, voffB);
;             PG8_BAR; PG8_WAIT_L(0); PG8_MMA(0, 1, At, B1); PG8_BAR;
;             PG8_LDA(At, 0, 1); PG8_STAGE(PG8_SA(0, 0), a2, voffA);
;             PG8_BAR; PG8_WAIT_L(0); PG8_MMA(1, 0, At, B0); PG8_BAR; PG8_SCHED;
;             PG8_STAGE(PG8_SB(0, 1), b2 + hstep, voffB);
;             PG8_WAIT_V(6); PG8_BAR; PG8_MMA(1, 1, At, B1); PG8_BAR;
.LBB0_761:
	s_add_u32 s100, s68, 0xb3f80
	s_addc_u32 s101, s69, 0
	s_mov_b32 m0, s54
	s_nop 0
	global_load_lds_dwordx4 v130, s[100:101]
	s_mov_b32 m0, s55
	s_nop 0
	global_load_lds_dwordx4 v134, s[100:101]
	ds_read_b128 v[170:173], v147
	ds_read_b128 v[174:177], v148
	ds_read_b128 v[178:181], v149
	ds_read_b128 v[182:185], v150
	s_add_u32 s30, s28, 0x100
	s_addc_u32 s31, s29, 0
	s_cmp_eq_u32 s10, 40
	s_cselect_b32 s37, s5, s31
	s_cselect_b32 s36, s4, s30
	s_cselect_b32 s35, s1, s69
	s_cselect_b32 s34, s0, s68
	s_mov_b32 m0, s58
	ds_read_b128 v[186:189], v145
	ds_read_b128 v[190:193], v145 offset:1024
	ds_read_b128 v[194:197], v145 offset:2048
	ds_read_b128 v[198:201], v145 offset:3072
	ds_read_b128 v[202:205], v145 offset:4096
	ds_read_b128 v[206:209], v145 offset:5120
	ds_read_b128 v[210:213], v145 offset:6144
	ds_read_b128 v[214:217], v145 offset:7168
	global_load_lds_dwordx4 v136, s[28:29]
	s_mov_b32 m0, s59
	s_nop 0
	global_load_lds_dwordx4 v138, s[28:29]
	ds_read_b128 v[218:221], v151
	ds_read_b128 v[222:225], v152
	ds_read_b128 v[226:229], v153
	ds_read_b128 v[230:233], v154
	s_waitcnt vmcnt(8)
	s_waitcnt lgkmcnt(0)
	s_barrier
	s_setprio 1
	v_mfma_f32_16x16x32_bf16 v[124:127], v[170:173], v[186:189], v[124:127]
	v_mfma_f32_16x16x32_bf16 v[120:123], v[178:181], v[186:189], v[120:123]
	v_mfma_f32_16x16x32_bf16 v[116:119], v[170:173], v[194:197], v[116:119]
	v_mfma_f32_16x16x32_bf16 v[112:115], v[178:181], v[194:197], v[112:115]
	v_mfma_f32_16x16x32_bf16 v[100:103], v[170:173], v[202:205], v[100:103]
	v_mfma_f32_16x16x32_bf16 v[96:99], v[178:181], v[202:205], v[96:99]
	v_mfma_f32_16x16x32_bf16 v[84:87], v[170:173], v[210:213], v[84:87]
	v_mfma_f32_16x16x32_bf16 v[80:83], v[178:181], v[210:213], v[80:83]
	v_mfma_f32_16x16x32_bf16 v[124:127], v[174:177], v[190:193], v[124:127]
	v_mfma_f32_16x16x32_bf16 v[120:123], v[182:185], v[190:193], v[120:123]
	v_mfma_f32_16x16x32_bf16 v[116:119], v[174:177], v[198:201], v[116:119]
	v_mfma_f32_16x16x32_bf16 v[112:115], v[182:185], v[198:201], v[112:115]
	v_mfma_f32_16x16x32_bf16 v[100:103], v[174:177], v[206:209], v[100:103]
	v_mfma_f32_16x16x32_bf16 v[96:99], v[182:185], v[206:209], v[96:99]
	v_mfma_f32_16x16x32_bf16 v[84:87], v[174:177], v[214:217], v[84:87]
	v_mfma_f32_16x16x32_bf16 v[80:83], v[182:185], v[214:217], v[80:83]
	v_mfma_f32_16x16x32_bf16 v[108:111], v[218:221], v[186:189], v[108:111]
	v_mfma_f32_16x16x32_bf16 v[104:107], v[226:229], v[186:189], v[104:107]
	v_mfma_f32_16x16x32_bf16 v[92:95], v[218:221], v[194:197], v[92:95]
	v_mfma_f32_16x16x32_bf16 v[88:91], v[226:229], v[194:197], v[88:91]
	v_mfma_f32_16x16x32_bf16 v[76:79], v[218:221], v[202:205], v[76:79]
	v_mfma_f32_16x16x32_bf16 v[72:75], v[226:229], v[202:205], v[72:75]
	v_mfma_f32_16x16x32_bf16 v[68:71], v[218:221], v[210:213], v[68:71]
	v_mfma_f32_16x16x32_bf16 v[64:67], v[226:229], v[210:213], v[64:67]
	v_mfma_f32_16x16x32_bf16 v[108:111], v[222:225], v[190:193], v[108:111]
	v_mfma_f32_16x16x32_bf16 v[104:107], v[230:233], v[190:193], v[104:107]
	v_mfma_f32_16x16x32_bf16 v[92:95], v[222:225], v[198:201], v[92:95]
	v_mfma_f32_16x16x32_bf16 v[88:91], v[230:233], v[198:201], v[88:91]
	v_mfma_f32_16x16x32_bf16 v[76:79], v[222:225], v[206:209], v[76:79]
	v_mfma_f32_16x16x32_bf16 v[72:75], v[230:233], v[206:209], v[72:75]
	v_mfma_f32_16x16x32_bf16 v[68:71], v[222:225], v[214:217], v[68:71]
	v_mfma_f32_16x16x32_bf16 v[64:67], v[230:233], v[214:217], v[64:67]
	s_setprio 0
	s_barrier
	s_mov_b32 m0, s43
	s_nop 0
	global_load_lds_dwordx4 v130, s[34:35]
	s_mov_b32 m0, s44
	s_nop 0
	global_load_lds_dwordx4 v134, s[34:35]
	s_mov_b32 m0, s42
	ds_read_b128 v[186:189], v145 offset:16384
	ds_read_b128 v[190:193], v145 offset:17408
	ds_read_b128 v[194:197], v145 offset:18432
	ds_read_b128 v[198:201], v145 offset:19456
	ds_read_b128 v[202:205], v145 offset:20480
	ds_read_b128 v[206:209], v145 offset:21504
	ds_read_b128 v[210:213], v145 offset:22528
	ds_read_b128 v[214:217], v145 offset:23552
	global_load_lds_dwordx4 v128, s[36:37]
	s_mov_b32 m0, s45
	s_nop 0
	global_load_lds_dwordx4 v132, s[36:37]
	s_waitcnt vmcnt(6)
	s_waitcnt lgkmcnt(0)
	s_barrier
	s_setprio 1
	v_mfma_f32_16x16x32_bf16 v[60:63], v[170:173], v[186:189], v[60:63]
	v_mfma_f32_16x16x32_bf16 v[56:59], v[178:181], v[186:189], v[56:59]
	v_mfma_f32_16x16x32_bf16 v[52:55], v[170:173], v[194:197], v[52:55]
	v_mfma_f32_16x16x32_bf16 v[48:51], v[178:181], v[194:197], v[48:51]
	v_mfma_f32_16x16x32_bf16 v[36:39], v[170:173], v[202:205], v[36:39]
	v_mfma_f32_16x16x32_bf16 v[32:35], v[178:181], v[202:205], v[32:35]
	v_mfma_f32_16x16x32_bf16 v[20:23], v[170:173], v[210:213], v[20:23]
	v_mfma_f32_16x16x32_bf16 v[16:19], v[178:181], v[210:213], v[16:19]
	v_mfma_f32_16x16x32_bf16 v[60:63], v[174:177], v[190:193], v[60:63]
	v_mfma_f32_16x16x32_bf16 v[56:59], v[182:185], v[190:193], v[56:59]
	v_mfma_f32_16x16x32_bf16 v[52:55], v[174:177], v[198:201], v[52:55]
	v_mfma_f32_16x16x32_bf16 v[48:51], v[182:185], v[198:201], v[48:51]
	v_mfma_f32_16x16x32_bf16 v[36:39], v[174:177], v[206:209], v[36:39]
	v_mfma_f32_16x16x32_bf16 v[32:35], v[182:185], v[206:209], v[32:35]
	v_mfma_f32_16x16x32_bf16 v[20:23], v[174:177], v[214:217], v[20:23]
	v_mfma_f32_16x16x32_bf16 v[16:19], v[182:185], v[214:217], v[16:19]
	v_mfma_f32_16x16x32_bf16 v[44:47], v[218:221], v[186:189], v[44:47]
	v_mfma_f32_16x16x32_bf16 v[40:43], v[226:229], v[186:189], v[40:43]
	v_mfma_f32_16x16x32_bf16 v[28:31], v[218:221], v[194:197], v[28:31]
	v_mfma_f32_16x16x32_bf16 v[24:27], v[226:229], v[194:197], v[24:27]
	v_mfma_f32_16x16x32_bf16 v[12:15], v[218:221], v[202:205], v[12:15]
	v_mfma_f32_16x16x32_bf16 v[8:11], v[226:229], v[202:205], v[8:11]
	v_mfma_f32_16x16x32_bf16 v[4:7], v[218:221], v[210:213], v[4:7]
	v_mfma_f32_16x16x32_bf16 v[0:3], v[226:229], v[210:213], v[0:3]
	v_mfma_f32_16x16x32_bf16 v[44:47], v[222:225], v[190:193], v[44:47]
	v_mfma_f32_16x16x32_bf16 v[40:43], v[230:233], v[190:193], v[40:43]
	v_mfma_f32_16x16x32_bf16 v[28:31], v[222:225], v[198:201], v[28:31]
	v_mfma_f32_16x16x32_bf16 v[24:27], v[230:233], v[198:201], v[24:27]
	v_mfma_f32_16x16x32_bf16 v[12:15], v[222:225], v[206:209], v[12:15]
	v_mfma_f32_16x16x32_bf16 v[8:11], v[230:233], v[206:209], v[8:11]
	v_mfma_f32_16x16x32_bf16 v[4:7], v[222:225], v[214:217], v[4:7]
	v_mfma_f32_16x16x32_bf16 v[0:3], v[230:233], v[214:217], v[0:3]
	s_setprio 0
	s_barrier
; #define PG8_STAGE(bufoff, gbase, voff) do { _Pragma("unroll") for (int _i = 0; _i < 2; ++_i) \
;         __builtin_amdgcn_global_load_lds((const unsigned*)((const char*)(gbase) + (voff)[_i]), (PG8_LAS unsigned*)(lds + (bufoff) + ldsw + _i * 8192), 16, 0, 0); } while (0)
; #define PG8_LDA(dst, b, h) do { _Pragma("unroll") for (int m = 0; m < 4; ++m) _Pragma("unroll") for (int k = 0; k < 2; ++k) dst[m][k] = *(const PG8_LAS bf16x8*)(lds + PG8_SA(b, h) + aoff + m * 2048 + k * 1024); } while (0)
; #define PG8_LDB(dst, b, h) do { _Pragma("unroll") for (int n = 0; n < 2; ++n) _Pragma("unroll") for (int k = 0; k < 2; ++k) dst[n][k] = *(const PG8_LAS bf16x8*)(lds + PG8_SB(b, h) + boff + n * 2048 + k * 1024); } while (0)
; #define PG8_MMA(ai, bj, At, Bt) do { __builtin_amdgcn_s_setprio(1); _Pragma("unroll") for (int m = 0; m < 4; ++m) _Pragma("unroll") for (int n = 0; n < 2; ++n) _Pragma("unroll") for (int k = 0; k < 2; ++k) \
;         acc[ai][bj][m][n] = __builtin_amdgcn_mfma_f32_16x16x32_bf16(Bt[n][k], At[m][k], acc[ai][bj][m][n], 0, 0, 0); __builtin_amdgcn_s_setprio(0); } while (0)
; #define PG8_WAIT_V(n) asm volatile("s_waitcnt vmcnt(" #n ")" ::: "memory")
; #define PG8_WAIT_L(n) asm volatile("s_waitcnt lgkmcnt(" #n ")" ::: "memory")
; #define PG8_BAR __builtin_amdgcn_s_barrier()
; #define PG8_SCHED __builtin_amdgcn_sched_barrier(0)
; template <class Epi, class Sched, bool STAMP = false>
; __device__ __forceinline__ void gemm_phase(PG8_LAS unsigned char* lds, const Gemm g, const Sched& S, const Epi& E, unsigned long long* stamps) {
;     ...
;             PG8_LDB(B0, 1, 0); PG8_SCHED; PG8_LDA(At, 1, 0); PG8_STAGE(PG8_SA(0, 1), a2 + hstep, voffA);
;             PG8_WAIT_L(8); PG8_BAR; PG8_WAIT_L(0); PG8_MMA(0, 0, At, B0); PG8_BAR; PG8_SCHED;
;             PG8_LDB(B1, 1, 1); PG8_STAGE(PG8_SB(1, 0), b3, voffB);
;             PG8_BAR; PG8_WAIT_L(0); PG8_MMA(0, 1, At, B1); PG8_BAR;
;             PG8_LDA(At, 1, 1); PG8_STAGE(PG8_SA(1, 0), a3, voffA);
;             PG8_BAR; PG8_WAIT_L(0); PG8_MMA(1, 0, At, B0); PG8_BAR; PG8_SCHED;
;             PG8_STAGE(PG8_SB(1, 1), b3 + hstep, voffB);
;             PG8_WAIT_V(6); PG8_BAR; PG8_MMA(1, 1, At, B1); PG8_BAR;
;         }
.Lzp12_mid:
	s_add_u32 s28, s34, 0xb4000
	s_addc_u32 s29, s35, 0
	s_mov_b32 m0, s46
	s_nop 0
	global_load_lds_dwordx4 v130, s[28:29]
	s_mov_b32 m0, s47
	s_nop 0
	global_load_lds_dwordx4 v134, s[28:29]
	ds_read_b128 v[170:173], v155
	ds_read_b128 v[174:177], v156
	ds_read_b128 v[178:181], v157
	ds_read_b128 v[182:185], v165
	s_add_u32 s28, s36, 0xb4000
	s_addc_u32 s29, s37, 0
	s_mov_b32 m0, s48
	ds_read_b128 v[186:189], v145 offset:32768
	ds_read_b128 v[190:193], v145 offset:33792
	ds_read_b128 v[194:197], v145 offset:34816
	ds_read_b128 v[198:201], v145 offset:35840
	ds_read_b128 v[202:205], v145 offset:36864
	ds_read_b128 v[206:209], v145 offset:37888
	ds_read_b128 v[210:213], v145 offset:38912
	ds_read_b128 v[214:217], v145 offset:39936
	global_load_lds_dwordx4 v128, s[28:29]
	s_mov_b32 m0, s49
	s_nop 0
	global_load_lds_dwordx4 v132, s[28:29]
	ds_read_b128 v[218:221], v166
	ds_read_b128 v[222:225], v167
	ds_read_b128 v[226:229], v168
	ds_read_b128 v[230:233], v169
	s_waitcnt vmcnt(8)
	s_waitcnt lgkmcnt(0)
	s_barrier
	s_setprio 1
	v_mfma_f32_16x16x32_bf16 v[124:127], v[170:173], v[186:189], v[124:127]
	v_mfma_f32_16x16x32_bf16 v[120:123], v[178:181], v[186:189], v[120:123]
	v_mfma_f32_16x16x32_bf16 v[116:119], v[170:173], v[194:197], v[116:119]
	v_mfma_f32_16x16x32_bf16 v[112:115], v[178:181], v[194:197], v[112:115]
	v_mfma_f32_16x16x32_bf16 v[100:103], v[170:173], v[202:205], v[100:103]
	v_mfma_f32_16x16x32_bf16 v[96:99], v[178:181], v[202:205], v[96:99]
	v_mfma_f32_16x16x32_bf16 v[84:87], v[170:173], v[210:213], v[84:87]
	v_mfma_f32_16x16x32_bf16 v[80:83], v[178:181], v[210:213], v[80:83]
	v_mfma_f32_16x16x32_bf16 v[124:127], v[174:177], v[190:193], v[124:127]
	v_mfma_f32_16x16x32_bf16 v[120:123], v[182:185], v[190:193], v[120:123]
	v_mfma_f32_16x16x32_bf16 v[116:119], v[174:177], v[198:201], v[116:119]
	v_mfma_f32_16x16x32_bf16 v[112:115], v[182:185], v[198:201], v[112:115]
	v_mfma_f32_16x16x32_bf16 v[100:103], v[174:177], v[206:209], v[100:103]
	v_mfma_f32_16x16x32_bf16 v[96:99], v[182:185], v[206:209], v[96:99]
	v_mfma_f32_16x16x32_bf16 v[84:87], v[174:177], v[214:217], v[84:87]
	v_mfma_f32_16x16x32_bf16 v[80:83], v[182:185], v[214:217], v[80:83]
	v_mfma_f32_16x16x32_bf16 v[108:111], v[218:221], v[186:189], v[108:111]
	v_mfma_f32_16x16x32_bf16 v[104:107], v[226:229], v[186:189], v[104:107]
	v_mfma_f32_16x16x32_bf16 v[92:95], v[218:221], v[194:197], v[92:95]
	v_mfma_f32_16x16x32_bf16 v[88:91], v[226:229], v[194:197], v[88:91]
	v_mfma_f32_16x16x32_bf16 v[76:79], v[218:221], v[202:205], v[76:79]
	v_mfma_f32_16x16x32_bf16 v[72:75], v[226:229], v[202:205], v[72:75]
	v_mfma_f32_16x16x32_bf16 v[68:71], v[218:221], v[210:213], v[68:71]
	v_mfma_f32_16x16x32_bf16 v[64:67], v[226:229], v[210:213], v[64:67]
	v_mfma_f32_16x16x32_bf16 v[108:111], v[222:225], v[190:193], v[108:111]
	v_mfma_f32_16x16x32_bf16 v[104:107], v[230:233], v[190:193], v[104:107]
	v_mfma_f32_16x16x32_bf16 v[92:95], v[222:225], v[198:201], v[92:95]
	v_mfma_f32_16x16x32_bf16 v[88:91], v[230:233], v[198:201], v[88:91]
	v_mfma_f32_16x16x32_bf16 v[76:79], v[222:225], v[206:209], v[76:79]
	v_mfma_f32_16x16x32_bf16 v[72:75], v[230:233], v[206:209], v[72:75]
	v_mfma_f32_16x16x32_bf16 v[68:71], v[222:225], v[214:217], v[68:71]
	v_mfma_f32_16x16x32_bf16 v[64:67], v[230:233], v[214:217], v[64:67]
	s_setprio 0
	s_barrier
	s_mov_b32 m0, s50
	s_add_u32 s100, s34, 0x80
	s_addc_u32 s101, s35, 0
	global_load_lds_dwordx4 v130, s[100:101]
	s_mov_b32 m0, s51
	s_nop 0
	global_load_lds_dwordx4 v134, s[100:101]
	s_mov_b32 m0, s52
	ds_read_b128 v[186:189], v145 offset:49152
	ds_read_b128 v[190:193], v145 offset:50176
	ds_read_b128 v[194:197], v145 offset:51200
	ds_read_b128 v[198:201], v145 offset:52224
	ds_read_b128 v[202:205], v145 offset:53248
	ds_read_b128 v[206:209], v145 offset:54272
	ds_read_b128 v[210:213], v145 offset:55296
	ds_read_b128 v[214:217], v145 offset:56320
	s_add_u32 s100, s36, 0x80
	s_addc_u32 s101, s37, 0
	global_load_lds_dwordx4 v128, s[100:101]
	s_mov_b32 m0, s53
	s_nop 0
	global_load_lds_dwordx4 v132, s[100:101]
	s_waitcnt vmcnt(6)
	s_waitcnt lgkmcnt(0)
	s_barrier
	s_setprio 1
	v_mfma_f32_16x16x32_bf16 v[60:63], v[170:173], v[186:189], v[60:63]
	v_mfma_f32_16x16x32_bf16 v[56:59], v[178:181], v[186:189], v[56:59]
	v_mfma_f32_16x16x32_bf16 v[52:55], v[170:173], v[194:197], v[52:55]
	v_mfma_f32_16x16x32_bf16 v[48:51], v[178:181], v[194:197], v[48:51]
	v_mfma_f32_16x16x32_bf16 v[36:39], v[170:173], v[202:205], v[36:39]
	v_mfma_f32_16x16x32_bf16 v[32:35], v[178:181], v[202:205], v[32:35]
	v_mfma_f32_16x16x32_bf16 v[20:23], v[170:173], v[210:213], v[20:23]
	v_mfma_f32_16x16x32_bf16 v[16:19], v[178:181], v[210:213], v[16:19]
	v_mfma_f32_16x16x32_bf16 v[60:63], v[174:177], v[190:193], v[60:63]
	v_mfma_f32_16x16x32_bf16 v[56:59], v[182:185], v[190:193], v[56:59]
	v_mfma_f32_16x16x32_bf16 v[52:55], v[174:177], v[198:201], v[52:55]
	v_mfma_f32_16x16x32_bf16 v[48:51], v[182:185], v[198:201], v[48:51]
	v_mfma_f32_16x16x32_bf16 v[36:39], v[174:177], v[206:209], v[36:39]
	v_mfma_f32_16x16x32_bf16 v[32:35], v[182:185], v[206:209], v[32:35]
	v_mfma_f32_16x16x32_bf16 v[20:23], v[174:177], v[214:217], v[20:23]
	v_mfma_f32_16x16x32_bf16 v[16:19], v[182:185], v[214:217], v[16:19]
	v_mfma_f32_16x16x32_bf16 v[44:47], v[218:221], v[186:189], v[44:47]
	v_mfma_f32_16x16x32_bf16 v[40:43], v[226:229], v[186:189], v[40:43]
	v_mfma_f32_16x16x32_bf16 v[28:31], v[218:221], v[194:197], v[28:31]
	v_mfma_f32_16x16x32_bf16 v[24:27], v[226:229], v[194:197], v[24:27]
	v_mfma_f32_16x16x32_bf16 v[12:15], v[218:221], v[202:205], v[12:15]
	v_mfma_f32_16x16x32_bf16 v[8:11], v[226:229], v[202:205], v[8:11]
	v_mfma_f32_16x16x32_bf16 v[4:7], v[218:221], v[210:213], v[4:7]
	v_mfma_f32_16x16x32_bf16 v[0:3], v[226:229], v[210:213], v[0:3]
	v_mfma_f32_16x16x32_bf16 v[44:47], v[222:225], v[190:193], v[44:47]
	v_mfma_f32_16x16x32_bf16 v[40:43], v[230:233], v[190:193], v[40:43]
	v_mfma_f32_16x16x32_bf16 v[28:31], v[222:225], v[198:201], v[28:31]
	v_mfma_f32_16x16x32_bf16 v[24:27], v[230:233], v[198:201], v[24:27]
	v_mfma_f32_16x16x32_bf16 v[12:15], v[222:225], v[206:209], v[12:15]
	v_mfma_f32_16x16x32_bf16 v[8:11], v[230:233], v[206:209], v[8:11]
	v_mfma_f32_16x16x32_bf16 v[4:7], v[222:225], v[214:217], v[4:7]
	v_mfma_f32_16x16x32_bf16 v[0:3], v[230:233], v[214:217], v[0:3]
	s_setprio 0
	s_add_i32 s10, s10, 2
	s_add_u32 s68, s68, 0x100
	s_addc_u32 s69, s69, 0
	s_cmp_gt_u32 s10, 41
	s_mov_b64 s[28:29], s[30:31]
	s_barrier
;     DI void operator()(const f32x4 (&acc)[2][2][4][2], const Unit& u, int wr, int wc, int fr, int fq) const {
;         const int row0 = u.pm * BM + wr * 64 + fr, col0 = u.pn * BM + wc * 32 + 8 * fq;
; #pragma unroll
;         for (int ai = 0; ai < 2; ++ai)
; #pragma unroll
;             for (int m = 0; m < 4; ++m) { u16* rowp = O + (size_t)(row0 + ai * HALF + m * 16) * ldc + col0;
; #pragma unroll
;                 for (int bj = 0; bj < 2; ++bj) { const f32x4 v0 = acc[ai][bj][m][0], v1 = acc[ai][bj][m][1];
;                     uint4 w = {pack2(v0[0], v0[1]), pack2(v0[2], v0[3]), pack2(v1[0], v1[1]), pack2(v1[2], v1[3])}; *(uint4*)(rowp + bj * HALF) = w; } }
	s_cbranch_scc0 .LBB0_761
	v_lshl_add_u32 v170, s64, 8, v144
	v_lshl_or_b32 v172, s67, 8, v146
	v_ashrrev_i32_e32 v171, 31, v170
	v_ashrrev_i32_e32 v173, 31, v172
	v_lshlrev_b64 v[174:175], 11, v[170:171]
	v_lshl_add_u64 v[174:175], s[14:15], 0, v[174:175]
	v_lshlrev_b64 v[172:173], 1, v[172:173]
	v_lshl_add_u64 v[174:175], v[174:175], 0, v[172:173]
	v_cvt_pk_bf16_f32 v60, v60, v61
	v_cvt_pk_bf16_f32 v61, v62, v63
	v_cvt_pk_bf16_f32 v62, v56, v57
	v_add_co_u32_e32 v56, vcc, s60, v174
	v_cvt_pk_bf16_f32 v68, v68, v69
	v_cvt_pk_bf16_f32 v69, v70, v71
	v_cvt_pk_bf16_f32 v70, v64, v65
	v_lshl_add_u64 v[64:65], v[174:175], 0, s[16:17]
	v_addc_co_u32_e32 v57, vcc, 0, v175, vcc
	v_cvt_pk_bf16_f32 v44, v44, v45
	v_cvt_pk_bf16_f32 v45, v46, v47
	v_cvt_pk_bf16_f32 v46, v40, v41
	v_cvt_pk_bf16_f32 v47, v42, v43
	v_cvt_pk_bf16_f32 v108, v108, v109
	v_cvt_pk_bf16_f32 v109, v110, v111
	v_cvt_pk_bf16_f32 v110, v104, v105
	v_or_b32_e32 v104, 16, v170
	global_store_dwordx4 v[64:65], v[44:47], off offset:256
	v_ashrrev_i32_e32 v105, 31, v104
	v_cvt_pk_bf16_f32 v92, v92, v93
	v_add_co_u32_e32 v46, vcc, s61, v174
	v_cvt_pk_bf16_f32 v93, v94, v95
	v_cvt_pk_bf16_f32 v94, v88, v89
	v_or_b32_e32 v88, 32, v170
	v_lshl_add_u64 v[44:45], v[174:175], 0, s[18:19]
	v_addc_co_u32_e32 v47, vcc, 0, v175, vcc
	v_cvt_pk_bf16_f32 v28, v28, v29
	v_cvt_pk_bf16_f32 v29, v30, v31
	v_cvt_pk_bf16_f32 v30, v24, v25
	v_cvt_pk_bf16_f32 v31, v26, v27
	v_lshlrev_b64 v[104:105], 11, v[104:105]
	v_ashrrev_i32_e32 v89, 31, v88
	v_cvt_pk_bf16_f32 v76, v76, v77
	v_cvt_pk_bf16_f32 v77, v78, v79
	v_cvt_pk_bf16_f32 v78, v72, v73
	v_or_b32_e32 v72, 48, v170
	global_store_dwordx4 v[44:45], v[28:31], off offset:256
	v_cvt_pk_bf16_f32 v111, v106, v107
	v_lshl_add_u64 v[104:105], s[14:15], 0, v[104:105]
	v_add_co_u32_e32 v30, vcc, s62, v174
	v_lshlrev_b64 v[88:89], 11, v[88:89]
	v_ashrrev_i32_e32 v73, 31, v72
	v_lshl_add_u64 v[28:29], v[174:175], 0, s[20:21]
	v_addc_co_u32_e32 v31, vcc, 0, v175, vcc
	v_cvt_pk_bf16_f32 v12, v12, v13
	v_cvt_pk_bf16_f32 v13, v14, v15
	v_cvt_pk_bf16_f32 v14, v8, v9
	v_cvt_pk_bf16_f32 v15, v10, v11
	global_store_dwordx4 v[174:175], v[108:111], off offset:256
	v_cvt_pk_bf16_f32 v95, v90, v91
	v_lshl_add_u64 v[88:89], s[14:15], 0, v[88:89]
	v_lshl_add_u64 v[108:109], v[104:105], 0, v[172:173]
	v_lshlrev_b64 v[72:73], 11, v[72:73]
	global_store_dwordx4 v[28:29], v[12:15], off offset:256
	global_store_dwordx4 v[108:109], v[92:95], off offset:256
	v_cvt_pk_bf16_f32 v79, v74, v75
	v_add_co_u32_e32 v14, vcc, s63, v174
	v_lshl_add_u64 v[92:93], v[88:89], 0, v[172:173]
	v_lshl_add_u64 v[72:73], s[14:15], 0, v[72:73]
	v_addc_co_u32_e32 v15, vcc, 0, v175, vcc
	v_cvt_pk_bf16_f32 v124, v124, v125
	v_cvt_pk_bf16_f32 v125, v126, v127
	v_cvt_pk_bf16_f32 v126, v120, v121
	v_cvt_pk_bf16_f32 v127, v122, v123
	v_cvt_pk_bf16_f32 v104, v116, v117
	v_cvt_pk_bf16_f32 v105, v118, v119
	v_cvt_pk_bf16_f32 v106, v112, v113
	v_cvt_pk_bf16_f32 v107, v114, v115
	v_cvt_pk_bf16_f32 v88, v100, v101
	v_cvt_pk_bf16_f32 v89, v102, v103
	v_cvt_pk_bf16_f32 v90, v96, v97
	v_cvt_pk_bf16_f32 v91, v98, v99
	global_store_dwordx4 v[92:93], v[76:79], off offset:256
	v_cvt_pk_bf16_f32 v74, v80, v81
	v_cvt_pk_bf16_f32 v75, v82, v83
	v_lshl_add_u64 v[76:77], v[72:73], 0, v[172:173]
	v_cvt_pk_bf16_f32 v72, v84, v85
	v_cvt_pk_bf16_f32 v73, v86, v87
	v_cvt_pk_bf16_f32 v71, v66, v67
	v_cvt_pk_bf16_f32 v63, v58, v59
	v_cvt_pk_bf16_f32 v40, v52, v53
	v_cvt_pk_bf16_f32 v41, v54, v55
	v_cvt_pk_bf16_f32 v42, v48, v49
	v_cvt_pk_bf16_f32 v43, v50, v51
	v_cvt_pk_bf16_f32 v24, v36, v37
	v_cvt_pk_bf16_f32 v25, v38, v39
	v_cvt_pk_bf16_f32 v26, v32, v33
	v_cvt_pk_bf16_f32 v27, v34, v35
	v_lshl_add_u64 v[12:13], v[174:175], 0, s[26:27]
	v_cvt_pk_bf16_f32 v8, v20, v21
	v_cvt_pk_bf16_f32 v9, v22, v23
	v_cvt_pk_bf16_f32 v10, v16, v17
	v_cvt_pk_bf16_f32 v11, v18, v19
	v_cvt_pk_bf16_f32 v4, v4, v5
	v_cvt_pk_bf16_f32 v5, v6, v7
	v_cvt_pk_bf16_f32 v6, v0, v1
	v_cvt_pk_bf16_f32 v7, v2, v3
	s_and_b64 vcc, exec, s[2:3]
	s_mov_b32 s67, s65
	s_mov_b32 s64, s66
	s_mov_b64 s[30:31], s[0:1]
	s_mov_b64 s[28:29], s[4:5]
	global_store_dwordx4 v[174:175], v[124:127], off
	global_store_dwordx4 v[108:109], v[104:107], off
	global_store_dwordx4 v[92:93], v[88:91], off
	global_store_dwordx4 v[76:77], v[72:75], off
	global_store_dwordx4 v[76:77], v[68:71], off offset:256
	global_store_dwordx4 v[56:57], v[60:63], off
	global_store_dwordx4 v[46:47], v[40:43], off
	global_store_dwordx4 v[30:31], v[24:27], off
	global_store_dwordx4 v[14:15], v[8:11], off
	global_store_dwordx4 v[12:13], v[4:7], off offset:256
	s_cbranch_vccz .LBB0_750
	s_waitcnt vmcnt(0)
	s_cmpk_gt_u32 s40, 0xff
	s_cbranch_scc1 .LBB0_765
	s_barrier
